# g2 + GEMM K-loops: first iteration peeled (first MFMA per accumulator takes C=0), per-tile accumulator zero-init removed
# speedup vs baseline: 1.0469x; 1.0059x over previous
; #define G_GLOAD(XR, WR, KT) { _Pragma("unroll") for (int i_ = 0; i_ < 4; ++i_) XR[i_] = *(const u32x4*)(Xt + ((size_t)(64 * i_) * ldx + (KT) * 64) * 2 + xoff); \
;     _Pragma("unroll") for (int i_ = 0; i_ < 4; ++i_) WR[i_] = *(const u32x4*)(Wtb + ((size_t)(64 * i_) * K + (KT) * 64) * 2 + woff); }
; #define G_LSTORE(XR, WR, STG) { char* xs_ = lds + (STG) * G_STAGE; char* ws_ = xs_ + G_XB; \
;     _Pragma("unroll") for (int i_ = 0; i_ < 4; ++i_) *(u32x4*)(xs_ + (lrow + 64 * i_) * LROW + lch * 16) = XR[i_]; \
;     _Pragma("unroll") for (int i_ = 0; i_ < 4; ++i_) *(u32x4*)(ws_ + (lrow + 64 * i_) * LROW + lch * 16) = WR[i_]; }
; template <class Epi>
; DI void gemm_phase(const bf16_t* __restrict__ X, const int ldx, const bf16_t* __restrict__ Wt, const int N, const int K, const Epi& epi, char* lds) {
;     ...
;     const bool has_next = !Epi::kFull && (chunk + 8 < nchunks);
;     const int Ln = (has_next ? chunk + 8 : chunk) * 32 + slot, band_n = Ln / (4 * nNt), rem_n = Ln % (4 * nNt);
;     const char* Xt_n = (const char*)(X + (size_t)((band_n * 4 + (rem_n & 3)) * 256) * ldx);
;     const char* Wtb_n = (const char*)(Wt + (size_t)((rem_n >> 2) * 256) * K);
;     ...
;     asm volatile("" ::: "memory");
;     if (Epi::kFull || chunk == xcd) {
;       G_GLOAD(xr0, wr0, 0);
;       G_LSTORE(xr0, wr0, 0);
;       __syncthreads();
;       G_GLOAD(xr0, wr0, 1);
;     }
; #pragma unroll
;     for (int c = 0; c < 2; ++c)
; #pragma unroll
;       for (int a = 0; a < 2; ++a)
; #pragma unroll
;         for (int b = 0; b < 2; ++b)
; #pragma unroll
;           for (int i = 0; i < 16; ++i) acc[c][a][b][i] = 0.f;
.LBB0_85:
	s_add_i32 s46, s26, 8
	s_cmp_gt_u32 s26, 59
	s_cselect_b64 s[24:25], -1, 0
	s_cmp_lt_u32 s26, 60
	s_cselect_b32 s26, s46, s26
	s_cselect_b32 s5, 0, 15
	s_cselect_b32 s28, 1, 15
	s_lshl_b32 s26, s26, 5
	v_readlane_b32 s27, v254, 3
	s_add_i32 s26, s26, s27
	s_mul_hi_u32 s27, s26, 0xf0f0f0f1
	s_lshr_b32 s27, s27, 6
	s_mul_i32 s29, s27, 0x44
	s_sub_i32 s31, s26, s29
	s_lshl_b32 s26, s27, 10
	s_lshl_b32 s27, s31, 8
	s_and_b32 s27, s27, 0x300
	s_or_b32 s26, s27, s26
	s_ashr_i32 s27, s26, 31
	s_lshl_b64 s[26:27], s[26:27], 11
	s_add_u32 s29, s6, s26
	s_addc_u32 s30, s7, s27
	s_lshl_b32 s26, s31, 17
	s_and_b32 s26, s26, 0xf80000
	s_add_u32 s31, s44, s26
	v_mov_b32_e32 v2, 0
	s_addc_u32 s33, s45, 0
	s_mov_b32 s34, 3
	v_mov_b32_e32 v3, v2
	s_waitcnt vmcnt(5)
	s_waitcnt vmcnt(4)
	s_waitcnt vmcnt(3)
	s_waitcnt vmcnt(2)
	s_waitcnt vmcnt(1)
	s_waitcnt vmcnt(0)
	v_add_u32_e32 v232, s91, v162
	v_add_u32_e32 v233, s1, v162
	v_add_u32_e32 v234, s76, v162
	v_add_u32_e32 v235, v178, v179
	v_add_u32_e32 v236, v178, v180
	v_add_u32_e32 v237, v181, v173
	ds_read_b128 v[164:167], v235
	ds_read_b128 v[168:171], v235 offset:4608
	ds_read_b128 v[174:177], v236 offset:36864
	ds_read_b128 v[194:197], v236 offset:41472
	ds_read_b128 v[202:205], v236 offset:46080
	ds_read_b128 v[210:213], v236 offset:50688
	ds_read_b128 v[214:217], v184 offset:32
	ds_read_b128 v[218:221], v184 offset:4640
	s_add_i32 s35, s34, -3
	s_cmp_lt_u32 s35, 14
	s_cselect_b64 s[36:37], -1, 0
	s_and_b64 s[26:27], s[36:37], exec
	s_cselect_b32 s27, s11, s33
	s_cselect_b32 s26, s10, s31
	s_cselect_b32 s39, s9, s30
	s_cselect_b32 s38, s8, s29
	s_add_i32 s47, s34, -1
	s_waitcnt lgkmcnt(5)
	v_mfma_f32_32x32x16_bf16 v[114:129], v[174:177], v[164:167], 0
	v_mfma_f32_32x32x16_bf16 v[82:97], v[174:177], v[168:171], 0
	s_waitcnt lgkmcnt(4)
	v_mfma_f32_32x32x16_bf16 v[98:113], v[194:197], v[164:167], 0
	v_mfma_f32_32x32x16_bf16 v[66:81], v[194:197], v[168:171], 0
	s_waitcnt lgkmcnt(3)
	v_mfma_f32_32x32x16_bf16 v[50:65], v[202:205], v[164:167], 0
	s_and_b64 s[36:37], s[36:37], exec
	s_cselect_b32 s36, s47, s5
	v_mfma_f32_32x32x16_bf16 v[18:33], v[202:205], v[168:171], 0
	s_waitcnt lgkmcnt(2)
	v_mfma_f32_32x32x16_bf16 v[34:49], v[210:213], v[164:167], 0
	ds_read_b128 v[164:167], v185 offset:36896
	ds_read_b128 v[174:177], v185 offset:41504
	v_mfma_f32_32x32x16_bf16 v[2:17], v[210:213], v[168:171], 0
	s_lshl_b32 s96, s36, 7
	s_add_u32 s100, s38, s96
	s_addc_u32 s101, s39, 0
	s_waitcnt vmcnt(6)
	ds_write_b128 v186, v[142:145] offset:9216
	ds_write_b128 v186, v[134:137]
	global_load_dwordx4 v[134:137], v162, s[100:101]
	global_load_dwordx4 v[142:145], v232, s[100:101]
	s_waitcnt vmcnt(7)
	ds_write_b128 v186, v[130:133] offset:18432
	s_waitcnt vmcnt(6)
	ds_write_b128 v186, v[150:153] offset:27648
	global_load_dwordx4 v[130:133], v233, s[100:101]
	global_load_dwordx4 v[150:153], v234, s[100:101]
	ds_read_b128 v[168:171], v185 offset:46112
	ds_read_b128 v[194:197], v185 offset:50720
	ds_read_b128 v[202:205], v184 offset:64
	ds_read_b128 v[210:213], v184 offset:4672
	s_waitcnt lgkmcnt(9)
	v_mfma_f32_32x32x16_bf16 v[114:129], v[164:167], v[214:217], v[114:129]
	v_mfma_f32_32x32x16_bf16 v[82:97], v[164:167], v[218:221], v[82:97]
	s_waitcnt lgkmcnt(8)
	v_mfma_f32_32x32x16_bf16 v[98:113], v[174:177], v[214:217], v[98:113]
	v_mfma_f32_32x32x16_bf16 v[66:81], v[174:177], v[218:221], v[66:81]
	s_waitcnt lgkmcnt(3)
	v_mfma_f32_32x32x16_bf16 v[50:65], v[168:171], v[214:217], v[50:65]
	v_mfma_f32_32x32x16_bf16 v[18:33], v[168:171], v[218:221], v[18:33]
	ds_read_b128 v[164:167], v185 offset:36928
	ds_read_b128 v[168:171], v185 offset:41536
	s_waitcnt lgkmcnt(4)
	v_mfma_f32_32x32x16_bf16 v[34:49], v[194:197], v[214:217], v[34:49]
	v_mfma_f32_32x32x16_bf16 v[2:17], v[194:197], v[218:221], v[2:17]
	s_add_u32 s100, s26, s96
	s_addc_u32 s101, s27, 0
	s_waitcnt vmcnt(6)
	ds_write_b128 v187, v[154:157] offset:9216
	ds_write_b128 v187, v[138:141]
	global_load_dwordx4 v[138:141], v162, s[100:101]
	global_load_dwordx4 v[154:157], v232, s[100:101]
	ds_read_b128 v[174:177], v185 offset:46144
	ds_read_b128 v[194:197], v185 offset:50752
	ds_read_b128 v[214:217], v184 offset:96
	ds_read_b128 v[218:221], v184 offset:4704
	s_waitcnt lgkmcnt(7)
	v_mfma_f32_32x32x16_bf16 v[114:129], v[164:167], v[202:205], v[114:129]
	v_mfma_f32_32x32x16_bf16 v[82:97], v[164:167], v[210:213], v[82:97]
	s_waitcnt lgkmcnt(6)
	v_mfma_f32_32x32x16_bf16 v[98:113], v[168:171], v[202:205], v[98:113]
	v_mfma_f32_32x32x16_bf16 v[66:81], v[168:171], v[210:213], v[66:81]
	s_waitcnt lgkmcnt(3)
	v_mfma_f32_32x32x16_bf16 v[50:65], v[174:177], v[202:205], v[50:65]
	ds_read_b128 v[164:167], v185 offset:36960
	ds_read_b128 v[168:171], v185 offset:41568
	v_mfma_f32_32x32x16_bf16 v[18:33], v[174:177], v[210:213], v[18:33]
	s_waitcnt lgkmcnt(4)
	v_mfma_f32_32x32x16_bf16 v[34:49], v[194:197], v[202:205], v[34:49]
	v_mfma_f32_32x32x16_bf16 v[2:17], v[194:197], v[210:213], v[2:17]
	s_waitcnt vmcnt(7)
	ds_write_b128 v187, v[146:149] offset:18432
	s_waitcnt vmcnt(6)
	ds_write_b128 v187, v[158:161] offset:27648
	global_load_dwordx4 v[146:149], v233, s[100:101]
	global_load_dwordx4 v[158:161], v234, s[100:101]
	ds_read_b128 v[174:177], v185 offset:46176
	ds_read_b128 v[194:197], v185 offset:50784
	s_waitcnt lgkmcnt(5)
	v_mfma_f32_32x32x16_bf16 v[114:129], v[164:167], v[214:217], v[114:129]
	v_mfma_f32_32x32x16_bf16 v[82:97], v[164:167], v[218:221], v[82:97]
	s_waitcnt lgkmcnt(4)
	v_mfma_f32_32x32x16_bf16 v[98:113], v[168:171], v[214:217], v[98:113]
	v_mfma_f32_32x32x16_bf16 v[66:81], v[168:171], v[218:221], v[66:81]
	s_waitcnt lgkmcnt(1)
	v_mfma_f32_32x32x16_bf16 v[50:65], v[174:177], v[214:217], v[50:65]
	v_mfma_f32_32x32x16_bf16 v[18:33], v[174:177], v[218:221], v[18:33]
	s_waitcnt lgkmcnt(0)
	v_mfma_f32_32x32x16_bf16 v[34:49], v[194:197], v[214:217], v[34:49]
	v_mfma_f32_32x32x16_bf16 v[2:17], v[194:197], v[218:221], v[2:17]
	s_barrier
	ds_read_b128 v[164:167], v188
	ds_read_b128 v[168:171], v188 offset:4608
	ds_read_b128 v[174:177], v189
	ds_read_b128 v[194:197], v189 offset:4608
	ds_read_b128 v[202:205], v189 offset:9216
	ds_read_b128 v[210:213], v189 offset:13824
	ds_read_b128 v[214:217], v237 offset:32
	ds_read_b128 v[218:221], v190 offset:32
	s_cmp_lt_u32 s35, 13
	s_cselect_b64 s[26:27], -1, 0
	s_and_b64 s[26:27], s[26:27], exec
	s_cselect_b32 s37, s9, s30
	s_cselect_b32 s36, s8, s29
	s_cselect_b32 s27, s11, s33
	s_cselect_b32 s26, s10, s31
	s_waitcnt lgkmcnt(5)
	v_mfma_f32_32x32x16_bf16 v[114:129], v[174:177], v[164:167], v[114:129]
	v_mfma_f32_32x32x16_bf16 v[82:97], v[174:177], v[168:171], v[82:97]
	s_waitcnt lgkmcnt(4)
	v_mfma_f32_32x32x16_bf16 v[98:113], v[194:197], v[164:167], v[98:113]
	v_mfma_f32_32x32x16_bf16 v[66:81], v[194:197], v[168:171], v[66:81]
	s_waitcnt lgkmcnt(3)
	v_mfma_f32_32x32x16_bf16 v[50:65], v[202:205], v[164:167], v[50:65]
	v_add_u32_e32 v172, v182, v173
	s_cselect_b32 s38, s34, s28
	v_mfma_f32_32x32x16_bf16 v[18:33], v[202:205], v[168:171], v[18:33]
	s_waitcnt lgkmcnt(2)
	v_mfma_f32_32x32x16_bf16 v[34:49], v[210:213], v[164:167], v[34:49]
	ds_read_b128 v[164:167], v172 offset:32
	ds_read_b128 v[174:177], v191 offset:32
	v_mfma_f32_32x32x16_bf16 v[2:17], v[210:213], v[168:171], v[2:17]
	s_lshl_b32 s96, s38, 7
	s_add_u32 s100, s36, s96
	s_addc_u32 s101, s37, 0
	s_waitcnt vmcnt(6)
	ds_write_b128 v183, v[142:145] offset:9216
	ds_write_b128 v183, v[134:137]
	global_load_dwordx4 v[134:137], v162, s[100:101]
	global_load_dwordx4 v[142:145], v232, s[100:101]
	s_waitcnt vmcnt(7)
	ds_write_b128 v183, v[130:133] offset:18432
	s_waitcnt vmcnt(6)
	ds_write_b128 v183, v[150:153] offset:27648
	global_load_dwordx4 v[130:133], v233, s[100:101]
	global_load_dwordx4 v[150:153], v234, s[100:101]
	ds_read_b128 v[168:171], v208 offset:32
	ds_read_b128 v[194:197], v209 offset:32
	ds_read_b128 v[202:205], v237 offset:64
	ds_read_b128 v[210:213], v190 offset:64
	s_waitcnt lgkmcnt(9)
	v_mfma_f32_32x32x16_bf16 v[114:129], v[164:167], v[214:217], v[114:129]
	v_mfma_f32_32x32x16_bf16 v[82:97], v[164:167], v[218:221], v[82:97]
	s_waitcnt lgkmcnt(8)
	v_mfma_f32_32x32x16_bf16 v[98:113], v[174:177], v[214:217], v[98:113]
	v_mfma_f32_32x32x16_bf16 v[66:81], v[174:177], v[218:221], v[66:81]
	s_waitcnt lgkmcnt(3)
	v_mfma_f32_32x32x16_bf16 v[50:65], v[168:171], v[214:217], v[50:65]
	v_mfma_f32_32x32x16_bf16 v[18:33], v[168:171], v[218:221], v[18:33]
	ds_read_b128 v[164:167], v172 offset:64
	ds_read_b128 v[168:171], v191 offset:64
	s_waitcnt lgkmcnt(4)
	v_mfma_f32_32x32x16_bf16 v[34:49], v[194:197], v[214:217], v[34:49]
	v_mfma_f32_32x32x16_bf16 v[2:17], v[194:197], v[218:221], v[2:17]
	s_add_u32 s100, s26, s96
	s_addc_u32 s101, s27, 0
	s_waitcnt vmcnt(6)
	ds_write_b128 v183, v[154:157] offset:46080
	ds_write_b128 v183, v[138:141] offset:36864
	global_load_dwordx4 v[138:141], v162, s[100:101]
	global_load_dwordx4 v[154:157], v232, s[100:101]
	ds_read_b128 v[174:177], v208 offset:64
	ds_read_b128 v[194:197], v209 offset:64
	ds_read_b128 v[214:217], v237 offset:96
	ds_read_b128 v[218:221], v190 offset:96
	s_waitcnt lgkmcnt(7)
	v_mfma_f32_32x32x16_bf16 v[114:129], v[164:167], v[202:205], v[114:129]
	v_mfma_f32_32x32x16_bf16 v[82:97], v[164:167], v[210:213], v[82:97]
	s_waitcnt lgkmcnt(6)
	v_mfma_f32_32x32x16_bf16 v[98:113], v[168:171], v[202:205], v[98:113]
	v_mfma_f32_32x32x16_bf16 v[66:81], v[168:171], v[210:213], v[66:81]
	s_waitcnt lgkmcnt(3)
	v_mfma_f32_32x32x16_bf16 v[50:65], v[174:177], v[202:205], v[50:65]
	ds_read_b128 v[164:167], v172 offset:96
	ds_read_b128 v[168:171], v191 offset:96
	v_mfma_f32_32x32x16_bf16 v[18:33], v[174:177], v[210:213], v[18:33]
	s_waitcnt lgkmcnt(4)
	v_mfma_f32_32x32x16_bf16 v[34:49], v[194:197], v[202:205], v[34:49]
	v_mfma_f32_32x32x16_bf16 v[2:17], v[194:197], v[210:213], v[2:17]
	s_waitcnt vmcnt(7)
	ds_write_b128 v183, v[146:149] offset:55296
	s_waitcnt vmcnt(6)
	ds_write_b128 v183, v[158:161] offset:64512
	global_load_dwordx4 v[146:149], v233, s[100:101]
	global_load_dwordx4 v[158:161], v234, s[100:101]
	ds_read_b128 v[174:177], v208 offset:96
	ds_read_b128 v[194:197], v209 offset:96
	s_waitcnt lgkmcnt(5)
	v_mfma_f32_32x32x16_bf16 v[114:129], v[164:167], v[214:217], v[114:129]
	v_mfma_f32_32x32x16_bf16 v[82:97], v[164:167], v[218:221], v[82:97]
	s_waitcnt lgkmcnt(4)
	v_mfma_f32_32x32x16_bf16 v[98:113], v[168:171], v[214:217], v[98:113]
	v_mfma_f32_32x32x16_bf16 v[66:81], v[168:171], v[218:221], v[66:81]
	s_waitcnt lgkmcnt(1)
	v_mfma_f32_32x32x16_bf16 v[50:65], v[174:177], v[214:217], v[50:65]
	v_mfma_f32_32x32x16_bf16 v[18:33], v[174:177], v[218:221], v[18:33]
	s_waitcnt lgkmcnt(0)
	v_mfma_f32_32x32x16_bf16 v[34:49], v[194:197], v[214:217], v[34:49]
	v_mfma_f32_32x32x16_bf16 v[2:17], v[194:197], v[218:221], v[2:17]
	s_add_i32 s34, s34, 2
	s_cmp_gt_u32 s35, 13
	s_barrier
	s_cbranch_scc0 .LBB0_86
	s_branch .Lkexit_0

;   DI void operator()(int tok0, int feat0, f32x16 (&acc)[2][2], int r, int hh) const {
;     const int seg = feat0 >> 10, c0 = feat0 & 1023;
; #pragma unroll
;     for (int mt = 0; mt < 2; ++mt) {
;       const int tok = tok0 + mt * 32 + r, b = tok >> 14, s = tok & (SEQ - 1);
;       if (seg < 2) {
;     ...
;       } else if (feat0 == 4096) {
;         if (hh == 0) {
; #pragma unroll
;           for (int i = 0; i < 16; ++i) {
;             const float xv = acc[0][mt][i] + bf[i];
;             const float ls = fminf(xv, 0.f) - log1pf(expf(-fabsf(xv)));
;             lf[((size_t)(b * 16 + i)) * SEQ + s] = ls;
;           }
;         }
.Lkexit_0:
	v_mov_b32_e32 v212, v192
	s_ashr_i32 s47, s2, 14
	v_ashrrev_i32_e32 v164, 1, v212
	v_and_b32_e32 v164, 0xffffff80, v164
	v_bfe_u32 v0, v212, 5, 1
	v_add_u32_e32 v165, s3, v164
	s_movk_i32 s3, 0x1000
	v_ashrrev_i32_e32 v213, 10, v165
	v_and_b32_e32 v210, 0x380, v165
	v_and_b32_e32 v166, 0xdf, v212
	v_lshlrev_b32_e32 v211, 4, v0
	v_cmp_eq_u32_e32 vcc, s3, v165
	v_cmp_eq_u32_e64 s[10:11], 0, v0
	s_movk_i32 s3, 0x400
	v_mov_b32_e32 v0, s4
	v_or_b32_e32 v164, s4, v166
	v_cmp_lt_i32_e64 s[8:9], 1, v213
	v_or_b32_e32 v215, v210, v211
	s_and_b64 s[26:27], s[10:11], vcc
	v_cmp_gt_u32_e32 vcc, s3, v165
	v_bitop3_b32 v214, v166, s53, v0 bitop3:0xc8
	s_and_saveexec_b64 s[2:3], s[8:9]
	s_xor_b64 s[28:29], exec, s[2:3]
	s_cbranch_execz .LBB0_99
	v_cmp_lt_i32_e64 s[10:11], 2, v213
	s_and_saveexec_b64 s[2:3], s[10:11]
	s_xor_b64 s[30:31], exec, s[2:3]
	s_cbranch_execz .LBB0_96
	v_cmp_ne_u32_e64 s[10:11], 3, v213
	s_and_saveexec_b64 s[2:3], s[10:11]
	s_xor_b64 s[34:35], exec, s[2:3]
	s_cbranch_execz .LBB0_93
	s_and_saveexec_b64 s[36:37], s[26:27]
	s_cbranch_execz .LBB0_92
	v_lshlrev_b32_e32 v0, 2, v214
	v_lshl_add_u64 v[166:167], s[16:17], 0, v[0:1]
	global_load_dword v0, v1, s[18:19]
	v_mov_b32_e32 v197, 0x7f800000
	v_mov_b32_e32 v196, 0x3ecc95a3
	s_lshl_b32 s38, s47, 4
	s_ashr_i32 s39, s38, 31
	s_lshl_b64 s[2:3], s[38:39], 16
	s_waitcnt vmcnt(0)
	v_add_f32_e32 v0, v114, v0
	v_mul_f32_e64 v168, |v0|, s54
	v_fma_f32 v169, |v0|, s54, -v168
	v_rndne_f32_e32 v170, v168
	v_fma_f32 v169, |v0|, s55, v169
	v_sub_f32_e32 v168, v168, v170
	v_add_f32_e32 v168, v168, v169
	v_exp_f32_e32 v168, v168
	v_cvt_i32_f32_e32 v169, v170
	v_cmp_ngt_f32_e64 s[10:11], |v0|, s56
	v_min_f32_e32 v165, 0, v0
	v_ldexp_f32 v168, v168, v169
	v_cndmask_b32_e64 v168, 0, v168, s[10:11]
	v_cmp_nlt_f32_e64 s[10:11], |v0|, s57
	s_nop 1
	v_cndmask_b32_e64 v0, v197, v168, s[10:11]
	v_add_f32_e32 v170, 1.0, v0
	v_add_f32_e32 v168, -1.0, v170
	v_sub_f32_e32 v169, v168, v170
	v_add_f32_e32 v169, 1.0, v169
	v_sub_f32_e32 v168, v0, v168
	v_add_f32_e32 v171, v168, v169
	v_frexp_mant_f32_e32 v168, v170
	v_cmp_gt_f32_e64 s[10:11], s59, v168
	v_cvt_f64_f32_e32 v[168:169], v170
	v_frexp_exp_i32_f64_e32 v168, v[168:169]
	v_subbrev_co_u32_e64 v168, s[10:11], 0, v168, s[10:11]
	v_sub_u32_e32 v169, 0, v168
	v_ldexp_f32 v170, v170, v169
	v_ldexp_f32 v169, v171, v169
	v_add_f32_e32 v171, -1.0, v170
	v_add_f32_e32 v172, 1.0, v171
	v_sub_f32_e32 v172, v170, v172
	v_add_f32_e32 v172, v169, v172
	v_add_f32_e32 v174, v171, v172
	v_sub_f32_e32 v171, v171, v174
	v_add_f32_e32 v171, v172, v171
	v_add_f32_e32 v172, 1.0, v170
	v_add_f32_e32 v175, -1.0, v172
	v_sub_f32_e32 v170, v170, v175
	v_add_f32_e32 v169, v169, v170
	v_add_f32_e32 v170, v172, v169
	v_sub_f32_e32 v172, v172, v170
	v_add_f32_e32 v169, v169, v172
	v_rcp_f32_e32 v172, v170
	v_cvt_f32_i32_e32 v168, v168
	v_cmp_neq_f32_e64 s[10:11], s58, v0
	v_mul_f32_e32 v175, v174, v172
	v_mul_f32_e32 v176, v170, v175
	v_fma_f32 v177, v175, v170, -v176
	v_fmac_f32_e32 v177, v175, v169
	v_add_f32_e32 v194, v176, v177
	v_sub_f32_e32 v195, v174, v194
	v_sub_f32_e32 v174, v174, v195
	v_sub_f32_e32 v176, v194, v176
	v_sub_f32_e32 v174, v174, v194
	v_add_f32_e32 v171, v171, v174
	v_sub_f32_e32 v174, v176, v177
	v_add_f32_e32 v171, v174, v171
	v_add_f32_e32 v174, v195, v171
	v_mul_f32_e32 v176, v172, v174
	v_mul_f32_e32 v177, v170, v176
	v_fma_f32 v170, v176, v170, -v177
	v_fmac_f32_e32 v170, v176, v169
	v_sub_f32_e32 v169, v195, v174
	v_add_f32_e32 v169, v171, v169
	v_add_f32_e32 v171, v177, v170
	v_sub_f32_e32 v194, v174, v171
	v_sub_f32_e32 v174, v174, v194
	v_sub_f32_e32 v177, v171, v177
	v_sub_f32_e32 v171, v174, v171
	v_add_f32_e32 v169, v169, v171
	v_sub_f32_e32 v170, v177, v170
	v_add_f32_e32 v169, v170, v169
	v_add_f32_e32 v170, v175, v176
	v_add_f32_e32 v169, v194, v169
	v_sub_f32_e32 v171, v170, v175
	v_mul_f32_e32 v169, v172, v169
	v_sub_f32_e32 v171, v176, v171
	v_add_f32_e32 v169, v171, v169
	v_mul_f32_e32 v175, 0x3f317218, v168
	v_add_f32_e32 v171, v170, v169
	v_fma_f32 v176, v168, s60, -v175
	v_mul_f32_e32 v172, v171, v171
	v_fmac_f32_e32 v176, 0xb102e308, v168
	v_sub_f32_e32 v168, v171, v170
	v_fmamk_f32 v174, v172, 0x3e9b6dac, v196
	v_sub_f32_e32 v168, v169, v168
	v_add_f32_e32 v169, v175, v176
	v_fmaak_f32 v174, v172, v174, 0x3f2aaada
	v_sub_f32_e32 v170, v169, v175
	v_ldexp_f32 v175, v171, 1
	v_mul_f32_e32 v171, v171, v172
	v_mul_f32_e32 v171, v171, v174
	v_add_f32_e32 v172, v175, v171
	v_sub_f32_e32 v174, v172, v175
	v_ldexp_f32 v168, v168, 1
	v_sub_f32_e32 v171, v171, v174
	v_add_f32_e32 v168, v168, v171
	v_add_f32_e32 v171, v172, v168
	v_sub_f32_e32 v172, v171, v172
	v_sub_f32_e32 v168, v168, v172
	v_add_f32_e32 v172, v169, v171
	v_sub_f32_e32 v174, v172, v169
	v_sub_f32_e32 v175, v172, v174
	v_sub_f32_e32 v170, v176, v170
	v_sub_f32_e32 v169, v169, v175
	v_sub_f32_e32 v171, v171, v174
	v_add_f32_e32 v169, v171, v169
	v_add_f32_e32 v171, v170, v168
	v_sub_f32_e32 v174, v171, v170
	v_sub_f32_e32 v175, v171, v174
	v_sub_f32_e32 v170, v170, v175
	v_sub_f32_e32 v168, v168, v174
	v_add_f32_e32 v169, v171, v169
	v_add_f32_e32 v168, v168, v170
	v_add_f32_e32 v170, v172, v169
	v_sub_f32_e32 v171, v170, v172
	v_sub_f32_e32 v169, v169, v171
	v_add_f32_e32 v168, v168, v169
	v_add_f32_e32 v168, v170, v168
	v_cndmask_b32_e64 v168, v197, v168, s[10:11]
	v_cmp_lt_f32_e64 s[10:11], |v0|, s61
	s_nop 1
	v_cndmask_b32_e64 v0, v168, v0, s[10:11]
	v_sub_f32_e32 v0, v165, v0
	v_lshl_add_u64 v[168:169], v[166:167], 0, s[2:3]
	global_store_dword v[168:169], v0, off
	global_load_dword v0, v1, s[18:19] offset:4
	s_or_b32 s2, s38, 1
	s_ashr_i32 s3, s2, 31
	s_lshl_b64 s[2:3], s[2:3], 16
	s_waitcnt vmcnt(0)
;   DI void operator()(int tok0, int feat0, f32x16 (&acc)[2][2], int r, int hh) const {
;     ...
;           for (int i = 0; i < 16; ++i) {
;             const float xv = acc[0][mt][i] + bf[i];
;             const float ls = fminf(xv, 0.f) - log1pf(expf(-fabsf(xv)));
;             lf[((size_t)(b * 16 + i)) * SEQ + s] = ls;
	v_add_f32_e32 v0, v115, v0
	v_mul_f32_e64 v168, |v0|, s54
	v_fma_f32 v169, |v0|, s54, -v168
	v_rndne_f32_e32 v170, v168
	v_fma_f32 v169, |v0|, s55, v169
	v_sub_f32_e32 v168, v168, v170
	v_add_f32_e32 v168, v168, v169
	v_exp_f32_e32 v168, v168
	v_cvt_i32_f32_e32 v169, v170
	v_cmp_ngt_f32_e64 s[10:11], |v0|, s56
	v_min_f32_e32 v165, 0, v0
	v_ldexp_f32 v168, v168, v169
	v_cndmask_b32_e64 v168, 0, v168, s[10:11]
	v_cmp_nlt_f32_e64 s[10:11], |v0|, s57
	s_nop 1
	v_cndmask_b32_e64 v0, v197, v168, s[10:11]
	v_add_f32_e32 v170, 1.0, v0
	v_add_f32_e32 v168, -1.0, v170
	v_sub_f32_e32 v169, v168, v170
	v_add_f32_e32 v169, 1.0, v169
	v_sub_f32_e32 v168, v0, v168
	v_add_f32_e32 v171, v168, v169
	v_frexp_mant_f32_e32 v168, v170
	v_cmp_gt_f32_e64 s[10:11], s59, v168
	v_cvt_f64_f32_e32 v[168:169], v170
	v_frexp_exp_i32_f64_e32 v168, v[168:169]
	v_subbrev_co_u32_e64 v168, s[10:11], 0, v168, s[10:11]
	v_sub_u32_e32 v169, 0, v168
	v_ldexp_f32 v170, v170, v169
	v_ldexp_f32 v169, v171, v169
	v_add_f32_e32 v171, -1.0, v170
	v_add_f32_e32 v172, 1.0, v171
	v_sub_f32_e32 v172, v170, v172
	v_add_f32_e32 v172, v169, v172
	v_add_f32_e32 v174, v171, v172
	v_sub_f32_e32 v171, v171, v174
	v_add_f32_e32 v171, v172, v171
	v_add_f32_e32 v172, 1.0, v170
	v_add_f32_e32 v175, -1.0, v172
	v_sub_f32_e32 v170, v170, v175
	v_add_f32_e32 v169, v169, v170
	v_add_f32_e32 v170, v172, v169
	v_sub_f32_e32 v172, v172, v170
	v_add_f32_e32 v169, v169, v172
	v_rcp_f32_e32 v172, v170
	v_cvt_f32_i32_e32 v168, v168
	v_cmp_neq_f32_e64 s[10:11], s58, v0
	v_mul_f32_e32 v175, v174, v172
	v_mul_f32_e32 v176, v170, v175
	v_fma_f32 v177, v175, v170, -v176
	v_fmac_f32_e32 v177, v175, v169
	v_add_f32_e32 v194, v176, v177
	v_sub_f32_e32 v195, v174, v194
	v_sub_f32_e32 v174, v174, v195
	v_sub_f32_e32 v176, v194, v176
	v_sub_f32_e32 v174, v174, v194
	v_add_f32_e32 v171, v171, v174
	v_sub_f32_e32 v174, v176, v177
	v_add_f32_e32 v171, v174, v171
	v_add_f32_e32 v174, v195, v171
	v_mul_f32_e32 v176, v172, v174
	v_mul_f32_e32 v177, v170, v176
	v_fma_f32 v170, v176, v170, -v177
	v_fmac_f32_e32 v170, v176, v169
	v_sub_f32_e32 v169, v195, v174
	v_add_f32_e32 v169, v171, v169
	v_add_f32_e32 v171, v177, v170
	v_sub_f32_e32 v194, v174, v171
	v_sub_f32_e32 v174, v174, v194
	v_sub_f32_e32 v177, v171, v177
	v_sub_f32_e32 v171, v174, v171
	v_add_f32_e32 v169, v169, v171
	v_sub_f32_e32 v170, v177, v170
	v_add_f32_e32 v169, v170, v169
	v_add_f32_e32 v170, v175, v176
	v_add_f32_e32 v169, v194, v169
	v_sub_f32_e32 v171, v170, v175
	v_mul_f32_e32 v169, v172, v169
	v_sub_f32_e32 v171, v176, v171
	v_add_f32_e32 v169, v171, v169
	v_mul_f32_e32 v175, 0x3f317218, v168
	v_add_f32_e32 v171, v170, v169
	v_fma_f32 v176, v168, s60, -v175
	v_mul_f32_e32 v172, v171, v171
	v_fmac_f32_e32 v176, 0xb102e308, v168
	v_sub_f32_e32 v168, v171, v170
	v_fmamk_f32 v174, v172, 0x3e9b6dac, v196
	v_sub_f32_e32 v168, v169, v168
	v_add_f32_e32 v169, v175, v176
	v_fmaak_f32 v174, v172, v174, 0x3f2aaada
	v_sub_f32_e32 v170, v169, v175
	v_ldexp_f32 v175, v171, 1
	v_mul_f32_e32 v171, v171, v172
	v_mul_f32_e32 v171, v171, v174
	v_add_f32_e32 v172, v175, v171
	v_sub_f32_e32 v174, v172, v175
	v_ldexp_f32 v168, v168, 1
	v_sub_f32_e32 v171, v171, v174
	v_add_f32_e32 v168, v168, v171
	v_add_f32_e32 v171, v172, v168
	v_sub_f32_e32 v172, v171, v172
	v_sub_f32_e32 v168, v168, v172
	v_add_f32_e32 v172, v169, v171
	v_sub_f32_e32 v174, v172, v169
	v_sub_f32_e32 v175, v172, v174
	v_sub_f32_e32 v170, v176, v170
	v_sub_f32_e32 v169, v169, v175
	v_sub_f32_e32 v171, v171, v174
	v_add_f32_e32 v169, v171, v169
	v_add_f32_e32 v171, v170, v168
	v_sub_f32_e32 v174, v171, v170
	v_sub_f32_e32 v175, v171, v174
	v_sub_f32_e32 v170, v170, v175
	v_sub_f32_e32 v168, v168, v174
	v_add_f32_e32 v169, v171, v169
	v_add_f32_e32 v168, v168, v170
	v_add_f32_e32 v170, v172, v169
	v_sub_f32_e32 v171, v170, v172
	v_sub_f32_e32 v169, v169, v171
	v_add_f32_e32 v168, v168, v169
	v_add_f32_e32 v168, v170, v168
	v_cndmask_b32_e64 v168, v197, v168, s[10:11]
	v_cmp_lt_f32_e64 s[10:11], |v0|, s61
	s_nop 1
	v_cndmask_b32_e64 v0, v168, v0, s[10:11]
	v_sub_f32_e32 v0, v165, v0
	v_lshl_add_u64 v[168:169], v[166:167], 0, s[2:3]
	global_store_dword v[168:169], v0, off
	global_load_dword v0, v1, s[18:19] offset:8
	s_or_b32 s2, s38, 2
	s_ashr_i32 s3, s2, 31
	s_lshl_b64 s[2:3], s[2:3], 16
	s_waitcnt vmcnt(0)
;   DI void operator()(int tok0, int feat0, f32x16 (&acc)[2][2], int r, int hh) const {
;     ...
;           for (int i = 0; i < 16; ++i) {
;             const float xv = acc[0][mt][i] + bf[i];
;             const float ls = fminf(xv, 0.f) - log1pf(expf(-fabsf(xv)));
;             lf[((size_t)(b * 16 + i)) * SEQ + s] = ls;
	v_add_f32_e32 v0, v116, v0
	v_mul_f32_e64 v168, |v0|, s54
	v_fma_f32 v169, |v0|, s54, -v168
	v_rndne_f32_e32 v170, v168
	v_fma_f32 v169, |v0|, s55, v169
	v_sub_f32_e32 v168, v168, v170
	v_add_f32_e32 v168, v168, v169
	v_exp_f32_e32 v168, v168
	v_cvt_i32_f32_e32 v169, v170
	v_cmp_ngt_f32_e64 s[10:11], |v0|, s56
	v_min_f32_e32 v165, 0, v0
	v_ldexp_f32 v168, v168, v169
	v_cndmask_b32_e64 v168, 0, v168, s[10:11]
	v_cmp_nlt_f32_e64 s[10:11], |v0|, s57
	s_nop 1
	v_cndmask_b32_e64 v0, v197, v168, s[10:11]
	v_add_f32_e32 v170, 1.0, v0
	v_add_f32_e32 v168, -1.0, v170
	v_sub_f32_e32 v169, v168, v170
	v_add_f32_e32 v169, 1.0, v169
	v_sub_f32_e32 v168, v0, v168
	v_add_f32_e32 v171, v168, v169
	v_frexp_mant_f32_e32 v168, v170
	v_cmp_gt_f32_e64 s[10:11], s59, v168
	v_cvt_f64_f32_e32 v[168:169], v170
	v_frexp_exp_i32_f64_e32 v168, v[168:169]
	v_subbrev_co_u32_e64 v168, s[10:11], 0, v168, s[10:11]
	v_sub_u32_e32 v169, 0, v168
	v_ldexp_f32 v170, v170, v169
	v_ldexp_f32 v169, v171, v169
	v_add_f32_e32 v171, -1.0, v170
	v_add_f32_e32 v172, 1.0, v171
	v_sub_f32_e32 v172, v170, v172
	v_add_f32_e32 v172, v169, v172
	v_add_f32_e32 v174, v171, v172
	v_sub_f32_e32 v171, v171, v174
	v_add_f32_e32 v171, v172, v171
	v_add_f32_e32 v172, 1.0, v170
	v_add_f32_e32 v175, -1.0, v172
	v_sub_f32_e32 v170, v170, v175
	v_add_f32_e32 v169, v169, v170
	v_add_f32_e32 v170, v172, v169
	v_sub_f32_e32 v172, v172, v170
	v_add_f32_e32 v169, v169, v172
	v_rcp_f32_e32 v172, v170
	v_cvt_f32_i32_e32 v168, v168
	v_cmp_neq_f32_e64 s[10:11], s58, v0
	v_mul_f32_e32 v175, v174, v172
	v_mul_f32_e32 v176, v170, v175
	v_fma_f32 v177, v175, v170, -v176
	v_fmac_f32_e32 v177, v175, v169
	v_add_f32_e32 v194, v176, v177
	v_sub_f32_e32 v195, v174, v194
	v_sub_f32_e32 v174, v174, v195
	v_sub_f32_e32 v176, v194, v176
	v_sub_f32_e32 v174, v174, v194
	v_add_f32_e32 v171, v171, v174
	v_sub_f32_e32 v174, v176, v177
	v_add_f32_e32 v171, v174, v171
	v_add_f32_e32 v174, v195, v171
	v_mul_f32_e32 v176, v172, v174
	v_mul_f32_e32 v177, v170, v176
	v_fma_f32 v170, v176, v170, -v177
	v_fmac_f32_e32 v170, v176, v169
	v_sub_f32_e32 v169, v195, v174
	v_add_f32_e32 v169, v171, v169
	v_add_f32_e32 v171, v177, v170
	v_sub_f32_e32 v194, v174, v171
	v_sub_f32_e32 v174, v174, v194
	v_sub_f32_e32 v177, v171, v177
	v_sub_f32_e32 v171, v174, v171
	v_add_f32_e32 v169, v169, v171
	v_sub_f32_e32 v170, v177, v170
	v_add_f32_e32 v169, v170, v169
	v_add_f32_e32 v170, v175, v176
	v_add_f32_e32 v169, v194, v169
	v_sub_f32_e32 v171, v170, v175
	v_mul_f32_e32 v169, v172, v169
	v_sub_f32_e32 v171, v176, v171
	v_add_f32_e32 v169, v171, v169
	v_mul_f32_e32 v175, 0x3f317218, v168
	v_add_f32_e32 v171, v170, v169
	v_fma_f32 v176, v168, s60, -v175
	v_mul_f32_e32 v172, v171, v171
	v_fmac_f32_e32 v176, 0xb102e308, v168
	v_sub_f32_e32 v168, v171, v170
	v_fmamk_f32 v174, v172, 0x3e9b6dac, v196
	v_sub_f32_e32 v168, v169, v168
	v_add_f32_e32 v169, v175, v176
	v_fmaak_f32 v174, v172, v174, 0x3f2aaada
	v_sub_f32_e32 v170, v169, v175
	v_ldexp_f32 v175, v171, 1
	v_mul_f32_e32 v171, v171, v172
	v_mul_f32_e32 v171, v171, v174
	v_add_f32_e32 v172, v175, v171
	v_sub_f32_e32 v174, v172, v175
	v_ldexp_f32 v168, v168, 1
	v_sub_f32_e32 v171, v171, v174
	v_add_f32_e32 v168, v168, v171
	v_add_f32_e32 v171, v172, v168
	v_sub_f32_e32 v172, v171, v172
	v_sub_f32_e32 v168, v168, v172
	v_add_f32_e32 v172, v169, v171
	v_sub_f32_e32 v174, v172, v169
	v_sub_f32_e32 v175, v172, v174
	v_sub_f32_e32 v170, v176, v170
	v_sub_f32_e32 v169, v169, v175
	v_sub_f32_e32 v171, v171, v174
	v_add_f32_e32 v169, v171, v169
	v_add_f32_e32 v171, v170, v168
	v_sub_f32_e32 v174, v171, v170
	v_sub_f32_e32 v175, v171, v174
	v_sub_f32_e32 v170, v170, v175
	v_sub_f32_e32 v168, v168, v174
	v_add_f32_e32 v169, v171, v169
	v_add_f32_e32 v168, v168, v170
	v_add_f32_e32 v170, v172, v169
	v_sub_f32_e32 v171, v170, v172
	v_sub_f32_e32 v169, v169, v171
	v_add_f32_e32 v168, v168, v169
	v_add_f32_e32 v168, v170, v168
	v_cndmask_b32_e64 v168, v197, v168, s[10:11]
	v_cmp_lt_f32_e64 s[10:11], |v0|, s61
	s_nop 1
	v_cndmask_b32_e64 v0, v168, v0, s[10:11]
	v_sub_f32_e32 v0, v165, v0
	v_lshl_add_u64 v[168:169], v[166:167], 0, s[2:3]
	global_store_dword v[168:169], v0, off
	global_load_dword v0, v1, s[18:19] offset:12
	s_or_b32 s2, s38, 3
	s_ashr_i32 s3, s2, 31
	s_lshl_b64 s[2:3], s[2:3], 16
	s_waitcnt vmcnt(0)
;   DI void operator()(int tok0, int feat0, f32x16 (&acc)[2][2], int r, int hh) const {
;     ...
;           for (int i = 0; i < 16; ++i) {
;             const float xv = acc[0][mt][i] + bf[i];
;             const float ls = fminf(xv, 0.f) - log1pf(expf(-fabsf(xv)));
;             lf[((size_t)(b * 16 + i)) * SEQ + s] = ls;
	v_add_f32_e32 v0, v117, v0
	v_mul_f32_e64 v168, |v0|, s54
	v_fma_f32 v169, |v0|, s54, -v168
	v_rndne_f32_e32 v170, v168
	v_fma_f32 v169, |v0|, s55, v169
	v_sub_f32_e32 v168, v168, v170
	v_add_f32_e32 v168, v168, v169
	v_exp_f32_e32 v168, v168
	v_cvt_i32_f32_e32 v169, v170
	v_cmp_ngt_f32_e64 s[10:11], |v0|, s56
	v_min_f32_e32 v165, 0, v0
	v_ldexp_f32 v168, v168, v169
	v_cndmask_b32_e64 v168, 0, v168, s[10:11]
	v_cmp_nlt_f32_e64 s[10:11], |v0|, s57
	s_nop 1
	v_cndmask_b32_e64 v0, v197, v168, s[10:11]
	v_add_f32_e32 v170, 1.0, v0
	v_add_f32_e32 v168, -1.0, v170
	v_sub_f32_e32 v169, v168, v170
	v_add_f32_e32 v169, 1.0, v169
	v_sub_f32_e32 v168, v0, v168
	v_add_f32_e32 v171, v168, v169
	v_frexp_mant_f32_e32 v168, v170
	v_cmp_gt_f32_e64 s[10:11], s59, v168
	v_cvt_f64_f32_e32 v[168:169], v170
	v_frexp_exp_i32_f64_e32 v168, v[168:169]
	v_subbrev_co_u32_e64 v168, s[10:11], 0, v168, s[10:11]
	v_sub_u32_e32 v169, 0, v168
	v_ldexp_f32 v170, v170, v169
	v_ldexp_f32 v169, v171, v169
	v_add_f32_e32 v171, -1.0, v170
	v_add_f32_e32 v172, 1.0, v171
	v_sub_f32_e32 v172, v170, v172
	v_add_f32_e32 v172, v169, v172
	v_add_f32_e32 v174, v171, v172
	v_sub_f32_e32 v171, v171, v174
	v_add_f32_e32 v171, v172, v171
	v_add_f32_e32 v172, 1.0, v170
	v_add_f32_e32 v175, -1.0, v172
	v_sub_f32_e32 v170, v170, v175
	v_add_f32_e32 v169, v169, v170
	v_add_f32_e32 v170, v172, v169
	v_sub_f32_e32 v172, v172, v170
	v_add_f32_e32 v169, v169, v172
	v_rcp_f32_e32 v172, v170
	v_cvt_f32_i32_e32 v168, v168
	v_cmp_neq_f32_e64 s[10:11], s58, v0
	v_mul_f32_e32 v175, v174, v172
	v_mul_f32_e32 v176, v170, v175
	v_fma_f32 v177, v175, v170, -v176
	v_fmac_f32_e32 v177, v175, v169
	v_add_f32_e32 v194, v176, v177
	v_sub_f32_e32 v195, v174, v194
	v_sub_f32_e32 v174, v174, v195
	v_sub_f32_e32 v176, v194, v176
	v_sub_f32_e32 v174, v174, v194
	v_add_f32_e32 v171, v171, v174
	v_sub_f32_e32 v174, v176, v177
	v_add_f32_e32 v171, v174, v171
	v_add_f32_e32 v174, v195, v171
	v_mul_f32_e32 v176, v172, v174
	v_mul_f32_e32 v177, v170, v176
	v_fma_f32 v170, v176, v170, -v177
	v_fmac_f32_e32 v170, v176, v169
	v_sub_f32_e32 v169, v195, v174
	v_add_f32_e32 v169, v171, v169
	v_add_f32_e32 v171, v177, v170
	v_sub_f32_e32 v194, v174, v171
	v_sub_f32_e32 v174, v174, v194
	v_sub_f32_e32 v177, v171, v177
	v_sub_f32_e32 v171, v174, v171
	v_add_f32_e32 v169, v169, v171
	v_sub_f32_e32 v170, v177, v170
	v_add_f32_e32 v169, v170, v169
	v_add_f32_e32 v170, v175, v176
	v_add_f32_e32 v169, v194, v169
	v_sub_f32_e32 v171, v170, v175
	v_mul_f32_e32 v169, v172, v169
	v_sub_f32_e32 v171, v176, v171
	v_add_f32_e32 v169, v171, v169
	v_mul_f32_e32 v175, 0x3f317218, v168
	v_add_f32_e32 v171, v170, v169
	v_fma_f32 v176, v168, s60, -v175
	v_mul_f32_e32 v172, v171, v171
	v_fmac_f32_e32 v176, 0xb102e308, v168
	v_sub_f32_e32 v168, v171, v170
	v_fmamk_f32 v174, v172, 0x3e9b6dac, v196
	v_sub_f32_e32 v168, v169, v168
	v_add_f32_e32 v169, v175, v176
	v_fmaak_f32 v174, v172, v174, 0x3f2aaada
	v_sub_f32_e32 v170, v169, v175
	v_ldexp_f32 v175, v171, 1
	v_mul_f32_e32 v171, v171, v172
	v_mul_f32_e32 v171, v171, v174
	v_add_f32_e32 v172, v175, v171
	v_sub_f32_e32 v174, v172, v175
	v_ldexp_f32 v168, v168, 1
	v_sub_f32_e32 v171, v171, v174
	v_add_f32_e32 v168, v168, v171
	v_add_f32_e32 v171, v172, v168
	v_sub_f32_e32 v172, v171, v172
	v_sub_f32_e32 v168, v168, v172
	v_add_f32_e32 v172, v169, v171
	v_sub_f32_e32 v174, v172, v169
	v_sub_f32_e32 v175, v172, v174
	v_sub_f32_e32 v170, v176, v170
	v_sub_f32_e32 v169, v169, v175
	v_sub_f32_e32 v171, v171, v174
	v_add_f32_e32 v169, v171, v169
	v_add_f32_e32 v171, v170, v168
	v_sub_f32_e32 v174, v171, v170
	v_sub_f32_e32 v175, v171, v174
	v_sub_f32_e32 v170, v170, v175
	v_sub_f32_e32 v168, v168, v174
	v_add_f32_e32 v169, v171, v169
	v_add_f32_e32 v168, v168, v170
	v_add_f32_e32 v170, v172, v169
	v_sub_f32_e32 v171, v170, v172
	v_sub_f32_e32 v169, v169, v171
	v_add_f32_e32 v168, v168, v169
	v_add_f32_e32 v168, v170, v168
	v_cndmask_b32_e64 v168, v197, v168, s[10:11]
	v_cmp_lt_f32_e64 s[10:11], |v0|, s61
	s_nop 1
	v_cndmask_b32_e64 v0, v168, v0, s[10:11]
	v_sub_f32_e32 v0, v165, v0
	v_lshl_add_u64 v[168:169], v[166:167], 0, s[2:3]
	global_store_dword v[168:169], v0, off
	global_load_dword v0, v1, s[18:19] offset:16
	s_or_b32 s2, s38, 4
	s_ashr_i32 s3, s2, 31
	s_lshl_b64 s[2:3], s[2:3], 16
	s_waitcnt vmcnt(0)
;   DI void operator()(int tok0, int feat0, f32x16 (&acc)[2][2], int r, int hh) const {
;     ...
;           for (int i = 0; i < 16; ++i) {
;             const float xv = acc[0][mt][i] + bf[i];
;             const float ls = fminf(xv, 0.f) - log1pf(expf(-fabsf(xv)));
;             lf[((size_t)(b * 16 + i)) * SEQ + s] = ls;
	v_add_f32_e32 v0, v118, v0
	v_mul_f32_e64 v168, |v0|, s54
	v_fma_f32 v169, |v0|, s54, -v168
	v_rndne_f32_e32 v170, v168
	v_fma_f32 v169, |v0|, s55, v169
	v_sub_f32_e32 v168, v168, v170
	v_add_f32_e32 v168, v168, v169
	v_exp_f32_e32 v168, v168
	v_cvt_i32_f32_e32 v169, v170
	v_cmp_ngt_f32_e64 s[10:11], |v0|, s56
	v_min_f32_e32 v165, 0, v0
	v_ldexp_f32 v168, v168, v169
	v_cndmask_b32_e64 v168, 0, v168, s[10:11]
	v_cmp_nlt_f32_e64 s[10:11], |v0|, s57
	s_nop 1
	v_cndmask_b32_e64 v0, v197, v168, s[10:11]
	v_add_f32_e32 v170, 1.0, v0
	v_add_f32_e32 v168, -1.0, v170
	v_sub_f32_e32 v169, v168, v170
	v_add_f32_e32 v169, 1.0, v169
	v_sub_f32_e32 v168, v0, v168
	v_add_f32_e32 v171, v168, v169
	v_frexp_mant_f32_e32 v168, v170
	v_cmp_gt_f32_e64 s[10:11], s59, v168
	v_cvt_f64_f32_e32 v[168:169], v170
	v_frexp_exp_i32_f64_e32 v168, v[168:169]
	v_subbrev_co_u32_e64 v168, s[10:11], 0, v168, s[10:11]
	v_sub_u32_e32 v169, 0, v168
	v_ldexp_f32 v170, v170, v169
	v_ldexp_f32 v169, v171, v169
	v_add_f32_e32 v171, -1.0, v170
	v_add_f32_e32 v172, 1.0, v171
	v_sub_f32_e32 v172, v170, v172
	v_add_f32_e32 v172, v169, v172
	v_add_f32_e32 v174, v171, v172
	v_sub_f32_e32 v171, v171, v174
	v_add_f32_e32 v171, v172, v171
	v_add_f32_e32 v172, 1.0, v170
	v_add_f32_e32 v175, -1.0, v172
	v_sub_f32_e32 v170, v170, v175
	v_add_f32_e32 v169, v169, v170
	v_add_f32_e32 v170, v172, v169
	v_sub_f32_e32 v172, v172, v170
	v_add_f32_e32 v169, v169, v172
	v_rcp_f32_e32 v172, v170
	v_cvt_f32_i32_e32 v168, v168
	v_cmp_neq_f32_e64 s[10:11], s58, v0
	v_mul_f32_e32 v175, v174, v172
	v_mul_f32_e32 v176, v170, v175
	v_fma_f32 v177, v175, v170, -v176
	v_fmac_f32_e32 v177, v175, v169
	v_add_f32_e32 v194, v176, v177
	v_sub_f32_e32 v195, v174, v194
	v_sub_f32_e32 v174, v174, v195
	v_sub_f32_e32 v176, v194, v176
	v_sub_f32_e32 v174, v174, v194
	v_add_f32_e32 v171, v171, v174
	v_sub_f32_e32 v174, v176, v177
	v_add_f32_e32 v171, v174, v171
	v_add_f32_e32 v174, v195, v171
	v_mul_f32_e32 v176, v172, v174
	v_mul_f32_e32 v177, v170, v176
	v_fma_f32 v170, v176, v170, -v177
	v_fmac_f32_e32 v170, v176, v169
	v_sub_f32_e32 v169, v195, v174
	v_add_f32_e32 v169, v171, v169
	v_add_f32_e32 v171, v177, v170
	v_sub_f32_e32 v194, v174, v171
	v_sub_f32_e32 v174, v174, v194
	v_sub_f32_e32 v177, v171, v177
	v_sub_f32_e32 v171, v174, v171
	v_add_f32_e32 v169, v169, v171
	v_sub_f32_e32 v170, v177, v170
	v_add_f32_e32 v169, v170, v169
	v_add_f32_e32 v170, v175, v176
	v_add_f32_e32 v169, v194, v169
	v_sub_f32_e32 v171, v170, v175
	v_mul_f32_e32 v169, v172, v169
	v_sub_f32_e32 v171, v176, v171
	v_add_f32_e32 v169, v171, v169
	v_mul_f32_e32 v175, 0x3f317218, v168
	v_add_f32_e32 v171, v170, v169
	v_fma_f32 v176, v168, s60, -v175
	v_mul_f32_e32 v172, v171, v171
	v_fmac_f32_e32 v176, 0xb102e308, v168
	v_sub_f32_e32 v168, v171, v170
	v_fmamk_f32 v174, v172, 0x3e9b6dac, v196
	v_sub_f32_e32 v168, v169, v168
	v_add_f32_e32 v169, v175, v176
	v_fmaak_f32 v174, v172, v174, 0x3f2aaada
	v_sub_f32_e32 v170, v169, v175
	v_ldexp_f32 v175, v171, 1
	v_mul_f32_e32 v171, v171, v172
	v_mul_f32_e32 v171, v171, v174
	v_add_f32_e32 v172, v175, v171
	v_sub_f32_e32 v174, v172, v175
	v_ldexp_f32 v168, v168, 1
	v_sub_f32_e32 v171, v171, v174
	v_add_f32_e32 v168, v168, v171
	v_add_f32_e32 v171, v172, v168
	v_sub_f32_e32 v172, v171, v172
	v_sub_f32_e32 v168, v168, v172
	v_add_f32_e32 v172, v169, v171
	v_sub_f32_e32 v174, v172, v169
	v_sub_f32_e32 v175, v172, v174
	v_sub_f32_e32 v170, v176, v170
	v_sub_f32_e32 v169, v169, v175
	v_sub_f32_e32 v171, v171, v174
	v_add_f32_e32 v169, v171, v169
	v_add_f32_e32 v171, v170, v168
	v_sub_f32_e32 v174, v171, v170
	v_sub_f32_e32 v175, v171, v174
	v_sub_f32_e32 v170, v170, v175
	v_sub_f32_e32 v168, v168, v174
	v_add_f32_e32 v169, v171, v169
	v_add_f32_e32 v168, v168, v170
	v_add_f32_e32 v170, v172, v169
	v_sub_f32_e32 v171, v170, v172
	v_sub_f32_e32 v169, v169, v171
	v_add_f32_e32 v168, v168, v169
	v_add_f32_e32 v168, v170, v168
	v_cndmask_b32_e64 v168, v197, v168, s[10:11]
	v_cmp_lt_f32_e64 s[10:11], |v0|, s61
	s_nop 1
	v_cndmask_b32_e64 v0, v168, v0, s[10:11]
	v_sub_f32_e32 v0, v165, v0
	v_lshl_add_u64 v[168:169], v[166:167], 0, s[2:3]
	global_store_dword v[168:169], v0, off
	global_load_dword v0, v1, s[18:19] offset:20
	s_or_b32 s2, s38, 5
	s_ashr_i32 s3, s2, 31
	s_lshl_b64 s[2:3], s[2:3], 16
	s_waitcnt vmcnt(0)
;   DI void operator()(int tok0, int feat0, f32x16 (&acc)[2][2], int r, int hh) const {
;     ...
;           for (int i = 0; i < 16; ++i) {
;             const float xv = acc[0][mt][i] + bf[i];
;             const float ls = fminf(xv, 0.f) - log1pf(expf(-fabsf(xv)));
;             lf[((size_t)(b * 16 + i)) * SEQ + s] = ls;
	v_add_f32_e32 v0, v119, v0
	v_mul_f32_e64 v168, |v0|, s54
	v_fma_f32 v169, |v0|, s54, -v168
	v_rndne_f32_e32 v170, v168
	v_fma_f32 v169, |v0|, s55, v169
	v_sub_f32_e32 v168, v168, v170
	v_add_f32_e32 v168, v168, v169
	v_exp_f32_e32 v168, v168
	v_cvt_i32_f32_e32 v169, v170
	v_cmp_ngt_f32_e64 s[10:11], |v0|, s56
	v_min_f32_e32 v165, 0, v0
	v_ldexp_f32 v168, v168, v169
	v_cndmask_b32_e64 v168, 0, v168, s[10:11]
	v_cmp_nlt_f32_e64 s[10:11], |v0|, s57
	s_nop 1
	v_cndmask_b32_e64 v0, v197, v168, s[10:11]
	v_add_f32_e32 v170, 1.0, v0
	v_add_f32_e32 v168, -1.0, v170
	v_sub_f32_e32 v169, v168, v170
	v_add_f32_e32 v169, 1.0, v169
	v_sub_f32_e32 v168, v0, v168
	v_add_f32_e32 v171, v168, v169
	v_frexp_mant_f32_e32 v168, v170
	v_cmp_gt_f32_e64 s[10:11], s59, v168
	v_cvt_f64_f32_e32 v[168:169], v170
	v_frexp_exp_i32_f64_e32 v168, v[168:169]
	v_subbrev_co_u32_e64 v168, s[10:11], 0, v168, s[10:11]
	v_sub_u32_e32 v169, 0, v168
	v_ldexp_f32 v170, v170, v169
	v_ldexp_f32 v169, v171, v169
	v_add_f32_e32 v171, -1.0, v170
	v_add_f32_e32 v172, 1.0, v171
	v_sub_f32_e32 v172, v170, v172
	v_add_f32_e32 v172, v169, v172
	v_add_f32_e32 v174, v171, v172
	v_sub_f32_e32 v171, v171, v174
	v_add_f32_e32 v171, v172, v171
	v_add_f32_e32 v172, 1.0, v170
	v_add_f32_e32 v175, -1.0, v172
	v_sub_f32_e32 v170, v170, v175
	v_add_f32_e32 v169, v169, v170
	v_add_f32_e32 v170, v172, v169
	v_sub_f32_e32 v172, v172, v170
	v_add_f32_e32 v169, v169, v172
	v_rcp_f32_e32 v172, v170
	v_cvt_f32_i32_e32 v168, v168
	v_cmp_neq_f32_e64 s[10:11], s58, v0
	v_mul_f32_e32 v175, v174, v172
	v_mul_f32_e32 v176, v170, v175
	v_fma_f32 v177, v175, v170, -v176
	v_fmac_f32_e32 v177, v175, v169
	v_add_f32_e32 v194, v176, v177
	v_sub_f32_e32 v195, v174, v194
	v_sub_f32_e32 v174, v174, v195
	v_sub_f32_e32 v176, v194, v176
	v_sub_f32_e32 v174, v174, v194
	v_add_f32_e32 v171, v171, v174
	v_sub_f32_e32 v174, v176, v177
	v_add_f32_e32 v171, v174, v171
	v_add_f32_e32 v174, v195, v171
	v_mul_f32_e32 v176, v172, v174
	v_mul_f32_e32 v177, v170, v176
	v_fma_f32 v170, v176, v170, -v177
	v_fmac_f32_e32 v170, v176, v169
	v_sub_f32_e32 v169, v195, v174
	v_add_f32_e32 v169, v171, v169
	v_add_f32_e32 v171, v177, v170
	v_sub_f32_e32 v194, v174, v171
	v_sub_f32_e32 v174, v174, v194
	v_sub_f32_e32 v177, v171, v177
	v_sub_f32_e32 v171, v174, v171
	v_add_f32_e32 v169, v169, v171
	v_sub_f32_e32 v170, v177, v170
	v_add_f32_e32 v169, v170, v169
	v_add_f32_e32 v170, v175, v176
	v_add_f32_e32 v169, v194, v169
	v_sub_f32_e32 v171, v170, v175
	v_mul_f32_e32 v169, v172, v169
	v_sub_f32_e32 v171, v176, v171
	v_add_f32_e32 v169, v171, v169
	v_mul_f32_e32 v175, 0x3f317218, v168
	v_add_f32_e32 v171, v170, v169
	v_fma_f32 v176, v168, s60, -v175
	v_mul_f32_e32 v172, v171, v171
	v_fmac_f32_e32 v176, 0xb102e308, v168
	v_sub_f32_e32 v168, v171, v170
	v_fmamk_f32 v174, v172, 0x3e9b6dac, v196
	v_sub_f32_e32 v168, v169, v168
	v_add_f32_e32 v169, v175, v176
	v_fmaak_f32 v174, v172, v174, 0x3f2aaada
	v_sub_f32_e32 v170, v169, v175
	v_ldexp_f32 v175, v171, 1
	v_mul_f32_e32 v171, v171, v172
	v_mul_f32_e32 v171, v171, v174
	v_add_f32_e32 v172, v175, v171
	v_sub_f32_e32 v174, v172, v175
	v_ldexp_f32 v168, v168, 1
	v_sub_f32_e32 v171, v171, v174
	v_add_f32_e32 v168, v168, v171
	v_add_f32_e32 v171, v172, v168
	v_sub_f32_e32 v172, v171, v172
	v_sub_f32_e32 v168, v168, v172
	v_add_f32_e32 v172, v169, v171
	v_sub_f32_e32 v174, v172, v169
	v_sub_f32_e32 v175, v172, v174
	v_sub_f32_e32 v170, v176, v170
	v_sub_f32_e32 v169, v169, v175
	v_sub_f32_e32 v171, v171, v174
	v_add_f32_e32 v169, v171, v169
	v_add_f32_e32 v171, v170, v168
	v_sub_f32_e32 v174, v171, v170
	v_sub_f32_e32 v175, v171, v174
	v_sub_f32_e32 v170, v170, v175
	v_sub_f32_e32 v168, v168, v174
	v_add_f32_e32 v169, v171, v169
	v_add_f32_e32 v168, v168, v170
	v_add_f32_e32 v170, v172, v169
	v_sub_f32_e32 v171, v170, v172
	v_sub_f32_e32 v169, v169, v171
	v_add_f32_e32 v168, v168, v169
	v_add_f32_e32 v168, v170, v168
	v_cndmask_b32_e64 v168, v197, v168, s[10:11]
	v_cmp_lt_f32_e64 s[10:11], |v0|, s61
	s_nop 1
	v_cndmask_b32_e64 v0, v168, v0, s[10:11]
	v_sub_f32_e32 v0, v165, v0
	v_lshl_add_u64 v[168:169], v[166:167], 0, s[2:3]
	global_store_dword v[168:169], v0, off
	global_load_dword v0, v1, s[18:19] offset:24
	s_or_b32 s2, s38, 6
	s_ashr_i32 s3, s2, 31
	s_lshl_b64 s[2:3], s[2:3], 16
	s_waitcnt vmcnt(0)
;   DI void operator()(int tok0, int feat0, f32x16 (&acc)[2][2], int r, int hh) const {
;     ...
;           for (int i = 0; i < 16; ++i) {
;             const float xv = acc[0][mt][i] + bf[i];
;             const float ls = fminf(xv, 0.f) - log1pf(expf(-fabsf(xv)));
;             lf[((size_t)(b * 16 + i)) * SEQ + s] = ls;
	v_add_f32_e32 v0, v120, v0
	v_mul_f32_e64 v168, |v0|, s54
	v_fma_f32 v169, |v0|, s54, -v168
	v_rndne_f32_e32 v170, v168
	v_fma_f32 v169, |v0|, s55, v169
	v_sub_f32_e32 v168, v168, v170
	v_add_f32_e32 v168, v168, v169
	v_exp_f32_e32 v168, v168
	v_cvt_i32_f32_e32 v169, v170
	v_cmp_ngt_f32_e64 s[10:11], |v0|, s56
	v_min_f32_e32 v165, 0, v0
	v_ldexp_f32 v168, v168, v169
	v_cndmask_b32_e64 v168, 0, v168, s[10:11]
	v_cmp_nlt_f32_e64 s[10:11], |v0|, s57
	s_nop 1
	v_cndmask_b32_e64 v0, v197, v168, s[10:11]
	v_add_f32_e32 v170, 1.0, v0
	v_add_f32_e32 v168, -1.0, v170
	v_sub_f32_e32 v169, v168, v170
	v_add_f32_e32 v169, 1.0, v169
	v_sub_f32_e32 v168, v0, v168
	v_add_f32_e32 v171, v168, v169
	v_frexp_mant_f32_e32 v168, v170
	v_cmp_gt_f32_e64 s[10:11], s59, v168
	v_cvt_f64_f32_e32 v[168:169], v170
	v_frexp_exp_i32_f64_e32 v168, v[168:169]
	v_subbrev_co_u32_e64 v168, s[10:11], 0, v168, s[10:11]
	v_sub_u32_e32 v169, 0, v168
	v_ldexp_f32 v170, v170, v169
	v_ldexp_f32 v169, v171, v169
	v_add_f32_e32 v171, -1.0, v170
	v_add_f32_e32 v172, 1.0, v171
	v_sub_f32_e32 v172, v170, v172
	v_add_f32_e32 v172, v169, v172
	v_add_f32_e32 v174, v171, v172
	v_sub_f32_e32 v171, v171, v174
	v_add_f32_e32 v171, v172, v171
	v_add_f32_e32 v172, 1.0, v170
	v_add_f32_e32 v175, -1.0, v172
	v_sub_f32_e32 v170, v170, v175
	v_add_f32_e32 v169, v169, v170
	v_add_f32_e32 v170, v172, v169
	v_sub_f32_e32 v172, v172, v170
	v_add_f32_e32 v169, v169, v172
	v_rcp_f32_e32 v172, v170
	v_cvt_f32_i32_e32 v168, v168
	v_cmp_neq_f32_e64 s[10:11], s58, v0
	v_mul_f32_e32 v175, v174, v172
	v_mul_f32_e32 v176, v170, v175
	v_fma_f32 v177, v175, v170, -v176
	v_fmac_f32_e32 v177, v175, v169
	v_add_f32_e32 v194, v176, v177
	v_sub_f32_e32 v195, v174, v194
	v_sub_f32_e32 v174, v174, v195
	v_sub_f32_e32 v176, v194, v176
	v_sub_f32_e32 v174, v174, v194
	v_add_f32_e32 v171, v171, v174
	v_sub_f32_e32 v174, v176, v177
	v_add_f32_e32 v171, v174, v171
	v_add_f32_e32 v174, v195, v171
	v_mul_f32_e32 v176, v172, v174
	v_mul_f32_e32 v177, v170, v176
	v_fma_f32 v170, v176, v170, -v177
	v_fmac_f32_e32 v170, v176, v169
	v_sub_f32_e32 v169, v195, v174
	v_add_f32_e32 v169, v171, v169
	v_add_f32_e32 v171, v177, v170
	v_sub_f32_e32 v194, v174, v171
	v_sub_f32_e32 v174, v174, v194
	v_sub_f32_e32 v177, v171, v177
	v_sub_f32_e32 v171, v174, v171
	v_add_f32_e32 v169, v169, v171
	v_sub_f32_e32 v170, v177, v170
	v_add_f32_e32 v169, v170, v169
	v_add_f32_e32 v170, v175, v176
	v_add_f32_e32 v169, v194, v169
	v_sub_f32_e32 v171, v170, v175
	v_mul_f32_e32 v169, v172, v169
	v_sub_f32_e32 v171, v176, v171
	v_add_f32_e32 v169, v171, v169
	v_mul_f32_e32 v175, 0x3f317218, v168
	v_add_f32_e32 v171, v170, v169
	v_fma_f32 v176, v168, s60, -v175
	v_mul_f32_e32 v172, v171, v171
	v_fmac_f32_e32 v176, 0xb102e308, v168
	v_sub_f32_e32 v168, v171, v170
	v_fmamk_f32 v174, v172, 0x3e9b6dac, v196
	v_sub_f32_e32 v168, v169, v168
	v_add_f32_e32 v169, v175, v176
	v_fmaak_f32 v174, v172, v174, 0x3f2aaada
	v_sub_f32_e32 v170, v169, v175
	v_ldexp_f32 v175, v171, 1
	v_mul_f32_e32 v171, v171, v172
	v_mul_f32_e32 v171, v171, v174
	v_add_f32_e32 v172, v175, v171
	v_sub_f32_e32 v174, v172, v175
	v_ldexp_f32 v168, v168, 1
	v_sub_f32_e32 v171, v171, v174
	v_add_f32_e32 v168, v168, v171
	v_add_f32_e32 v171, v172, v168
	v_sub_f32_e32 v172, v171, v172
	v_sub_f32_e32 v168, v168, v172
	v_add_f32_e32 v172, v169, v171
	v_sub_f32_e32 v174, v172, v169
	v_sub_f32_e32 v175, v172, v174
	v_sub_f32_e32 v170, v176, v170
	v_sub_f32_e32 v169, v169, v175
	v_sub_f32_e32 v171, v171, v174
	v_add_f32_e32 v169, v171, v169
	v_add_f32_e32 v171, v170, v168
	v_sub_f32_e32 v174, v171, v170
	v_sub_f32_e32 v175, v171, v174
	v_sub_f32_e32 v170, v170, v175
	v_sub_f32_e32 v168, v168, v174
	v_add_f32_e32 v169, v171, v169
	v_add_f32_e32 v168, v168, v170
	v_add_f32_e32 v170, v172, v169
	v_sub_f32_e32 v171, v170, v172
	v_sub_f32_e32 v169, v169, v171
	v_add_f32_e32 v168, v168, v169
	v_add_f32_e32 v168, v170, v168
	v_cndmask_b32_e64 v168, v197, v168, s[10:11]
	v_cmp_lt_f32_e64 s[10:11], |v0|, s61
	s_nop 1
	v_cndmask_b32_e64 v0, v168, v0, s[10:11]
	v_sub_f32_e32 v0, v165, v0
	v_lshl_add_u64 v[168:169], v[166:167], 0, s[2:3]
	global_store_dword v[168:169], v0, off
	global_load_dword v0, v1, s[18:19] offset:28
	s_or_b32 s2, s38, 7
	s_ashr_i32 s3, s2, 31
	s_lshl_b64 s[2:3], s[2:3], 16
	s_waitcnt vmcnt(0)
;   DI void operator()(int tok0, int feat0, f32x16 (&acc)[2][2], int r, int hh) const {
;     ...
;           for (int i = 0; i < 16; ++i) {
;             const float xv = acc[0][mt][i] + bf[i];
;             const float ls = fminf(xv, 0.f) - log1pf(expf(-fabsf(xv)));
;             lf[((size_t)(b * 16 + i)) * SEQ + s] = ls;
;           }
	v_add_f32_e32 v0, v121, v0
	v_mul_f32_e64 v168, |v0|, s54
	v_fma_f32 v169, |v0|, s54, -v168
	v_rndne_f32_e32 v170, v168
	v_fma_f32 v169, |v0|, s55, v169
	v_sub_f32_e32 v168, v168, v170
	v_add_f32_e32 v168, v168, v169
	v_exp_f32_e32 v168, v168
	v_cvt_i32_f32_e32 v169, v170
	v_cmp_ngt_f32_e64 s[10:11], |v0|, s56
	v_min_f32_e32 v165, 0, v0
	v_ldexp_f32 v168, v168, v169
	v_cndmask_b32_e64 v168, 0, v168, s[10:11]
	v_cmp_nlt_f32_e64 s[10:11], |v0|, s57
	s_nop 1
	v_cndmask_b32_e64 v0, v197, v168, s[10:11]
	v_add_f32_e32 v170, 1.0, v0
	v_add_f32_e32 v168, -1.0, v170
	v_sub_f32_e32 v169, v168, v170
	v_add_f32_e32 v169, 1.0, v169
	v_sub_f32_e32 v168, v0, v168
	v_add_f32_e32 v171, v168, v169
	v_frexp_mant_f32_e32 v168, v170
	v_cmp_gt_f32_e64 s[10:11], s59, v168
	v_cvt_f64_f32_e32 v[168:169], v170
	v_frexp_exp_i32_f64_e32 v168, v[168:169]
	v_subbrev_co_u32_e64 v168, s[10:11], 0, v168, s[10:11]
	v_sub_u32_e32 v169, 0, v168
	v_ldexp_f32 v170, v170, v169
	v_ldexp_f32 v169, v171, v169
	v_add_f32_e32 v171, -1.0, v170
	v_add_f32_e32 v172, 1.0, v171
	v_sub_f32_e32 v172, v170, v172
	v_add_f32_e32 v172, v169, v172
	v_add_f32_e32 v174, v171, v172
	v_sub_f32_e32 v171, v171, v174
	v_add_f32_e32 v171, v172, v171
	v_add_f32_e32 v172, 1.0, v170
	v_add_f32_e32 v175, -1.0, v172
	v_sub_f32_e32 v170, v170, v175
	v_add_f32_e32 v169, v169, v170
	v_add_f32_e32 v170, v172, v169
	v_sub_f32_e32 v172, v172, v170
	v_add_f32_e32 v169, v169, v172
	v_rcp_f32_e32 v172, v170
	v_cvt_f32_i32_e32 v168, v168
	v_cmp_neq_f32_e64 s[10:11], s58, v0
	v_mul_f32_e32 v175, v174, v172
	v_mul_f32_e32 v176, v170, v175
	v_fma_f32 v177, v175, v170, -v176
	v_fmac_f32_e32 v177, v175, v169
	v_add_f32_e32 v194, v176, v177
	v_sub_f32_e32 v195, v174, v194
	v_sub_f32_e32 v174, v174, v195
	v_sub_f32_e32 v176, v194, v176
	v_sub_f32_e32 v174, v174, v194
	v_add_f32_e32 v171, v171, v174
	v_sub_f32_e32 v174, v176, v177
	v_add_f32_e32 v171, v174, v171
	v_add_f32_e32 v174, v195, v171
	v_mul_f32_e32 v176, v172, v174
	v_mul_f32_e32 v177, v170, v176
	v_fma_f32 v170, v176, v170, -v177
	v_fmac_f32_e32 v170, v176, v169
	v_sub_f32_e32 v169, v195, v174
	v_add_f32_e32 v169, v171, v169
	v_add_f32_e32 v171, v177, v170
	v_sub_f32_e32 v194, v174, v171
	v_sub_f32_e32 v174, v174, v194
	v_sub_f32_e32 v177, v171, v177
	v_sub_f32_e32 v171, v174, v171
	v_add_f32_e32 v169, v169, v171
	v_sub_f32_e32 v170, v177, v170
	v_add_f32_e32 v169, v170, v169
	v_add_f32_e32 v170, v175, v176
	v_add_f32_e32 v169, v194, v169
	v_sub_f32_e32 v171, v170, v175
	v_mul_f32_e32 v169, v172, v169
	v_sub_f32_e32 v171, v176, v171
	v_add_f32_e32 v169, v171, v169
	v_mul_f32_e32 v175, 0x3f317218, v168
	v_add_f32_e32 v171, v170, v169
	v_fma_f32 v176, v168, s60, -v175
	v_mul_f32_e32 v172, v171, v171
	v_fmac_f32_e32 v176, 0xb102e308, v168
	v_sub_f32_e32 v168, v171, v170
	v_fmamk_f32 v174, v172, 0x3e9b6dac, v196
	v_sub_f32_e32 v168, v169, v168
	v_add_f32_e32 v169, v175, v176
	v_fmaak_f32 v174, v172, v174, 0x3f2aaada
	v_sub_f32_e32 v170, v169, v175
	v_ldexp_f32 v175, v171, 1
	v_mul_f32_e32 v171, v171, v172
	v_mul_f32_e32 v171, v171, v174
	v_add_f32_e32 v172, v175, v171
	v_sub_f32_e32 v174, v172, v175
	v_ldexp_f32 v168, v168, 1
	v_sub_f32_e32 v171, v171, v174
	v_add_f32_e32 v168, v168, v171
	v_add_f32_e32 v171, v172, v168
	v_sub_f32_e32 v172, v171, v172
	v_sub_f32_e32 v168, v168, v172
	v_add_f32_e32 v172, v169, v171
	v_sub_f32_e32 v174, v172, v169
	v_sub_f32_e32 v175, v172, v174
	v_sub_f32_e32 v170, v176, v170
	v_sub_f32_e32 v169, v169, v175
	v_sub_f32_e32 v171, v171, v174
	v_add_f32_e32 v169, v171, v169
	v_add_f32_e32 v171, v170, v168
	v_sub_f32_e32 v174, v171, v170
	v_sub_f32_e32 v175, v171, v174
	v_sub_f32_e32 v170, v170, v175
	v_sub_f32_e32 v168, v168, v174
	v_add_f32_e32 v169, v171, v169
	v_add_f32_e32 v168, v168, v170
	v_add_f32_e32 v170, v172, v169
	v_sub_f32_e32 v171, v170, v172
	v_sub_f32_e32 v169, v169, v171
	v_add_f32_e32 v168, v168, v169
	v_add_f32_e32 v168, v170, v168
	v_cndmask_b32_e64 v168, v197, v168, s[10:11]
	v_cmp_lt_f32_e64 s[10:11], |v0|, s61
	s_nop 1
	v_cndmask_b32_e64 v0, v168, v0, s[10:11]
	v_sub_f32_e32 v0, v165, v0
	v_lshl_add_u64 v[168:169], v[166:167], 0, s[2:3]
	global_store_dword v[168:169], v0, off
	global_load_dword v0, v1, s[18:19] offset:32
	s_or_b32 s2, s38, 8
	s_ashr_i32 s3, s2, 31
	s_lshl_b64 s[2:3], s[2:3], 16
	s_waitcnt vmcnt(0)
;   DI void operator()(int tok0, int feat0, f32x16 (&acc)[2][2], int r, int hh) const {
;     ...
;           for (int i = 0; i < 16; ++i) {
;             const float xv = acc[0][mt][i] + bf[i];
;             const float ls = fminf(xv, 0.f) - log1pf(expf(-fabsf(xv)));
;             lf[((size_t)(b * 16 + i)) * SEQ + s] = ls;
;           }
	v_add_f32_e32 v0, v122, v0
	v_mul_f32_e64 v168, |v0|, s54
	v_fma_f32 v169, |v0|, s54, -v168
	v_rndne_f32_e32 v170, v168
	v_fma_f32 v169, |v0|, s55, v169
	v_sub_f32_e32 v168, v168, v170
	v_add_f32_e32 v168, v168, v169
	v_exp_f32_e32 v168, v168
	v_cvt_i32_f32_e32 v169, v170
	v_cmp_ngt_f32_e64 s[10:11], |v0|, s56
	v_min_f32_e32 v165, 0, v0
	v_ldexp_f32 v168, v168, v169
	v_cndmask_b32_e64 v168, 0, v168, s[10:11]
	v_cmp_nlt_f32_e64 s[10:11], |v0|, s57
	s_nop 1
	v_cndmask_b32_e64 v0, v197, v168, s[10:11]
	v_add_f32_e32 v170, 1.0, v0
	v_add_f32_e32 v168, -1.0, v170
	v_sub_f32_e32 v169, v168, v170
	v_add_f32_e32 v169, 1.0, v169
	v_sub_f32_e32 v168, v0, v168
	v_add_f32_e32 v171, v168, v169
	v_frexp_mant_f32_e32 v168, v170
	v_cmp_gt_f32_e64 s[10:11], s59, v168
	v_cvt_f64_f32_e32 v[168:169], v170
	v_frexp_exp_i32_f64_e32 v168, v[168:169]
	v_subbrev_co_u32_e64 v168, s[10:11], 0, v168, s[10:11]
	v_sub_u32_e32 v169, 0, v168
	v_ldexp_f32 v170, v170, v169
	v_ldexp_f32 v169, v171, v169
	v_add_f32_e32 v171, -1.0, v170
	v_add_f32_e32 v172, 1.0, v171
	v_sub_f32_e32 v172, v170, v172
	v_add_f32_e32 v172, v169, v172
	v_add_f32_e32 v174, v171, v172
	v_sub_f32_e32 v171, v171, v174
	v_add_f32_e32 v171, v172, v171
	v_add_f32_e32 v172, 1.0, v170
	v_add_f32_e32 v175, -1.0, v172
	v_sub_f32_e32 v170, v170, v175
	v_add_f32_e32 v169, v169, v170
	v_add_f32_e32 v170, v172, v169
	v_sub_f32_e32 v172, v172, v170
	v_add_f32_e32 v169, v169, v172
	v_rcp_f32_e32 v172, v170
	v_cvt_f32_i32_e32 v168, v168
	v_cmp_neq_f32_e64 s[10:11], s58, v0
	v_mul_f32_e32 v175, v174, v172
	v_mul_f32_e32 v176, v170, v175
	v_fma_f32 v177, v175, v170, -v176
	v_fmac_f32_e32 v177, v175, v169
	v_add_f32_e32 v194, v176, v177
	v_sub_f32_e32 v195, v174, v194
	v_sub_f32_e32 v174, v174, v195
	v_sub_f32_e32 v176, v194, v176
	v_sub_f32_e32 v174, v174, v194
	v_add_f32_e32 v171, v171, v174
	v_sub_f32_e32 v174, v176, v177
	v_add_f32_e32 v171, v174, v171
	v_add_f32_e32 v174, v195, v171
	v_mul_f32_e32 v176, v172, v174
	v_mul_f32_e32 v177, v170, v176
	v_fma_f32 v170, v176, v170, -v177
	v_fmac_f32_e32 v170, v176, v169
	v_sub_f32_e32 v169, v195, v174
	v_add_f32_e32 v169, v171, v169
	v_add_f32_e32 v171, v177, v170
	v_sub_f32_e32 v194, v174, v171
	v_sub_f32_e32 v174, v174, v194
	v_sub_f32_e32 v177, v171, v177
	v_sub_f32_e32 v171, v174, v171
	v_add_f32_e32 v169, v169, v171
	v_sub_f32_e32 v170, v177, v170
	v_add_f32_e32 v169, v170, v169
	v_add_f32_e32 v170, v175, v176
	v_add_f32_e32 v169, v194, v169
	v_sub_f32_e32 v171, v170, v175
	v_mul_f32_e32 v169, v172, v169
	v_sub_f32_e32 v171, v176, v171
	v_add_f32_e32 v169, v171, v169
	v_mul_f32_e32 v175, 0x3f317218, v168
	v_add_f32_e32 v171, v170, v169
	v_fma_f32 v176, v168, s60, -v175
	v_mul_f32_e32 v172, v171, v171
	v_fmac_f32_e32 v176, 0xb102e308, v168
	v_sub_f32_e32 v168, v171, v170
	v_fmamk_f32 v174, v172, 0x3e9b6dac, v196
	v_sub_f32_e32 v168, v169, v168
	v_add_f32_e32 v169, v175, v176
	v_fmaak_f32 v174, v172, v174, 0x3f2aaada
	v_sub_f32_e32 v170, v169, v175
	v_ldexp_f32 v175, v171, 1
	v_mul_f32_e32 v171, v171, v172
	v_mul_f32_e32 v171, v171, v174
	v_add_f32_e32 v172, v175, v171
	v_sub_f32_e32 v174, v172, v175
	v_ldexp_f32 v168, v168, 1
	v_sub_f32_e32 v171, v171, v174
	v_add_f32_e32 v168, v168, v171
	v_add_f32_e32 v171, v172, v168
	v_sub_f32_e32 v172, v171, v172
	v_sub_f32_e32 v168, v168, v172
	v_add_f32_e32 v172, v169, v171
	v_sub_f32_e32 v174, v172, v169
	v_sub_f32_e32 v175, v172, v174
	v_sub_f32_e32 v170, v176, v170
	v_sub_f32_e32 v169, v169, v175
	v_sub_f32_e32 v171, v171, v174
	v_add_f32_e32 v169, v171, v169
	v_add_f32_e32 v171, v170, v168
	v_sub_f32_e32 v174, v171, v170
	v_sub_f32_e32 v175, v171, v174
	v_sub_f32_e32 v170, v170, v175
	v_sub_f32_e32 v168, v168, v174
	v_add_f32_e32 v169, v171, v169
	v_add_f32_e32 v168, v168, v170
	v_add_f32_e32 v170, v172, v169
	v_sub_f32_e32 v171, v170, v172
	v_sub_f32_e32 v169, v169, v171
	v_add_f32_e32 v168, v168, v169
	v_add_f32_e32 v168, v170, v168
	v_cndmask_b32_e64 v168, v197, v168, s[10:11]
	v_cmp_lt_f32_e64 s[10:11], |v0|, s61
	s_nop 1
	v_cndmask_b32_e64 v0, v168, v0, s[10:11]
	v_sub_f32_e32 v0, v165, v0
	v_lshl_add_u64 v[168:169], v[166:167], 0, s[2:3]
	global_store_dword v[168:169], v0, off
	global_load_dword v0, v1, s[18:19] offset:36
	s_or_b32 s2, s38, 9
	s_ashr_i32 s3, s2, 31
	s_lshl_b64 s[2:3], s[2:3], 16
	s_waitcnt vmcnt(0)
;   DI void operator()(int tok0, int feat0, f32x16 (&acc)[2][2], int r, int hh) const {
;     ...
;           for (int i = 0; i < 16; ++i) {
;             const float xv = acc[0][mt][i] + bf[i];
;             const float ls = fminf(xv, 0.f) - log1pf(expf(-fabsf(xv)));
;             lf[((size_t)(b * 16 + i)) * SEQ + s] = ls;
;           }
	v_add_f32_e32 v0, v123, v0
	v_mul_f32_e64 v168, |v0|, s54
	v_fma_f32 v169, |v0|, s54, -v168
	v_rndne_f32_e32 v170, v168
	v_fma_f32 v169, |v0|, s55, v169
	v_sub_f32_e32 v168, v168, v170
	v_add_f32_e32 v168, v168, v169
	v_exp_f32_e32 v168, v168
	v_cvt_i32_f32_e32 v169, v170
	v_cmp_ngt_f32_e64 s[10:11], |v0|, s56
	v_min_f32_e32 v165, 0, v0
	v_ldexp_f32 v168, v168, v169
	v_cndmask_b32_e64 v168, 0, v168, s[10:11]
	v_cmp_nlt_f32_e64 s[10:11], |v0|, s57
	s_nop 1
	v_cndmask_b32_e64 v0, v197, v168, s[10:11]
	v_add_f32_e32 v170, 1.0, v0
	v_add_f32_e32 v168, -1.0, v170
	v_sub_f32_e32 v169, v168, v170
	v_add_f32_e32 v169, 1.0, v169
	v_sub_f32_e32 v168, v0, v168
	v_add_f32_e32 v171, v168, v169
	v_frexp_mant_f32_e32 v168, v170
	v_cmp_gt_f32_e64 s[10:11], s59, v168
	v_cvt_f64_f32_e32 v[168:169], v170
	v_frexp_exp_i32_f64_e32 v168, v[168:169]
	v_subbrev_co_u32_e64 v168, s[10:11], 0, v168, s[10:11]
	v_sub_u32_e32 v169, 0, v168
	v_ldexp_f32 v170, v170, v169
	v_ldexp_f32 v169, v171, v169
	v_add_f32_e32 v171, -1.0, v170
	v_add_f32_e32 v172, 1.0, v171
	v_sub_f32_e32 v172, v170, v172
	v_add_f32_e32 v172, v169, v172
	v_add_f32_e32 v174, v171, v172
	v_sub_f32_e32 v171, v171, v174
	v_add_f32_e32 v171, v172, v171
	v_add_f32_e32 v172, 1.0, v170
	v_add_f32_e32 v175, -1.0, v172
	v_sub_f32_e32 v170, v170, v175
	v_add_f32_e32 v169, v169, v170
	v_add_f32_e32 v170, v172, v169
	v_sub_f32_e32 v172, v172, v170
	v_add_f32_e32 v169, v169, v172
	v_rcp_f32_e32 v172, v170
	v_cvt_f32_i32_e32 v168, v168
	v_cmp_neq_f32_e64 s[10:11], s58, v0
	v_mul_f32_e32 v175, v174, v172
	v_mul_f32_e32 v176, v170, v175
	v_fma_f32 v177, v175, v170, -v176
	v_fmac_f32_e32 v177, v175, v169
	v_add_f32_e32 v194, v176, v177
	v_sub_f32_e32 v195, v174, v194
	v_sub_f32_e32 v174, v174, v195
	v_sub_f32_e32 v176, v194, v176
	v_sub_f32_e32 v174, v174, v194
	v_add_f32_e32 v171, v171, v174
	v_sub_f32_e32 v174, v176, v177
	v_add_f32_e32 v171, v174, v171
	v_add_f32_e32 v174, v195, v171
	v_mul_f32_e32 v176, v172, v174
	v_mul_f32_e32 v177, v170, v176
	v_fma_f32 v170, v176, v170, -v177
	v_fmac_f32_e32 v170, v176, v169
	v_sub_f32_e32 v169, v195, v174
	v_add_f32_e32 v169, v171, v169
	v_add_f32_e32 v171, v177, v170
	v_sub_f32_e32 v194, v174, v171
	v_sub_f32_e32 v174, v174, v194
	v_sub_f32_e32 v177, v171, v177
	v_sub_f32_e32 v171, v174, v171
	v_add_f32_e32 v169, v169, v171
	v_sub_f32_e32 v170, v177, v170
	v_add_f32_e32 v169, v170, v169
	v_add_f32_e32 v170, v175, v176
	v_add_f32_e32 v169, v194, v169
	v_sub_f32_e32 v171, v170, v175
	v_mul_f32_e32 v169, v172, v169
	v_sub_f32_e32 v171, v176, v171
	v_add_f32_e32 v169, v171, v169
	v_mul_f32_e32 v175, 0x3f317218, v168
	v_add_f32_e32 v171, v170, v169
	v_fma_f32 v176, v168, s60, -v175
	v_mul_f32_e32 v172, v171, v171
	v_fmac_f32_e32 v176, 0xb102e308, v168
	v_sub_f32_e32 v168, v171, v170
	v_fmamk_f32 v174, v172, 0x3e9b6dac, v196
	v_sub_f32_e32 v168, v169, v168
	v_add_f32_e32 v169, v175, v176
	v_fmaak_f32 v174, v172, v174, 0x3f2aaada
	v_sub_f32_e32 v170, v169, v175
	v_ldexp_f32 v175, v171, 1
	v_mul_f32_e32 v171, v171, v172
	v_mul_f32_e32 v171, v171, v174
	v_add_f32_e32 v172, v175, v171
	v_sub_f32_e32 v174, v172, v175
	v_ldexp_f32 v168, v168, 1
	v_sub_f32_e32 v171, v171, v174
	v_add_f32_e32 v168, v168, v171
	v_add_f32_e32 v171, v172, v168
	v_sub_f32_e32 v172, v171, v172
	v_sub_f32_e32 v168, v168, v172
	v_add_f32_e32 v172, v169, v171
	v_sub_f32_e32 v174, v172, v169
	v_sub_f32_e32 v175, v172, v174
	v_sub_f32_e32 v170, v176, v170
	v_sub_f32_e32 v169, v169, v175
	v_sub_f32_e32 v171, v171, v174
	v_add_f32_e32 v169, v171, v169
	v_add_f32_e32 v171, v170, v168
	v_sub_f32_e32 v174, v171, v170
	v_sub_f32_e32 v175, v171, v174
	v_sub_f32_e32 v170, v170, v175
	v_sub_f32_e32 v168, v168, v174
	v_add_f32_e32 v169, v171, v169
	v_add_f32_e32 v168, v168, v170
	v_add_f32_e32 v170, v172, v169
	v_sub_f32_e32 v171, v170, v172
	v_sub_f32_e32 v169, v169, v171
	v_add_f32_e32 v168, v168, v169
	v_add_f32_e32 v168, v170, v168
	v_cndmask_b32_e64 v168, v197, v168, s[10:11]
	v_cmp_lt_f32_e64 s[10:11], |v0|, s61
	s_nop 1
	v_cndmask_b32_e64 v0, v168, v0, s[10:11]
	v_sub_f32_e32 v0, v165, v0
	v_lshl_add_u64 v[168:169], v[166:167], 0, s[2:3]
	global_store_dword v[168:169], v0, off
	global_load_dword v0, v1, s[18:19] offset:40
	s_or_b32 s2, s38, 10
	s_ashr_i32 s3, s2, 31
	s_lshl_b64 s[2:3], s[2:3], 16
	s_waitcnt vmcnt(0)
;   DI void operator()(int tok0, int feat0, f32x16 (&acc)[2][2], int r, int hh) const {
;     ...
;           for (int i = 0; i < 16; ++i) {
;             const float xv = acc[0][mt][i] + bf[i];
;             const float ls = fminf(xv, 0.f) - log1pf(expf(-fabsf(xv)));
;             lf[((size_t)(b * 16 + i)) * SEQ + s] = ls;
;           }
	v_add_f32_e32 v0, v124, v0
	v_mul_f32_e64 v168, |v0|, s54
	v_fma_f32 v169, |v0|, s54, -v168
	v_rndne_f32_e32 v170, v168
	v_fma_f32 v169, |v0|, s55, v169
	v_sub_f32_e32 v168, v168, v170
	v_add_f32_e32 v168, v168, v169
	v_exp_f32_e32 v168, v168
	v_cvt_i32_f32_e32 v169, v170
	v_cmp_ngt_f32_e64 s[10:11], |v0|, s56
	v_min_f32_e32 v165, 0, v0
	v_ldexp_f32 v168, v168, v169
	v_cndmask_b32_e64 v168, 0, v168, s[10:11]
	v_cmp_nlt_f32_e64 s[10:11], |v0|, s57
	s_nop 1
	v_cndmask_b32_e64 v0, v197, v168, s[10:11]
	v_add_f32_e32 v170, 1.0, v0
	v_add_f32_e32 v168, -1.0, v170
	v_sub_f32_e32 v169, v168, v170
	v_add_f32_e32 v169, 1.0, v169
	v_sub_f32_e32 v168, v0, v168
	v_add_f32_e32 v171, v168, v169
	v_frexp_mant_f32_e32 v168, v170
	v_cmp_gt_f32_e64 s[10:11], s59, v168
	v_cvt_f64_f32_e32 v[168:169], v170
	v_frexp_exp_i32_f64_e32 v168, v[168:169]
	v_subbrev_co_u32_e64 v168, s[10:11], 0, v168, s[10:11]
	v_sub_u32_e32 v169, 0, v168
	v_ldexp_f32 v170, v170, v169
	v_ldexp_f32 v169, v171, v169
	v_add_f32_e32 v171, -1.0, v170
	v_add_f32_e32 v172, 1.0, v171
	v_sub_f32_e32 v172, v170, v172
	v_add_f32_e32 v172, v169, v172
	v_add_f32_e32 v174, v171, v172
	v_sub_f32_e32 v171, v171, v174
	v_add_f32_e32 v171, v172, v171
	v_add_f32_e32 v172, 1.0, v170
	v_add_f32_e32 v175, -1.0, v172
	v_sub_f32_e32 v170, v170, v175
	v_add_f32_e32 v169, v169, v170
	v_add_f32_e32 v170, v172, v169
	v_sub_f32_e32 v172, v172, v170
	v_add_f32_e32 v169, v169, v172
	v_rcp_f32_e32 v172, v170
	v_cvt_f32_i32_e32 v168, v168
	v_cmp_neq_f32_e64 s[10:11], s58, v0
	v_mul_f32_e32 v175, v174, v172
	v_mul_f32_e32 v176, v170, v175
	v_fma_f32 v177, v175, v170, -v176
	v_fmac_f32_e32 v177, v175, v169
	v_add_f32_e32 v194, v176, v177
	v_sub_f32_e32 v195, v174, v194
	v_sub_f32_e32 v174, v174, v195
	v_sub_f32_e32 v176, v194, v176
	v_sub_f32_e32 v174, v174, v194
	v_add_f32_e32 v171, v171, v174
	v_sub_f32_e32 v174, v176, v177
	v_add_f32_e32 v171, v174, v171
	v_add_f32_e32 v174, v195, v171
	v_mul_f32_e32 v176, v172, v174
	v_mul_f32_e32 v177, v170, v176
	v_fma_f32 v170, v176, v170, -v177
	v_fmac_f32_e32 v170, v176, v169
	v_sub_f32_e32 v169, v195, v174
	v_add_f32_e32 v169, v171, v169
	v_add_f32_e32 v171, v177, v170
	v_sub_f32_e32 v194, v174, v171
	v_sub_f32_e32 v174, v174, v194
	v_sub_f32_e32 v177, v171, v177
	v_sub_f32_e32 v171, v174, v171
	v_add_f32_e32 v169, v169, v171
	v_sub_f32_e32 v170, v177, v170
	v_add_f32_e32 v169, v170, v169
	v_add_f32_e32 v170, v175, v176
	v_add_f32_e32 v169, v194, v169
	v_sub_f32_e32 v171, v170, v175
	v_mul_f32_e32 v169, v172, v169
	v_sub_f32_e32 v171, v176, v171
	v_add_f32_e32 v169, v171, v169
	v_mul_f32_e32 v175, 0x3f317218, v168
	v_add_f32_e32 v171, v170, v169
	v_fma_f32 v176, v168, s60, -v175
	v_mul_f32_e32 v172, v171, v171
	v_fmac_f32_e32 v176, 0xb102e308, v168
	v_sub_f32_e32 v168, v171, v170
	v_fmamk_f32 v174, v172, 0x3e9b6dac, v196
	v_sub_f32_e32 v168, v169, v168
	v_add_f32_e32 v169, v175, v176
	v_fmaak_f32 v174, v172, v174, 0x3f2aaada
	v_sub_f32_e32 v170, v169, v175
	v_ldexp_f32 v175, v171, 1
	v_mul_f32_e32 v171, v171, v172
	v_mul_f32_e32 v171, v171, v174
	v_add_f32_e32 v172, v175, v171
	v_sub_f32_e32 v174, v172, v175
	v_ldexp_f32 v168, v168, 1
	v_sub_f32_e32 v171, v171, v174
	v_add_f32_e32 v168, v168, v171
	v_add_f32_e32 v171, v172, v168
	v_sub_f32_e32 v172, v171, v172
	v_sub_f32_e32 v168, v168, v172
	v_add_f32_e32 v172, v169, v171
	v_sub_f32_e32 v174, v172, v169
	v_sub_f32_e32 v175, v172, v174
	v_sub_f32_e32 v170, v176, v170
	v_sub_f32_e32 v169, v169, v175
	v_sub_f32_e32 v171, v171, v174
	v_add_f32_e32 v169, v171, v169
	v_add_f32_e32 v171, v170, v168
	v_sub_f32_e32 v174, v171, v170
	v_sub_f32_e32 v175, v171, v174
	v_sub_f32_e32 v170, v170, v175
	v_sub_f32_e32 v168, v168, v174
	v_add_f32_e32 v169, v171, v169
	v_add_f32_e32 v168, v168, v170
	v_add_f32_e32 v170, v172, v169
	v_sub_f32_e32 v171, v170, v172
	v_sub_f32_e32 v169, v169, v171
	v_add_f32_e32 v168, v168, v169
	v_add_f32_e32 v168, v170, v168
	v_cndmask_b32_e64 v168, v197, v168, s[10:11]
	v_cmp_lt_f32_e64 s[10:11], |v0|, s61
	s_nop 1
	v_cndmask_b32_e64 v0, v168, v0, s[10:11]
	v_sub_f32_e32 v0, v165, v0
	v_lshl_add_u64 v[168:169], v[166:167], 0, s[2:3]
	global_store_dword v[168:169], v0, off
	global_load_dword v0, v1, s[18:19] offset:44
	s_or_b32 s2, s38, 11
	s_ashr_i32 s3, s2, 31
	s_lshl_b64 s[2:3], s[2:3], 16
	s_waitcnt vmcnt(0)
;   DI void operator()(int tok0, int feat0, f32x16 (&acc)[2][2], int r, int hh) const {
;     ...
;           for (int i = 0; i < 16; ++i) {
;             const float xv = acc[0][mt][i] + bf[i];
;             const float ls = fminf(xv, 0.f) - log1pf(expf(-fabsf(xv)));
;             lf[((size_t)(b * 16 + i)) * SEQ + s] = ls;
;           }
	v_add_f32_e32 v0, v125, v0
	v_mul_f32_e64 v168, |v0|, s54
	v_fma_f32 v169, |v0|, s54, -v168
	v_rndne_f32_e32 v170, v168
	v_fma_f32 v169, |v0|, s55, v169
	v_sub_f32_e32 v168, v168, v170
	v_add_f32_e32 v168, v168, v169
	v_exp_f32_e32 v168, v168
	v_cvt_i32_f32_e32 v169, v170
	v_cmp_ngt_f32_e64 s[10:11], |v0|, s56
	v_min_f32_e32 v165, 0, v0
	v_ldexp_f32 v168, v168, v169
	v_cndmask_b32_e64 v168, 0, v168, s[10:11]
	v_cmp_nlt_f32_e64 s[10:11], |v0|, s57
	s_nop 1
	v_cndmask_b32_e64 v0, v197, v168, s[10:11]
	v_add_f32_e32 v170, 1.0, v0
	v_add_f32_e32 v168, -1.0, v170
	v_sub_f32_e32 v169, v168, v170
	v_add_f32_e32 v169, 1.0, v169
	v_sub_f32_e32 v168, v0, v168
	v_add_f32_e32 v171, v168, v169
	v_frexp_mant_f32_e32 v168, v170
	v_cmp_gt_f32_e64 s[10:11], s59, v168
	v_cvt_f64_f32_e32 v[168:169], v170
	v_frexp_exp_i32_f64_e32 v168, v[168:169]
	v_subbrev_co_u32_e64 v168, s[10:11], 0, v168, s[10:11]
	v_sub_u32_e32 v169, 0, v168
	v_ldexp_f32 v170, v170, v169
	v_ldexp_f32 v169, v171, v169
	v_add_f32_e32 v171, -1.0, v170
	v_add_f32_e32 v172, 1.0, v171
	v_sub_f32_e32 v172, v170, v172
	v_add_f32_e32 v172, v169, v172
	v_add_f32_e32 v174, v171, v172
	v_sub_f32_e32 v171, v171, v174
	v_add_f32_e32 v171, v172, v171
	v_add_f32_e32 v172, 1.0, v170
	v_add_f32_e32 v175, -1.0, v172
	v_sub_f32_e32 v170, v170, v175
	v_add_f32_e32 v169, v169, v170
	v_add_f32_e32 v170, v172, v169
	v_sub_f32_e32 v172, v172, v170
	v_add_f32_e32 v169, v169, v172
	v_rcp_f32_e32 v172, v170
	v_cvt_f32_i32_e32 v168, v168
	v_cmp_neq_f32_e64 s[10:11], s58, v0
	v_mul_f32_e32 v175, v174, v172
	v_mul_f32_e32 v176, v170, v175
	v_fma_f32 v177, v175, v170, -v176
	v_fmac_f32_e32 v177, v175, v169
	v_add_f32_e32 v194, v176, v177
	v_sub_f32_e32 v195, v174, v194
	v_sub_f32_e32 v174, v174, v195
	v_sub_f32_e32 v176, v194, v176
	v_sub_f32_e32 v174, v174, v194
	v_add_f32_e32 v171, v171, v174
	v_sub_f32_e32 v174, v176, v177
	v_add_f32_e32 v171, v174, v171
	v_add_f32_e32 v174, v195, v171
	v_mul_f32_e32 v176, v172, v174
	v_mul_f32_e32 v177, v170, v176
	v_fma_f32 v170, v176, v170, -v177
	v_fmac_f32_e32 v170, v176, v169
	v_sub_f32_e32 v169, v195, v174
	v_add_f32_e32 v169, v171, v169
	v_add_f32_e32 v171, v177, v170
	v_sub_f32_e32 v194, v174, v171
	v_sub_f32_e32 v174, v174, v194
	v_sub_f32_e32 v177, v171, v177
	v_sub_f32_e32 v171, v174, v171
	v_add_f32_e32 v169, v169, v171
	v_sub_f32_e32 v170, v177, v170
	v_add_f32_e32 v169, v170, v169
	v_add_f32_e32 v170, v175, v176
	v_add_f32_e32 v169, v194, v169
	v_sub_f32_e32 v171, v170, v175
	v_mul_f32_e32 v169, v172, v169
	v_sub_f32_e32 v171, v176, v171
	v_add_f32_e32 v169, v171, v169
	v_mul_f32_e32 v175, 0x3f317218, v168
	v_add_f32_e32 v171, v170, v169
	v_fma_f32 v176, v168, s60, -v175
	v_mul_f32_e32 v172, v171, v171
	v_fmac_f32_e32 v176, 0xb102e308, v168
	v_sub_f32_e32 v168, v171, v170
	v_fmamk_f32 v174, v172, 0x3e9b6dac, v196
	v_sub_f32_e32 v168, v169, v168
	v_add_f32_e32 v169, v175, v176
	v_fmaak_f32 v174, v172, v174, 0x3f2aaada
	v_sub_f32_e32 v170, v169, v175
	v_ldexp_f32 v175, v171, 1
	v_mul_f32_e32 v171, v171, v172
	v_mul_f32_e32 v171, v171, v174
	v_add_f32_e32 v172, v175, v171
	v_sub_f32_e32 v174, v172, v175
	v_ldexp_f32 v168, v168, 1
	v_sub_f32_e32 v171, v171, v174
	v_add_f32_e32 v168, v168, v171
	v_add_f32_e32 v171, v172, v168
	v_sub_f32_e32 v172, v171, v172
	v_sub_f32_e32 v168, v168, v172
	v_add_f32_e32 v172, v169, v171
	v_sub_f32_e32 v174, v172, v169
	v_sub_f32_e32 v175, v172, v174
	v_sub_f32_e32 v170, v176, v170
	v_sub_f32_e32 v169, v169, v175
	v_sub_f32_e32 v171, v171, v174
	v_add_f32_e32 v169, v171, v169
	v_add_f32_e32 v171, v170, v168
	v_sub_f32_e32 v174, v171, v170
	v_sub_f32_e32 v175, v171, v174
	v_sub_f32_e32 v170, v170, v175
	v_sub_f32_e32 v168, v168, v174
	v_add_f32_e32 v169, v171, v169
	v_add_f32_e32 v168, v168, v170
	v_add_f32_e32 v170, v172, v169
	v_sub_f32_e32 v171, v170, v172
	v_sub_f32_e32 v169, v169, v171
	v_add_f32_e32 v168, v168, v169
	v_add_f32_e32 v168, v170, v168
	v_cndmask_b32_e64 v168, v197, v168, s[10:11]
	v_cmp_lt_f32_e64 s[10:11], |v0|, s61
	s_nop 1
	v_cndmask_b32_e64 v0, v168, v0, s[10:11]
	v_sub_f32_e32 v0, v165, v0
	v_lshl_add_u64 v[168:169], v[166:167], 0, s[2:3]
	global_store_dword v[168:169], v0, off
	global_load_dword v0, v1, s[18:19] offset:48
	s_or_b32 s2, s38, 12
	s_ashr_i32 s3, s2, 31
	s_lshl_b64 s[2:3], s[2:3], 16
	s_waitcnt vmcnt(0)
;   DI void operator()(int tok0, int feat0, f32x16 (&acc)[2][2], int r, int hh) const {
;     ...
;           for (int i = 0; i < 16; ++i) {
;             const float xv = acc[0][mt][i] + bf[i];
;             const float ls = fminf(xv, 0.f) - log1pf(expf(-fabsf(xv)));
;             lf[((size_t)(b * 16 + i)) * SEQ + s] = ls;
;           }
	v_add_f32_e32 v0, v126, v0
	v_mul_f32_e64 v168, |v0|, s54
	v_fma_f32 v169, |v0|, s54, -v168
	v_rndne_f32_e32 v170, v168
	v_fma_f32 v169, |v0|, s55, v169
	v_sub_f32_e32 v168, v168, v170
	v_add_f32_e32 v168, v168, v169
	v_exp_f32_e32 v168, v168
	v_cvt_i32_f32_e32 v169, v170
	v_cmp_ngt_f32_e64 s[10:11], |v0|, s56
	v_min_f32_e32 v165, 0, v0
	v_ldexp_f32 v168, v168, v169
	v_cndmask_b32_e64 v168, 0, v168, s[10:11]
	v_cmp_nlt_f32_e64 s[10:11], |v0|, s57
	s_nop 1
	v_cndmask_b32_e64 v0, v197, v168, s[10:11]
	v_add_f32_e32 v170, 1.0, v0
	v_add_f32_e32 v168, -1.0, v170
	v_sub_f32_e32 v169, v168, v170
	v_add_f32_e32 v169, 1.0, v169
	v_sub_f32_e32 v168, v0, v168
	v_add_f32_e32 v171, v168, v169
	v_frexp_mant_f32_e32 v168, v170
	v_cmp_gt_f32_e64 s[10:11], s59, v168
	v_cvt_f64_f32_e32 v[168:169], v170
	v_frexp_exp_i32_f64_e32 v168, v[168:169]
	v_subbrev_co_u32_e64 v168, s[10:11], 0, v168, s[10:11]
	v_sub_u32_e32 v169, 0, v168
	v_ldexp_f32 v170, v170, v169
	v_ldexp_f32 v169, v171, v169
	v_add_f32_e32 v171, -1.0, v170
	v_add_f32_e32 v172, 1.0, v171
	v_sub_f32_e32 v172, v170, v172
	v_add_f32_e32 v172, v169, v172
	v_add_f32_e32 v174, v171, v172
	v_sub_f32_e32 v171, v171, v174
	v_add_f32_e32 v171, v172, v171
	v_add_f32_e32 v172, 1.0, v170
	v_add_f32_e32 v175, -1.0, v172
	v_sub_f32_e32 v170, v170, v175
	v_add_f32_e32 v169, v169, v170
	v_add_f32_e32 v170, v172, v169
	v_sub_f32_e32 v172, v172, v170
	v_add_f32_e32 v169, v169, v172
	v_rcp_f32_e32 v172, v170
	v_cvt_f32_i32_e32 v168, v168
	v_cmp_neq_f32_e64 s[10:11], s58, v0
	v_mul_f32_e32 v175, v174, v172
	v_mul_f32_e32 v176, v170, v175
	v_fma_f32 v177, v175, v170, -v176
	v_fmac_f32_e32 v177, v175, v169
	v_add_f32_e32 v194, v176, v177
	v_sub_f32_e32 v195, v174, v194
	v_sub_f32_e32 v174, v174, v195
	v_sub_f32_e32 v176, v194, v176
	v_sub_f32_e32 v174, v174, v194
	v_add_f32_e32 v171, v171, v174
	v_sub_f32_e32 v174, v176, v177
	v_add_f32_e32 v171, v174, v171
	v_add_f32_e32 v174, v195, v171
	v_mul_f32_e32 v176, v172, v174
	v_mul_f32_e32 v177, v170, v176
	v_fma_f32 v170, v176, v170, -v177
	v_fmac_f32_e32 v170, v176, v169
	v_sub_f32_e32 v169, v195, v174
	v_add_f32_e32 v169, v171, v169
	v_add_f32_e32 v171, v177, v170
	v_sub_f32_e32 v194, v174, v171
	v_sub_f32_e32 v174, v174, v194
	v_sub_f32_e32 v177, v171, v177
	v_sub_f32_e32 v171, v174, v171
	v_add_f32_e32 v169, v169, v171
	v_sub_f32_e32 v170, v177, v170
	v_add_f32_e32 v169, v170, v169
	v_add_f32_e32 v170, v175, v176
	v_add_f32_e32 v169, v194, v169
	v_sub_f32_e32 v171, v170, v175
	v_mul_f32_e32 v169, v172, v169
	v_sub_f32_e32 v171, v176, v171
	v_add_f32_e32 v169, v171, v169
	v_mul_f32_e32 v175, 0x3f317218, v168
	v_add_f32_e32 v171, v170, v169
	v_fma_f32 v176, v168, s60, -v175
	v_mul_f32_e32 v172, v171, v171
	v_fmac_f32_e32 v176, 0xb102e308, v168
	v_sub_f32_e32 v168, v171, v170
	v_fmamk_f32 v174, v172, 0x3e9b6dac, v196
	v_sub_f32_e32 v168, v169, v168
	v_add_f32_e32 v169, v175, v176
	v_fmaak_f32 v174, v172, v174, 0x3f2aaada
	v_sub_f32_e32 v170, v169, v175
	v_ldexp_f32 v175, v171, 1
	v_mul_f32_e32 v171, v171, v172
	v_mul_f32_e32 v171, v171, v174
	v_add_f32_e32 v172, v175, v171
	v_sub_f32_e32 v174, v172, v175
	v_ldexp_f32 v168, v168, 1
	v_sub_f32_e32 v171, v171, v174
	v_add_f32_e32 v168, v168, v171
	v_add_f32_e32 v171, v172, v168
	v_sub_f32_e32 v172, v171, v172
	v_sub_f32_e32 v168, v168, v172
	v_add_f32_e32 v172, v169, v171
	v_sub_f32_e32 v174, v172, v169
	v_sub_f32_e32 v175, v172, v174
	v_sub_f32_e32 v170, v176, v170
	v_sub_f32_e32 v169, v169, v175
	v_sub_f32_e32 v171, v171, v174
	v_add_f32_e32 v169, v171, v169
	v_add_f32_e32 v171, v170, v168
	v_sub_f32_e32 v174, v171, v170
	v_sub_f32_e32 v175, v171, v174
	v_sub_f32_e32 v170, v170, v175
	v_sub_f32_e32 v168, v168, v174
	v_add_f32_e32 v169, v171, v169
	v_add_f32_e32 v168, v168, v170
	v_add_f32_e32 v170, v172, v169
	v_sub_f32_e32 v171, v170, v172
	v_sub_f32_e32 v169, v169, v171
	v_add_f32_e32 v168, v168, v169
	v_add_f32_e32 v168, v170, v168
	v_cndmask_b32_e64 v168, v197, v168, s[10:11]
	v_cmp_lt_f32_e64 s[10:11], |v0|, s61
	s_nop 1
	v_cndmask_b32_e64 v0, v168, v0, s[10:11]
	v_sub_f32_e32 v0, v165, v0
	v_lshl_add_u64 v[168:169], v[166:167], 0, s[2:3]
	global_store_dword v[168:169], v0, off
	global_load_dword v0, v1, s[18:19] offset:52
	s_or_b32 s2, s38, 13
	s_ashr_i32 s3, s2, 31
	s_lshl_b64 s[2:3], s[2:3], 16
	s_waitcnt vmcnt(0)
;   DI void operator()(int tok0, int feat0, f32x16 (&acc)[2][2], int r, int hh) const {
;     ...
;           for (int i = 0; i < 16; ++i) {
;             const float xv = acc[0][mt][i] + bf[i];
;             const float ls = fminf(xv, 0.f) - log1pf(expf(-fabsf(xv)));
;             lf[((size_t)(b * 16 + i)) * SEQ + s] = ls;
;           }
	v_add_f32_e32 v0, v127, v0
	v_mul_f32_e64 v168, |v0|, s54
	v_fma_f32 v169, |v0|, s54, -v168
	v_rndne_f32_e32 v170, v168
	v_fma_f32 v169, |v0|, s55, v169
	v_sub_f32_e32 v168, v168, v170
	v_add_f32_e32 v168, v168, v169
	v_exp_f32_e32 v168, v168
	v_cvt_i32_f32_e32 v169, v170
	v_cmp_ngt_f32_e64 s[10:11], |v0|, s56
	v_min_f32_e32 v165, 0, v0
	v_ldexp_f32 v168, v168, v169
	v_cndmask_b32_e64 v168, 0, v168, s[10:11]
	v_cmp_nlt_f32_e64 s[10:11], |v0|, s57
	s_nop 1
	v_cndmask_b32_e64 v0, v197, v168, s[10:11]
	v_add_f32_e32 v170, 1.0, v0
	v_add_f32_e32 v168, -1.0, v170
	v_sub_f32_e32 v169, v168, v170
	v_add_f32_e32 v169, 1.0, v169
	v_sub_f32_e32 v168, v0, v168
	v_add_f32_e32 v171, v168, v169
	v_frexp_mant_f32_e32 v168, v170
	v_cmp_gt_f32_e64 s[10:11], s59, v168
	v_cvt_f64_f32_e32 v[168:169], v170
	v_frexp_exp_i32_f64_e32 v168, v[168:169]
	v_subbrev_co_u32_e64 v168, s[10:11], 0, v168, s[10:11]
	v_sub_u32_e32 v169, 0, v168
	v_ldexp_f32 v170, v170, v169
	v_ldexp_f32 v169, v171, v169
	v_add_f32_e32 v171, -1.0, v170
	v_add_f32_e32 v172, 1.0, v171
	v_sub_f32_e32 v172, v170, v172
	v_add_f32_e32 v172, v169, v172
	v_add_f32_e32 v174, v171, v172
	v_sub_f32_e32 v171, v171, v174
	v_add_f32_e32 v171, v172, v171
	v_add_f32_e32 v172, 1.0, v170
	v_add_f32_e32 v175, -1.0, v172
	v_sub_f32_e32 v170, v170, v175
	v_add_f32_e32 v169, v169, v170
	v_add_f32_e32 v170, v172, v169
	v_sub_f32_e32 v172, v172, v170
	v_add_f32_e32 v169, v169, v172
	v_rcp_f32_e32 v172, v170
	v_cvt_f32_i32_e32 v168, v168
	v_cmp_neq_f32_e64 s[10:11], s58, v0
	v_mul_f32_e32 v175, v174, v172
	v_mul_f32_e32 v176, v170, v175
	v_fma_f32 v177, v175, v170, -v176
	v_fmac_f32_e32 v177, v175, v169
	v_add_f32_e32 v194, v176, v177
	v_sub_f32_e32 v195, v174, v194
	v_sub_f32_e32 v174, v174, v195
	v_sub_f32_e32 v176, v194, v176
	v_sub_f32_e32 v174, v174, v194
	v_add_f32_e32 v171, v171, v174
	v_sub_f32_e32 v174, v176, v177
	v_add_f32_e32 v171, v174, v171
	v_add_f32_e32 v174, v195, v171
	v_mul_f32_e32 v176, v172, v174
	v_mul_f32_e32 v177, v170, v176
	v_fma_f32 v170, v176, v170, -v177
	v_fmac_f32_e32 v170, v176, v169
	v_sub_f32_e32 v169, v195, v174
	v_add_f32_e32 v169, v171, v169
	v_add_f32_e32 v171, v177, v170
	v_sub_f32_e32 v194, v174, v171
	v_sub_f32_e32 v174, v174, v194
	v_sub_f32_e32 v177, v171, v177
	v_sub_f32_e32 v171, v174, v171
	v_add_f32_e32 v169, v169, v171
	v_sub_f32_e32 v170, v177, v170
	v_add_f32_e32 v169, v170, v169
	v_add_f32_e32 v170, v175, v176
	v_add_f32_e32 v169, v194, v169
	v_sub_f32_e32 v171, v170, v175
	v_mul_f32_e32 v169, v172, v169
	v_sub_f32_e32 v171, v176, v171
	v_add_f32_e32 v169, v171, v169
	v_mul_f32_e32 v175, 0x3f317218, v168
	v_add_f32_e32 v171, v170, v169
	v_fma_f32 v176, v168, s60, -v175
	v_mul_f32_e32 v172, v171, v171
	v_fmac_f32_e32 v176, 0xb102e308, v168
	v_sub_f32_e32 v168, v171, v170
	v_fmamk_f32 v174, v172, 0x3e9b6dac, v196
	v_sub_f32_e32 v168, v169, v168
	v_add_f32_e32 v169, v175, v176
	v_fmaak_f32 v174, v172, v174, 0x3f2aaada
	v_sub_f32_e32 v170, v169, v175
	v_ldexp_f32 v175, v171, 1
	v_mul_f32_e32 v171, v171, v172
	v_mul_f32_e32 v171, v171, v174
	v_add_f32_e32 v172, v175, v171
	v_sub_f32_e32 v174, v172, v175
	v_ldexp_f32 v168, v168, 1
	v_sub_f32_e32 v171, v171, v174
	v_add_f32_e32 v168, v168, v171
	v_add_f32_e32 v171, v172, v168
	v_sub_f32_e32 v172, v171, v172
	v_sub_f32_e32 v168, v168, v172
	v_add_f32_e32 v172, v169, v171
	v_sub_f32_e32 v174, v172, v169
	v_sub_f32_e32 v175, v172, v174
	v_sub_f32_e32 v170, v176, v170
	v_sub_f32_e32 v169, v169, v175
	v_sub_f32_e32 v171, v171, v174
	v_add_f32_e32 v169, v171, v169
	v_add_f32_e32 v171, v170, v168
	v_sub_f32_e32 v174, v171, v170
	v_sub_f32_e32 v175, v171, v174
	v_sub_f32_e32 v170, v170, v175
	v_sub_f32_e32 v168, v168, v174
	v_add_f32_e32 v169, v171, v169
	v_add_f32_e32 v168, v168, v170
	v_add_f32_e32 v170, v172, v169
	v_sub_f32_e32 v171, v170, v172
	v_sub_f32_e32 v169, v169, v171
	v_add_f32_e32 v168, v168, v169
	v_add_f32_e32 v168, v170, v168
	v_cndmask_b32_e64 v168, v197, v168, s[10:11]
	v_cmp_lt_f32_e64 s[10:11], |v0|, s61
	s_nop 1
	v_cndmask_b32_e64 v0, v168, v0, s[10:11]
	v_sub_f32_e32 v0, v165, v0
	v_lshl_add_u64 v[168:169], v[166:167], 0, s[2:3]
	global_store_dword v[168:169], v0, off
	global_load_dword v0, v1, s[18:19] offset:56
	s_or_b32 s2, s38, 14
	s_ashr_i32 s3, s2, 31
	s_lshl_b64 s[2:3], s[2:3], 16
	s_waitcnt vmcnt(0)
;   DI void operator()(int tok0, int feat0, f32x16 (&acc)[2][2], int r, int hh) const {
;     ...
;           for (int i = 0; i < 16; ++i) {
;             const float xv = acc[0][mt][i] + bf[i];
;             const float ls = fminf(xv, 0.f) - log1pf(expf(-fabsf(xv)));
;             lf[((size_t)(b * 16 + i)) * SEQ + s] = ls;
;           }
	v_add_f32_e32 v0, v128, v0
	v_mul_f32_e64 v168, |v0|, s54
	v_fma_f32 v169, |v0|, s54, -v168
	v_rndne_f32_e32 v170, v168
	v_fma_f32 v169, |v0|, s55, v169
	v_sub_f32_e32 v168, v168, v170
	v_add_f32_e32 v168, v168, v169
	v_exp_f32_e32 v168, v168
	v_cvt_i32_f32_e32 v169, v170
	v_cmp_ngt_f32_e64 s[10:11], |v0|, s56
	v_min_f32_e32 v165, 0, v0
	v_ldexp_f32 v168, v168, v169
	v_cndmask_b32_e64 v168, 0, v168, s[10:11]
	v_cmp_nlt_f32_e64 s[10:11], |v0|, s57
	s_nop 1
	v_cndmask_b32_e64 v0, v197, v168, s[10:11]
	v_add_f32_e32 v170, 1.0, v0
	v_add_f32_e32 v168, -1.0, v170
	v_sub_f32_e32 v169, v168, v170
	v_add_f32_e32 v169, 1.0, v169
	v_sub_f32_e32 v168, v0, v168
	v_add_f32_e32 v171, v168, v169
	v_frexp_mant_f32_e32 v168, v170
	v_cmp_gt_f32_e64 s[10:11], s59, v168
	v_cvt_f64_f32_e32 v[168:169], v170
	v_frexp_exp_i32_f64_e32 v168, v[168:169]
	v_subbrev_co_u32_e64 v168, s[10:11], 0, v168, s[10:11]
	v_sub_u32_e32 v169, 0, v168
	v_ldexp_f32 v170, v170, v169
	v_ldexp_f32 v169, v171, v169
	v_add_f32_e32 v171, -1.0, v170
	v_add_f32_e32 v172, 1.0, v171
	v_sub_f32_e32 v172, v170, v172
	v_add_f32_e32 v172, v169, v172
	v_add_f32_e32 v174, v171, v172
	v_sub_f32_e32 v171, v171, v174
	v_add_f32_e32 v171, v172, v171
	v_add_f32_e32 v172, 1.0, v170
	v_add_f32_e32 v175, -1.0, v172
	v_sub_f32_e32 v170, v170, v175
	v_add_f32_e32 v169, v169, v170
	v_add_f32_e32 v170, v172, v169
	v_sub_f32_e32 v172, v172, v170
	v_add_f32_e32 v169, v169, v172
	v_rcp_f32_e32 v172, v170
	v_cvt_f32_i32_e32 v168, v168
	v_cmp_neq_f32_e64 s[10:11], s58, v0
	v_mul_f32_e32 v175, v174, v172
	v_mul_f32_e32 v176, v170, v175
	v_fma_f32 v177, v175, v170, -v176
	v_fmac_f32_e32 v177, v175, v169
	v_add_f32_e32 v194, v176, v177
	v_sub_f32_e32 v195, v174, v194
	v_sub_f32_e32 v174, v174, v195
	v_sub_f32_e32 v176, v194, v176
	v_sub_f32_e32 v174, v174, v194
	v_add_f32_e32 v171, v171, v174
	v_sub_f32_e32 v174, v176, v177
	v_add_f32_e32 v171, v174, v171
	v_add_f32_e32 v174, v195, v171
	v_mul_f32_e32 v176, v172, v174
	v_mul_f32_e32 v177, v170, v176
	v_fma_f32 v170, v176, v170, -v177
	v_fmac_f32_e32 v170, v176, v169
	v_sub_f32_e32 v169, v195, v174
	v_add_f32_e32 v169, v171, v169
	v_add_f32_e32 v171, v177, v170
	v_sub_f32_e32 v194, v174, v171
	v_sub_f32_e32 v174, v174, v194
	v_sub_f32_e32 v177, v171, v177
	v_sub_f32_e32 v171, v174, v171
	v_add_f32_e32 v169, v169, v171
	v_sub_f32_e32 v170, v177, v170
	v_add_f32_e32 v169, v170, v169
	v_add_f32_e32 v170, v175, v176
	v_add_f32_e32 v169, v194, v169
	v_sub_f32_e32 v171, v170, v175
	v_mul_f32_e32 v169, v172, v169
	v_sub_f32_e32 v171, v176, v171
	v_add_f32_e32 v169, v171, v169
	v_mul_f32_e32 v175, 0x3f317218, v168
	v_add_f32_e32 v171, v170, v169
	v_fma_f32 v176, v168, s60, -v175
	v_mul_f32_e32 v172, v171, v171
	v_fmac_f32_e32 v176, 0xb102e308, v168
	v_sub_f32_e32 v168, v171, v170
	v_fmamk_f32 v174, v172, 0x3e9b6dac, v196
	v_sub_f32_e32 v168, v169, v168
	v_add_f32_e32 v169, v175, v176
	v_fmaak_f32 v174, v172, v174, 0x3f2aaada
	v_sub_f32_e32 v170, v169, v175
	v_ldexp_f32 v175, v171, 1
	v_mul_f32_e32 v171, v171, v172
	v_mul_f32_e32 v171, v171, v174
	v_add_f32_e32 v172, v175, v171
	v_sub_f32_e32 v174, v172, v175
	v_ldexp_f32 v168, v168, 1
	v_sub_f32_e32 v171, v171, v174
	v_add_f32_e32 v168, v168, v171
	v_add_f32_e32 v171, v172, v168
	v_sub_f32_e32 v172, v171, v172
	v_sub_f32_e32 v168, v168, v172
	v_add_f32_e32 v172, v169, v171
	v_sub_f32_e32 v174, v172, v169
	v_sub_f32_e32 v175, v172, v174
	v_sub_f32_e32 v170, v176, v170
	v_sub_f32_e32 v169, v169, v175
	v_sub_f32_e32 v171, v171, v174
	v_add_f32_e32 v169, v171, v169
	v_add_f32_e32 v171, v170, v168
	v_sub_f32_e32 v174, v171, v170
	v_sub_f32_e32 v175, v171, v174
	v_sub_f32_e32 v170, v170, v175
	v_sub_f32_e32 v168, v168, v174
	v_add_f32_e32 v169, v171, v169
	v_add_f32_e32 v168, v168, v170
	v_add_f32_e32 v170, v172, v169
	v_sub_f32_e32 v171, v170, v172
	v_sub_f32_e32 v169, v169, v171
	v_add_f32_e32 v168, v168, v169
	v_add_f32_e32 v168, v170, v168
	v_cndmask_b32_e64 v168, v197, v168, s[10:11]
	v_cmp_lt_f32_e64 s[10:11], |v0|, s61
	s_nop 1
	v_cndmask_b32_e64 v0, v168, v0, s[10:11]
	v_sub_f32_e32 v0, v165, v0
	v_lshl_add_u64 v[168:169], v[166:167], 0, s[2:3]
	global_store_dword v[168:169], v0, off
	global_load_dword v0, v1, s[18:19] offset:60
	s_or_b32 s2, s38, 15
	s_ashr_i32 s3, s2, 31
	s_lshl_b64 s[4:5], s[2:3], 16
	v_lshl_add_u64 v[166:167], v[166:167], 0, s[4:5]
	s_waitcnt vmcnt(0)
;   DI void operator()(int tok0, int feat0, f32x16 (&acc)[2][2], int r, int hh) const {
;     ...
;           for (int i = 0; i < 16; ++i) {
;             const float xv = acc[0][mt][i] + bf[i];
;             const float ls = fminf(xv, 0.f) - log1pf(expf(-fabsf(xv)));
;             lf[((size_t)(b * 16 + i)) * SEQ + s] = ls;
;           }
	v_add_f32_e32 v0, v129, v0
	v_mul_f32_e64 v168, |v0|, s54
	v_fma_f32 v169, |v0|, s54, -v168
	v_rndne_f32_e32 v170, v168
	v_fma_f32 v169, |v0|, s55, v169
	v_sub_f32_e32 v168, v168, v170
	v_add_f32_e32 v168, v168, v169
	v_exp_f32_e32 v168, v168
	v_cvt_i32_f32_e32 v169, v170
	v_cmp_ngt_f32_e64 s[10:11], |v0|, s56
	v_min_f32_e32 v165, 0, v0
	v_ldexp_f32 v168, v168, v169
	v_cndmask_b32_e64 v168, 0, v168, s[10:11]
	v_cmp_nlt_f32_e64 s[10:11], |v0|, s57
	s_nop 1
	v_cndmask_b32_e64 v0, v197, v168, s[10:11]
	v_add_f32_e32 v170, 1.0, v0
	v_add_f32_e32 v168, -1.0, v170
	v_sub_f32_e32 v169, v168, v170
	v_add_f32_e32 v169, 1.0, v169
	v_sub_f32_e32 v168, v0, v168
	v_add_f32_e32 v171, v168, v169
	v_frexp_mant_f32_e32 v168, v170
	v_cmp_gt_f32_e64 s[10:11], s59, v168
	v_cvt_f64_f32_e32 v[168:169], v170
	v_frexp_exp_i32_f64_e32 v168, v[168:169]
	v_subbrev_co_u32_e64 v168, s[10:11], 0, v168, s[10:11]
	v_sub_u32_e32 v169, 0, v168
	v_ldexp_f32 v170, v170, v169
	v_ldexp_f32 v169, v171, v169
	v_add_f32_e32 v171, -1.0, v170
	v_add_f32_e32 v172, 1.0, v171
	v_sub_f32_e32 v172, v170, v172
	v_add_f32_e32 v172, v169, v172
	v_add_f32_e32 v174, v171, v172
	v_sub_f32_e32 v171, v171, v174
	v_add_f32_e32 v171, v172, v171
	v_add_f32_e32 v172, 1.0, v170
	v_add_f32_e32 v175, -1.0, v172
	v_sub_f32_e32 v170, v170, v175
	v_add_f32_e32 v169, v169, v170
	v_add_f32_e32 v170, v172, v169
	v_sub_f32_e32 v172, v172, v170
	v_add_f32_e32 v169, v169, v172
	v_rcp_f32_e32 v172, v170
	v_cvt_f32_i32_e32 v168, v168
	v_cmp_neq_f32_e64 s[10:11], s58, v0
	v_mul_f32_e32 v175, v174, v172
	v_mul_f32_e32 v176, v170, v175
	v_fma_f32 v177, v175, v170, -v176
	v_fmac_f32_e32 v177, v175, v169
	v_add_f32_e32 v194, v176, v177
	v_sub_f32_e32 v195, v174, v194
	v_sub_f32_e32 v174, v174, v195
	v_sub_f32_e32 v176, v194, v176
	v_sub_f32_e32 v174, v174, v194
	v_add_f32_e32 v171, v171, v174
	v_sub_f32_e32 v174, v176, v177
	v_add_f32_e32 v171, v174, v171
	v_add_f32_e32 v174, v195, v171
	v_mul_f32_e32 v176, v172, v174
	v_mul_f32_e32 v177, v170, v176
	v_fma_f32 v170, v176, v170, -v177
	v_fmac_f32_e32 v170, v176, v169
	v_sub_f32_e32 v169, v195, v174
	v_add_f32_e32 v169, v171, v169
	v_add_f32_e32 v171, v177, v170
	v_sub_f32_e32 v194, v174, v171
	v_sub_f32_e32 v174, v174, v194
	v_sub_f32_e32 v177, v171, v177
	v_sub_f32_e32 v171, v174, v171
	v_add_f32_e32 v169, v169, v171
	v_sub_f32_e32 v170, v177, v170
	v_add_f32_e32 v169, v170, v169
	v_add_f32_e32 v170, v175, v176
	v_add_f32_e32 v169, v194, v169
	v_sub_f32_e32 v171, v170, v175
	v_mul_f32_e32 v169, v172, v169
	v_sub_f32_e32 v171, v176, v171
	v_add_f32_e32 v169, v171, v169
	v_mul_f32_e32 v175, 0x3f317218, v168
	v_add_f32_e32 v171, v170, v169
	v_fma_f32 v176, v168, s60, -v175
	v_mul_f32_e32 v172, v171, v171
	v_fmac_f32_e32 v176, 0xb102e308, v168
	v_sub_f32_e32 v168, v171, v170
	v_fmamk_f32 v174, v172, 0x3e9b6dac, v196
	v_sub_f32_e32 v168, v169, v168
	v_add_f32_e32 v169, v175, v176
	v_fmaak_f32 v174, v172, v174, 0x3f2aaada
	v_sub_f32_e32 v170, v169, v175
	v_ldexp_f32 v175, v171, 1
	v_mul_f32_e32 v171, v171, v172
	v_mul_f32_e32 v171, v171, v174
	v_add_f32_e32 v172, v175, v171
	v_sub_f32_e32 v174, v172, v175
	v_ldexp_f32 v168, v168, 1
	v_sub_f32_e32 v171, v171, v174
	v_add_f32_e32 v168, v168, v171
	v_add_f32_e32 v171, v172, v168
	v_sub_f32_e32 v172, v171, v172
	v_sub_f32_e32 v168, v168, v172
	v_add_f32_e32 v172, v169, v171
	v_sub_f32_e32 v174, v172, v169
	v_sub_f32_e32 v175, v172, v174
	v_sub_f32_e32 v170, v176, v170
	v_sub_f32_e32 v169, v169, v175
	v_sub_f32_e32 v171, v171, v174
	v_add_f32_e32 v169, v171, v169
	v_add_f32_e32 v171, v170, v168
	v_sub_f32_e32 v174, v171, v170
	v_sub_f32_e32 v175, v171, v174
	v_sub_f32_e32 v170, v170, v175
	v_sub_f32_e32 v168, v168, v174
	v_add_f32_e32 v169, v171, v169
	v_add_f32_e32 v168, v168, v170
	v_add_f32_e32 v170, v172, v169
	v_sub_f32_e32 v171, v170, v172
	v_sub_f32_e32 v169, v169, v171
	v_add_f32_e32 v168, v168, v169
	v_add_f32_e32 v168, v170, v168
	v_cndmask_b32_e64 v168, v197, v168, s[10:11]
	v_cmp_lt_f32_e64 s[10:11], |v0|, s61
	s_nop 1
	v_cndmask_b32_e64 v0, v168, v0, s[10:11]
	v_sub_f32_e32 v0, v165, v0
	global_store_dword v[166:167], v0, off

; #define G_GLOAD(XR, WR, KT) { _Pragma("unroll") for (int i_ = 0; i_ < 4; ++i_) XR[i_] = *(const u32x4*)(Xt + ((size_t)(64 * i_) * ldx + (KT) * 64) * 2 + xoff); \
;     _Pragma("unroll") for (int i_ = 0; i_ < 4; ++i_) WR[i_] = *(const u32x4*)(Wtb + ((size_t)(64 * i_) * K + (KT) * 64) * 2 + woff); }
; #define G_LSTORE(XR, WR, STG) { char* xs_ = lds + (STG) * G_STAGE; char* ws_ = xs_ + G_XB; \
;     _Pragma("unroll") for (int i_ = 0; i_ < 4; ++i_) *(u32x4*)(xs_ + (lrow + 64 * i_) * LROW + lch * 16) = XR[i_]; \
;     _Pragma("unroll") for (int i_ = 0; i_ < 4; ++i_) *(u32x4*)(ws_ + (lrow + 64 * i_) * LROW + lch * 16) = WR[i_]; }
; template <class Epi>
; DI void gemm_phase(const bf16_t* __restrict__ X, const int ldx, const bf16_t* __restrict__ Wt, const int N, const int K, const Epi& epi, char* lds) {
;     ...
;     const int L = chunk * 32 + slot, band = L / (4 * nNt), rem = L % (4 * nNt);
;     const int mt_ = band * 4 + (rem & 3), nt_ = rem >> 2;
;     const char* Xt = (const char*)(X + (size_t)(mt_ * 256) * ldx);
;     const char* Wtb = (const char*)(Wt + (size_t)(nt_ * 256) * K);
;     const unsigned xoff = (unsigned)(lrow * ldx + lch * 8) * 2u, woff = (unsigned)(lrow * K + lch * 8) * 2u;
;     const bool has_next = !Epi::kFull && (chunk + 8 < nchunks);
;     const int Ln = (has_next ? chunk + 8 : chunk) * 32 + slot, band_n = Ln / (4 * nNt), rem_n = Ln % (4 * nNt);
;     const char* Xt_n = (const char*)(X + (size_t)((band_n * 4 + (rem_n & 3)) * 256) * ldx);
;     const char* Wtb_n = (const char*)(Wt + (size_t)((rem_n >> 2) * 256) * K);
;     f32x16 acc[2][2][2];
;     ...
;     asm volatile("" ::: "memory");
;     if (Epi::kFull || chunk == xcd) {
;       G_GLOAD(xr0, wr0, 0);
;       G_LSTORE(xr0, wr0, 0);
;       __syncthreads();
;       G_GLOAD(xr0, wr0, 1);
;     }
.LBB0_268:
	s_lshl_b32 s2, s34, 5
	v_readlane_b32 s3, v254, 3
	s_add_i32 s2, s2, s3
	s_lshr_b32 s2, s2, 2
	s_and_b32 s2, s2, 0xffffffc
	s_or_b32 s2, s2, s90
	s_lshl_b32 s4, s2, 8
	s_mov_b32 s5, s97
	s_lshl_b64 s[20:21], s[4:5], 11
	s_add_u32 s20, s12, s20
	s_addc_u32 s21, s13, s21
	v_lshl_add_u64 v[178:179], s[20:21], 0, v[162:163]
	s_waitcnt vmcnt(2)
	v_add_co_u32_e32 v48, vcc, s91, v178
	s_mov_b64 s[22:23], 0x40000
	s_nop 0
	v_addc_co_u32_e32 v49, vcc, 0, v179, vcc
	v_add_co_u32_e32 v74, vcc, s1, v178
	global_load_dwordx4 v[24:27], v[178:179], off
	global_load_dwordx4 v[28:31], v[48:49], off
	v_addc_co_u32_e32 v75, vcc, 0, v179, vcc
	v_add_co_u32_e32 v76, vcc, s76, v178
	global_load_dwordx4 v[32:35], v[164:165], off
	global_load_dwordx4 v[36:39], v[198:199], off
	global_load_dwordx4 v[40:43], v[206:207], off
	global_load_dwordx4 v[44:47], v[170:171], off
	v_addc_co_u32_e32 v77, vcc, 0, v179, vcc
	global_load_dwordx4 v[66:69], v[74:75], off
	global_load_dwordx4 v[70:73], v[76:77], off
	v_mov_b32_e32 v2, 0
	v_lshl_add_u64 v[180:181], v[178:179], 0, s[22:23]
	s_mov_b64 s[22:23], 0x60000
	s_mov_b32 s21, 0
	s_movk_i32 s3, 0x100
	v_mov_b32_e32 v3, v2
	s_waitcnt vmcnt(9)
	s_waitcnt vmcnt(8)
	v_mov_b32_e32 v22, v2
	v_lshl_add_u64 v[182:183], v[178:179], 0, s[22:23]
	v_mov_b32_e32 v23, v2
	v_mov_b32_e32 v104, v2
	s_waitcnt vmcnt(5)
	ds_write_b128 v222, v[32:35] offset:36864
	s_waitcnt vmcnt(4)
	ds_write_b128 v222, v[36:39] offset:46080
	s_waitcnt vmcnt(3)
	ds_write_b128 v222, v[40:43] offset:55296
	s_waitcnt vmcnt(2)
	ds_write_b128 v222, v[44:47] offset:64512
	ds_write_b128 v222, v[24:27]
	ds_write_b128 v222, v[28:31] offset:9216
	s_waitcnt vmcnt(1)
	ds_write_b128 v222, v[66:69] offset:18432
	s_waitcnt vmcnt(0)
	ds_write_b128 v222, v[70:73] offset:27648
	s_waitcnt lgkmcnt(0)
	s_barrier
	global_load_dwordx4 v[130:133], v[174:175], off
	global_load_dwordx4 v[150:153], v[176:177], off
	global_load_dwordx4 v[158:161], v[172:173], off
	global_load_dwordx4 v[138:141], v[164:165], off offset:128
	global_load_dwordx4 v[146:149], v[76:77], off offset:128
	global_load_dwordx4 v[134:137], v[74:75], off offset:128
	global_load_dwordx4 v[154:157], v[48:49], off offset:128
	global_load_dwordx4 v[142:145], v[178:179], off offset:128
	v_mov_b32_e32 v105, v2
	v_mov_b32_e32 v118, v2
	v_mov_b32_e32 v119, v2
	v_mov_b32_e32 v120, v2
	v_mov_b32_e32 v121, v2
	v_mov_b32_e32 v122, v2
	v_mov_b32_e32 v123, v2
	v_mov_b32_e32 v124, v2
	v_mov_b32_e32 v125, v2
	v_mov_b32_e32 v126, v2
	v_mov_b32_e32 v127, v2
	v_mov_b32_e32 v128, v2
	v_mov_b32_e32 v129, v2
	v_readfirstlane_b32 vcc_lo, v162
	v_readfirstlane_b32 s98, v178
	v_readfirstlane_b32 s99, v179
	v_readfirstlane_b32 s100, v164
	v_readfirstlane_b32 s101, v165
	s_nop 4
	s_sub_u32 s98, s98, vcc_lo
	s_subb_u32 s99, s99, 0
	s_sub_u32 s100, s100, vcc_lo
	s_subb_u32 s101, s101, 0
	v_add_u32_e32 v179, s91, v162
	v_add_u32_e32 v181, s1, v162
	v_add_u32_e32 v183, s76, v162
	v_add_u32_e32 v178, v191, v208
	v_add_u32_e32 v180, v191, v209
	v_add_u32_e32 v182, v210, v190
	ds_read_b128 v[166:169], v178
	ds_read_b128 v[184:187], v178 offset:4608
	ds_read_b128 v[194:197], v180 offset:36864
	ds_read_b128 v[202:205], v180 offset:41472
	ds_read_b128 v[224:227], v180 offset:46080
	ds_read_b128 v[228:231], v180 offset:50688
	ds_read_b128 v[232:235], v212 offset:32
	ds_read_b128 v[236:239], v212 offset:4640
	s_add_i32 s5, s21, 2
	s_cmp_lt_u32 s21, 14
	s_cselect_b32 s96, s3, 0x780
	s_min_u32 s20, s21, 12
	s_lshl_b32 s20, s20, 7
	s_addk_i32 s3, 0x100
	s_cmp_gt_u32 s21, 13
	s_waitcnt lgkmcnt(5)
	v_mfma_f32_32x32x16_bf16 v[114:129], v[194:197], v[166:169], 0
	v_mfma_f32_32x32x16_bf16 v[66:81], v[194:197], v[184:187], 0
	s_waitcnt lgkmcnt(4)
	v_mfma_f32_32x32x16_bf16 v[98:113], v[202:205], v[166:169], 0
	v_mfma_f32_32x32x16_bf16 v[34:49], v[202:205], v[184:187], 0
	s_waitcnt lgkmcnt(3)
	v_mfma_f32_32x32x16_bf16 v[82:97], v[224:227], v[166:169], 0
	v_mfma_f32_32x32x16_bf16 v[18:33], v[224:227], v[184:187], 0
	s_waitcnt lgkmcnt(2)
	v_mfma_f32_32x32x16_bf16 v[50:65], v[228:231], v[166:169], 0
	ds_read_b128 v[166:169], v213 offset:36896
	ds_read_b128 v[194:197], v213 offset:41504
	v_mfma_f32_32x32x16_bf16 v[2:17], v[228:231], v[184:187], 0
	s_waitcnt vmcnt(1)
	ds_write_b128 v214, v[154:157] offset:9216
	s_waitcnt vmcnt(0)
	ds_write_b128 v214, v[142:145]
	s_add_u32 vcc_lo, s98, s96
	s_addc_u32 vcc_hi, s99, 0
	global_load_dwordx4 v[142:145], v162, vcc
	global_load_dwordx4 v[154:157], v179, vcc
	ds_write_b128 v214, v[134:137] offset:18432
	ds_write_b128 v214, v[146:149] offset:27648
	global_load_dwordx4 v[134:137], v181, vcc
	global_load_dwordx4 v[146:149], v183, vcc
	ds_read_b128 v[184:187], v213 offset:46112
	ds_read_b128 v[202:205], v213 offset:50720
	ds_read_b128 v[224:227], v212 offset:64
	ds_read_b128 v[228:231], v212 offset:4672
	s_waitcnt lgkmcnt(9)
	v_mfma_f32_32x32x16_bf16 v[114:129], v[166:169], v[232:235], v[114:129]
	v_mfma_f32_32x32x16_bf16 v[66:81], v[166:169], v[236:239], v[66:81]
	s_waitcnt lgkmcnt(8)
	v_mfma_f32_32x32x16_bf16 v[98:113], v[194:197], v[232:235], v[98:113]
	v_mfma_f32_32x32x16_bf16 v[34:49], v[194:197], v[236:239], v[34:49]
	s_waitcnt lgkmcnt(3)
	v_mfma_f32_32x32x16_bf16 v[82:97], v[184:187], v[232:235], v[82:97]
	v_mfma_f32_32x32x16_bf16 v[18:33], v[184:187], v[236:239], v[18:33]
	ds_read_b128 v[166:169], v213 offset:36928
	ds_read_b128 v[184:187], v213 offset:41536
	s_waitcnt lgkmcnt(4)
	v_mfma_f32_32x32x16_bf16 v[50:65], v[202:205], v[232:235], v[50:65]
	v_mfma_f32_32x32x16_bf16 v[2:17], v[202:205], v[236:239], v[2:17]
	ds_write_b128 v215, v[150:153] offset:9216
	ds_write_b128 v215, v[138:141]
	s_add_u32 vcc_lo, s100, s96
	s_addc_u32 vcc_hi, s101, 0
	global_load_dwordx4 v[138:141], v162, vcc
	global_load_dwordx4 v[150:153], v179, vcc
	ds_read_b128 v[194:197], v213 offset:46144
	ds_read_b128 v[202:205], v213 offset:50752
	ds_read_b128 v[232:235], v212 offset:96
	ds_read_b128 v[236:239], v212 offset:4704
	s_waitcnt lgkmcnt(7)
	v_mfma_f32_32x32x16_bf16 v[114:129], v[166:169], v[224:227], v[114:129]
	v_mfma_f32_32x32x16_bf16 v[66:81], v[166:169], v[228:231], v[66:81]
	s_waitcnt lgkmcnt(6)
	v_mfma_f32_32x32x16_bf16 v[98:113], v[184:187], v[224:227], v[98:113]
	v_mfma_f32_32x32x16_bf16 v[34:49], v[184:187], v[228:231], v[34:49]
	s_waitcnt lgkmcnt(3)
	v_mfma_f32_32x32x16_bf16 v[82:97], v[194:197], v[224:227], v[82:97]
	ds_read_b128 v[166:169], v213 offset:36960
	ds_read_b128 v[184:187], v213 offset:41568
	v_mfma_f32_32x32x16_bf16 v[18:33], v[194:197], v[228:231], v[18:33]
	s_waitcnt lgkmcnt(4)
	v_mfma_f32_32x32x16_bf16 v[50:65], v[202:205], v[224:227], v[50:65]
	v_mfma_f32_32x32x16_bf16 v[2:17], v[202:205], v[228:231], v[2:17]
	ds_write_b128 v215, v[130:133] offset:18432
	ds_write_b128 v215, v[158:161] offset:27648
	global_load_dwordx4 v[130:133], v181, vcc
	global_load_dwordx4 v[158:161], v183, vcc
	ds_read_b128 v[194:197], v213 offset:46176
	ds_read_b128 v[202:205], v213 offset:50784
	s_waitcnt lgkmcnt(5)
	v_mfma_f32_32x32x16_bf16 v[114:129], v[166:169], v[232:235], v[114:129]
	v_mfma_f32_32x32x16_bf16 v[66:81], v[166:169], v[236:239], v[66:81]
	s_waitcnt lgkmcnt(4)
	v_mfma_f32_32x32x16_bf16 v[98:113], v[184:187], v[232:235], v[98:113]
	v_mfma_f32_32x32x16_bf16 v[34:49], v[184:187], v[236:239], v[34:49]
	s_waitcnt lgkmcnt(1)
	v_mfma_f32_32x32x16_bf16 v[82:97], v[194:197], v[232:235], v[82:97]
	v_mfma_f32_32x32x16_bf16 v[18:33], v[194:197], v[236:239], v[18:33]
	s_waitcnt lgkmcnt(0)
	v_mfma_f32_32x32x16_bf16 v[50:65], v[202:205], v[232:235], v[50:65]
	v_mfma_f32_32x32x16_bf16 v[2:17], v[202:205], v[236:239], v[2:17]
	s_barrier
	ds_read_b128 v[166:169], v216
	ds_read_b128 v[184:187], v216 offset:4608
	ds_read_b128 v[194:197], v217
	ds_read_b128 v[202:205], v217 offset:4608
	ds_read_b128 v[224:227], v217 offset:9216
	ds_read_b128 v[228:231], v217 offset:13824
	ds_read_b128 v[232:235], v182 offset:32
	ds_read_b128 v[236:239], v218 offset:32
	s_waitcnt lgkmcnt(5)
	v_mfma_f32_32x32x16_bf16 v[114:129], v[194:197], v[166:169], v[114:129]
	v_mfma_f32_32x32x16_bf16 v[66:81], v[194:197], v[184:187], v[66:81]
	s_waitcnt lgkmcnt(4)
	v_mfma_f32_32x32x16_bf16 v[98:113], v[202:205], v[166:169], v[98:113]
	v_mfma_f32_32x32x16_bf16 v[34:49], v[202:205], v[184:187], v[34:49]
	s_waitcnt lgkmcnt(3)
	v_mfma_f32_32x32x16_bf16 v[82:97], v[224:227], v[166:169], v[82:97]
	v_add_u32_e32 v223, v211, v190
	v_mfma_f32_32x32x16_bf16 v[18:33], v[224:227], v[184:187], v[18:33]
	s_waitcnt lgkmcnt(2)
	v_mfma_f32_32x32x16_bf16 v[50:65], v[228:231], v[166:169], v[50:65]
	ds_read_b128 v[166:169], v223 offset:32
	ds_read_b128 v[194:197], v219 offset:32
	v_mfma_f32_32x32x16_bf16 v[2:17], v[228:231], v[184:187], v[2:17]
	s_mov_b32 s21, s97
	s_waitcnt vmcnt(6)
	ds_write_b128 v222, v[154:157] offset:9216
	ds_write_b128 v222, v[142:145]
	s_add_u32 vcc_lo, s98, s20
	s_addc_u32 vcc_hi, s99, 0
	global_load_dwordx4 v[142:145], v162, vcc offset:384
	global_load_dwordx4 v[154:157], v179, vcc offset:384
	s_waitcnt vmcnt(7)
	ds_write_b128 v222, v[134:137] offset:18432
	s_waitcnt vmcnt(6)
	ds_write_b128 v222, v[146:149] offset:27648
	global_load_dwordx4 v[134:137], v181, vcc offset:384
	global_load_dwordx4 v[146:149], v183, vcc offset:384
	ds_read_b128 v[184:187], v220 offset:32
	ds_read_b128 v[202:205], v221 offset:32
	ds_read_b128 v[224:227], v182 offset:64
	ds_read_b128 v[228:231], v218 offset:64
	s_waitcnt lgkmcnt(9)
	v_mfma_f32_32x32x16_bf16 v[114:129], v[166:169], v[232:235], v[114:129]
	v_mfma_f32_32x32x16_bf16 v[66:81], v[166:169], v[236:239], v[66:81]
	s_waitcnt lgkmcnt(8)
	v_mfma_f32_32x32x16_bf16 v[98:113], v[194:197], v[232:235], v[98:113]
	v_mfma_f32_32x32x16_bf16 v[34:49], v[194:197], v[236:239], v[34:49]
	s_waitcnt lgkmcnt(3)
	v_mfma_f32_32x32x16_bf16 v[82:97], v[184:187], v[232:235], v[82:97]
	v_mfma_f32_32x32x16_bf16 v[18:33], v[184:187], v[236:239], v[18:33]
	ds_read_b128 v[166:169], v223 offset:64
	ds_read_b128 v[184:187], v219 offset:64
	s_waitcnt lgkmcnt(4)
	v_mfma_f32_32x32x16_bf16 v[50:65], v[202:205], v[232:235], v[50:65]
	v_mfma_f32_32x32x16_bf16 v[2:17], v[202:205], v[236:239], v[2:17]
	s_waitcnt vmcnt(6)
	ds_write_b128 v222, v[150:153] offset:46080
	ds_write_b128 v222, v[138:141] offset:36864
	s_add_u32 vcc_lo, s100, s20
	s_addc_u32 vcc_hi, s101, 0
	global_load_dwordx4 v[138:141], v162, vcc offset:384
	global_load_dwordx4 v[150:153], v179, vcc offset:384
	ds_read_b128 v[194:197], v220 offset:64
	ds_read_b128 v[202:205], v221 offset:64
	ds_read_b128 v[232:235], v182 offset:96
	ds_read_b128 v[236:239], v218 offset:96
	s_waitcnt lgkmcnt(7)
	v_mfma_f32_32x32x16_bf16 v[114:129], v[166:169], v[224:227], v[114:129]
	v_mfma_f32_32x32x16_bf16 v[66:81], v[166:169], v[228:231], v[66:81]
	s_waitcnt lgkmcnt(6)
	v_mfma_f32_32x32x16_bf16 v[98:113], v[184:187], v[224:227], v[98:113]
	v_mfma_f32_32x32x16_bf16 v[34:49], v[184:187], v[228:231], v[34:49]
	s_waitcnt lgkmcnt(3)
	v_mfma_f32_32x32x16_bf16 v[82:97], v[194:197], v[224:227], v[82:97]
	ds_read_b128 v[166:169], v223 offset:96
	ds_read_b128 v[184:187], v219 offset:96
	v_mfma_f32_32x32x16_bf16 v[18:33], v[194:197], v[228:231], v[18:33]
	s_waitcnt lgkmcnt(4)
	v_mfma_f32_32x32x16_bf16 v[50:65], v[202:205], v[224:227], v[50:65]
	v_mfma_f32_32x32x16_bf16 v[2:17], v[202:205], v[228:231], v[2:17]
	s_waitcnt vmcnt(7)
	ds_write_b128 v222, v[130:133] offset:55296
	s_waitcnt vmcnt(6)
	ds_write_b128 v222, v[158:161] offset:64512
	global_load_dwordx4 v[130:133], v181, vcc offset:384
	global_load_dwordx4 v[158:161], v183, vcc offset:384
	ds_read_b128 v[194:197], v220 offset:96
	ds_read_b128 v[202:205], v221 offset:96
	s_waitcnt lgkmcnt(5)
	v_mfma_f32_32x32x16_bf16 v[114:129], v[166:169], v[232:235], v[114:129]
	v_mfma_f32_32x32x16_bf16 v[66:81], v[166:169], v[236:239], v[66:81]
	s_waitcnt lgkmcnt(4)
	v_mfma_f32_32x32x16_bf16 v[98:113], v[184:187], v[232:235], v[98:113]
	v_mfma_f32_32x32x16_bf16 v[34:49], v[184:187], v[236:239], v[34:49]
	s_waitcnt lgkmcnt(1)
	v_mfma_f32_32x32x16_bf16 v[82:97], v[194:197], v[232:235], v[82:97]
	v_mfma_f32_32x32x16_bf16 v[18:33], v[194:197], v[236:239], v[18:33]
	s_waitcnt lgkmcnt(0)
	v_mfma_f32_32x32x16_bf16 v[50:65], v[202:205], v[232:235], v[50:65]
	v_mfma_f32_32x32x16_bf16 v[2:17], v[202:205], v[236:239], v[2:17]
	s_mov_b32 s21, s5
	s_cmp_gt_u32 s21, 15
	s_barrier
	s_cbranch_scc0 .LBB0_269
	s_branch .Lkexit_1

; #define RL_LOAD(XV, G) { constexpr int mt__ = (G) >> 2, half__ = ((G) >> 1) & 1, nt__ = (G) & 1; \
;     _Pragma("unroll") for (int gq = 0; gq < 4; ++gq) XV[gq] = *(const f32x4*)(xin + rbase + (size_t)mt__ * 32 * 1024 + half__ * 64 + nt__ * 32 + 4 * gq); }
; #define RL_FOLD(XV, G, SM, SQ) { constexpr int mt__ = (G) >> 2, half__ = ((G) >> 1) & 1, nt__ = (G) & 1; \
;     _Pragma("unroll") for (int gq = 0; gq < 4; ++gq) _Pragma("unroll") for (int jj = 0; jj < 4; ++jj) { \
;       const float y = ALPHA * XV[gq][jj] + acc[half__][nt__][mt__][4 * gq + jj]; acc[half__][nt__][mt__][4 * gq + jj] = y; SM += y; SQ += y * y; } }
; #define SB __builtin_amdgcn_sched_barrier(0)
;   DI void full(const int mt_, const int nt_, f32x16 (&acc)[2][2][2], const int tw, const int fw, const int r, const int hh, char* lds, const int tid) const {
;     float* part = (float*)(lds + G_STAGE);
;     const size_t rbase = (size_t)(mt_ * 256 + tw * 64 + r) * 1024 + nt_ * 256 + fw * 128 + 16 * hh;
;     f32x4 xa[4], xc[4], xe[4];
;     ...
;     float sm0 = 0.f, sq0 = 0.f, sm1 = 0.f, sq1 = 0.f;
;     RL_LOAD(xa, 0); RL_LOAD(xc, 1); RL_LOAD(xe, 2); SB;
;     RL_FOLD(xa, 0, sm0, sq0); SB; RL_LOAD(xa, 3); SB;
;     RL_FOLD(xc, 1, sm0, sq0); SB; RL_LOAD(xc, 4); SB;
;     RL_FOLD(xe, 2, sm0, sq0); SB; RL_LOAD(xe, 5); SB;
;     RL_FOLD(xa, 3, sm0, sq0); SB; RL_LOAD(xa, 6); SB;
;     RL_FOLD(xc, 4, sm1, sq1); SB; RL_LOAD(xc, 7); SB;
;     RL_FOLD(xe, 5, sm1, sq1); SB;
;     RL_FOLD(xa, 6, sm1, sq1); SB;
;     RL_FOLD(xc, 7, sm1, sq1);
.Lkexit_1:
	v_mov_b32_e32 v184, v192
	s_waitcnt vmcnt(1)
	v_ashrrev_i32_e32 v130, 1, v184
	v_and_b32_e32 v223, 0xdf, v184
	v_and_b32_e32 v182, 0xffffff80, v130
	v_or_b32_e32 v0, s4, v223
	v_ashrrev_i32_e32 v183, 31, v182
	v_bfe_u32 v224, v184, 5, 1
	v_lshl_add_u64 v[130:131], v[182:183], 2, s[18:19]
	v_lshlrev_b64 v[132:133], 12, v[0:1]
	v_lshl_add_u64 v[130:131], v[130:131], 0, v[132:133]
	v_lshlrev_b32_e32 v132, 6, v224
	v_mov_b32_e32 v133, v1
	v_lshl_add_u64 v[186:187], v[130:131], 0, v[132:133]
	global_load_dwordx4 v[130:133], v[186:187], off offset:48
	global_load_dwordx4 v[134:137], v[186:187], off offset:32
	global_load_dwordx4 v[138:141], v[186:187], off offset:16
	global_load_dwordx4 v[142:145], v[186:187], off
	global_load_dwordx4 v[194:197], v[186:187], off offset:176
	global_load_dwordx4 v[202:205], v[186:187], off offset:160
	global_load_dwordx4 v[226:229], v[186:187], off offset:144
	global_load_dwordx4 v[146:149], v[186:187], off offset:128
	global_load_dwordx4 v[230:233], v[186:187], off offset:304
	global_load_dwordx4 v[234:237], v[186:187], off offset:288
	global_load_dwordx4 v[238:241], v[186:187], off offset:272
	global_load_dwordx4 v[242:245], v[186:187], off offset:256
	s_waitcnt vmcnt(8)
	v_pk_fma_f32 v[178:179], v[142:143], s[0:1], v[114:115] op_sel_hi:[1,0,1]
	v_pk_fma_f32 v[180:181], v[144:145], s[0:1], v[116:117] op_sel_hi:[1,0,1]
	v_add_f32_e32 v114, 0, v178
	v_add_f32_e32 v142, v179, v114
	v_mul_f32_e32 v114, v179, v179
	v_pk_fma_f32 v[114:115], v[178:179], v[178:179], v[114:115] op_sel_hi:[1,1,0]
	v_add_f32_e32 v116, v180, v142
	v_pk_fma_f32 v[114:115], v[180:181], v[180:181], v[114:115]
	v_add_f32_e32 v117, v181, v116
	v_mul_f32_e32 v116, v181, v181
	v_pk_fma_f32 v[158:159], v[138:139], s[0:1], v[118:119] op_sel_hi:[1,0,1]
	v_pk_add_f32 v[114:115], v[116:117], v[114:115] op_sel_hi:[0,1]
	v_add_f32_e32 v116, v158, v117
	v_pk_fma_f32 v[114:115], v[158:159], v[158:159], v[114:115]
	v_add_f32_e32 v117, v159, v116
	v_mul_f32_e32 v116, v159, v159
	v_pk_fma_f32 v[160:161], v[140:141], s[0:1], v[120:121] op_sel_hi:[1,0,1]
	v_pk_add_f32 v[114:115], v[116:117], v[114:115] op_sel_hi:[0,1]
	v_add_f32_e32 v116, v160, v117
	v_pk_fma_f32 v[114:115], v[160:161], v[160:161], v[114:115]
	v_add_f32_e32 v117, v161, v116
	v_mul_f32_e32 v116, v161, v161
	v_pk_fma_f32 v[154:155], v[134:135], s[0:1], v[122:123] op_sel_hi:[1,0,1]
	v_pk_add_f32 v[114:115], v[116:117], v[114:115] op_sel_hi:[0,1]
	v_add_f32_e32 v116, v154, v117
	v_pk_fma_f32 v[114:115], v[154:155], v[154:155], v[114:115]
	v_add_f32_e32 v117, v155, v116
	v_mul_f32_e32 v116, v155, v155
	v_pk_fma_f32 v[156:157], v[136:137], s[0:1], v[124:125] op_sel_hi:[1,0,1]
	v_pk_add_f32 v[114:115], v[116:117], v[114:115] op_sel_hi:[0,1]
	v_add_f32_e32 v116, v156, v117
	v_pk_fma_f32 v[114:115], v[156:157], v[156:157], v[114:115]
	v_add_f32_e32 v124, v157, v116
	v_mul_f32_e32 v116, v157, v157
	v_pk_add_f32 v[114:115], v[116:117], v[114:115] op_sel_hi:[0,1]
	v_pk_fma_f32 v[152:153], v[130:131], s[0:1], v[126:127] op_sel_hi:[1,0,1]
	v_pk_fma_f32 v[150:151], v[132:133], s[0:1], v[128:129] op_sel_hi:[1,0,1]
	v_pk_fma_f32 v[114:115], v[152:153], v[152:153], v[114:115]
	v_mul_f32_e32 v116, v153, v153
	v_pk_add_f32 v[114:115], v[116:117], v[114:115] op_sel_hi:[0,1]
	v_pk_fma_f32 v[114:115], v[150:151], v[150:151], v[114:115]
	v_mul_f32_e32 v116, v151, v151
	v_pk_add_f32 v[118:119], v[116:117], v[114:115] op_sel_hi:[0,1]
	global_load_dwordx4 v[114:117], v[186:187], off offset:432
	global_load_dwordx4 v[246:249], v[186:187], off offset:416
	global_load_dwordx4 v[250:253], v[186:187], off offset:400
	global_load_dwordx4 v[120:123], v[186:187], off offset:384
	v_add_f32_e32 v124, v152, v124
	v_add_f32_e32 v124, v153, v124
	v_add_f32_e32 v124, v150, v124
	v_add_f32_e32 v124, v151, v124
	s_waitcnt vmcnt(8)
	v_pk_fma_f32 v[144:145], v[146:147], s[0:1], v[98:99] op_sel_hi:[1,0,1]
	v_pk_fma_f32 v[148:149], v[148:149], s[0:1], v[100:101] op_sel_hi:[1,0,1]
	v_add_f32_e32 v124, v144, v124
	v_pk_fma_f32 v[98:99], v[144:145], v[144:145], v[118:119]
	v_add_f32_e32 v119, v145, v124
	v_mul_f32_e32 v118, v145, v145
	v_pk_add_f32 v[98:99], v[118:119], v[98:99] op_sel_hi:[0,1]
	v_add_f32_e32 v100, v148, v119
	v_pk_fma_f32 v[98:99], v[148:149], v[148:149], v[98:99]
	v_add_f32_e32 v101, v149, v100
	v_mul_f32_e32 v100, v149, v149
	v_pk_fma_f32 v[138:139], v[226:227], s[0:1], v[102:103] op_sel_hi:[1,0,1]
	v_pk_add_f32 v[98:99], v[100:101], v[98:99] op_sel_hi:[0,1]
	v_add_f32_e32 v100, v138, v101
	v_pk_fma_f32 v[98:99], v[138:139], v[138:139], v[98:99]
	v_add_f32_e32 v101, v139, v100
	v_mul_f32_e32 v100, v139, v139
	v_pk_fma_f32 v[146:147], v[228:229], s[0:1], v[104:105] op_sel_hi:[1,0,1]
	v_pk_add_f32 v[98:99], v[100:101], v[98:99] op_sel_hi:[0,1]
	v_add_f32_e32 v100, v146, v101
	v_pk_fma_f32 v[98:99], v[146:147], v[146:147], v[98:99]
	v_add_f32_e32 v101, v147, v100
	v_mul_f32_e32 v100, v147, v147
	v_pk_fma_f32 v[130:131], v[202:203], s[0:1], v[106:107] op_sel_hi:[1,0,1]
	v_pk_add_f32 v[98:99], v[100:101], v[98:99] op_sel_hi:[0,1]
	v_add_f32_e32 v100, v130, v101
	v_pk_fma_f32 v[98:99], v[130:131], v[130:131], v[98:99]
	v_add_f32_e32 v101, v131, v100
	v_mul_f32_e32 v100, v131, v131
	v_pk_fma_f32 v[140:141], v[204:205], s[0:1], v[108:109] op_sel_hi:[1,0,1]
	v_pk_add_f32 v[98:99], v[100:101], v[98:99] op_sel_hi:[0,1]
	v_add_f32_e32 v100, v140, v101
	v_pk_fma_f32 v[98:99], v[140:141], v[140:141], v[98:99]
	v_add_f32_e32 v106, v141, v100
	v_mul_f32_e32 v100, v141, v141
	v_pk_add_f32 v[102:103], v[100:101], v[98:99] op_sel_hi:[0,1]
	v_pk_fma_f32 v[124:125], v[194:195], s[0:1], v[110:111] op_sel_hi:[1,0,1]
	v_pk_fma_f32 v[134:135], v[196:197], s[0:1], v[112:113] op_sel_hi:[1,0,1]
	v_add_co_u32_e32 v188, vcc, s91, v186
	s_mov_b64 s[20:21], 0x20000
	s_nop 0
	v_addc_co_u32_e32 v189, vcc, 0, v187, vcc
	v_lshl_add_u64 v[104:105], v[186:187], 0, s[20:21]
	global_load_dwordx4 v[194:197], v[188:189], off
	global_load_dwordx4 v[98:101], v[104:105], off offset:48
	global_load_dwordx4 v[202:205], v[104:105], off offset:32
	global_load_dwordx4 v[226:229], v[104:105], off offset:16
	v_add_f32_e32 v104, v124, v106
	v_pk_fma_f32 v[102:103], v[124:125], v[124:125], v[102:103]
	v_add_f32_e32 v105, v125, v104
	v_mul_f32_e32 v104, v125, v125
	v_pk_add_f32 v[102:103], v[104:105], v[102:103] op_sel_hi:[0,1]
	v_add_f32_e32 v104, v134, v105
	v_pk_fma_f32 v[102:103], v[134:135], v[134:135], v[102:103]
	v_add_f32_e32 v105, v135, v104
	v_mul_f32_e32 v104, v135, v135
	v_pk_add_f32 v[102:103], v[104:105], v[102:103] op_sel_hi:[0,1]
	s_waitcnt vmcnt(8)
; #define RL_LOAD(XV, G) { constexpr int mt__ = (G) >> 2, half__ = ((G) >> 1) & 1, nt__ = (G) & 1; \
;     _Pragma("unroll") for (int gq = 0; gq < 4; ++gq) XV[gq] = *(const f32x4*)(xin + rbase + (size_t)mt__ * 32 * 1024 + half__ * 64 + nt__ * 32 + 4 * gq); }
; #define RL_FOLD(XV, G, SM, SQ) { constexpr int mt__ = (G) >> 2, half__ = ((G) >> 1) & 1, nt__ = (G) & 1; \
;     _Pragma("unroll") for (int gq = 0; gq < 4; ++gq) _Pragma("unroll") for (int jj = 0; jj < 4; ++jj) { \
;       const float y = ALPHA * XV[gq][jj] + acc[half__][nt__][mt__][4 * gq + jj]; acc[half__][nt__][mt__][4 * gq + jj] = y; SM += y; SQ += y * y; } }
; #define SB __builtin_amdgcn_sched_barrier(0)
;   DI void full(const int mt_, const int nt_, f32x16 (&acc)[2][2][2], const int tw, const int fw, const int r, const int hh, char* lds, const int tid) const {
;     ...
;     float sm0 = 0.f, sq0 = 0.f, sm1 = 0.f, sq1 = 0.f;
;     RL_LOAD(xa, 0); RL_LOAD(xc, 1); RL_LOAD(xe, 2); SB;
;     RL_FOLD(xa, 0, sm0, sq0); SB; RL_LOAD(xa, 3); SB;
;     RL_FOLD(xc, 1, sm0, sq0); SB; RL_LOAD(xc, 4); SB;
;     RL_FOLD(xe, 2, sm0, sq0); SB; RL_LOAD(xe, 5); SB;
;     RL_FOLD(xa, 3, sm0, sq0); SB; RL_LOAD(xa, 6); SB;
;     RL_FOLD(xc, 4, sm1, sq1); SB; RL_LOAD(xc, 7); SB;
;     RL_FOLD(xe, 5, sm1, sq1); SB;
;     RL_FOLD(xa, 6, sm1, sq1); SB;
;     RL_FOLD(xc, 7, sm1, sq1);
	v_pk_fma_f32 v[132:133], v[242:243], s[0:1], v[82:83] op_sel_hi:[1,0,1]
	v_pk_fma_f32 v[142:143], v[244:245], s[0:1], v[84:85] op_sel_hi:[1,0,1]
	v_add_f32_e32 v104, v132, v105
	v_pk_fma_f32 v[82:83], v[132:133], v[132:133], v[102:103]
	v_add_f32_e32 v103, v133, v104
	v_mul_f32_e32 v102, v133, v133
	v_pk_add_f32 v[82:83], v[102:103], v[82:83] op_sel_hi:[0,1]
	v_add_f32_e32 v84, v142, v103
	v_pk_fma_f32 v[82:83], v[142:143], v[142:143], v[82:83]
	v_add_f32_e32 v85, v143, v84
	v_mul_f32_e32 v84, v143, v143
	v_pk_fma_f32 v[126:127], v[238:239], s[0:1], v[86:87] op_sel_hi:[1,0,1]
	v_pk_add_f32 v[82:83], v[84:85], v[82:83] op_sel_hi:[0,1]
	v_add_f32_e32 v84, v126, v85
	v_pk_fma_f32 v[82:83], v[126:127], v[126:127], v[82:83]
	v_add_f32_e32 v85, v127, v84
	v_mul_f32_e32 v84, v127, v127
	v_pk_fma_f32 v[136:137], v[240:241], s[0:1], v[88:89] op_sel_hi:[1,0,1]
	v_pk_add_f32 v[82:83], v[84:85], v[82:83] op_sel_hi:[0,1]
	v_add_f32_e32 v84, v136, v85
	v_pk_fma_f32 v[82:83], v[136:137], v[136:137], v[82:83]
	v_add_f32_e32 v85, v137, v84
	v_mul_f32_e32 v84, v137, v137
	v_pk_fma_f32 v[112:113], v[234:235], s[0:1], v[90:91] op_sel_hi:[1,0,1]
	v_pk_add_f32 v[82:83], v[84:85], v[82:83] op_sel_hi:[0,1]
	v_add_f32_e32 v84, v112, v85
	v_pk_fma_f32 v[82:83], v[112:113], v[112:113], v[82:83]
	v_add_f32_e32 v85, v113, v84
	v_mul_f32_e32 v84, v113, v113
	v_pk_fma_f32 v[128:129], v[236:237], s[0:1], v[92:93] op_sel_hi:[1,0,1]
	v_pk_add_f32 v[82:83], v[84:85], v[82:83] op_sel_hi:[0,1]
	v_add_f32_e32 v84, v128, v85
	v_pk_fma_f32 v[82:83], v[128:129], v[128:129], v[82:83]
	v_add_f32_e32 v90, v129, v84
	v_mul_f32_e32 v84, v129, v129
	v_pk_add_f32 v[86:87], v[84:85], v[82:83] op_sel_hi:[0,1]
	v_pk_fma_f32 v[106:107], v[230:231], s[0:1], v[94:95] op_sel_hi:[1,0,1]
	v_pk_fma_f32 v[118:119], v[232:233], s[0:1], v[96:97] op_sel_hi:[1,0,1]
	s_mov_b64 s[20:21], 0x20080
	v_lshl_add_u64 v[88:89], v[186:187], 0, s[20:21]
	global_load_dwordx4 v[82:85], v[88:89], off offset:48
	global_load_dwordx4 v[230:233], v[88:89], off offset:32
	global_load_dwordx4 v[234:237], v[188:189], off offset:128
	global_load_dwordx4 v[238:241], v[88:89], off offset:16
	v_add_f32_e32 v88, v106, v90
	v_pk_fma_f32 v[86:87], v[106:107], v[106:107], v[86:87]
	v_add_f32_e32 v89, v107, v88
	v_mul_f32_e32 v88, v107, v107
	v_pk_add_f32 v[86:87], v[88:89], v[86:87] op_sel_hi:[0,1]
	v_add_f32_e32 v88, v118, v89
	v_pk_fma_f32 v[86:87], v[118:119], v[118:119], v[86:87]
	v_add_f32_e32 v89, v119, v88
	v_mul_f32_e32 v88, v119, v119
	v_pk_add_f32 v[86:87], v[88:89], v[86:87] op_sel_hi:[0,1]
	s_waitcnt vmcnt(8)
	v_pk_fma_f32 v[104:105], v[120:121], s[0:1], v[50:51] op_sel_hi:[1,0,1]
	v_pk_fma_f32 v[122:123], v[122:123], s[0:1], v[52:53] op_sel_hi:[1,0,1]
	v_add_f32_e32 v88, v104, v89
	v_pk_fma_f32 v[50:51], v[104:105], v[104:105], v[86:87]
	v_add_f32_e32 v87, v105, v88
	v_mul_f32_e32 v86, v105, v105
	v_add_f32_e32 v52, v122, v87
	v_pk_add_f32 v[50:51], v[86:87], v[50:51] op_sel_hi:[0,1]
	v_add_f32_e32 v52, v123, v52
	v_pk_fma_f32 v[102:103], v[250:251], s[0:1], v[54:55] op_sel_hi:[1,0,1]
	v_pk_fma_f32 v[50:51], v[122:123], v[122:123], v[50:51]
	v_add_f32_e32 v55, v102, v52
	v_mul_f32_e32 v54, v123, v123
	v_mov_b32_e32 v52, v102
	v_mov_b32_e32 v53, v123
	v_pk_add_f32 v[50:51], v[54:55], v[50:51] op_sel_hi:[0,1]
	v_pk_fma_f32 v[50:51], v[52:53], v[52:53], v[50:51]
	v_add_f32_e32 v52, v103, v55
	v_pk_fma_f32 v[120:121], v[252:253], s[0:1], v[56:57] op_sel_hi:[1,0,1]
	v_mul_f32_e32 v54, v103, v103
	v_add_f32_e32 v55, v120, v52
	v_mov_b32_e32 v52, v120
	v_mov_b32_e32 v53, v103
	v_pk_add_f32 v[50:51], v[54:55], v[50:51] op_sel_hi:[0,1]
	v_pk_fma_f32 v[50:51], v[52:53], v[52:53], v[50:51]
	v_add_f32_e32 v52, v121, v55
	v_pk_fma_f32 v[94:95], v[246:247], s[0:1], v[58:59] op_sel_hi:[1,0,1]
	v_mul_f32_e32 v54, v121, v121
	v_add_f32_e32 v55, v94, v52
	v_mov_b32_e32 v52, v94
	v_mov_b32_e32 v53, v121
	v_pk_add_f32 v[50:51], v[54:55], v[50:51] op_sel_hi:[0,1]
	v_pk_fma_f32 v[50:51], v[52:53], v[52:53], v[50:51]
	v_add_f32_e32 v52, v95, v55
	v_pk_fma_f32 v[108:109], v[248:249], s[0:1], v[60:61] op_sel_hi:[1,0,1]
	v_mul_f32_e32 v54, v95, v95
	v_add_f32_e32 v55, v108, v52
	v_mov_b32_e32 v52, v108
	v_mov_b32_e32 v53, v95
	v_pk_add_f32 v[50:51], v[54:55], v[50:51] op_sel_hi:[0,1]
	v_pk_fma_f32 v[50:51], v[52:53], v[52:53], v[50:51]
	v_pk_fma_f32 v[96:97], v[114:115], s[0:1], v[62:63] op_sel_hi:[1,0,1]
	v_mul_f32_e32 v54, v109, v109
	v_pk_fma_f32 v[110:111], v[116:117], s[0:1], v[64:65] op_sel_hi:[1,0,1]
	v_add_f32_e32 v58, v109, v55
	v_pk_add_f32 v[50:51], v[54:55], v[50:51] op_sel_hi:[0,1]
	v_mov_b32_e32 v54, v110
	v_mov_b32_e32 v55, v97
	v_mov_b32_e32 v52, v96
	v_mov_b32_e32 v53, v109
	v_pk_mul_f32 v[114:115], v[110:111], v[110:111]
	s_mov_b64 s[20:21], 0x20100
	v_lshl_add_u64 v[56:57], v[186:187], 0, s[20:21]
	global_load_dwordx4 v[242:245], v[56:57], off offset:48
	global_load_dwordx4 v[246:249], v[56:57], off offset:32
	global_load_dwordx4 v[250:253], v[188:189], off offset:256
	global_load_dwordx4 v[166:169], v[56:57], off offset:16
	v_add_f32_e32 v56, v96, v58
	v_add_f32_e32 v56, v97, v56
	v_add_f32_e32 v114, v110, v56
	s_waitcnt vmcnt(11)
	v_pk_fma_f32 v[90:91], v[194:195], s[0:1], v[66:67] op_sel_hi:[1,0,1]
	v_pk_fma_f32 v[92:93], v[196:197], s[0:1], v[68:69] op_sel_hi:[1,0,1]
	v_add_f32_e32 v56, 0, v90
	v_add_f32_e32 v58, v91, v56
	v_mul_f32_e32 v56, v91, v91
	v_pk_fma_f32 v[56:57], v[90:91], v[90:91], v[56:57] op_sel_hi:[1,1,0]
	v_add_f32_e32 v58, v92, v58
	v_pk_fma_f32 v[56:57], v[92:93], v[92:93], v[56:57]
	v_add_f32_e32 v59, v93, v58
	v_mul_f32_e32 v58, v93, v93
	s_waitcnt vmcnt(8)
; #define RL_LOAD(XV, G) { constexpr int mt__ = (G) >> 2, half__ = ((G) >> 1) & 1, nt__ = (G) & 1; \
;     _Pragma("unroll") for (int gq = 0; gq < 4; ++gq) XV[gq] = *(const f32x4*)(xin + rbase + (size_t)mt__ * 32 * 1024 + half__ * 64 + nt__ * 32 + 4 * gq); }
; #define RL_FOLD(XV, G, SM, SQ) { constexpr int mt__ = (G) >> 2, half__ = ((G) >> 1) & 1, nt__ = (G) & 1; \
;     _Pragma("unroll") for (int gq = 0; gq < 4; ++gq) _Pragma("unroll") for (int jj = 0; jj < 4; ++jj) { \
;       const float y = ALPHA * XV[gq][jj] + acc[half__][nt__][mt__][4 * gq + jj]; acc[half__][nt__][mt__][4 * gq + jj] = y; SM += y; SQ += y * y; } }
; #define SB __builtin_amdgcn_sched_barrier(0)
;   DI void full(const int mt_, const int nt_, f32x16 (&acc)[2][2][2], const int tw, const int fw, const int r, const int hh, char* lds, const int tid) const {
;     ...
;     float sm0 = 0.f, sq0 = 0.f, sm1 = 0.f, sq1 = 0.f;
;     RL_LOAD(xa, 0); RL_LOAD(xc, 1); RL_LOAD(xe, 2); SB;
;     RL_FOLD(xa, 0, sm0, sq0); SB; RL_LOAD(xa, 3); SB;
;     RL_FOLD(xc, 1, sm0, sq0); SB; RL_LOAD(xc, 4); SB;
;     RL_FOLD(xe, 2, sm0, sq0); SB; RL_LOAD(xe, 5); SB;
;     RL_FOLD(xa, 3, sm0, sq0); SB; RL_LOAD(xa, 6); SB;
;     RL_FOLD(xc, 4, sm1, sq1); SB; RL_LOAD(xc, 7); SB;
;     RL_FOLD(xe, 5, sm1, sq1); SB;
;     RL_FOLD(xa, 6, sm1, sq1); SB;
;     RL_FOLD(xc, 7, sm1, sq1);
	v_pk_fma_f32 v[86:87], v[226:227], s[0:1], v[70:71] op_sel_hi:[1,0,1]
	v_pk_add_f32 v[56:57], v[58:59], v[56:57] op_sel_hi:[0,1]
	v_add_f32_e32 v58, v86, v59
	v_pk_fma_f32 v[56:57], v[86:87], v[86:87], v[56:57]
	v_add_f32_e32 v59, v87, v58
	v_mul_f32_e32 v58, v87, v87
	v_pk_fma_f32 v[88:89], v[228:229], s[0:1], v[72:73] op_sel_hi:[1,0,1]
	v_pk_add_f32 v[56:57], v[58:59], v[56:57] op_sel_hi:[0,1]
	v_add_f32_e32 v58, v88, v59
	v_pk_fma_f32 v[56:57], v[88:89], v[88:89], v[56:57]
	v_add_f32_e32 v59, v89, v58
	v_mul_f32_e32 v58, v89, v89
	v_pk_fma_f32 v[70:71], v[202:203], s[0:1], v[74:75] op_sel_hi:[1,0,1]
	v_pk_add_f32 v[56:57], v[58:59], v[56:57] op_sel_hi:[0,1]
	v_add_f32_e32 v58, v70, v59
	v_pk_fma_f32 v[56:57], v[70:71], v[70:71], v[56:57]
	v_add_f32_e32 v59, v71, v58
	v_mul_f32_e32 v58, v71, v71
	v_pk_fma_f32 v[72:73], v[204:205], s[0:1], v[76:77] op_sel_hi:[1,0,1]
	v_pk_add_f32 v[56:57], v[58:59], v[56:57] op_sel_hi:[0,1]
	v_add_f32_e32 v58, v72, v59
	v_pk_fma_f32 v[56:57], v[72:73], v[72:73], v[56:57]
	v_add_f32_e32 v59, v73, v58
	v_mul_f32_e32 v58, v73, v73
	v_pk_fma_f32 v[50:51], v[52:53], v[52:53], v[50:51]
	v_mul_f32_e32 v52, v97, v97
	v_pk_add_f32 v[56:57], v[58:59], v[56:57] op_sel_hi:[0,1]
	v_pk_fma_f32 v[68:69], v[98:99], s[0:1], v[78:79] op_sel_hi:[1,0,1]
	v_pk_fma_f32 v[66:67], v[100:101], s[0:1], v[80:81] op_sel_hi:[1,0,1]
	v_pk_add_f32 v[50:51], v[52:53], v[50:51] op_sel_hi:[0,1]
	v_pk_fma_f32 v[74:75], v[54:55], v[54:55], v[50:51]
	s_mov_b64 s[20:21], 0x20180
	v_lshl_add_u64 v[54:55], v[186:187], 0, s[20:21]
	global_load_dwordx4 v[50:53], v[54:55], off offset:48
	global_load_dwordx4 v[76:79], v[54:55], off offset:32
	global_load_dwordx4 v[98:101], v[188:189], off offset:384
	s_nop 0
	global_load_dwordx4 v[186:189], v[54:55], off offset:16
	v_add_f32_e32 v58, v68, v59
	v_pk_fma_f32 v[54:55], v[68:69], v[68:69], v[56:57]
	v_add_f32_e32 v57, v69, v58
	v_mul_f32_e32 v56, v69, v69
	v_pk_add_f32 v[54:55], v[56:57], v[54:55] op_sel_hi:[0,1]
	v_add_f32_e32 v56, v66, v57
	v_pk_fma_f32 v[54:55], v[66:67], v[66:67], v[54:55]
	v_add_f32_e32 v57, v67, v56
	v_mul_f32_e32 v56, v67, v67
	v_pk_add_f32 v[54:55], v[56:57], v[54:55] op_sel_hi:[0,1]
	s_waitcnt vmcnt(9)
	v_pk_fma_f32 v[60:61], v[234:235], s[0:1], v[34:35] op_sel_hi:[1,0,1]
	v_pk_fma_f32 v[64:65], v[236:237], s[0:1], v[36:37] op_sel_hi:[1,0,1]
	v_add_f32_e32 v56, v60, v57
	v_pk_fma_f32 v[34:35], v[60:61], v[60:61], v[54:55]
	v_add_f32_e32 v55, v61, v56
	v_mul_f32_e32 v54, v61, v61
	v_pk_add_f32 v[34:35], v[54:55], v[34:35] op_sel_hi:[0,1]
	v_add_f32_e32 v36, v64, v55
	v_pk_fma_f32 v[34:35], v[64:65], v[64:65], v[34:35]
	v_add_f32_e32 v37, v65, v36
	v_mul_f32_e32 v36, v65, v65
	s_waitcnt vmcnt(8)
	v_pk_fma_f32 v[56:57], v[238:239], s[0:1], v[38:39] op_sel_hi:[1,0,1]
	v_pk_add_f32 v[34:35], v[36:37], v[34:35] op_sel_hi:[0,1]
	v_add_f32_e32 v36, v56, v37
	v_pk_fma_f32 v[34:35], v[56:57], v[56:57], v[34:35]
	v_add_f32_e32 v37, v57, v36
	v_mul_f32_e32 v36, v57, v57
	v_pk_fma_f32 v[62:63], v[240:241], s[0:1], v[40:41] op_sel_hi:[1,0,1]
	v_pk_add_f32 v[34:35], v[36:37], v[34:35] op_sel_hi:[0,1]
	v_add_f32_e32 v36, v62, v37
	v_pk_fma_f32 v[34:35], v[62:63], v[62:63], v[34:35]
	v_add_f32_e32 v37, v63, v36
	v_mul_f32_e32 v36, v63, v63
	v_pk_fma_f32 v[54:55], v[230:231], s[0:1], v[42:43] op_sel_hi:[1,0,1]
	v_pk_add_f32 v[34:35], v[36:37], v[34:35] op_sel_hi:[0,1]
	v_add_f32_e32 v36, v54, v37
	v_pk_fma_f32 v[34:35], v[54:55], v[54:55], v[34:35]
	v_add_f32_e32 v37, v55, v36
	v_mul_f32_e32 v36, v55, v55
	v_pk_fma_f32 v[58:59], v[232:233], s[0:1], v[44:45] op_sel_hi:[1,0,1]
	v_pk_add_f32 v[34:35], v[36:37], v[34:35] op_sel_hi:[0,1]
	v_add_f32_e32 v36, v58, v37
	v_pk_fma_f32 v[34:35], v[58:59], v[58:59], v[34:35]
	v_add_f32_e32 v37, v59, v36
	v_mul_f32_e32 v36, v59, v59
	v_pk_fma_f32 v[44:45], v[82:83], s[0:1], v[46:47] op_sel_hi:[1,0,1]
	v_pk_add_f32 v[34:35], v[36:37], v[34:35] op_sel_hi:[0,1]
	v_add_f32_e32 v36, v44, v37
	v_pk_fma_f32 v[34:35], v[44:45], v[44:45], v[34:35]
	v_add_f32_e32 v37, v45, v36
	v_mul_f32_e32 v36, v45, v45
	v_pk_fma_f32 v[46:47], v[84:85], s[0:1], v[48:49] op_sel_hi:[1,0,1]
	v_pk_add_f32 v[34:35], v[36:37], v[34:35] op_sel_hi:[0,1]
	v_add_f32_e32 v36, v46, v37
	v_pk_fma_f32 v[34:35], v[46:47], v[46:47], v[34:35]
	v_add_f32_e32 v37, v47, v36
	v_mul_f32_e32 v36, v47, v47
	v_pk_add_f32 v[34:35], v[36:37], v[34:35] op_sel_hi:[0,1]
	s_waitcnt vmcnt(5)
	v_pk_fma_f32 v[38:39], v[250:251], s[0:1], v[18:19] op_sel_hi:[1,0,1]
	v_pk_fma_f32 v[42:43], v[252:253], s[0:1], v[20:21] op_sel_hi:[1,0,1]
	v_add_f32_e32 v36, v38, v37
	v_pk_fma_f32 v[18:19], v[38:39], v[38:39], v[34:35]
	v_add_f32_e32 v35, v39, v36
	v_mul_f32_e32 v34, v39, v39
	v_pk_add_f32 v[18:19], v[34:35], v[18:19] op_sel_hi:[0,1]
	v_add_f32_e32 v20, v42, v35
	v_pk_fma_f32 v[18:19], v[42:43], v[42:43], v[18:19]
	v_add_f32_e32 v21, v43, v20
	v_mul_f32_e32 v20, v43, v43
	s_waitcnt vmcnt(4)
; #define RL_LOAD(XV, G) { constexpr int mt__ = (G) >> 2, half__ = ((G) >> 1) & 1, nt__ = (G) & 1; \
;     _Pragma("unroll") for (int gq = 0; gq < 4; ++gq) XV[gq] = *(const f32x4*)(xin + rbase + (size_t)mt__ * 32 * 1024 + half__ * 64 + nt__ * 32 + 4 * gq); }
; #define RL_FOLD(XV, G, SM, SQ) { constexpr int mt__ = (G) >> 2, half__ = ((G) >> 1) & 1, nt__ = (G) & 1; \
;     _Pragma("unroll") for (int gq = 0; gq < 4; ++gq) _Pragma("unroll") for (int jj = 0; jj < 4; ++jj) { \
;       const float y = ALPHA * XV[gq][jj] + acc[half__][nt__][mt__][4 * gq + jj]; acc[half__][nt__][mt__][4 * gq + jj] = y; SM += y; SQ += y * y; } }
; #define SB __builtin_amdgcn_sched_barrier(0)
;   DI void full(const int mt_, const int nt_, f32x16 (&acc)[2][2][2], const int tw, const int fw, const int r, const int hh, char* lds, const int tid) const {
;     ...
;     float sm0 = 0.f, sq0 = 0.f, sm1 = 0.f, sq1 = 0.f;
;     RL_LOAD(xa, 0); RL_LOAD(xc, 1); RL_LOAD(xe, 2); SB;
;     RL_FOLD(xa, 0, sm0, sq0); SB; RL_LOAD(xa, 3); SB;
;     RL_FOLD(xc, 1, sm0, sq0); SB; RL_LOAD(xc, 4); SB;
;     RL_FOLD(xe, 2, sm0, sq0); SB; RL_LOAD(xe, 5); SB;
;     RL_FOLD(xa, 3, sm0, sq0); SB; RL_LOAD(xa, 6); SB;
;     RL_FOLD(xc, 4, sm1, sq1); SB; RL_LOAD(xc, 7); SB;
;     RL_FOLD(xe, 5, sm1, sq1); SB;
;     RL_FOLD(xa, 6, sm1, sq1); SB;
;     RL_FOLD(xc, 7, sm1, sq1);
;     ...
;     sm0 += __shfl_xor(sm0, 32, 64); sq0 += __shfl_xor(sq0, 32, 64); sm1 += __shfl_xor(sm1, 32, 64); sq1 += __shfl_xor(sq1, 32, 64);
;     if (hh == 0) {
;       float* pp = part + ((fw * 256) + tw * 64 + r) * 2; pp[0] = sm0; pp[1] = sq0;
;       pp[64] = sm1; pp[65] = sq1;
	v_pk_fma_f32 v[34:35], v[166:167], s[0:1], v[22:23] op_sel_hi:[1,0,1]
	v_pk_add_f32 v[18:19], v[20:21], v[18:19] op_sel_hi:[0,1]
	v_add_f32_e32 v20, v34, v21
	v_pk_fma_f32 v[18:19], v[34:35], v[34:35], v[18:19]
	v_add_f32_e32 v21, v35, v20
	v_mul_f32_e32 v20, v35, v35
	v_pk_fma_f32 v[40:41], v[168:169], s[0:1], v[24:25] op_sel_hi:[1,0,1]
	v_pk_add_f32 v[18:19], v[20:21], v[18:19] op_sel_hi:[0,1]
	v_add_f32_e32 v20, v40, v21
	v_pk_fma_f32 v[18:19], v[40:41], v[40:41], v[18:19]
	v_add_f32_e32 v21, v41, v20
	v_mul_f32_e32 v20, v41, v41
	v_pk_fma_f32 v[26:27], v[246:247], s[0:1], v[26:27] op_sel_hi:[1,0,1]
	v_pk_add_f32 v[18:19], v[20:21], v[18:19] op_sel_hi:[0,1]
	v_add_f32_e32 v20, v26, v21
	v_pk_fma_f32 v[18:19], v[26:27], v[26:27], v[18:19]
	v_add_f32_e32 v21, v27, v20
	v_mul_f32_e32 v20, v27, v27
	v_pk_fma_f32 v[36:37], v[248:249], s[0:1], v[28:29] op_sel_hi:[1,0,1]
	v_pk_add_f32 v[18:19], v[20:21], v[18:19] op_sel_hi:[0,1]
	v_add_f32_e32 v20, v36, v21
	v_pk_fma_f32 v[18:19], v[36:37], v[36:37], v[18:19]
	v_add_f32_e32 v21, v37, v20
	v_mul_f32_e32 v20, v37, v37
	v_pk_fma_f32 v[24:25], v[242:243], s[0:1], v[30:31] op_sel_hi:[1,0,1]
	v_pk_add_f32 v[18:19], v[20:21], v[18:19] op_sel_hi:[0,1]
	v_add_f32_e32 v20, v24, v21
	v_pk_fma_f32 v[18:19], v[24:25], v[24:25], v[18:19]
	v_add_f32_e32 v21, v25, v20
	v_mul_f32_e32 v20, v25, v25
	v_pk_fma_f32 v[28:29], v[244:245], s[0:1], v[32:33] op_sel_hi:[1,0,1]
	v_pk_add_f32 v[18:19], v[20:21], v[18:19] op_sel_hi:[0,1]
	v_add_f32_e32 v20, v28, v21
	v_pk_fma_f32 v[18:19], v[28:29], v[28:29], v[18:19]
	v_add_f32_e32 v22, v29, v20
	v_mul_f32_e32 v20, v29, v29
	v_pk_add_f32 v[20:21], v[20:21], v[18:19] op_sel_hi:[0,1]
	s_waitcnt vmcnt(1)
	v_pk_fma_f32 v[18:19], v[98:99], s[0:1], v[2:3] op_sel_hi:[1,0,1]
	s_waitcnt vmcnt(0)
	v_pk_fma_f32 v[6:7], v[186:187], s[0:1], v[6:7] op_sel_hi:[1,0,1]
	v_add_f32_e32 v22, v18, v22
	v_pk_fma_f32 v[2:3], v[18:19], v[18:19], v[20:21]
	v_add_f32_e32 v21, v19, v22
	v_pk_fma_f32 v[22:23], v[100:101], s[0:1], v[4:5] op_sel_hi:[1,0,1]
	v_mul_f32_e32 v20, v19, v19
	v_add_f32_e32 v4, v22, v21
	v_pk_add_f32 v[2:3], v[20:21], v[2:3] op_sel_hi:[0,1]
	v_add_f32_e32 v4, v23, v4
	v_pk_fma_f32 v[2:3], v[22:23], v[22:23], v[2:3]
	v_add_f32_e32 v21, v6, v4
	v_mul_f32_e32 v20, v23, v23
	v_mov_b32_e32 v4, v6
	v_mov_b32_e32 v5, v23
	v_pk_add_f32 v[2:3], v[20:21], v[2:3] op_sel_hi:[0,1]
	v_pk_fma_f32 v[2:3], v[4:5], v[4:5], v[2:3]
	v_add_f32_e32 v4, v7, v21
	v_pk_fma_f32 v[20:21], v[188:189], s[0:1], v[8:9] op_sel_hi:[1,0,1]
	v_mul_f32_e32 v8, v7, v7
	v_add_f32_e32 v9, v20, v4
	v_mov_b32_e32 v4, v20
	v_mov_b32_e32 v5, v7
	v_pk_add_f32 v[2:3], v[8:9], v[2:3] op_sel_hi:[0,1]
	v_pk_fma_f32 v[4:5], v[4:5], v[4:5], v[2:3]
	v_add_f32_e32 v8, v21, v9
	v_pk_fma_f32 v[2:3], v[76:77], s[0:1], v[10:11] op_sel_hi:[1,0,1]
	v_mul_f32_e32 v10, v21, v21
	v_add_f32_e32 v11, v2, v8
	v_mov_b32_e32 v8, v2
	v_mov_b32_e32 v9, v21
	v_pk_add_f32 v[4:5], v[10:11], v[4:5] op_sel_hi:[0,1]
	v_pk_fma_f32 v[4:5], v[8:9], v[8:9], v[4:5]
	v_add_f32_e32 v10, v3, v11
	v_pk_fma_f32 v[8:9], v[78:79], s[0:1], v[12:13] op_sel_hi:[1,0,1]
	v_mul_f32_e32 v12, v3, v3
	v_add_f32_e32 v13, v8, v10
	v_mov_b32_e32 v10, v8
	v_mov_b32_e32 v11, v3
	v_pk_add_f32 v[4:5], v[12:13], v[4:5] op_sel_hi:[0,1]
	v_pk_fma_f32 v[10:11], v[10:11], v[10:11], v[4:5]
	v_add_f32_e32 v12, v9, v13
	v_pk_fma_f32 v[4:5], v[50:51], s[0:1], v[14:15] op_sel_hi:[1,0,1]
	v_mul_f32_e32 v14, v9, v9
	v_add_f32_e32 v15, v4, v12
	v_mov_b32_e32 v12, v4
	v_mov_b32_e32 v13, v9
	v_pk_add_f32 v[10:11], v[14:15], v[10:11] op_sel_hi:[0,1]
	v_pk_fma_f32 v[12:13], v[12:13], v[12:13], v[10:11]
	v_pk_fma_f32 v[10:11], v[52:53], s[0:1], v[16:17] op_sel_hi:[1,0,1]
	v_mul_f32_e32 v30, v5, v5
	v_mov_b32_e32 v16, v10
	v_mov_b32_e32 v17, v5
	v_pk_add_f32 v[12:13], v[30:31], v[12:13] op_sel_hi:[0,1]
	v_pk_fma_f32 v[12:13], v[16:17], v[16:17], v[12:13]
	v_pk_mul_f32 v[16:17], v[10:11], v[10:11]
	v_add_f32_e32 v14, v5, v15
	v_mov_b32_e32 v15, v17
	v_and_b32_e32 v17, 64, v201
	v_xor_b32_e32 v16, 32, v201
	v_add_u32_e32 v17, 64, v17
	v_add_f32_e32 v14, v10, v14
	v_pk_mov_b32 v[12:13], v[10:11], v[12:13] op_sel:[1,0]
	v_cmp_lt_i32_e32 vcc, v16, v17
	v_pk_add_f32 v[12:13], v[12:13], v[14:15]
	v_pk_mov_b32 v[14:15], v[110:111], v[74:75] op_sel:[1,0]
	v_cndmask_b32_e32 v16, v201, v16, vcc
	v_pk_add_f32 v[14:15], v[14:15], v[114:115]
	v_lshlrev_b32_e32 v31, 2, v16
	ds_bpermute_b32 v16, v31, v14
	ds_bpermute_b32 v17, v31, v15
	ds_bpermute_b32 v30, v31, v12
	ds_bpermute_b32 v31, v31, v13
	v_cmp_eq_u32_e32 vcc, 0, v224
	s_and_saveexec_b64 s[20:21], vcc
	s_cbranch_execz .LBB0_272
	v_lshlrev_b32_e32 v32, 3, v184
	v_and_b32_e32 v32, 0xfffffef8, v32
	v_add_u32_e32 v32, 0, v32
	v_add_u32_e32 v32, 0x12000, v32
	s_waitcnt lgkmcnt(2)
	v_pk_add_f32 v[14:15], v[14:15], v[16:17]
	s_waitcnt lgkmcnt(0)
	v_pk_add_f32 v[12:13], v[12:13], v[30:31]
	ds_write2_b64 v32, v[14:15], v[12:13] offset1:32

; template <class Epi>
; DI void gemm_phase(const bf16_t* __restrict__ X, const int ldx, const bf16_t* __restrict__ Wt, const int N, const int K, const Epi& epi, char* lds) {
;     ...
;   for (int chunk = xcd; chunk < nchunks; chunk += 8) {
;     const int L = chunk * 32 + slot, band = L / (4 * nNt), rem = L % (4 * nNt);
;     const int mt_ = band * 4 + (rem & 3), nt_ = rem >> 2;
;     const char* Xt = (const char*)(X + (size_t)(mt_ * 256) * ldx);
;     const char* Wtb = (const char*)(Wt + (size_t)(nt_ * 256) * K);
;     const unsigned xoff = (unsigned)(lrow * ldx + lch * 8) * 2u, woff = (unsigned)(lrow * K + lch * 8) * 2u;
;     const bool has_next = !Epi::kFull && (chunk + 8 < nchunks);
;     const int Ln = (has_next ? chunk + 8 : chunk) * 32 + slot, band_n = Ln / (4 * nNt), rem_n = Ln % (4 * nNt);
;     const char* Xt_n = (const char*)(X + (size_t)((band_n * 4 + (rem_n & 3)) * 256) * ldx);
;     const char* Wtb_n = (const char*)(Wt + (size_t)((rem_n >> 2) * 256) * K);
;     f32x16 acc[2][2][2];
.LBB0_310:
	s_add_i32 s36, s10, 8
	s_cmp_gt_u32 s10, 47
	s_cselect_b64 s[24:25], -1, 0
	s_cmp_lt_u32 s10, 48
	s_cselect_b32 s10, s36, s10
	s_cselect_b32 s5, 0, 15
	s_cselect_b32 s12, 1, 15
	s_lshl_b32 s10, s10, 5
	v_readlane_b32 s11, v254, 3
	s_add_i32 s10, s10, s11
	s_lshr_b32 s11, s10, 3
	s_mul_hi_u32 s11, s11, 0x24924925
	s_mul_i32 s14, s11, 56
	s_sub_i32 s26, s10, s14
	s_lshl_b32 s10, s11, 10
	s_lshl_b32 s11, s26, 8
	s_and_b32 s11, s11, 0x300
	s_or_b32 s10, s11, s10
	s_ashr_i32 s11, s10, 31
	s_lshl_b64 s[10:11], s[10:11], 11
	s_add_u32 s14, s30, s10
	s_addc_u32 s15, s31, s11
	s_lshl_b32 s10, s26, 17
	s_and_b32 s10, s10, 0x780000
	s_add_u32 s26, s34, s10
	v_mov_b32_e32 v2, 0
	s_mov_b32 s13, 3
	s_addc_u32 s27, s35, 0
	v_mov_b32_e32 v3, v2
	s_waitcnt vmcnt(5)
	s_waitcnt vmcnt(4)
	s_waitcnt vmcnt(3)
	s_waitcnt vmcnt(2)
	s_waitcnt vmcnt(1)
	s_waitcnt vmcnt(0)
	v_add_u32_e32 v232, s91, v170
	v_add_u32_e32 v233, s1, v170
	v_add_u32_e32 v234, s76, v170
	v_add_u32_e32 v235, v184, v185
	v_add_u32_e32 v236, v184, v186
	v_add_u32_e32 v237, v187, v175
	ds_read_b128 v[162:165], v235
	ds_read_b128 v[166:169], v235 offset:4608
	ds_read_b128 v[176:179], v236 offset:36864
	ds_read_b128 v[180:183], v236 offset:41472
	ds_read_b128 v[216:219], v236 offset:46080
	ds_read_b128 v[220:223], v236 offset:50688
	ds_read_b128 v[224:227], v189 offset:32
	ds_read_b128 v[228:231], v189 offset:4640
	s_add_i32 s28, s13, -3
	s_cmp_lt_u32 s28, 14
	s_cselect_b64 s[38:39], -1, 0
	s_and_b64 s[10:11], s[38:39], exec
	s_cselect_b32 s11, s9, s27
	s_cselect_b32 s10, s8, s26
	s_cselect_b32 s41, s7, s15
	s_cselect_b32 s40, s6, s14
	s_add_i32 s29, s13, -1
	s_waitcnt lgkmcnt(5)
	v_mfma_f32_32x32x16_bf16 v[114:129], v[176:179], v[162:165], 0
	v_mfma_f32_32x32x16_bf16 v[82:97], v[176:179], v[166:169], 0
	s_waitcnt lgkmcnt(4)
	v_mfma_f32_32x32x16_bf16 v[98:113], v[180:183], v[162:165], 0
	v_mfma_f32_32x32x16_bf16 v[66:81], v[180:183], v[166:169], 0
	s_waitcnt lgkmcnt(3)
	v_mfma_f32_32x32x16_bf16 v[50:65], v[216:219], v[162:165], 0
	s_and_b64 s[38:39], s[38:39], exec
	s_cselect_b32 s29, s29, s5
	v_mfma_f32_32x32x16_bf16 v[18:33], v[216:219], v[166:169], 0
	s_waitcnt lgkmcnt(2)
	v_mfma_f32_32x32x16_bf16 v[34:49], v[220:223], v[162:165], 0
	ds_read_b128 v[162:165], v190 offset:36896
	ds_read_b128 v[176:179], v190 offset:41504
	v_mfma_f32_32x32x16_bf16 v[2:17], v[220:223], v[166:169], 0
	s_lshl_b32 s96, s29, 7
	s_add_u32 s100, s40, s96
	s_addc_u32 s101, s41, 0
	s_waitcnt vmcnt(3)
	ds_write_b128 v191, v[138:141] offset:9216
	ds_write_b128 v191, v[134:137]
	global_load_dwordx4 v[134:137], v170, s[100:101]
	global_load_dwordx4 v[138:141], v232, s[100:101]
	ds_write_b128 v191, v[130:133] offset:18432
	ds_write_b128 v191, v[142:145] offset:27648
	global_load_dwordx4 v[130:133], v233, s[100:101]
	global_load_dwordx4 v[142:145], v234, s[100:101]
	ds_read_b128 v[166:169], v190 offset:46112
	ds_read_b128 v[180:183], v190 offset:50720
	ds_read_b128 v[216:219], v189 offset:64
	ds_read_b128 v[220:223], v189 offset:4672
	s_waitcnt lgkmcnt(9)
	v_mfma_f32_32x32x16_bf16 v[114:129], v[162:165], v[224:227], v[114:129]
	v_mfma_f32_32x32x16_bf16 v[82:97], v[162:165], v[228:231], v[82:97]
	s_waitcnt lgkmcnt(8)
	v_mfma_f32_32x32x16_bf16 v[98:113], v[176:179], v[224:227], v[98:113]
	v_mfma_f32_32x32x16_bf16 v[66:81], v[176:179], v[228:231], v[66:81]
	s_waitcnt lgkmcnt(3)
	v_mfma_f32_32x32x16_bf16 v[50:65], v[166:169], v[224:227], v[50:65]
	v_mfma_f32_32x32x16_bf16 v[18:33], v[166:169], v[228:231], v[18:33]
	ds_read_b128 v[162:165], v190 offset:36928
	ds_read_b128 v[166:169], v190 offset:41536
	s_waitcnt lgkmcnt(4)
	v_mfma_f32_32x32x16_bf16 v[34:49], v[180:183], v[224:227], v[34:49]
	v_mfma_f32_32x32x16_bf16 v[2:17], v[180:183], v[228:231], v[2:17]
	s_add_u32 s100, s10, s96
	s_addc_u32 s101, s11, 0
	s_waitcnt vmcnt(6)
	ds_write_b128 v208, v[154:157] offset:9216
	s_waitcnt vmcnt(5)
	ds_write_b128 v208, v[146:149]
	global_load_dwordx4 v[146:149], v170, s[100:101]
	global_load_dwordx4 v[154:157], v232, s[100:101]
	ds_read_b128 v[176:179], v190 offset:46144
	ds_read_b128 v[180:183], v190 offset:50752
	ds_read_b128 v[224:227], v189 offset:96
	ds_read_b128 v[228:231], v189 offset:4704
	s_waitcnt lgkmcnt(7)
	v_mfma_f32_32x32x16_bf16 v[114:129], v[162:165], v[216:219], v[114:129]
	v_mfma_f32_32x32x16_bf16 v[82:97], v[162:165], v[220:223], v[82:97]
	s_waitcnt lgkmcnt(6)
	v_mfma_f32_32x32x16_bf16 v[98:113], v[166:169], v[216:219], v[98:113]
	v_mfma_f32_32x32x16_bf16 v[66:81], v[166:169], v[220:223], v[66:81]
	s_waitcnt lgkmcnt(3)
	v_mfma_f32_32x32x16_bf16 v[50:65], v[176:179], v[216:219], v[50:65]
	ds_read_b128 v[162:165], v190 offset:36960
	ds_read_b128 v[166:169], v190 offset:41568
	v_mfma_f32_32x32x16_bf16 v[18:33], v[176:179], v[220:223], v[18:33]
	s_waitcnt lgkmcnt(4)
	v_mfma_f32_32x32x16_bf16 v[34:49], v[180:183], v[216:219], v[34:49]
	v_mfma_f32_32x32x16_bf16 v[2:17], v[180:183], v[220:223], v[2:17]
	ds_write_b128 v208, v[150:153] offset:18432
	s_waitcnt vmcnt(6)
	ds_write_b128 v208, v[158:161] offset:27648
	global_load_dwordx4 v[150:153], v233, s[100:101]
	global_load_dwordx4 v[158:161], v234, s[100:101]
	ds_read_b128 v[176:179], v190 offset:46176
	ds_read_b128 v[180:183], v190 offset:50784
	s_waitcnt lgkmcnt(5)
	v_mfma_f32_32x32x16_bf16 v[114:129], v[162:165], v[224:227], v[114:129]
	v_mfma_f32_32x32x16_bf16 v[82:97], v[162:165], v[228:231], v[82:97]
	s_waitcnt lgkmcnt(4)
	v_mfma_f32_32x32x16_bf16 v[98:113], v[166:169], v[224:227], v[98:113]
	v_mfma_f32_32x32x16_bf16 v[66:81], v[166:169], v[228:231], v[66:81]
	s_waitcnt lgkmcnt(1)
	v_mfma_f32_32x32x16_bf16 v[50:65], v[176:179], v[224:227], v[50:65]
	v_mfma_f32_32x32x16_bf16 v[18:33], v[176:179], v[228:231], v[18:33]
	s_waitcnt lgkmcnt(0)
	v_mfma_f32_32x32x16_bf16 v[34:49], v[180:183], v[224:227], v[34:49]
	v_mfma_f32_32x32x16_bf16 v[2:17], v[180:183], v[228:231], v[2:17]
	s_barrier
	ds_read_b128 v[162:165], v209
	ds_read_b128 v[166:169], v209 offset:4608
	ds_read_b128 v[176:179], v210
	ds_read_b128 v[180:183], v210 offset:4608
	ds_read_b128 v[216:219], v210 offset:9216
	ds_read_b128 v[220:223], v210 offset:13824
	ds_read_b128 v[224:227], v237 offset:32
	ds_read_b128 v[228:231], v211 offset:32
	s_cmp_lt_u32 s28, 13
	s_cselect_b64 s[10:11], -1, 0
	s_and_b64 s[10:11], s[10:11], exec
	s_cselect_b32 s39, s7, s15
	s_cselect_b32 s38, s6, s14
	s_cselect_b32 s11, s9, s27
	s_cselect_b32 s10, s8, s26
	s_waitcnt lgkmcnt(5)
	v_mfma_f32_32x32x16_bf16 v[114:129], v[176:179], v[162:165], v[114:129]
	v_mfma_f32_32x32x16_bf16 v[82:97], v[176:179], v[166:169], v[82:97]
	s_waitcnt lgkmcnt(4)
	v_mfma_f32_32x32x16_bf16 v[98:113], v[180:183], v[162:165], v[98:113]
	v_mfma_f32_32x32x16_bf16 v[66:81], v[180:183], v[166:169], v[66:81]
	s_waitcnt lgkmcnt(3)
	v_mfma_f32_32x32x16_bf16 v[50:65], v[216:219], v[162:165], v[50:65]
	v_add_u32_e32 v174, v188, v175
	s_cselect_b32 s29, s13, s12
	v_mfma_f32_32x32x16_bf16 v[18:33], v[216:219], v[166:169], v[18:33]
	s_waitcnt lgkmcnt(2)
	v_mfma_f32_32x32x16_bf16 v[34:49], v[220:223], v[162:165], v[34:49]
	ds_read_b128 v[162:165], v174 offset:32
	ds_read_b128 v[176:179], v212 offset:32
	v_mfma_f32_32x32x16_bf16 v[2:17], v[220:223], v[166:169], v[2:17]
	s_lshl_b32 s96, s29, 7
	s_add_u32 s100, s38, s96
	s_addc_u32 s101, s39, 0
	s_waitcnt vmcnt(6)
	ds_write_b128 v215, v[138:141] offset:9216
	ds_write_b128 v215, v[134:137]
	global_load_dwordx4 v[134:137], v170, s[100:101]
	global_load_dwordx4 v[138:141], v232, s[100:101]
	s_waitcnt vmcnt(7)
	ds_write_b128 v215, v[130:133] offset:18432
	s_waitcnt vmcnt(6)
	ds_write_b128 v215, v[142:145] offset:27648
	global_load_dwordx4 v[130:133], v233, s[100:101]
	global_load_dwordx4 v[142:145], v234, s[100:101]
	ds_read_b128 v[166:169], v213 offset:32
	ds_read_b128 v[180:183], v214 offset:32
	ds_read_b128 v[216:219], v237 offset:64
	ds_read_b128 v[220:223], v211 offset:64
	s_waitcnt lgkmcnt(9)
	v_mfma_f32_32x32x16_bf16 v[114:129], v[162:165], v[224:227], v[114:129]
	v_mfma_f32_32x32x16_bf16 v[82:97], v[162:165], v[228:231], v[82:97]
	s_waitcnt lgkmcnt(8)
	v_mfma_f32_32x32x16_bf16 v[98:113], v[176:179], v[224:227], v[98:113]
	v_mfma_f32_32x32x16_bf16 v[66:81], v[176:179], v[228:231], v[66:81]
	s_waitcnt lgkmcnt(3)
	v_mfma_f32_32x32x16_bf16 v[50:65], v[166:169], v[224:227], v[50:65]
	v_mfma_f32_32x32x16_bf16 v[18:33], v[166:169], v[228:231], v[18:33]
	ds_read_b128 v[162:165], v174 offset:64
	ds_read_b128 v[166:169], v212 offset:64
	s_waitcnt lgkmcnt(4)
	v_mfma_f32_32x32x16_bf16 v[34:49], v[180:183], v[224:227], v[34:49]
	v_mfma_f32_32x32x16_bf16 v[2:17], v[180:183], v[228:231], v[2:17]
	s_add_u32 s100, s10, s96
	s_addc_u32 s101, s11, 0
	s_waitcnt vmcnt(6)
	ds_write_b128 v215, v[154:157] offset:46080
	ds_write_b128 v215, v[146:149] offset:36864
	global_load_dwordx4 v[146:149], v170, s[100:101]
	global_load_dwordx4 v[154:157], v232, s[100:101]
	ds_read_b128 v[176:179], v213 offset:64
	ds_read_b128 v[180:183], v214 offset:64
	ds_read_b128 v[224:227], v237 offset:96
	ds_read_b128 v[228:231], v211 offset:96
	s_waitcnt lgkmcnt(7)
	v_mfma_f32_32x32x16_bf16 v[114:129], v[162:165], v[216:219], v[114:129]
	v_mfma_f32_32x32x16_bf16 v[82:97], v[162:165], v[220:223], v[82:97]
	s_waitcnt lgkmcnt(6)
	v_mfma_f32_32x32x16_bf16 v[98:113], v[166:169], v[216:219], v[98:113]
	v_mfma_f32_32x32x16_bf16 v[66:81], v[166:169], v[220:223], v[66:81]
	s_waitcnt lgkmcnt(3)
	v_mfma_f32_32x32x16_bf16 v[50:65], v[176:179], v[216:219], v[50:65]
	ds_read_b128 v[162:165], v174 offset:96
	ds_read_b128 v[166:169], v212 offset:96
	v_mfma_f32_32x32x16_bf16 v[18:33], v[176:179], v[220:223], v[18:33]
	s_waitcnt lgkmcnt(4)
	v_mfma_f32_32x32x16_bf16 v[34:49], v[180:183], v[216:219], v[34:49]
	v_mfma_f32_32x32x16_bf16 v[2:17], v[180:183], v[220:223], v[2:17]
	s_waitcnt vmcnt(7)
	ds_write_b128 v215, v[150:153] offset:55296
	s_waitcnt vmcnt(6)
	ds_write_b128 v215, v[158:161] offset:64512
	global_load_dwordx4 v[150:153], v233, s[100:101]
	global_load_dwordx4 v[158:161], v234, s[100:101]
	ds_read_b128 v[176:179], v213 offset:96
	ds_read_b128 v[180:183], v214 offset:96
	s_waitcnt lgkmcnt(5)
	v_mfma_f32_32x32x16_bf16 v[114:129], v[162:165], v[224:227], v[114:129]
	v_mfma_f32_32x32x16_bf16 v[82:97], v[162:165], v[228:231], v[82:97]
	s_waitcnt lgkmcnt(4)
	v_mfma_f32_32x32x16_bf16 v[98:113], v[166:169], v[224:227], v[98:113]
	v_mfma_f32_32x32x16_bf16 v[66:81], v[166:169], v[228:231], v[66:81]
	s_waitcnt lgkmcnt(1)
	v_mfma_f32_32x32x16_bf16 v[50:65], v[176:179], v[224:227], v[50:65]
	v_mfma_f32_32x32x16_bf16 v[18:33], v[176:179], v[228:231], v[18:33]
	s_waitcnt lgkmcnt(0)
	v_mfma_f32_32x32x16_bf16 v[34:49], v[180:183], v[224:227], v[34:49]
	v_mfma_f32_32x32x16_bf16 v[2:17], v[180:183], v[228:231], v[2:17]
	s_add_i32 s13, s13, 2
	s_cmp_gt_u32 s28, 13
	s_barrier
	s_cbranch_scc0 .LBB0_311
	s_branch .Lkexit_2

; DI unsigned pk2(float lo, float hi) { f32x2 v = {lo, hi}; bf16x2v b = __builtin_convertvector(v, bf16x2v); return __builtin_bit_cast(unsigned, b); }
; DI bf16_t f2bf(float x) { return (bf16_t)(pk2(x, 0.f) & 0xffffu); }
; DI float sigmoidf_(float x) { return __builtin_amdgcn_rcpf(1.f + __builtin_amdgcn_exp2f(-LOG2E * x)); }
; DI float siluf_(float x) { return x * __builtin_amdgcn_rcpf(1.f + __builtin_amdgcn_exp2f(-LOG2E * x)); }
; DI int swz32(int s) { return (s & ~12) | ((s & 4) << 1) | ((s & 8) >> 1); }
;   DI void operator()(int tok0, int feat0, f32x16 (&acc)[2][2], int r, int hh) const {
;     const int seg = feat0 >> 9, c0 = feat0 & 511;
; #pragma unroll
;     for (int mt = 0; mt < 2; ++mt) {
;       const int tok = tok0 + mt * 32 + r, b = tok >> 14, s = tok & (SEQ - 1);
; #pragma unroll
;       for (int nt = 0; nt < 2; ++nt)
; #pragma unroll
;         for (int gp = 0; gp < 2; ++gp) {
;           const int c = c0 + nt * 32 + 16 * hh + 8 * gp;
;           float v[8];
; #pragma unroll
;           for (int e = 0; e < 8; ++e) v[e] = acc[nt][mt][8 * gp + e];
;           if (seg == 0 || seg == 3) {
;             u32x4 o = {pk2(siluf_(v[0]), siluf_(v[1])), pk2(siluf_(v[2]), siluf_(v[3])), pk2(siluf_(v[4]), siluf_(v[5])), pk2(siluf_(v[6]), siluf_(v[7]))};
;             *(u32x4*)((seg == 0 ? aq : ag) + (size_t)tok * 512 + c) = o;
;           } else if (seg == 1) {
; #pragma unroll
;             for (int h2 = 0; h2 < 2; ++h2) {
;               f32x4 lbv = *(const f32x4*)(lb + c + 4 * h2), o;
; #pragma unroll
;               for (int e = 0; e < 4; ++e) o[e] = __logf(lbv[e] + (1.f - lbv[e]) * sigmoidf_(v[4 * h2 + e]));
;               *(f32x4*)(alf + (size_t)tok * 512 + c + 4 * h2) = o;
;             }
;           } else if (seg == 4 || seg == 5) {
;             const float sc = seg == 4 ? 0.125f * LOG2E : 1.f;
;             u32x4 o = {pk2(v[0] * sc, v[1] * sc), pk2(v[2] * sc, v[3] * sc), pk2(v[4] * sc, v[5] * sc), pk2(v[6] * sc, v[7] * sc)};
;             *(u32x4*)((seg == 4 ? bq : bk) + (size_t)tok * 512 + c) = o;
;           } else {
;             bf16_t* dst = (seg == 2 ? aiT : bvT) + ((size_t)((b * 4 + (c >> 7)) * 128 + (c & 127))) * SEQ + (seg == 2 ? s : swz32(s));
; #pragma unroll
;             for (int e = 0; e < 8; ++e) dst[(size_t)e * SEQ] = f2bf(v[e]);
.Lkexit_2:
	v_mov_b32_e32 v0, v192
	s_ashr_i32 s2, s2, 5
	v_ashrrev_i32_e32 v162, 1, v0
	v_and_b32_e32 v162, 0xffffff80, v162
	v_lshrrev_b32_e32 v165, 1, v0
	v_add_u32_e32 v162, s3, v162
	v_and_b32_e32 v164, 0xdf, v0
	v_and_b32_e32 v0, 16, v165
	s_movk_i32 s3, 0x180
	v_and_or_b32 v216, v162, s3, v0
	s_movk_i32 s3, 0x200
	v_ashrrev_i32_e32 v163, 9, v162
	v_cmp_gt_u32_e64 s[12:13], s3, v162
	s_movk_i32 s3, 0x1ff
	v_cmp_lt_u32_e32 vcc, s3, v162
	v_cmp_ne_u32_e64 s[6:7], 3, v163
	s_and_b64 s[26:27], vcc, s[6:7]
	v_and_b32_e32 v0, 0xfffffc00, v162
	v_cmp_eq_u32_e32 vcc, 4, v163
	v_mov_b32_e32 v162, 0x3e38aa3b
	v_cmp_ne_u32_e64 s[8:9], 1, v163
	v_cmp_eq_u32_e64 s[10:11], 2, v163
	v_cndmask_b32_e32 v174, 1.0, v162, vcc
	v_bfrev_b32_e32 v162, 48
	v_mov_b32_e32 v163, 0xa000000
	v_or_b32_e32 v180, s4, v164
	v_cndmask_b32_e32 v172, v162, v163, vcc
	v_mov_b32_e32 v162, s4
	s_and_b32 s37, s2, 0xfffffe00
	s_movk_i32 s2, 0x3fd3
	v_bitop3_b32 v163, v164, s53, v162 bitop3:0xc8
	v_bitop3_b32 v162, v164, s2, v162 bitop3:0xc8
	v_lshlrev_b32_e32 v164, 1, v180
	s_movk_i32 s3, 0x800
	v_and_b32_e32 v218, 8, v164
	v_and_b32_e32 v219, 4, v165
	v_cmp_ne_u32_e64 s[6:7], s3, v0
	v_mov_b32_e32 v0, 0x6000000
	v_or3_b32 v162, v162, v218, v219
	v_ashrrev_i32_e32 v181, 31, v180
	v_cndmask_b32_e64 v0, v207, v0, s[10:11]
	v_mov_b32_e32 v173, v1
	v_cndmask_b32_e64 v217, v162, v163, s[10:11]
	v_lshlrev_b64 v[178:179], 10, v[180:181]
	v_lshlrev_b64 v[176:177], 11, v[180:181]
	s_and_saveexec_b64 s[2:3], s[26:27]
	s_xor_b64 s[4:5], exec, s[2:3]
	s_cbranch_execz .LBB0_322
	s_and_saveexec_b64 s[2:3], s[8:9]
	s_xor_b64 s[14:15], exec, s[2:3]
	s_cbranch_execz .LBB0_319
	s_and_saveexec_b64 s[2:3], s[6:7]
	s_xor_b64 s[28:29], exec, s[2:3]
	s_cbranch_execz .LBB0_316
	v_or_b32_e32 v164, s37, v216
	v_ashrrev_i32_e32 v165, 31, v164
	v_lshl_add_u64 v[162:163], s[16:17], 0, v[0:1]
	v_lshlrev_b64 v[164:165], 15, v[164:165]
	v_lshl_add_u64 v[162:163], v[162:163], 0, v[164:165]
	v_lshlrev_b32_e32 v164, 1, v217
	v_mov_b32_e32 v165, v1
	v_lshl_add_u64 v[162:163], v[162:163], 0, v[164:165]
	v_cvt_pk_bf16_f32 v164, v114, s0
	global_store_short v[162:163], v164, off
	v_add_co_u32_e32 v164, vcc, 0x8000, v162
	v_cvt_pk_bf16_f32 v166, v115, s0
	s_nop 0
	v_addc_co_u32_e32 v165, vcc, 0, v163, vcc
	global_store_short v[164:165], v166, off
	v_add_co_u32_e32 v164, vcc, s65, v162
	v_cvt_pk_bf16_f32 v166, v116, s0
	s_nop 0
	v_addc_co_u32_e32 v165, vcc, 0, v163, vcc
	global_store_short v[164:165], v166, off
	v_add_co_u32_e32 v164, vcc, 0x18000, v162
	v_cvt_pk_bf16_f32 v166, v117, s0
	s_nop 0
	v_addc_co_u32_e32 v165, vcc, 0, v163, vcc
	global_store_short v[164:165], v166, off
	v_add_co_u32_e32 v164, vcc, s91, v162
	v_cvt_pk_bf16_f32 v166, v118, s0
	s_nop 0
	v_addc_co_u32_e32 v165, vcc, 0, v163, vcc
	global_store_short v[164:165], v166, off
	v_add_co_u32_e32 v164, vcc, 0x28000, v162
	v_cvt_pk_bf16_f32 v166, v119, s0
	s_nop 0
	v_addc_co_u32_e32 v165, vcc, 0, v163, vcc
	global_store_short v[164:165], v166, off
	v_add_co_u32_e32 v164, vcc, 0x30000, v162
	v_cvt_pk_bf16_f32 v166, v120, s0
	s_nop 0
	v_addc_co_u32_e32 v165, vcc, 0, v163, vcc
	v_add_co_u32_e32 v162, vcc, 0x38000, v162
	global_store_short v[164:165], v166, off
	v_cvt_pk_bf16_f32 v164, v121, s0
	v_addc_co_u32_e32 v163, vcc, 0, v163, vcc
	global_store_short v[162:163], v164, off

; #define G_GLOAD(XR, WR, KT) { _Pragma("unroll") for (int i_ = 0; i_ < 4; ++i_) XR[i_] = *(const u32x4*)(Xt + ((size_t)(64 * i_) * ldx + (KT) * 64) * 2 + xoff); \
;     _Pragma("unroll") for (int i_ = 0; i_ < 4; ++i_) WR[i_] = *(const u32x4*)(Wtb + ((size_t)(64 * i_) * K + (KT) * 64) * 2 + woff); }
; #define G_LSTORE(XR, WR, STG) { char* xs_ = lds + (STG) * G_STAGE; char* ws_ = xs_ + G_XB; \
;     _Pragma("unroll") for (int i_ = 0; i_ < 4; ++i_) *(u32x4*)(xs_ + (lrow + 64 * i_) * LROW + lch * 16) = XR[i_]; \
;     _Pragma("unroll") for (int i_ = 0; i_ < 4; ++i_) *(u32x4*)(ws_ + (lrow + 64 * i_) * LROW + lch * 16) = WR[i_]; }
; template <class Epi>
; DI void gemm_phase(const bf16_t* __restrict__ X, const int ldx, const bf16_t* __restrict__ Wt, const int N, const int K, const Epi& epi, char* lds) {
;     ...
;     const int L = chunk * 32 + slot, band = L / (4 * nNt), rem = L % (4 * nNt);
;     const int mt_ = band * 4 + (rem & 3), nt_ = rem >> 2;
;     const char* Xt = (const char*)(X + (size_t)(mt_ * 256) * ldx);
;     const char* Wtb = (const char*)(Wt + (size_t)(nt_ * 256) * K);
;     const unsigned xoff = (unsigned)(lrow * ldx + lch * 8) * 2u, woff = (unsigned)(lrow * K + lch * 8) * 2u;
;     const bool has_next = !Epi::kFull && (chunk + 8 < nchunks);
;     const int Ln = (has_next ? chunk + 8 : chunk) * 32 + slot, band_n = Ln / (4 * nNt), rem_n = Ln % (4 * nNt);
;     const char* Xt_n = (const char*)(X + (size_t)((band_n * 4 + (rem_n & 3)) * 256) * ldx);
;     const char* Wtb_n = (const char*)(Wt + (size_t)((rem_n >> 2) * 256) * K);
;     f32x16 acc[2][2][2];
;     ...
;     asm volatile("" ::: "memory");
;     if (Epi::kFull || chunk == xcd) {
;       G_GLOAD(xr0, wr0, 0);
;       G_LSTORE(xr0, wr0, 0);
;       __syncthreads();
;       G_GLOAD(xr0, wr0, 1);
;     }
.LBB0_700:
	s_lshl_b32 s2, s34, 5
	v_readlane_b32 s3, v254, 3
	s_add_i32 s2, s2, s3
	s_lshr_b32 s2, s2, 2
	s_and_b32 s2, s2, 0xffffffc
	s_or_b32 s2, s2, s90
	s_lshl_b32 s4, s2, 8
	s_mov_b32 s5, s97
	s_lshl_b64 s[18:19], s[4:5], 11
	s_add_u32 s18, s6, s18
	s_addc_u32 s19, s7, s19
	v_lshl_add_u64 v[178:179], s[18:19], 0, v[162:163]
	s_waitcnt vmcnt(2)
	v_add_co_u32_e32 v48, vcc, s91, v178
	s_mov_b64 s[20:21], 0x40000
	s_nop 0
	v_addc_co_u32_e32 v49, vcc, 0, v179, vcc
	v_add_co_u32_e32 v74, vcc, s1, v178
	global_load_dwordx4 v[24:27], v[178:179], off
	global_load_dwordx4 v[28:31], v[48:49], off
	v_addc_co_u32_e32 v75, vcc, 0, v179, vcc
	v_add_co_u32_e32 v76, vcc, s76, v178
	global_load_dwordx4 v[32:35], v[164:165], off
	global_load_dwordx4 v[36:39], v[198:199], off
	global_load_dwordx4 v[40:43], v[206:207], off
	global_load_dwordx4 v[44:47], v[170:171], off
	v_addc_co_u32_e32 v77, vcc, 0, v179, vcc
	global_load_dwordx4 v[66:69], v[74:75], off
	global_load_dwordx4 v[70:73], v[76:77], off
	v_mov_b32_e32 v2, 0
	v_lshl_add_u64 v[180:181], v[178:179], 0, s[20:21]
	s_mov_b64 s[20:21], 0x60000
	s_mov_b32 s19, 0
	s_movk_i32 s3, 0x100
	v_mov_b32_e32 v3, v2
	s_waitcnt vmcnt(9)
	s_waitcnt vmcnt(8)
	v_mov_b32_e32 v22, v2
	v_lshl_add_u64 v[182:183], v[178:179], 0, s[20:21]
	v_mov_b32_e32 v23, v2
	v_mov_b32_e32 v104, v2
	s_waitcnt vmcnt(5)
	ds_write_b128 v222, v[32:35] offset:36864
	s_waitcnt vmcnt(4)
	ds_write_b128 v222, v[36:39] offset:46080
	s_waitcnt vmcnt(3)
	ds_write_b128 v222, v[40:43] offset:55296
	s_waitcnt vmcnt(2)
	ds_write_b128 v222, v[44:47] offset:64512
	ds_write_b128 v222, v[24:27]
	ds_write_b128 v222, v[28:31] offset:9216
	s_waitcnt vmcnt(1)
	ds_write_b128 v222, v[66:69] offset:18432
	s_waitcnt vmcnt(0)
	ds_write_b128 v222, v[70:73] offset:27648
	s_waitcnt lgkmcnt(0)
	s_barrier
	global_load_dwordx4 v[130:133], v[174:175], off
	global_load_dwordx4 v[150:153], v[176:177], off
	global_load_dwordx4 v[158:161], v[172:173], off
	global_load_dwordx4 v[138:141], v[164:165], off offset:128
	global_load_dwordx4 v[146:149], v[76:77], off offset:128
	global_load_dwordx4 v[134:137], v[74:75], off offset:128
	global_load_dwordx4 v[154:157], v[48:49], off offset:128
	global_load_dwordx4 v[142:145], v[178:179], off offset:128
	v_mov_b32_e32 v105, v2
	v_mov_b32_e32 v118, v2
	v_mov_b32_e32 v119, v2
	v_mov_b32_e32 v120, v2
	v_mov_b32_e32 v121, v2
	v_mov_b32_e32 v122, v2
	v_mov_b32_e32 v123, v2
	v_mov_b32_e32 v124, v2
	v_mov_b32_e32 v125, v2
	v_mov_b32_e32 v126, v2
	v_mov_b32_e32 v127, v2
	v_mov_b32_e32 v128, v2
	v_mov_b32_e32 v129, v2
	v_readfirstlane_b32 vcc_lo, v162
	v_readfirstlane_b32 s98, v178
	v_readfirstlane_b32 s99, v179
	v_readfirstlane_b32 s100, v164
	v_readfirstlane_b32 s101, v165
	s_nop 4
	s_sub_u32 s98, s98, vcc_lo
	s_subb_u32 s99, s99, 0
	s_sub_u32 s100, s100, vcc_lo
	s_subb_u32 s101, s101, 0
	v_add_u32_e32 v179, s91, v162
	v_add_u32_e32 v181, s1, v162
	v_add_u32_e32 v183, s76, v162
	v_add_u32_e32 v178, v191, v208
	v_add_u32_e32 v180, v191, v209
	v_add_u32_e32 v182, v210, v190
	ds_read_b128 v[166:169], v178
	ds_read_b128 v[184:187], v178 offset:4608
	ds_read_b128 v[194:197], v180 offset:36864
	ds_read_b128 v[202:205], v180 offset:41472
	ds_read_b128 v[224:227], v180 offset:46080
	ds_read_b128 v[228:231], v180 offset:50688
	ds_read_b128 v[232:235], v212 offset:32
	ds_read_b128 v[236:239], v212 offset:4640
	s_add_i32 s5, s19, 2
	s_cmp_lt_u32 s19, 14
	s_cselect_b32 s96, s3, 0x780
	s_min_u32 s18, s19, 12
	s_lshl_b32 s18, s18, 7
	s_addk_i32 s3, 0x100
	s_cmp_gt_u32 s19, 13
	s_waitcnt lgkmcnt(5)
	v_mfma_f32_32x32x16_bf16 v[114:129], v[194:197], v[166:169], 0
	v_mfma_f32_32x32x16_bf16 v[66:81], v[194:197], v[184:187], 0
	s_waitcnt lgkmcnt(4)
	v_mfma_f32_32x32x16_bf16 v[98:113], v[202:205], v[166:169], 0
	v_mfma_f32_32x32x16_bf16 v[34:49], v[202:205], v[184:187], 0
	s_waitcnt lgkmcnt(3)
	v_mfma_f32_32x32x16_bf16 v[82:97], v[224:227], v[166:169], 0
	v_mfma_f32_32x32x16_bf16 v[18:33], v[224:227], v[184:187], 0
	s_waitcnt lgkmcnt(2)
	v_mfma_f32_32x32x16_bf16 v[50:65], v[228:231], v[166:169], 0
	ds_read_b128 v[166:169], v213 offset:36896
	ds_read_b128 v[194:197], v213 offset:41504
	v_mfma_f32_32x32x16_bf16 v[2:17], v[228:231], v[184:187], 0
	s_waitcnt vmcnt(1)
	ds_write_b128 v214, v[154:157] offset:9216
	s_waitcnt vmcnt(0)
	ds_write_b128 v214, v[142:145]
	s_add_u32 vcc_lo, s98, s96
	s_addc_u32 vcc_hi, s99, 0
	global_load_dwordx4 v[142:145], v162, vcc
	global_load_dwordx4 v[154:157], v179, vcc
	ds_write_b128 v214, v[134:137] offset:18432
	ds_write_b128 v214, v[146:149] offset:27648
	global_load_dwordx4 v[134:137], v181, vcc
	global_load_dwordx4 v[146:149], v183, vcc
	ds_read_b128 v[184:187], v213 offset:46112
	ds_read_b128 v[202:205], v213 offset:50720
	ds_read_b128 v[224:227], v212 offset:64
	ds_read_b128 v[228:231], v212 offset:4672
	s_waitcnt lgkmcnt(9)
	v_mfma_f32_32x32x16_bf16 v[114:129], v[166:169], v[232:235], v[114:129]
	v_mfma_f32_32x32x16_bf16 v[66:81], v[166:169], v[236:239], v[66:81]
	s_waitcnt lgkmcnt(8)
	v_mfma_f32_32x32x16_bf16 v[98:113], v[194:197], v[232:235], v[98:113]
	v_mfma_f32_32x32x16_bf16 v[34:49], v[194:197], v[236:239], v[34:49]
	s_waitcnt lgkmcnt(3)
	v_mfma_f32_32x32x16_bf16 v[82:97], v[184:187], v[232:235], v[82:97]
	v_mfma_f32_32x32x16_bf16 v[18:33], v[184:187], v[236:239], v[18:33]
	ds_read_b128 v[166:169], v213 offset:36928
	ds_read_b128 v[184:187], v213 offset:41536
	s_waitcnt lgkmcnt(4)
	v_mfma_f32_32x32x16_bf16 v[50:65], v[202:205], v[232:235], v[50:65]
	v_mfma_f32_32x32x16_bf16 v[2:17], v[202:205], v[236:239], v[2:17]
	ds_write_b128 v215, v[150:153] offset:9216
	ds_write_b128 v215, v[138:141]
	s_add_u32 vcc_lo, s100, s96
	s_addc_u32 vcc_hi, s101, 0
	global_load_dwordx4 v[138:141], v162, vcc
	global_load_dwordx4 v[150:153], v179, vcc
	ds_read_b128 v[194:197], v213 offset:46144
	ds_read_b128 v[202:205], v213 offset:50752
	ds_read_b128 v[232:235], v212 offset:96
	ds_read_b128 v[236:239], v212 offset:4704
	s_waitcnt lgkmcnt(7)
	v_mfma_f32_32x32x16_bf16 v[114:129], v[166:169], v[224:227], v[114:129]
	v_mfma_f32_32x32x16_bf16 v[66:81], v[166:169], v[228:231], v[66:81]
	s_waitcnt lgkmcnt(6)
	v_mfma_f32_32x32x16_bf16 v[98:113], v[184:187], v[224:227], v[98:113]
	v_mfma_f32_32x32x16_bf16 v[34:49], v[184:187], v[228:231], v[34:49]
	s_waitcnt lgkmcnt(3)
	v_mfma_f32_32x32x16_bf16 v[82:97], v[194:197], v[224:227], v[82:97]
	ds_read_b128 v[166:169], v213 offset:36960
	ds_read_b128 v[184:187], v213 offset:41568
	v_mfma_f32_32x32x16_bf16 v[18:33], v[194:197], v[228:231], v[18:33]
	s_waitcnt lgkmcnt(4)
	v_mfma_f32_32x32x16_bf16 v[50:65], v[202:205], v[224:227], v[50:65]
	v_mfma_f32_32x32x16_bf16 v[2:17], v[202:205], v[228:231], v[2:17]
	ds_write_b128 v215, v[130:133] offset:18432
	ds_write_b128 v215, v[158:161] offset:27648
	global_load_dwordx4 v[130:133], v181, vcc
	global_load_dwordx4 v[158:161], v183, vcc
	ds_read_b128 v[194:197], v213 offset:46176
	ds_read_b128 v[202:205], v213 offset:50784
	s_waitcnt lgkmcnt(5)
	v_mfma_f32_32x32x16_bf16 v[114:129], v[166:169], v[232:235], v[114:129]
	v_mfma_f32_32x32x16_bf16 v[66:81], v[166:169], v[236:239], v[66:81]
	s_waitcnt lgkmcnt(4)
	v_mfma_f32_32x32x16_bf16 v[98:113], v[184:187], v[232:235], v[98:113]
	v_mfma_f32_32x32x16_bf16 v[34:49], v[184:187], v[236:239], v[34:49]
	s_waitcnt lgkmcnt(1)
	v_mfma_f32_32x32x16_bf16 v[82:97], v[194:197], v[232:235], v[82:97]
	v_mfma_f32_32x32x16_bf16 v[18:33], v[194:197], v[236:239], v[18:33]
	s_waitcnt lgkmcnt(0)
	v_mfma_f32_32x32x16_bf16 v[50:65], v[202:205], v[232:235], v[50:65]
	v_mfma_f32_32x32x16_bf16 v[2:17], v[202:205], v[236:239], v[2:17]
	s_barrier
	ds_read_b128 v[166:169], v216
	ds_read_b128 v[184:187], v216 offset:4608
	ds_read_b128 v[194:197], v217
	ds_read_b128 v[202:205], v217 offset:4608
	ds_read_b128 v[224:227], v217 offset:9216
	ds_read_b128 v[228:231], v217 offset:13824
	ds_read_b128 v[232:235], v182 offset:32
	ds_read_b128 v[236:239], v218 offset:32
	s_waitcnt lgkmcnt(5)
	v_mfma_f32_32x32x16_bf16 v[114:129], v[194:197], v[166:169], v[114:129]
	v_mfma_f32_32x32x16_bf16 v[66:81], v[194:197], v[184:187], v[66:81]
	s_waitcnt lgkmcnt(4)
	v_mfma_f32_32x32x16_bf16 v[98:113], v[202:205], v[166:169], v[98:113]
	v_mfma_f32_32x32x16_bf16 v[34:49], v[202:205], v[184:187], v[34:49]
	s_waitcnt lgkmcnt(3)
	v_mfma_f32_32x32x16_bf16 v[82:97], v[224:227], v[166:169], v[82:97]
	v_add_u32_e32 v223, v211, v190
	v_mfma_f32_32x32x16_bf16 v[18:33], v[224:227], v[184:187], v[18:33]
	s_waitcnt lgkmcnt(2)
	v_mfma_f32_32x32x16_bf16 v[50:65], v[228:231], v[166:169], v[50:65]
	ds_read_b128 v[166:169], v223 offset:32
	ds_read_b128 v[194:197], v219 offset:32
	v_mfma_f32_32x32x16_bf16 v[2:17], v[228:231], v[184:187], v[2:17]
	s_mov_b32 s19, s97
	s_waitcnt vmcnt(6)
	ds_write_b128 v222, v[154:157] offset:9216
	ds_write_b128 v222, v[142:145]
	s_add_u32 vcc_lo, s98, s18
	s_addc_u32 vcc_hi, s99, 0
	global_load_dwordx4 v[142:145], v162, vcc offset:384
	global_load_dwordx4 v[154:157], v179, vcc offset:384
	s_waitcnt vmcnt(7)
	ds_write_b128 v222, v[134:137] offset:18432
	s_waitcnt vmcnt(6)
	ds_write_b128 v222, v[146:149] offset:27648
	global_load_dwordx4 v[134:137], v181, vcc offset:384
	global_load_dwordx4 v[146:149], v183, vcc offset:384
	ds_read_b128 v[184:187], v220 offset:32
	ds_read_b128 v[202:205], v221 offset:32
	ds_read_b128 v[224:227], v182 offset:64
	ds_read_b128 v[228:231], v218 offset:64
	s_waitcnt lgkmcnt(9)
	v_mfma_f32_32x32x16_bf16 v[114:129], v[166:169], v[232:235], v[114:129]
	v_mfma_f32_32x32x16_bf16 v[66:81], v[166:169], v[236:239], v[66:81]
	s_waitcnt lgkmcnt(8)
	v_mfma_f32_32x32x16_bf16 v[98:113], v[194:197], v[232:235], v[98:113]
	v_mfma_f32_32x32x16_bf16 v[34:49], v[194:197], v[236:239], v[34:49]
	s_waitcnt lgkmcnt(3)
	v_mfma_f32_32x32x16_bf16 v[82:97], v[184:187], v[232:235], v[82:97]
	v_mfma_f32_32x32x16_bf16 v[18:33], v[184:187], v[236:239], v[18:33]
	ds_read_b128 v[166:169], v223 offset:64
	ds_read_b128 v[184:187], v219 offset:64
	s_waitcnt lgkmcnt(4)
	v_mfma_f32_32x32x16_bf16 v[50:65], v[202:205], v[232:235], v[50:65]
	v_mfma_f32_32x32x16_bf16 v[2:17], v[202:205], v[236:239], v[2:17]
	s_waitcnt vmcnt(6)
	ds_write_b128 v222, v[150:153] offset:46080
	ds_write_b128 v222, v[138:141] offset:36864
	s_add_u32 vcc_lo, s100, s18
	s_addc_u32 vcc_hi, s101, 0
	global_load_dwordx4 v[138:141], v162, vcc offset:384
	global_load_dwordx4 v[150:153], v179, vcc offset:384
	ds_read_b128 v[194:197], v220 offset:64
	ds_read_b128 v[202:205], v221 offset:64
	ds_read_b128 v[232:235], v182 offset:96
	ds_read_b128 v[236:239], v218 offset:96
	s_waitcnt lgkmcnt(7)
	v_mfma_f32_32x32x16_bf16 v[114:129], v[166:169], v[224:227], v[114:129]
	v_mfma_f32_32x32x16_bf16 v[66:81], v[166:169], v[228:231], v[66:81]
	s_waitcnt lgkmcnt(6)
	v_mfma_f32_32x32x16_bf16 v[98:113], v[184:187], v[224:227], v[98:113]
	v_mfma_f32_32x32x16_bf16 v[34:49], v[184:187], v[228:231], v[34:49]
	s_waitcnt lgkmcnt(3)
	v_mfma_f32_32x32x16_bf16 v[82:97], v[194:197], v[224:227], v[82:97]
	ds_read_b128 v[166:169], v223 offset:96
	ds_read_b128 v[184:187], v219 offset:96
	v_mfma_f32_32x32x16_bf16 v[18:33], v[194:197], v[228:231], v[18:33]
	s_waitcnt lgkmcnt(4)
	v_mfma_f32_32x32x16_bf16 v[50:65], v[202:205], v[224:227], v[50:65]
	v_mfma_f32_32x32x16_bf16 v[2:17], v[202:205], v[228:231], v[2:17]
	s_waitcnt vmcnt(7)
	ds_write_b128 v222, v[130:133] offset:55296
	s_waitcnt vmcnt(6)
	ds_write_b128 v222, v[158:161] offset:64512
	global_load_dwordx4 v[130:133], v181, vcc offset:384
	global_load_dwordx4 v[158:161], v183, vcc offset:384
	ds_read_b128 v[194:197], v220 offset:96
	ds_read_b128 v[202:205], v221 offset:96
	s_waitcnt lgkmcnt(5)
	v_mfma_f32_32x32x16_bf16 v[114:129], v[166:169], v[232:235], v[114:129]
	v_mfma_f32_32x32x16_bf16 v[66:81], v[166:169], v[236:239], v[66:81]
	s_waitcnt lgkmcnt(4)
	v_mfma_f32_32x32x16_bf16 v[98:113], v[184:187], v[232:235], v[98:113]
	v_mfma_f32_32x32x16_bf16 v[34:49], v[184:187], v[236:239], v[34:49]
	s_waitcnt lgkmcnt(1)
	v_mfma_f32_32x32x16_bf16 v[82:97], v[194:197], v[232:235], v[82:97]
	v_mfma_f32_32x32x16_bf16 v[18:33], v[194:197], v[236:239], v[18:33]
	s_waitcnt lgkmcnt(0)
	v_mfma_f32_32x32x16_bf16 v[50:65], v[202:205], v[232:235], v[50:65]
	v_mfma_f32_32x32x16_bf16 v[2:17], v[202:205], v[236:239], v[2:17]
	s_mov_b32 s19, s5
	s_cmp_gt_u32 s19, 15
	s_barrier
	s_cbranch_scc0 .LBB0_701
	s_branch .Lkexit_3

; #define RL_LOAD(XV, G) { constexpr int mt__ = (G) >> 2, half__ = ((G) >> 1) & 1, nt__ = (G) & 1; \
;     _Pragma("unroll") for (int gq = 0; gq < 4; ++gq) XV[gq] = *(const f32x4*)(xin + rbase + (size_t)mt__ * 32 * 1024 + half__ * 64 + nt__ * 32 + 4 * gq); }
; #define RL_FOLD(XV, G, SM, SQ) { constexpr int mt__ = (G) >> 2, half__ = ((G) >> 1) & 1, nt__ = (G) & 1; \
;     _Pragma("unroll") for (int gq = 0; gq < 4; ++gq) _Pragma("unroll") for (int jj = 0; jj < 4; ++jj) { \
;       const float y = ALPHA * XV[gq][jj] + acc[half__][nt__][mt__][4 * gq + jj]; acc[half__][nt__][mt__][4 * gq + jj] = y; SM += y; SQ += y * y; } }
; #define SB __builtin_amdgcn_sched_barrier(0)
;   DI void full(const int mt_, const int nt_, f32x16 (&acc)[2][2][2], const int tw, const int fw, const int r, const int hh, char* lds, const int tid) const {
;     float* part = (float*)(lds + G_STAGE);
;     const size_t rbase = (size_t)(mt_ * 256 + tw * 64 + r) * 1024 + nt_ * 256 + fw * 128 + 16 * hh;
;     f32x4 xa[4], xc[4], xe[4];
;     ...
;     float sm0 = 0.f, sq0 = 0.f, sm1 = 0.f, sq1 = 0.f;
;     RL_LOAD(xa, 0); RL_LOAD(xc, 1); RL_LOAD(xe, 2); SB;
;     RL_FOLD(xa, 0, sm0, sq0); SB; RL_LOAD(xa, 3); SB;
;     RL_FOLD(xc, 1, sm0, sq0); SB; RL_LOAD(xc, 4); SB;
;     RL_FOLD(xe, 2, sm0, sq0); SB; RL_LOAD(xe, 5); SB;
;     RL_FOLD(xa, 3, sm0, sq0); SB; RL_LOAD(xa, 6); SB;
;     RL_FOLD(xc, 4, sm1, sq1); SB; RL_LOAD(xc, 7); SB;
;     RL_FOLD(xe, 5, sm1, sq1); SB;
;     RL_FOLD(xa, 6, sm1, sq1); SB;
;     RL_FOLD(xc, 7, sm1, sq1);
.Lkexit_3:
	v_mov_b32_e32 v184, v192
	s_waitcnt vmcnt(1)
	v_ashrrev_i32_e32 v130, 1, v184
	v_and_b32_e32 v223, 0xdf, v184
	v_and_b32_e32 v182, 0xffffff80, v130
	v_or_b32_e32 v0, s4, v223
	v_ashrrev_i32_e32 v183, 31, v182
	v_bfe_u32 v224, v184, 5, 1
	v_lshl_add_u64 v[130:131], v[182:183], 2, s[16:17]
	v_lshlrev_b64 v[132:133], 12, v[0:1]
	v_lshl_add_u64 v[130:131], v[130:131], 0, v[132:133]
	v_lshlrev_b32_e32 v132, 6, v224
	v_mov_b32_e32 v133, v1
	v_lshl_add_u64 v[186:187], v[130:131], 0, v[132:133]
	global_load_dwordx4 v[130:133], v[186:187], off offset:48
	global_load_dwordx4 v[134:137], v[186:187], off offset:32
	global_load_dwordx4 v[138:141], v[186:187], off offset:16
	global_load_dwordx4 v[142:145], v[186:187], off
	global_load_dwordx4 v[226:229], v[186:187], off offset:176
	global_load_dwordx4 v[230:233], v[186:187], off offset:160
	global_load_dwordx4 v[234:237], v[186:187], off offset:144
	global_load_dwordx4 v[146:149], v[186:187], off offset:128
	global_load_dwordx4 v[238:241], v[186:187], off offset:304
	global_load_dwordx4 v[242:245], v[186:187], off offset:288
	global_load_dwordx4 v[246:249], v[186:187], off offset:272
	global_load_dwordx4 v[250:253], v[186:187], off offset:256
	s_waitcnt vmcnt(8)
	v_pk_fma_f32 v[178:179], v[142:143], s[0:1], v[114:115] op_sel_hi:[1,0,1]
	v_pk_fma_f32 v[180:181], v[144:145], s[0:1], v[116:117] op_sel_hi:[1,0,1]
	v_add_f32_e32 v114, 0, v178
	v_add_f32_e32 v142, v179, v114
	v_mul_f32_e32 v114, v179, v179
	v_pk_fma_f32 v[114:115], v[178:179], v[178:179], v[114:115] op_sel_hi:[1,1,0]
	v_add_f32_e32 v116, v180, v142
	v_pk_fma_f32 v[114:115], v[180:181], v[180:181], v[114:115]
	v_add_f32_e32 v117, v181, v116
	v_mul_f32_e32 v116, v181, v181
	v_pk_fma_f32 v[158:159], v[138:139], s[0:1], v[118:119] op_sel_hi:[1,0,1]
	v_pk_add_f32 v[114:115], v[116:117], v[114:115] op_sel_hi:[0,1]
	v_add_f32_e32 v116, v158, v117
	v_pk_fma_f32 v[114:115], v[158:159], v[158:159], v[114:115]
	v_add_f32_e32 v117, v159, v116
	v_mul_f32_e32 v116, v159, v159
	v_pk_fma_f32 v[160:161], v[140:141], s[0:1], v[120:121] op_sel_hi:[1,0,1]
	v_pk_add_f32 v[114:115], v[116:117], v[114:115] op_sel_hi:[0,1]
	v_add_f32_e32 v116, v160, v117
	v_pk_fma_f32 v[114:115], v[160:161], v[160:161], v[114:115]
	v_add_f32_e32 v117, v161, v116
	v_mul_f32_e32 v116, v161, v161
	v_pk_fma_f32 v[154:155], v[134:135], s[0:1], v[122:123] op_sel_hi:[1,0,1]
	v_pk_add_f32 v[114:115], v[116:117], v[114:115] op_sel_hi:[0,1]
	v_add_f32_e32 v116, v154, v117
	v_pk_fma_f32 v[114:115], v[154:155], v[154:155], v[114:115]
	v_add_f32_e32 v117, v155, v116
	v_mul_f32_e32 v116, v155, v155
	v_pk_fma_f32 v[156:157], v[136:137], s[0:1], v[124:125] op_sel_hi:[1,0,1]
	v_pk_add_f32 v[114:115], v[116:117], v[114:115] op_sel_hi:[0,1]
	v_add_f32_e32 v116, v156, v117
	v_pk_fma_f32 v[114:115], v[156:157], v[156:157], v[114:115]
	v_add_f32_e32 v124, v157, v116
	v_mul_f32_e32 v116, v157, v157
	v_pk_add_f32 v[114:115], v[116:117], v[114:115] op_sel_hi:[0,1]
	v_pk_fma_f32 v[152:153], v[130:131], s[0:1], v[126:127] op_sel_hi:[1,0,1]
	v_pk_fma_f32 v[150:151], v[132:133], s[0:1], v[128:129] op_sel_hi:[1,0,1]
	v_pk_fma_f32 v[114:115], v[152:153], v[152:153], v[114:115]
	v_mul_f32_e32 v116, v153, v153
	v_pk_add_f32 v[114:115], v[116:117], v[114:115] op_sel_hi:[0,1]
	v_pk_fma_f32 v[114:115], v[150:151], v[150:151], v[114:115]
	v_mul_f32_e32 v116, v151, v151
	v_pk_add_f32 v[118:119], v[116:117], v[114:115] op_sel_hi:[0,1]
	global_load_dwordx4 v[114:117], v[186:187], off offset:432
	global_load_dwordx4 v[202:205], v[186:187], off offset:416
	global_load_dwordx4 v[194:197], v[186:187], off offset:400
	global_load_dwordx4 v[120:123], v[186:187], off offset:384
	v_add_f32_e32 v124, v152, v124
	v_add_f32_e32 v124, v153, v124
	v_add_f32_e32 v124, v150, v124
	v_add_f32_e32 v124, v151, v124
	s_waitcnt vmcnt(8)
	v_pk_fma_f32 v[144:145], v[146:147], s[0:1], v[98:99] op_sel_hi:[1,0,1]
	v_pk_fma_f32 v[148:149], v[148:149], s[0:1], v[100:101] op_sel_hi:[1,0,1]
	v_add_f32_e32 v124, v144, v124
	v_pk_fma_f32 v[98:99], v[144:145], v[144:145], v[118:119]
	v_add_f32_e32 v119, v145, v124
	v_mul_f32_e32 v118, v145, v145
	v_pk_add_f32 v[98:99], v[118:119], v[98:99] op_sel_hi:[0,1]
	v_add_f32_e32 v100, v148, v119
	v_pk_fma_f32 v[98:99], v[148:149], v[148:149], v[98:99]
	v_add_f32_e32 v101, v149, v100
	v_mul_f32_e32 v100, v149, v149
	v_pk_fma_f32 v[138:139], v[234:235], s[0:1], v[102:103] op_sel_hi:[1,0,1]
	v_pk_add_f32 v[98:99], v[100:101], v[98:99] op_sel_hi:[0,1]
	v_add_f32_e32 v100, v138, v101
	v_pk_fma_f32 v[98:99], v[138:139], v[138:139], v[98:99]
	v_add_f32_e32 v101, v139, v100
	v_mul_f32_e32 v100, v139, v139
	v_pk_fma_f32 v[146:147], v[236:237], s[0:1], v[104:105] op_sel_hi:[1,0,1]
	v_pk_add_f32 v[98:99], v[100:101], v[98:99] op_sel_hi:[0,1]
	v_add_f32_e32 v100, v146, v101
	v_pk_fma_f32 v[98:99], v[146:147], v[146:147], v[98:99]
	v_add_f32_e32 v101, v147, v100
	v_mul_f32_e32 v100, v147, v147
	v_pk_fma_f32 v[130:131], v[230:231], s[0:1], v[106:107] op_sel_hi:[1,0,1]
	v_pk_add_f32 v[98:99], v[100:101], v[98:99] op_sel_hi:[0,1]
	v_add_f32_e32 v100, v130, v101
	v_pk_fma_f32 v[98:99], v[130:131], v[130:131], v[98:99]
	v_add_f32_e32 v101, v131, v100
	v_mul_f32_e32 v100, v131, v131
	v_pk_fma_f32 v[140:141], v[232:233], s[0:1], v[108:109] op_sel_hi:[1,0,1]
	v_pk_add_f32 v[98:99], v[100:101], v[98:99] op_sel_hi:[0,1]
	v_add_f32_e32 v100, v140, v101
	v_pk_fma_f32 v[98:99], v[140:141], v[140:141], v[98:99]
	v_add_f32_e32 v106, v141, v100
	v_mul_f32_e32 v100, v141, v141
	v_pk_add_f32 v[102:103], v[100:101], v[98:99] op_sel_hi:[0,1]
	v_pk_fma_f32 v[124:125], v[226:227], s[0:1], v[110:111] op_sel_hi:[1,0,1]
	v_pk_fma_f32 v[134:135], v[228:229], s[0:1], v[112:113] op_sel_hi:[1,0,1]
	v_add_co_u32_e32 v188, vcc, s91, v186
	s_mov_b64 s[18:19], 0x20000
	s_nop 0
	v_addc_co_u32_e32 v189, vcc, 0, v187, vcc
	v_lshl_add_u64 v[104:105], v[186:187], 0, s[18:19]
	global_load_dwordx4 v[226:229], v[188:189], off
	global_load_dwordx4 v[98:101], v[104:105], off offset:48
	global_load_dwordx4 v[230:233], v[104:105], off offset:32
	global_load_dwordx4 v[234:237], v[104:105], off offset:16
	v_add_f32_e32 v104, v124, v106
	v_pk_fma_f32 v[102:103], v[124:125], v[124:125], v[102:103]
	v_add_f32_e32 v105, v125, v104
	v_mul_f32_e32 v104, v125, v125
	v_pk_add_f32 v[102:103], v[104:105], v[102:103] op_sel_hi:[0,1]
	v_add_f32_e32 v104, v134, v105
	v_pk_fma_f32 v[102:103], v[134:135], v[134:135], v[102:103]
	v_add_f32_e32 v105, v135, v104
	v_mul_f32_e32 v104, v135, v135
	v_pk_add_f32 v[102:103], v[104:105], v[102:103] op_sel_hi:[0,1]
	s_waitcnt vmcnt(8)
; #define RL_LOAD(XV, G) { constexpr int mt__ = (G) >> 2, half__ = ((G) >> 1) & 1, nt__ = (G) & 1; \
;     _Pragma("unroll") for (int gq = 0; gq < 4; ++gq) XV[gq] = *(const f32x4*)(xin + rbase + (size_t)mt__ * 32 * 1024 + half__ * 64 + nt__ * 32 + 4 * gq); }
; #define RL_FOLD(XV, G, SM, SQ) { constexpr int mt__ = (G) >> 2, half__ = ((G) >> 1) & 1, nt__ = (G) & 1; \
;     _Pragma("unroll") for (int gq = 0; gq < 4; ++gq) _Pragma("unroll") for (int jj = 0; jj < 4; ++jj) { \
;       const float y = ALPHA * XV[gq][jj] + acc[half__][nt__][mt__][4 * gq + jj]; acc[half__][nt__][mt__][4 * gq + jj] = y; SM += y; SQ += y * y; } }
; #define SB __builtin_amdgcn_sched_barrier(0)
;   DI void full(const int mt_, const int nt_, f32x16 (&acc)[2][2][2], const int tw, const int fw, const int r, const int hh, char* lds, const int tid) const {
;     ...
;     float sm0 = 0.f, sq0 = 0.f, sm1 = 0.f, sq1 = 0.f;
;     RL_LOAD(xa, 0); RL_LOAD(xc, 1); RL_LOAD(xe, 2); SB;
;     RL_FOLD(xa, 0, sm0, sq0); SB; RL_LOAD(xa, 3); SB;
;     RL_FOLD(xc, 1, sm0, sq0); SB; RL_LOAD(xc, 4); SB;
;     RL_FOLD(xe, 2, sm0, sq0); SB; RL_LOAD(xe, 5); SB;
;     RL_FOLD(xa, 3, sm0, sq0); SB; RL_LOAD(xa, 6); SB;
;     RL_FOLD(xc, 4, sm1, sq1); SB; RL_LOAD(xc, 7); SB;
;     RL_FOLD(xe, 5, sm1, sq1); SB;
;     RL_FOLD(xa, 6, sm1, sq1); SB;
;     RL_FOLD(xc, 7, sm1, sq1);
	v_pk_fma_f32 v[132:133], v[250:251], s[0:1], v[82:83] op_sel_hi:[1,0,1]
	v_pk_fma_f32 v[142:143], v[252:253], s[0:1], v[84:85] op_sel_hi:[1,0,1]
	v_add_f32_e32 v104, v132, v105
	v_pk_fma_f32 v[82:83], v[132:133], v[132:133], v[102:103]
	v_add_f32_e32 v103, v133, v104
	v_mul_f32_e32 v102, v133, v133
	v_pk_add_f32 v[82:83], v[102:103], v[82:83] op_sel_hi:[0,1]
	v_add_f32_e32 v84, v142, v103
	v_pk_fma_f32 v[82:83], v[142:143], v[142:143], v[82:83]
	v_add_f32_e32 v85, v143, v84
	v_mul_f32_e32 v84, v143, v143
	v_pk_fma_f32 v[126:127], v[246:247], s[0:1], v[86:87] op_sel_hi:[1,0,1]
	v_pk_add_f32 v[82:83], v[84:85], v[82:83] op_sel_hi:[0,1]
	v_add_f32_e32 v84, v126, v85
	v_pk_fma_f32 v[82:83], v[126:127], v[126:127], v[82:83]
	v_add_f32_e32 v85, v127, v84
	v_mul_f32_e32 v84, v127, v127
	v_pk_fma_f32 v[136:137], v[248:249], s[0:1], v[88:89] op_sel_hi:[1,0,1]
	v_pk_add_f32 v[82:83], v[84:85], v[82:83] op_sel_hi:[0,1]
	v_add_f32_e32 v84, v136, v85
	v_pk_fma_f32 v[82:83], v[136:137], v[136:137], v[82:83]
	v_add_f32_e32 v85, v137, v84
	v_mul_f32_e32 v84, v137, v137
	v_pk_fma_f32 v[112:113], v[242:243], s[0:1], v[90:91] op_sel_hi:[1,0,1]
	v_pk_add_f32 v[82:83], v[84:85], v[82:83] op_sel_hi:[0,1]
	v_add_f32_e32 v84, v112, v85
	v_pk_fma_f32 v[82:83], v[112:113], v[112:113], v[82:83]
	v_add_f32_e32 v85, v113, v84
	v_mul_f32_e32 v84, v113, v113
	v_pk_fma_f32 v[128:129], v[244:245], s[0:1], v[92:93] op_sel_hi:[1,0,1]
	v_pk_add_f32 v[82:83], v[84:85], v[82:83] op_sel_hi:[0,1]
	v_add_f32_e32 v84, v128, v85
	v_pk_fma_f32 v[82:83], v[128:129], v[128:129], v[82:83]
	v_add_f32_e32 v90, v129, v84
	v_mul_f32_e32 v84, v129, v129
	v_pk_add_f32 v[86:87], v[84:85], v[82:83] op_sel_hi:[0,1]
	v_pk_fma_f32 v[106:107], v[238:239], s[0:1], v[94:95] op_sel_hi:[1,0,1]
	v_pk_fma_f32 v[118:119], v[240:241], s[0:1], v[96:97] op_sel_hi:[1,0,1]
	s_mov_b64 s[18:19], 0x20080
	v_lshl_add_u64 v[88:89], v[186:187], 0, s[18:19]
	global_load_dwordx4 v[82:85], v[88:89], off offset:48
	global_load_dwordx4 v[238:241], v[88:89], off offset:32
	global_load_dwordx4 v[242:245], v[188:189], off offset:128
	global_load_dwordx4 v[246:249], v[88:89], off offset:16
	v_add_f32_e32 v88, v106, v90
	v_pk_fma_f32 v[86:87], v[106:107], v[106:107], v[86:87]
	v_add_f32_e32 v89, v107, v88
	v_mul_f32_e32 v88, v107, v107
	v_pk_add_f32 v[86:87], v[88:89], v[86:87] op_sel_hi:[0,1]
	v_add_f32_e32 v88, v118, v89
	v_pk_fma_f32 v[86:87], v[118:119], v[118:119], v[86:87]
	v_add_f32_e32 v89, v119, v88
	v_mul_f32_e32 v88, v119, v119
	v_pk_add_f32 v[86:87], v[88:89], v[86:87] op_sel_hi:[0,1]
	s_waitcnt vmcnt(8)
	v_pk_fma_f32 v[104:105], v[120:121], s[0:1], v[50:51] op_sel_hi:[1,0,1]
	v_pk_fma_f32 v[122:123], v[122:123], s[0:1], v[52:53] op_sel_hi:[1,0,1]
	v_add_f32_e32 v88, v104, v89
	v_pk_fma_f32 v[50:51], v[104:105], v[104:105], v[86:87]
	v_add_f32_e32 v87, v105, v88
	v_mul_f32_e32 v86, v105, v105
	v_add_f32_e32 v52, v122, v87
	v_pk_add_f32 v[50:51], v[86:87], v[50:51] op_sel_hi:[0,1]
	v_add_f32_e32 v52, v123, v52
	v_pk_fma_f32 v[102:103], v[194:195], s[0:1], v[54:55] op_sel_hi:[1,0,1]
	v_pk_fma_f32 v[50:51], v[122:123], v[122:123], v[50:51]
	v_add_f32_e32 v55, v102, v52
	v_mul_f32_e32 v54, v123, v123
	v_mov_b32_e32 v52, v102
	v_mov_b32_e32 v53, v123
	v_pk_add_f32 v[50:51], v[54:55], v[50:51] op_sel_hi:[0,1]
	v_pk_fma_f32 v[50:51], v[52:53], v[52:53], v[50:51]
	v_add_f32_e32 v52, v103, v55
	v_pk_fma_f32 v[120:121], v[196:197], s[0:1], v[56:57] op_sel_hi:[1,0,1]
	v_mul_f32_e32 v54, v103, v103
	v_add_f32_e32 v55, v120, v52
	v_mov_b32_e32 v52, v120
	v_mov_b32_e32 v53, v103
	v_pk_add_f32 v[50:51], v[54:55], v[50:51] op_sel_hi:[0,1]
	v_pk_fma_f32 v[50:51], v[52:53], v[52:53], v[50:51]
	v_add_f32_e32 v52, v121, v55
	v_pk_fma_f32 v[94:95], v[202:203], s[0:1], v[58:59] op_sel_hi:[1,0,1]
	v_mul_f32_e32 v54, v121, v121
	v_add_f32_e32 v55, v94, v52
	v_mov_b32_e32 v52, v94
	v_mov_b32_e32 v53, v121
	v_pk_add_f32 v[50:51], v[54:55], v[50:51] op_sel_hi:[0,1]
	v_pk_fma_f32 v[50:51], v[52:53], v[52:53], v[50:51]
	v_add_f32_e32 v52, v95, v55
	v_pk_fma_f32 v[108:109], v[204:205], s[0:1], v[60:61] op_sel_hi:[1,0,1]
	v_mul_f32_e32 v54, v95, v95
	v_add_f32_e32 v55, v108, v52
	v_mov_b32_e32 v52, v108
	v_mov_b32_e32 v53, v95
	v_pk_add_f32 v[50:51], v[54:55], v[50:51] op_sel_hi:[0,1]
	v_pk_fma_f32 v[50:51], v[52:53], v[52:53], v[50:51]
	v_pk_fma_f32 v[96:97], v[114:115], s[0:1], v[62:63] op_sel_hi:[1,0,1]
	v_mul_f32_e32 v54, v109, v109
	v_pk_fma_f32 v[110:111], v[116:117], s[0:1], v[64:65] op_sel_hi:[1,0,1]
	v_add_f32_e32 v58, v109, v55
	v_pk_add_f32 v[50:51], v[54:55], v[50:51] op_sel_hi:[0,1]
	v_mov_b32_e32 v54, v110
	v_mov_b32_e32 v55, v97
	v_mov_b32_e32 v52, v96
	v_mov_b32_e32 v53, v109
	v_pk_mul_f32 v[114:115], v[110:111], v[110:111]
	s_mov_b64 s[18:19], 0x20100
	v_lshl_add_u64 v[56:57], v[186:187], 0, s[18:19]
	global_load_dwordx4 v[194:197], v[56:57], off offset:48
	global_load_dwordx4 v[202:205], v[56:57], off offset:32
	global_load_dwordx4 v[250:253], v[188:189], off offset:256
	global_load_dwordx4 v[166:169], v[56:57], off offset:16
	v_add_f32_e32 v56, v96, v58
	v_add_f32_e32 v56, v97, v56
	v_add_f32_e32 v114, v110, v56
	s_waitcnt vmcnt(11)
	v_pk_fma_f32 v[90:91], v[226:227], s[0:1], v[66:67] op_sel_hi:[1,0,1]
	v_pk_fma_f32 v[92:93], v[228:229], s[0:1], v[68:69] op_sel_hi:[1,0,1]
	v_add_f32_e32 v56, 0, v90
	v_add_f32_e32 v58, v91, v56
	v_mul_f32_e32 v56, v91, v91
	v_pk_fma_f32 v[56:57], v[90:91], v[90:91], v[56:57] op_sel_hi:[1,1,0]
	v_add_f32_e32 v58, v92, v58
	v_pk_fma_f32 v[56:57], v[92:93], v[92:93], v[56:57]
	v_add_f32_e32 v59, v93, v58
	v_mul_f32_e32 v58, v93, v93
	s_waitcnt vmcnt(8)
; #define RL_LOAD(XV, G) { constexpr int mt__ = (G) >> 2, half__ = ((G) >> 1) & 1, nt__ = (G) & 1; \
;     _Pragma("unroll") for (int gq = 0; gq < 4; ++gq) XV[gq] = *(const f32x4*)(xin + rbase + (size_t)mt__ * 32 * 1024 + half__ * 64 + nt__ * 32 + 4 * gq); }
; #define RL_FOLD(XV, G, SM, SQ) { constexpr int mt__ = (G) >> 2, half__ = ((G) >> 1) & 1, nt__ = (G) & 1; \
;     _Pragma("unroll") for (int gq = 0; gq < 4; ++gq) _Pragma("unroll") for (int jj = 0; jj < 4; ++jj) { \
;       const float y = ALPHA * XV[gq][jj] + acc[half__][nt__][mt__][4 * gq + jj]; acc[half__][nt__][mt__][4 * gq + jj] = y; SM += y; SQ += y * y; } }
; #define SB __builtin_amdgcn_sched_barrier(0)
;   DI void full(const int mt_, const int nt_, f32x16 (&acc)[2][2][2], const int tw, const int fw, const int r, const int hh, char* lds, const int tid) const {
;     ...
;     float sm0 = 0.f, sq0 = 0.f, sm1 = 0.f, sq1 = 0.f;
;     RL_LOAD(xa, 0); RL_LOAD(xc, 1); RL_LOAD(xe, 2); SB;
;     RL_FOLD(xa, 0, sm0, sq0); SB; RL_LOAD(xa, 3); SB;
;     RL_FOLD(xc, 1, sm0, sq0); SB; RL_LOAD(xc, 4); SB;
;     RL_FOLD(xe, 2, sm0, sq0); SB; RL_LOAD(xe, 5); SB;
;     RL_FOLD(xa, 3, sm0, sq0); SB; RL_LOAD(xa, 6); SB;
;     RL_FOLD(xc, 4, sm1, sq1); SB; RL_LOAD(xc, 7); SB;
;     RL_FOLD(xe, 5, sm1, sq1); SB;
;     RL_FOLD(xa, 6, sm1, sq1); SB;
;     RL_FOLD(xc, 7, sm1, sq1);
	v_pk_fma_f32 v[86:87], v[234:235], s[0:1], v[70:71] op_sel_hi:[1,0,1]
	v_pk_add_f32 v[56:57], v[58:59], v[56:57] op_sel_hi:[0,1]
	v_add_f32_e32 v58, v86, v59
	v_pk_fma_f32 v[56:57], v[86:87], v[86:87], v[56:57]
	v_add_f32_e32 v59, v87, v58
	v_mul_f32_e32 v58, v87, v87
	v_pk_fma_f32 v[88:89], v[236:237], s[0:1], v[72:73] op_sel_hi:[1,0,1]
	v_pk_add_f32 v[56:57], v[58:59], v[56:57] op_sel_hi:[0,1]
	v_add_f32_e32 v58, v88, v59
	v_pk_fma_f32 v[56:57], v[88:89], v[88:89], v[56:57]
	v_add_f32_e32 v59, v89, v58
	v_mul_f32_e32 v58, v89, v89
	v_pk_fma_f32 v[70:71], v[230:231], s[0:1], v[74:75] op_sel_hi:[1,0,1]
	v_pk_add_f32 v[56:57], v[58:59], v[56:57] op_sel_hi:[0,1]
	v_add_f32_e32 v58, v70, v59
	v_pk_fma_f32 v[56:57], v[70:71], v[70:71], v[56:57]
	v_add_f32_e32 v59, v71, v58
	v_mul_f32_e32 v58, v71, v71
	v_pk_fma_f32 v[72:73], v[232:233], s[0:1], v[76:77] op_sel_hi:[1,0,1]
	v_pk_add_f32 v[56:57], v[58:59], v[56:57] op_sel_hi:[0,1]
	v_add_f32_e32 v58, v72, v59
	v_pk_fma_f32 v[56:57], v[72:73], v[72:73], v[56:57]
	v_add_f32_e32 v59, v73, v58
	v_mul_f32_e32 v58, v73, v73
	v_pk_fma_f32 v[50:51], v[52:53], v[52:53], v[50:51]
	v_mul_f32_e32 v52, v97, v97
	v_pk_add_f32 v[56:57], v[58:59], v[56:57] op_sel_hi:[0,1]
	v_pk_fma_f32 v[68:69], v[98:99], s[0:1], v[78:79] op_sel_hi:[1,0,1]
	v_pk_fma_f32 v[66:67], v[100:101], s[0:1], v[80:81] op_sel_hi:[1,0,1]
	v_pk_add_f32 v[50:51], v[52:53], v[50:51] op_sel_hi:[0,1]
	v_pk_fma_f32 v[74:75], v[54:55], v[54:55], v[50:51]
	s_mov_b64 s[18:19], 0x20180
	v_lshl_add_u64 v[54:55], v[186:187], 0, s[18:19]
	global_load_dwordx4 v[50:53], v[54:55], off offset:48
	global_load_dwordx4 v[76:79], v[54:55], off offset:32
	global_load_dwordx4 v[98:101], v[188:189], off offset:384
	s_nop 0
	global_load_dwordx4 v[186:189], v[54:55], off offset:16
	v_add_f32_e32 v58, v68, v59
	v_pk_fma_f32 v[54:55], v[68:69], v[68:69], v[56:57]
	v_add_f32_e32 v57, v69, v58
	v_mul_f32_e32 v56, v69, v69
	v_pk_add_f32 v[54:55], v[56:57], v[54:55] op_sel_hi:[0,1]
	v_add_f32_e32 v56, v66, v57
	v_pk_fma_f32 v[54:55], v[66:67], v[66:67], v[54:55]
	v_add_f32_e32 v57, v67, v56
	v_mul_f32_e32 v56, v67, v67
	v_pk_add_f32 v[54:55], v[56:57], v[54:55] op_sel_hi:[0,1]
	s_waitcnt vmcnt(9)
	v_pk_fma_f32 v[60:61], v[242:243], s[0:1], v[34:35] op_sel_hi:[1,0,1]
	v_pk_fma_f32 v[64:65], v[244:245], s[0:1], v[36:37] op_sel_hi:[1,0,1]
	v_add_f32_e32 v56, v60, v57
	v_pk_fma_f32 v[34:35], v[60:61], v[60:61], v[54:55]
	v_add_f32_e32 v55, v61, v56
	v_mul_f32_e32 v54, v61, v61
	v_pk_add_f32 v[34:35], v[54:55], v[34:35] op_sel_hi:[0,1]
	v_add_f32_e32 v36, v64, v55
	v_pk_fma_f32 v[34:35], v[64:65], v[64:65], v[34:35]
	v_add_f32_e32 v37, v65, v36
	v_mul_f32_e32 v36, v65, v65
	s_waitcnt vmcnt(8)
	v_pk_fma_f32 v[56:57], v[246:247], s[0:1], v[38:39] op_sel_hi:[1,0,1]
	v_pk_add_f32 v[34:35], v[36:37], v[34:35] op_sel_hi:[0,1]
	v_add_f32_e32 v36, v56, v37
	v_pk_fma_f32 v[34:35], v[56:57], v[56:57], v[34:35]
	v_add_f32_e32 v37, v57, v36
	v_mul_f32_e32 v36, v57, v57
	v_pk_fma_f32 v[62:63], v[248:249], s[0:1], v[40:41] op_sel_hi:[1,0,1]
	v_pk_add_f32 v[34:35], v[36:37], v[34:35] op_sel_hi:[0,1]
	v_add_f32_e32 v36, v62, v37
	v_pk_fma_f32 v[34:35], v[62:63], v[62:63], v[34:35]
	v_add_f32_e32 v37, v63, v36
	v_mul_f32_e32 v36, v63, v63
	v_pk_fma_f32 v[54:55], v[238:239], s[0:1], v[42:43] op_sel_hi:[1,0,1]
	v_pk_add_f32 v[34:35], v[36:37], v[34:35] op_sel_hi:[0,1]
	v_add_f32_e32 v36, v54, v37
	v_pk_fma_f32 v[34:35], v[54:55], v[54:55], v[34:35]
	v_add_f32_e32 v37, v55, v36
	v_mul_f32_e32 v36, v55, v55
	v_pk_fma_f32 v[58:59], v[240:241], s[0:1], v[44:45] op_sel_hi:[1,0,1]
	v_pk_add_f32 v[34:35], v[36:37], v[34:35] op_sel_hi:[0,1]
	v_add_f32_e32 v36, v58, v37
	v_pk_fma_f32 v[34:35], v[58:59], v[58:59], v[34:35]
	v_add_f32_e32 v37, v59, v36
	v_mul_f32_e32 v36, v59, v59
	v_pk_fma_f32 v[44:45], v[82:83], s[0:1], v[46:47] op_sel_hi:[1,0,1]
	v_pk_add_f32 v[34:35], v[36:37], v[34:35] op_sel_hi:[0,1]
	v_add_f32_e32 v36, v44, v37
	v_pk_fma_f32 v[34:35], v[44:45], v[44:45], v[34:35]
	v_add_f32_e32 v37, v45, v36
	v_mul_f32_e32 v36, v45, v45
	v_pk_fma_f32 v[46:47], v[84:85], s[0:1], v[48:49] op_sel_hi:[1,0,1]
	v_pk_add_f32 v[34:35], v[36:37], v[34:35] op_sel_hi:[0,1]
	v_add_f32_e32 v36, v46, v37
	v_pk_fma_f32 v[34:35], v[46:47], v[46:47], v[34:35]
	v_add_f32_e32 v37, v47, v36
	v_mul_f32_e32 v36, v47, v47
	v_pk_add_f32 v[34:35], v[36:37], v[34:35] op_sel_hi:[0,1]
	s_waitcnt vmcnt(5)
	v_pk_fma_f32 v[38:39], v[250:251], s[0:1], v[18:19] op_sel_hi:[1,0,1]
	v_pk_fma_f32 v[42:43], v[252:253], s[0:1], v[20:21] op_sel_hi:[1,0,1]
	v_add_f32_e32 v36, v38, v37
	v_pk_fma_f32 v[18:19], v[38:39], v[38:39], v[34:35]
	v_add_f32_e32 v35, v39, v36
	v_mul_f32_e32 v34, v39, v39
	v_pk_add_f32 v[18:19], v[34:35], v[18:19] op_sel_hi:[0,1]
	v_add_f32_e32 v20, v42, v35
	v_pk_fma_f32 v[18:19], v[42:43], v[42:43], v[18:19]
	v_add_f32_e32 v21, v43, v20
	v_mul_f32_e32 v20, v43, v43
	s_waitcnt vmcnt(4)
; #define RL_LOAD(XV, G) { constexpr int mt__ = (G) >> 2, half__ = ((G) >> 1) & 1, nt__ = (G) & 1; \
;     _Pragma("unroll") for (int gq = 0; gq < 4; ++gq) XV[gq] = *(const f32x4*)(xin + rbase + (size_t)mt__ * 32 * 1024 + half__ * 64 + nt__ * 32 + 4 * gq); }
; #define RL_FOLD(XV, G, SM, SQ) { constexpr int mt__ = (G) >> 2, half__ = ((G) >> 1) & 1, nt__ = (G) & 1; \
;     _Pragma("unroll") for (int gq = 0; gq < 4; ++gq) _Pragma("unroll") for (int jj = 0; jj < 4; ++jj) { \
;       const float y = ALPHA * XV[gq][jj] + acc[half__][nt__][mt__][4 * gq + jj]; acc[half__][nt__][mt__][4 * gq + jj] = y; SM += y; SQ += y * y; } }
; #define SB __builtin_amdgcn_sched_barrier(0)
;   DI void full(const int mt_, const int nt_, f32x16 (&acc)[2][2][2], const int tw, const int fw, const int r, const int hh, char* lds, const int tid) const {
;     ...
;     float sm0 = 0.f, sq0 = 0.f, sm1 = 0.f, sq1 = 0.f;
;     RL_LOAD(xa, 0); RL_LOAD(xc, 1); RL_LOAD(xe, 2); SB;
;     RL_FOLD(xa, 0, sm0, sq0); SB; RL_LOAD(xa, 3); SB;
;     RL_FOLD(xc, 1, sm0, sq0); SB; RL_LOAD(xc, 4); SB;
;     RL_FOLD(xe, 2, sm0, sq0); SB; RL_LOAD(xe, 5); SB;
;     RL_FOLD(xa, 3, sm0, sq0); SB; RL_LOAD(xa, 6); SB;
;     RL_FOLD(xc, 4, sm1, sq1); SB; RL_LOAD(xc, 7); SB;
;     RL_FOLD(xe, 5, sm1, sq1); SB;
;     RL_FOLD(xa, 6, sm1, sq1); SB;
;     RL_FOLD(xc, 7, sm1, sq1);
;     ...
;     sm0 += __shfl_xor(sm0, 32, 64); sq0 += __shfl_xor(sq0, 32, 64); sm1 += __shfl_xor(sm1, 32, 64); sq1 += __shfl_xor(sq1, 32, 64);
;     if (hh == 0) {
;       float* pp = part + ((fw * 256) + tw * 64 + r) * 2; pp[0] = sm0; pp[1] = sq0;
;       pp[64] = sm1; pp[65] = sq1;
	v_pk_fma_f32 v[34:35], v[166:167], s[0:1], v[22:23] op_sel_hi:[1,0,1]
	v_pk_add_f32 v[18:19], v[20:21], v[18:19] op_sel_hi:[0,1]
	v_add_f32_e32 v20, v34, v21
	v_pk_fma_f32 v[18:19], v[34:35], v[34:35], v[18:19]
	v_add_f32_e32 v21, v35, v20
	v_mul_f32_e32 v20, v35, v35
	v_pk_fma_f32 v[40:41], v[168:169], s[0:1], v[24:25] op_sel_hi:[1,0,1]
	v_pk_add_f32 v[18:19], v[20:21], v[18:19] op_sel_hi:[0,1]
	v_add_f32_e32 v20, v40, v21
	v_pk_fma_f32 v[18:19], v[40:41], v[40:41], v[18:19]
	v_add_f32_e32 v21, v41, v20
	v_mul_f32_e32 v20, v41, v41
	v_pk_fma_f32 v[26:27], v[202:203], s[0:1], v[26:27] op_sel_hi:[1,0,1]
	v_pk_add_f32 v[18:19], v[20:21], v[18:19] op_sel_hi:[0,1]
	v_add_f32_e32 v20, v26, v21
	v_pk_fma_f32 v[18:19], v[26:27], v[26:27], v[18:19]
	v_add_f32_e32 v21, v27, v20
	v_mul_f32_e32 v20, v27, v27
	v_pk_fma_f32 v[36:37], v[204:205], s[0:1], v[28:29] op_sel_hi:[1,0,1]
	v_pk_add_f32 v[18:19], v[20:21], v[18:19] op_sel_hi:[0,1]
	v_add_f32_e32 v20, v36, v21
	v_pk_fma_f32 v[18:19], v[36:37], v[36:37], v[18:19]
	v_add_f32_e32 v21, v37, v20
	v_mul_f32_e32 v20, v37, v37
	v_pk_fma_f32 v[24:25], v[194:195], s[0:1], v[30:31] op_sel_hi:[1,0,1]
	v_pk_add_f32 v[18:19], v[20:21], v[18:19] op_sel_hi:[0,1]
	v_add_f32_e32 v20, v24, v21
	v_pk_fma_f32 v[18:19], v[24:25], v[24:25], v[18:19]
	v_add_f32_e32 v21, v25, v20
	v_mul_f32_e32 v20, v25, v25
	v_pk_fma_f32 v[28:29], v[196:197], s[0:1], v[32:33] op_sel_hi:[1,0,1]
	v_pk_add_f32 v[18:19], v[20:21], v[18:19] op_sel_hi:[0,1]
	v_add_f32_e32 v20, v28, v21
	v_pk_fma_f32 v[18:19], v[28:29], v[28:29], v[18:19]
	v_add_f32_e32 v22, v29, v20
	v_mul_f32_e32 v20, v29, v29
	v_pk_add_f32 v[20:21], v[20:21], v[18:19] op_sel_hi:[0,1]
	s_waitcnt vmcnt(1)
	v_pk_fma_f32 v[18:19], v[98:99], s[0:1], v[2:3] op_sel_hi:[1,0,1]
	s_waitcnt vmcnt(0)
	v_pk_fma_f32 v[6:7], v[186:187], s[0:1], v[6:7] op_sel_hi:[1,0,1]
	v_add_f32_e32 v22, v18, v22
	v_pk_fma_f32 v[2:3], v[18:19], v[18:19], v[20:21]
	v_add_f32_e32 v21, v19, v22
	v_pk_fma_f32 v[22:23], v[100:101], s[0:1], v[4:5] op_sel_hi:[1,0,1]
	v_mul_f32_e32 v20, v19, v19
	v_add_f32_e32 v4, v22, v21
	v_pk_add_f32 v[2:3], v[20:21], v[2:3] op_sel_hi:[0,1]
	v_add_f32_e32 v4, v23, v4
	v_pk_fma_f32 v[2:3], v[22:23], v[22:23], v[2:3]
	v_add_f32_e32 v21, v6, v4
	v_mul_f32_e32 v20, v23, v23
	v_mov_b32_e32 v4, v6
	v_mov_b32_e32 v5, v23
	v_pk_add_f32 v[2:3], v[20:21], v[2:3] op_sel_hi:[0,1]
	v_pk_fma_f32 v[2:3], v[4:5], v[4:5], v[2:3]
	v_add_f32_e32 v4, v7, v21
	v_pk_fma_f32 v[20:21], v[188:189], s[0:1], v[8:9] op_sel_hi:[1,0,1]
	v_mul_f32_e32 v8, v7, v7
	v_add_f32_e32 v9, v20, v4
	v_mov_b32_e32 v4, v20
	v_mov_b32_e32 v5, v7
	v_pk_add_f32 v[2:3], v[8:9], v[2:3] op_sel_hi:[0,1]
	v_pk_fma_f32 v[4:5], v[4:5], v[4:5], v[2:3]
	v_add_f32_e32 v8, v21, v9
	v_pk_fma_f32 v[2:3], v[76:77], s[0:1], v[10:11] op_sel_hi:[1,0,1]
	v_mul_f32_e32 v10, v21, v21
	v_add_f32_e32 v11, v2, v8
	v_mov_b32_e32 v8, v2
	v_mov_b32_e32 v9, v21
	v_pk_add_f32 v[4:5], v[10:11], v[4:5] op_sel_hi:[0,1]
	v_pk_fma_f32 v[4:5], v[8:9], v[8:9], v[4:5]
	v_add_f32_e32 v10, v3, v11
	v_pk_fma_f32 v[8:9], v[78:79], s[0:1], v[12:13] op_sel_hi:[1,0,1]
	v_mul_f32_e32 v12, v3, v3
	v_add_f32_e32 v13, v8, v10
	v_mov_b32_e32 v10, v8
	v_mov_b32_e32 v11, v3
	v_pk_add_f32 v[4:5], v[12:13], v[4:5] op_sel_hi:[0,1]
	v_pk_fma_f32 v[10:11], v[10:11], v[10:11], v[4:5]
	v_add_f32_e32 v12, v9, v13
	v_pk_fma_f32 v[4:5], v[50:51], s[0:1], v[14:15] op_sel_hi:[1,0,1]
	v_mul_f32_e32 v14, v9, v9
	v_add_f32_e32 v15, v4, v12
	v_mov_b32_e32 v12, v4
	v_mov_b32_e32 v13, v9
	v_pk_add_f32 v[10:11], v[14:15], v[10:11] op_sel_hi:[0,1]
	v_pk_fma_f32 v[12:13], v[12:13], v[12:13], v[10:11]
	v_pk_fma_f32 v[10:11], v[52:53], s[0:1], v[16:17] op_sel_hi:[1,0,1]
	v_mul_f32_e32 v30, v5, v5
	v_mov_b32_e32 v16, v10
	v_mov_b32_e32 v17, v5
	v_pk_add_f32 v[12:13], v[30:31], v[12:13] op_sel_hi:[0,1]
	v_pk_fma_f32 v[12:13], v[16:17], v[16:17], v[12:13]
	v_pk_mul_f32 v[16:17], v[10:11], v[10:11]
	v_add_f32_e32 v14, v5, v15
	v_mov_b32_e32 v15, v17
	v_and_b32_e32 v17, 64, v201
	v_xor_b32_e32 v16, 32, v201
	v_add_u32_e32 v17, 64, v17
	v_add_f32_e32 v14, v10, v14
	v_pk_mov_b32 v[12:13], v[10:11], v[12:13] op_sel:[1,0]
	v_cmp_lt_i32_e32 vcc, v16, v17
	v_pk_add_f32 v[12:13], v[12:13], v[14:15]
	v_pk_mov_b32 v[14:15], v[110:111], v[74:75] op_sel:[1,0]
	v_cndmask_b32_e32 v16, v201, v16, vcc
	v_pk_add_f32 v[14:15], v[14:15], v[114:115]
	v_lshlrev_b32_e32 v31, 2, v16
	ds_bpermute_b32 v16, v31, v14
	ds_bpermute_b32 v17, v31, v15
	ds_bpermute_b32 v30, v31, v12
	ds_bpermute_b32 v31, v31, v13
	v_cmp_eq_u32_e32 vcc, 0, v224
	s_and_saveexec_b64 s[18:19], vcc
	s_cbranch_execz .LBB0_704
	v_lshlrev_b32_e32 v32, 3, v184
	v_and_b32_e32 v32, 0xfffffef8, v32
	v_add_u32_e32 v32, 0, v32
	v_add_u32_e32 v32, 0x12000, v32
	s_waitcnt lgkmcnt(2)
	v_pk_add_f32 v[14:15], v[14:15], v[16:17]
	s_waitcnt lgkmcnt(0)
	v_pk_add_f32 v[12:13], v[12:13], v[30:31]
	ds_write2_b64 v32, v[14:15], v[12:13] offset1:32

; #define G_GLOAD(XR, WR, KT) { _Pragma("unroll") for (int i_ = 0; i_ < 4; ++i_) XR[i_] = *(const u32x4*)(Xt + ((size_t)(64 * i_) * ldx + (KT) * 64) * 2 + xoff); \
;     _Pragma("unroll") for (int i_ = 0; i_ < 4; ++i_) WR[i_] = *(const u32x4*)(Wtb + ((size_t)(64 * i_) * K + (KT) * 64) * 2 + woff); }
; #define G_LSTORE(XR, WR, STG) { char* xs_ = lds + (STG) * G_STAGE; char* ws_ = xs_ + G_XB; \
;     _Pragma("unroll") for (int i_ = 0; i_ < 4; ++i_) *(u32x4*)(xs_ + (lrow + 64 * i_) * LROW + lch * 16) = XR[i_]; \
;     _Pragma("unroll") for (int i_ = 0; i_ < 4; ++i_) *(u32x4*)(ws_ + (lrow + 64 * i_) * LROW + lch * 16) = WR[i_]; }
; template <class Epi>
; DI void gemm_phase(const bf16_t* __restrict__ X, const int ldx, const bf16_t* __restrict__ Wt, const int N, const int K, const Epi& epi, char* lds) {
;     ...
;     const int L = chunk * 32 + slot, band = L / (4 * nNt), rem = L % (4 * nNt);
;     const int mt_ = band * 4 + (rem & 3), nt_ = rem >> 2;
;     const char* Xt = (const char*)(X + (size_t)(mt_ * 256) * ldx);
;     const char* Wtb = (const char*)(Wt + (size_t)(nt_ * 256) * K);
;     const unsigned xoff = (unsigned)(lrow * ldx + lch * 8) * 2u, woff = (unsigned)(lrow * K + lch * 8) * 2u;
;     const bool has_next = !Epi::kFull && (chunk + 8 < nchunks);
;     const int Ln = (has_next ? chunk + 8 : chunk) * 32 + slot, band_n = Ln / (4 * nNt), rem_n = Ln % (4 * nNt);
;     const char* Xt_n = (const char*)(X + (size_t)((band_n * 4 + (rem_n & 3)) * 256) * ldx);
;     const char* Wtb_n = (const char*)(Wt + (size_t)((rem_n >> 2) * 256) * K);
;     f32x16 acc[2][2][2];
;     ...
;     asm volatile("" ::: "memory");
;     if (Epi::kFull || chunk == xcd) {
;       G_GLOAD(xr0, wr0, 0);
;       G_LSTORE(xr0, wr0, 0);
;       __syncthreads();
;       G_GLOAD(xr0, wr0, 1);
;     }
; #pragma unroll
;     for (int c = 0; c < 2; ++c)
; #pragma unroll
;       for (int a = 0; a < 2; ++a)
; #pragma unroll
;         for (int b = 0; b < 2; ++b)
; #pragma unroll
;           for (int i = 0; i < 16; ++i) acc[c][a][b][i] = 0.f;
.LBB0_738:
	s_add_i32 s9, s16, 8
	s_cmpk_gt_u32 s16, 0x4f
	s_cselect_b64 s[4:5], -1, 0
	s_cmpk_lt_u32 s16, 0x50
	s_cselect_b32 s16, s9, s16
	s_cselect_b32 s21, 0, 15
	s_cselect_b32 s22, 1, 15
	s_lshl_b32 s16, s16, 5
	v_readlane_b32 s17, v254, 3
	s_add_i32 s16, s16, s17
	s_mul_hi_u32 s17, s16, 0xba2e8ba3
	s_lshr_b32 s17, s17, 6
	s_mul_i32 s23, s17, 0x58
	s_sub_i32 s26, s16, s23
	s_lshl_b32 s16, s17, 10
	s_lshl_b32 s17, s26, 8
	s_and_b32 s17, s17, 0x300
	s_or_b32 s16, s17, s16
	s_ashr_i32 s17, s16, 31
	s_lshl_b64 s[16:17], s[16:17], 11
	s_add_u32 s23, s2, s16
	s_addc_u32 s25, s18, s17
	s_lshl_b32 s16, s26, 17
	s_and_b32 s16, s16, 0xf80000
	s_add_u32 s26, s19, s16
	v_mov_b32_e32 v2, 0
	s_addc_u32 s27, s20, 0
	s_mov_b32 s28, 3
	v_mov_b32_e32 v3, v2
	s_waitcnt vmcnt(5)
	s_waitcnt vmcnt(4)
	s_waitcnt vmcnt(3)
	s_waitcnt vmcnt(2)
	s_waitcnt vmcnt(1)
	s_waitcnt vmcnt(0)
	v_add_u32_e32 v232, s91, v162
	v_add_u32_e32 v233, s1, v162
	v_add_u32_e32 v234, s76, v162
	v_add_u32_e32 v235, v171, v172
	v_add_u32_e32 v236, v171, v173
	v_add_u32_e32 v237, v174, v170
	ds_read_b128 v[164:167], v235
	ds_read_b128 v[188:191], v235 offset:4608
	ds_read_b128 v[194:197], v236 offset:36864
	ds_read_b128 v[202:205], v236 offset:41472
	ds_read_b128 v[206:209], v236 offset:46080
	ds_read_b128 v[210:213], v236 offset:50688
	ds_read_b128 v[214:217], v176 offset:32
	ds_read_b128 v[218:221], v176 offset:4640
	s_add_i32 s29, s28, -3
	s_cmp_lt_u32 s29, 14
	s_cselect_b64 s[30:31], -1, 0
	s_and_b64 s[16:17], s[30:31], exec
	s_cselect_b32 s17, s15, s27
	s_cselect_b32 s16, s14, s26
	s_cselect_b32 s35, s13, s25
	s_cselect_b32 s34, s12, s23
	s_add_i32 s33, s28, -1
	s_waitcnt lgkmcnt(5)
	v_mfma_f32_32x32x16_bf16 v[114:129], v[194:197], v[164:167], 0
	v_mfma_f32_32x32x16_bf16 v[82:97], v[194:197], v[188:191], 0
	s_waitcnt lgkmcnt(4)
	v_mfma_f32_32x32x16_bf16 v[98:113], v[202:205], v[164:167], 0
	v_mfma_f32_32x32x16_bf16 v[66:81], v[202:205], v[188:191], 0
	s_waitcnt lgkmcnt(3)
	v_mfma_f32_32x32x16_bf16 v[50:65], v[206:209], v[164:167], 0
	s_and_b64 s[30:31], s[30:31], exec
	s_cselect_b32 s30, s33, s21
	v_mfma_f32_32x32x16_bf16 v[18:33], v[206:209], v[188:191], 0
	s_waitcnt lgkmcnt(2)
	v_mfma_f32_32x32x16_bf16 v[34:49], v[210:213], v[164:167], 0
	ds_read_b128 v[164:167], v177 offset:36896
	ds_read_b128 v[194:197], v177 offset:41504
	v_mfma_f32_32x32x16_bf16 v[2:17], v[210:213], v[188:191], 0
	s_lshl_b32 s96, s30, 7
	s_add_u32 s100, s34, s96
	s_addc_u32 s101, s35, 0
	s_waitcnt vmcnt(6)
	ds_write_b128 v178, v[142:145] offset:9216
	ds_write_b128 v178, v[134:137]
	global_load_dwordx4 v[134:137], v162, s[100:101]
	global_load_dwordx4 v[142:145], v232, s[100:101]
	s_waitcnt vmcnt(7)
	ds_write_b128 v178, v[130:133] offset:18432
	s_waitcnt vmcnt(6)
	ds_write_b128 v178, v[150:153] offset:27648
	global_load_dwordx4 v[130:133], v233, s[100:101]
	global_load_dwordx4 v[150:153], v234, s[100:101]
	ds_read_b128 v[188:191], v177 offset:46112
	ds_read_b128 v[202:205], v177 offset:50720
	ds_read_b128 v[206:209], v176 offset:64
	ds_read_b128 v[210:213], v176 offset:4672
	s_waitcnt lgkmcnt(9)
	v_mfma_f32_32x32x16_bf16 v[114:129], v[164:167], v[214:217], v[114:129]
	v_mfma_f32_32x32x16_bf16 v[82:97], v[164:167], v[218:221], v[82:97]
	s_waitcnt lgkmcnt(8)
	v_mfma_f32_32x32x16_bf16 v[98:113], v[194:197], v[214:217], v[98:113]
	v_mfma_f32_32x32x16_bf16 v[66:81], v[194:197], v[218:221], v[66:81]
	s_waitcnt lgkmcnt(3)
	v_mfma_f32_32x32x16_bf16 v[50:65], v[188:191], v[214:217], v[50:65]
	v_mfma_f32_32x32x16_bf16 v[18:33], v[188:191], v[218:221], v[18:33]
	ds_read_b128 v[164:167], v177 offset:36928
	ds_read_b128 v[188:191], v177 offset:41536
	s_waitcnt lgkmcnt(4)
	v_mfma_f32_32x32x16_bf16 v[34:49], v[202:205], v[214:217], v[34:49]
	v_mfma_f32_32x32x16_bf16 v[2:17], v[202:205], v[218:221], v[2:17]
	s_add_u32 s100, s16, s96
	s_addc_u32 s101, s17, 0
	s_waitcnt vmcnt(6)
	ds_write_b128 v179, v[154:157] offset:9216
	ds_write_b128 v179, v[138:141]
	global_load_dwordx4 v[138:141], v162, s[100:101]
	global_load_dwordx4 v[154:157], v232, s[100:101]
	ds_read_b128 v[194:197], v177 offset:46144
	ds_read_b128 v[202:205], v177 offset:50752
	ds_read_b128 v[214:217], v176 offset:96
	ds_read_b128 v[218:221], v176 offset:4704
	s_waitcnt lgkmcnt(7)
	v_mfma_f32_32x32x16_bf16 v[114:129], v[164:167], v[206:209], v[114:129]
	v_mfma_f32_32x32x16_bf16 v[82:97], v[164:167], v[210:213], v[82:97]
	s_waitcnt lgkmcnt(6)
	v_mfma_f32_32x32x16_bf16 v[98:113], v[188:191], v[206:209], v[98:113]
	v_mfma_f32_32x32x16_bf16 v[66:81], v[188:191], v[210:213], v[66:81]
	s_waitcnt lgkmcnt(3)
	v_mfma_f32_32x32x16_bf16 v[50:65], v[194:197], v[206:209], v[50:65]
	ds_read_b128 v[164:167], v177 offset:36960
	ds_read_b128 v[188:191], v177 offset:41568
	v_mfma_f32_32x32x16_bf16 v[18:33], v[194:197], v[210:213], v[18:33]
	s_waitcnt lgkmcnt(4)
	v_mfma_f32_32x32x16_bf16 v[34:49], v[202:205], v[206:209], v[34:49]
	v_mfma_f32_32x32x16_bf16 v[2:17], v[202:205], v[210:213], v[2:17]
	s_waitcnt vmcnt(7)
	ds_write_b128 v179, v[146:149] offset:18432
	s_waitcnt vmcnt(6)
	ds_write_b128 v179, v[158:161] offset:27648
	global_load_dwordx4 v[146:149], v233, s[100:101]
	global_load_dwordx4 v[158:161], v234, s[100:101]
	ds_read_b128 v[194:197], v177 offset:46176
	ds_read_b128 v[202:205], v177 offset:50784
	s_waitcnt lgkmcnt(5)
	v_mfma_f32_32x32x16_bf16 v[114:129], v[164:167], v[214:217], v[114:129]
	v_mfma_f32_32x32x16_bf16 v[82:97], v[164:167], v[218:221], v[82:97]
	s_waitcnt lgkmcnt(4)
	v_mfma_f32_32x32x16_bf16 v[98:113], v[188:191], v[214:217], v[98:113]
	v_mfma_f32_32x32x16_bf16 v[66:81], v[188:191], v[218:221], v[66:81]
	s_waitcnt lgkmcnt(1)
	v_mfma_f32_32x32x16_bf16 v[50:65], v[194:197], v[214:217], v[50:65]
	v_mfma_f32_32x32x16_bf16 v[18:33], v[194:197], v[218:221], v[18:33]
	s_waitcnt lgkmcnt(0)
	v_mfma_f32_32x32x16_bf16 v[34:49], v[202:205], v[214:217], v[34:49]
	v_mfma_f32_32x32x16_bf16 v[2:17], v[202:205], v[218:221], v[2:17]
	s_barrier
; #define G_GLOAD(XR, WR, KT) { _Pragma("unroll") for (int i_ = 0; i_ < 4; ++i_) XR[i_] = *(const u32x4*)(Xt + ((size_t)(64 * i_) * ldx + (KT) * 64) * 2 + xoff); \
;     _Pragma("unroll") for (int i_ = 0; i_ < 4; ++i_) WR[i_] = *(const u32x4*)(Wtb + ((size_t)(64 * i_) * K + (KT) * 64) * 2 + woff); }
; #define G_LSTORE(XR, WR, STG) { char* xs_ = lds + (STG) * G_STAGE; char* ws_ = xs_ + G_XB; \
;     _Pragma("unroll") for (int i_ = 0; i_ < 4; ++i_) *(u32x4*)(xs_ + (lrow + 64 * i_) * LROW + lch * 16) = XR[i_]; \
;     _Pragma("unroll") for (int i_ = 0; i_ < 4; ++i_) *(u32x4*)(ws_ + (lrow + 64 * i_) * LROW + lch * 16) = WR[i_]; }
; template <class Epi>
; DI void gemm_phase(const bf16_t* __restrict__ X, const int ldx, const bf16_t* __restrict__ Wt, const int N, const int K, const Epi& epi, char* lds) {
;     ...
;     asm volatile("" ::: "memory");
;     if (Epi::kFull || chunk == xcd) {
;       G_GLOAD(xr0, wr0, 0);
;       G_LSTORE(xr0, wr0, 0);
;       __syncthreads();
;       G_GLOAD(xr0, wr0, 1);
;     }
; #pragma unroll
;     for (int c = 0; c < 2; ++c)
; #pragma unroll
;       for (int a = 0; a < 2; ++a)
; #pragma unroll
;         for (int b = 0; b < 2; ++b)
; #pragma unroll
;           for (int i = 0; i < 16; ++i) acc[c][a][b][i] = 0.f;
	ds_read_b128 v[164:167], v180
	ds_read_b128 v[188:191], v180 offset:4608
	ds_read_b128 v[194:197], v181
	ds_read_b128 v[202:205], v181 offset:4608
	ds_read_b128 v[206:209], v181 offset:9216
	ds_read_b128 v[210:213], v181 offset:13824
	ds_read_b128 v[214:217], v237 offset:32
	ds_read_b128 v[218:221], v182 offset:32
	s_cmp_lt_u32 s29, 13
	s_cselect_b64 s[16:17], -1, 0
	s_and_b64 s[16:17], s[16:17], exec
	s_cselect_b32 s31, s13, s25
	s_cselect_b32 s30, s12, s23
	s_cselect_b32 s17, s15, s27
	s_cselect_b32 s16, s14, s26
	s_waitcnt lgkmcnt(5)
	v_mfma_f32_32x32x16_bf16 v[114:129], v[194:197], v[164:167], v[114:129]
	v_mfma_f32_32x32x16_bf16 v[82:97], v[194:197], v[188:191], v[82:97]
	s_waitcnt lgkmcnt(4)
	v_mfma_f32_32x32x16_bf16 v[98:113], v[202:205], v[164:167], v[98:113]
	v_mfma_f32_32x32x16_bf16 v[66:81], v[202:205], v[188:191], v[66:81]
	s_waitcnt lgkmcnt(3)
	v_mfma_f32_32x32x16_bf16 v[50:65], v[206:209], v[164:167], v[50:65]
	v_add_u32_e32 v187, v175, v170
	s_cselect_b32 s33, s28, s22
	v_mfma_f32_32x32x16_bf16 v[18:33], v[206:209], v[188:191], v[18:33]
	s_waitcnt lgkmcnt(2)
	v_mfma_f32_32x32x16_bf16 v[34:49], v[210:213], v[164:167], v[34:49]
	ds_read_b128 v[164:167], v187 offset:32
	ds_read_b128 v[194:197], v183 offset:32
	v_mfma_f32_32x32x16_bf16 v[2:17], v[210:213], v[188:191], v[2:17]
	s_lshl_b32 s96, s33, 7
	s_add_u32 s100, s30, s96
	s_addc_u32 s101, s31, 0
	s_waitcnt vmcnt(6)
	ds_write_b128 v186, v[142:145] offset:9216
	ds_write_b128 v186, v[134:137]
	global_load_dwordx4 v[134:137], v162, s[100:101]
	global_load_dwordx4 v[142:145], v232, s[100:101]
	s_waitcnt vmcnt(7)
	ds_write_b128 v186, v[130:133] offset:18432
	s_waitcnt vmcnt(6)
	ds_write_b128 v186, v[150:153] offset:27648
	global_load_dwordx4 v[130:133], v233, s[100:101]
	global_load_dwordx4 v[150:153], v234, s[100:101]
	ds_read_b128 v[188:191], v184 offset:32
	ds_read_b128 v[202:205], v185 offset:32
	ds_read_b128 v[206:209], v237 offset:64
	ds_read_b128 v[210:213], v182 offset:64
	s_waitcnt lgkmcnt(9)
	v_mfma_f32_32x32x16_bf16 v[114:129], v[164:167], v[214:217], v[114:129]
	v_mfma_f32_32x32x16_bf16 v[82:97], v[164:167], v[218:221], v[82:97]
	s_waitcnt lgkmcnt(8)
	v_mfma_f32_32x32x16_bf16 v[98:113], v[194:197], v[214:217], v[98:113]
	v_mfma_f32_32x32x16_bf16 v[66:81], v[194:197], v[218:221], v[66:81]
	s_waitcnt lgkmcnt(3)
	v_mfma_f32_32x32x16_bf16 v[50:65], v[188:191], v[214:217], v[50:65]
	v_mfma_f32_32x32x16_bf16 v[18:33], v[188:191], v[218:221], v[18:33]
	ds_read_b128 v[164:167], v187 offset:64
	ds_read_b128 v[188:191], v183 offset:64
	s_waitcnt lgkmcnt(4)
	v_mfma_f32_32x32x16_bf16 v[34:49], v[202:205], v[214:217], v[34:49]
	v_mfma_f32_32x32x16_bf16 v[2:17], v[202:205], v[218:221], v[2:17]
	s_add_u32 s100, s16, s96
	s_addc_u32 s101, s17, 0
	s_waitcnt vmcnt(6)
	ds_write_b128 v186, v[154:157] offset:46080
	ds_write_b128 v186, v[138:141] offset:36864
	global_load_dwordx4 v[138:141], v162, s[100:101]
	global_load_dwordx4 v[154:157], v232, s[100:101]
	ds_read_b128 v[194:197], v184 offset:64
	ds_read_b128 v[202:205], v185 offset:64
	ds_read_b128 v[214:217], v237 offset:96
	ds_read_b128 v[218:221], v182 offset:96
	s_waitcnt lgkmcnt(7)
	v_mfma_f32_32x32x16_bf16 v[114:129], v[164:167], v[206:209], v[114:129]
	v_mfma_f32_32x32x16_bf16 v[82:97], v[164:167], v[210:213], v[82:97]
	s_waitcnt lgkmcnt(6)
	v_mfma_f32_32x32x16_bf16 v[98:113], v[188:191], v[206:209], v[98:113]
	v_mfma_f32_32x32x16_bf16 v[66:81], v[188:191], v[210:213], v[66:81]
	s_waitcnt lgkmcnt(3)
	v_mfma_f32_32x32x16_bf16 v[50:65], v[194:197], v[206:209], v[50:65]
	ds_read_b128 v[164:167], v187 offset:96
	ds_read_b128 v[188:191], v183 offset:96
	v_mfma_f32_32x32x16_bf16 v[18:33], v[194:197], v[210:213], v[18:33]
	s_waitcnt lgkmcnt(4)
	v_mfma_f32_32x32x16_bf16 v[34:49], v[202:205], v[206:209], v[34:49]
	v_mfma_f32_32x32x16_bf16 v[2:17], v[202:205], v[210:213], v[2:17]
	s_waitcnt vmcnt(7)
	ds_write_b128 v186, v[146:149] offset:55296
	s_waitcnt vmcnt(6)
	ds_write_b128 v186, v[158:161] offset:64512
	global_load_dwordx4 v[146:149], v233, s[100:101]
	global_load_dwordx4 v[158:161], v234, s[100:101]
	ds_read_b128 v[194:197], v184 offset:96
	ds_read_b128 v[202:205], v185 offset:96
	s_waitcnt lgkmcnt(5)
	v_mfma_f32_32x32x16_bf16 v[114:129], v[164:167], v[214:217], v[114:129]
	v_mfma_f32_32x32x16_bf16 v[82:97], v[164:167], v[218:221], v[82:97]
	s_waitcnt lgkmcnt(4)
	v_mfma_f32_32x32x16_bf16 v[98:113], v[188:191], v[214:217], v[98:113]
	v_mfma_f32_32x32x16_bf16 v[66:81], v[188:191], v[218:221], v[66:81]
	s_waitcnt lgkmcnt(1)
	v_mfma_f32_32x32x16_bf16 v[50:65], v[194:197], v[214:217], v[50:65]
	v_mfma_f32_32x32x16_bf16 v[18:33], v[194:197], v[218:221], v[18:33]
	s_waitcnt lgkmcnt(0)
	v_mfma_f32_32x32x16_bf16 v[34:49], v[202:205], v[214:217], v[34:49]
	v_mfma_f32_32x32x16_bf16 v[2:17], v[202:205], v[218:221], v[2:17]
	s_add_i32 s28, s28, 2
	s_cmp_gt_u32 s29, 13
	s_barrier
	s_cbranch_scc0 .LBB0_739
	s_branch .Lkexit_4

; DI unsigned pk2(float lo, float hi) { f32x2 v = {lo, hi}; bf16x2v b = __builtin_convertvector(v, bf16x2v); return __builtin_bit_cast(unsigned, b); }
; DI float siluf_(float x) { return x * __builtin_amdgcn_rcpf(1.f + __builtin_amdgcn_exp2f(-LOG2E * x)); }
;   DI void operator()(int tok0, int feat0, f32x16 (&acc)[2][2], int r, int hh) const {
;     const int u0 = (feat0 >> 6) * 32;
; #pragma unroll
;     for (int mt = 0; mt < 2; ++mt) {
;       bf16_t* dst = act + (size_t)(tok0 + mt * 32 + r) * DFF + u0 + 16 * hh;
; #pragma unroll
;       for (int gp = 0; gp < 2; ++gp) {
;         u32x4 o;
; #pragma unroll
;         for (int q = 0; q < 4; ++q) { const int i = 8 * gp + 2 * q; o[q] = pk2(siluf_(acc[0][mt][i]) * acc[1][mt][i], siluf_(acc[0][mt][i + 1]) * acc[1][mt][i + 1]); }
;         *(u32x4*)(dst + 8 * gp) = o;
;       }
;     }
;   }
.Lkexit_4:
	v_mov_b32_e32 v0, v192
	v_mov_b64_e32 v[166:167], s[6:7]
	v_ashrrev_i32_e32 v164, 1, v0
	v_and_b32_e32 v164, 0xffffff80, v164
	v_add_u32_e32 v164, s3, v164
	v_ashrrev_i32_e32 v164, 1, v164
	v_and_b32_e32 v165, 0xdf, v0
	v_or_b32_e32 v187, s8, v165
	v_ashrrev_i32_e32 v165, 31, v164
	v_mad_i64_i32 v[188:189], s[12:13], v187, s69, v[166:167]
	v_lshlrev_b64 v[168:169], 1, v[164:165]
	v_lshl_add_u64 v[164:165], v[188:189], 0, v[168:169]
	v_mul_f32_e32 v188, 0xbfb8aa3b, v114
	v_mul_f32_e32 v189, 0xbfb8aa3b, v115
	v_exp_f32_e32 v188, v188
	v_exp_f32_e32 v189, v189
	v_and_b32_e32 v0, 32, v0
	v_lshl_add_u64 v[164:165], v[164:165], 0, v[0:1]
	v_add_f32_e32 v188, 1.0, v188
	v_add_f32_e32 v189, 1.0, v189
	v_rcp_f32_e32 v188, v188
	v_rcp_f32_e32 v189, v189
	s_nop 0
	v_pk_mul_f32 v[114:115], v[114:115], v[188:189]
	s_nop 0
	v_pk_mul_f32 v[98:99], v[98:99], v[114:115]
	s_nop 0
	v_cvt_pk_bf16_f32 v98, v98, v99
	v_mul_f32_e32 v99, 0xbfb8aa3b, v116
	v_exp_f32_e32 v99, v99
	s_nop 0
	v_add_f32_e32 v99, 1.0, v99
	v_rcp_f32_e32 v114, v99
	v_mul_f32_e32 v99, 0xbfb8aa3b, v117
	v_exp_f32_e32 v99, v99
	s_nop 0
	v_add_f32_e32 v99, 1.0, v99
	v_rcp_f32_e32 v115, v99
	s_nop 0
	v_pk_mul_f32 v[114:115], v[116:117], v[114:115]
	s_nop 0
	v_pk_mul_f32 v[100:101], v[100:101], v[114:115]
	s_nop 0
	v_cvt_pk_bf16_f32 v99, v100, v101
	v_mul_f32_e32 v100, 0xbfb8aa3b, v118
	v_mul_f32_e32 v101, 0xbfb8aa3b, v119
	v_exp_f32_e32 v100, v100
	v_exp_f32_e32 v101, v101
	v_add_f32_e32 v100, 1.0, v100
	v_add_f32_e32 v101, 1.0, v101
	v_rcp_f32_e32 v100, v100
	v_rcp_f32_e32 v101, v101
	s_nop 0
	v_pk_mul_f32 v[100:101], v[118:119], v[100:101]
	s_nop 0
	v_pk_mul_f32 v[100:101], v[102:103], v[100:101]
	s_nop 0
	v_cvt_pk_bf16_f32 v100, v100, v101
	v_mul_f32_e32 v101, 0xbfb8aa3b, v120
	v_exp_f32_e32 v101, v101
	s_nop 0
	v_add_f32_e32 v101, 1.0, v101
	v_rcp_f32_e32 v102, v101
	v_mul_f32_e32 v101, 0xbfb8aa3b, v121
	v_exp_f32_e32 v101, v101
	s_nop 0
	v_add_f32_e32 v101, 1.0, v101
	v_rcp_f32_e32 v103, v101
	s_nop 0
	v_pk_mul_f32 v[102:103], v[120:121], v[102:103]
	s_nop 0
	v_pk_mul_f32 v[102:103], v[104:105], v[102:103]
	s_nop 0
	v_cvt_pk_bf16_f32 v101, v102, v103
	global_store_dwordx4 v[164:165], v[98:101], off
	s_nop 1
	v_mul_f32_e32 v98, 0xbfb8aa3b, v122
	v_mul_f32_e32 v99, 0xbfb8aa3b, v123
	v_exp_f32_e32 v98, v98
	v_exp_f32_e32 v99, v99
	v_add_f32_e32 v98, 1.0, v98
	v_add_f32_e32 v99, 1.0, v99
	v_rcp_f32_e32 v98, v98
	v_rcp_f32_e32 v99, v99
	s_nop 0
	v_pk_mul_f32 v[98:99], v[122:123], v[98:99]
	s_nop 0
	v_pk_mul_f32 v[98:99], v[106:107], v[98:99]
	s_nop 0
	v_cvt_pk_bf16_f32 v98, v98, v99
	v_mul_f32_e32 v99, 0xbfb8aa3b, v124
	v_exp_f32_e32 v99, v99
	s_nop 0
	v_add_f32_e32 v99, 1.0, v99
	v_rcp_f32_e32 v100, v99
	v_mul_f32_e32 v99, 0xbfb8aa3b, v125
	v_exp_f32_e32 v99, v99
	s_nop 0
	v_add_f32_e32 v99, 1.0, v99
	v_rcp_f32_e32 v101, v99
	s_nop 0
	v_pk_mul_f32 v[100:101], v[124:125], v[100:101]
	s_nop 0
	v_pk_mul_f32 v[100:101], v[108:109], v[100:101]
	s_nop 0
	v_cvt_pk_bf16_f32 v99, v100, v101
	v_mul_f32_e32 v100, 0xbfb8aa3b, v126
	v_mul_f32_e32 v101, 0xbfb8aa3b, v127
	v_exp_f32_e32 v100, v100
	v_exp_f32_e32 v101, v101
	v_add_f32_e32 v100, 1.0, v100
	v_add_f32_e32 v101, 1.0, v101
	v_rcp_f32_e32 v100, v100
	v_rcp_f32_e32 v101, v101
	s_nop 0
	v_pk_mul_f32 v[100:101], v[126:127], v[100:101]
	s_nop 0
	v_pk_mul_f32 v[100:101], v[110:111], v[100:101]
	s_nop 0
	v_cvt_pk_bf16_f32 v100, v100, v101
	v_mul_f32_e32 v101, 0xbfb8aa3b, v128
	v_exp_f32_e32 v101, v101
	s_nop 0
	v_add_f32_e32 v101, 1.0, v101
	v_rcp_f32_e32 v102, v101
	v_mul_f32_e32 v101, 0xbfb8aa3b, v129
	v_exp_f32_e32 v101, v101
	s_nop 0
	v_add_f32_e32 v101, 1.0, v101
	v_rcp_f32_e32 v103, v101
	s_nop 0
	v_pk_mul_f32 v[102:103], v[128:129], v[102:103]
	s_nop 0
	v_pk_mul_f32 v[102:103], v[112:113], v[102:103]
	s_nop 0
	v_cvt_pk_bf16_f32 v101, v102, v103
	global_store_dwordx4 v[164:165], v[98:101], off offset:16
	s_nop 1
	v_or_b32_e32 v98, 32, v187
	v_mad_i64_i32 v[98:99], s[12:13], v98, s69, v[166:167]
	v_lshl_add_u64 v[98:99], v[98:99], 0, v[168:169]
	v_lshl_add_u64 v[98:99], v[98:99], 0, v[0:1]
	v_mul_f32_e32 v0, 0xbfb8aa3b, v82
	v_exp_f32_e32 v0, v0
	s_nop 0
	v_add_f32_e32 v0, 1.0, v0
	v_rcp_f32_e32 v100, v0
	v_mul_f32_e32 v0, 0xbfb8aa3b, v83
	v_exp_f32_e32 v0, v0
	s_nop 0
	v_add_f32_e32 v0, 1.0, v0
	v_rcp_f32_e32 v101, v0
	v_mul_f32_e32 v0, 0xbfb8aa3b, v84
	v_exp_f32_e32 v0, v0
	v_pk_mul_f32 v[82:83], v[82:83], v[100:101]
	s_nop 0
	v_pk_mul_f32 v[66:67], v[66:67], v[82:83]
	v_add_f32_e32 v0, 1.0, v0
	v_rcp_f32_e32 v82, v0
	v_mul_f32_e32 v0, 0xbfb8aa3b, v85
	v_exp_f32_e32 v0, v0
	v_cvt_pk_bf16_f32 v66, v66, v67
	v_add_f32_e32 v0, 1.0, v0
	v_rcp_f32_e32 v83, v0
	v_mul_f32_e32 v0, 0xbfb8aa3b, v86
	v_exp_f32_e32 v0, v0
	v_pk_mul_f32 v[82:83], v[84:85], v[82:83]
	s_nop 0
	v_pk_mul_f32 v[68:69], v[68:69], v[82:83]
	v_add_f32_e32 v0, 1.0, v0
	v_cvt_pk_bf16_f32 v67, v68, v69
	v_rcp_f32_e32 v68, v0
	v_mul_f32_e32 v0, 0xbfb8aa3b, v87
	v_exp_f32_e32 v0, v0
	s_nop 0
	v_add_f32_e32 v0, 1.0, v0
	v_rcp_f32_e32 v69, v0
	v_mul_f32_e32 v0, 0xbfb8aa3b, v88
	v_exp_f32_e32 v0, v0
	v_pk_mul_f32 v[68:69], v[86:87], v[68:69]
	s_nop 0
	v_pk_mul_f32 v[68:69], v[70:71], v[68:69]
	v_add_f32_e32 v0, 1.0, v0
	v_rcp_f32_e32 v70, v0
	v_mul_f32_e32 v0, 0xbfb8aa3b, v89
	v_exp_f32_e32 v0, v0
	v_cvt_pk_bf16_f32 v68, v68, v69
	v_add_f32_e32 v0, 1.0, v0
	v_rcp_f32_e32 v71, v0
	v_mul_f32_e32 v0, 0xbfb8aa3b, v90
	v_exp_f32_e32 v0, v0
	v_pk_mul_f32 v[70:71], v[88:89], v[70:71]
	s_nop 0
	v_pk_mul_f32 v[70:71], v[72:73], v[70:71]
	v_add_f32_e32 v0, 1.0, v0
	v_cvt_pk_bf16_f32 v69, v70, v71
	global_store_dwordx4 v[98:99], v[66:69], off
	s_nop 1
	v_rcp_f32_e32 v66, v0
; DI unsigned pk2(float lo, float hi) { f32x2 v = {lo, hi}; bf16x2v b = __builtin_convertvector(v, bf16x2v); return __builtin_bit_cast(unsigned, b); }
; DI float siluf_(float x) { return x * __builtin_amdgcn_rcpf(1.f + __builtin_amdgcn_exp2f(-LOG2E * x)); }
;   DI void operator()(int tok0, int feat0, f32x16 (&acc)[2][2], int r, int hh) const {
;     const int u0 = (feat0 >> 6) * 32;
; #pragma unroll
;     for (int mt = 0; mt < 2; ++mt) {
;       bf16_t* dst = act + (size_t)(tok0 + mt * 32 + r) * DFF + u0 + 16 * hh;
; #pragma unroll
;       for (int gp = 0; gp < 2; ++gp) {
;         u32x4 o;
; #pragma unroll
;         for (int q = 0; q < 4; ++q) { const int i = 8 * gp + 2 * q; o[q] = pk2(siluf_(acc[0][mt][i]) * acc[1][mt][i], siluf_(acc[0][mt][i + 1]) * acc[1][mt][i + 1]); }
;         *(u32x4*)(dst + 8 * gp) = o;
;       }
;     }
;   }
	v_mul_f32_e32 v0, 0xbfb8aa3b, v91
	v_exp_f32_e32 v0, v0
	s_nop 0
	v_add_f32_e32 v0, 1.0, v0
	v_rcp_f32_e32 v67, v0
	v_mul_f32_e32 v0, 0xbfb8aa3b, v92
	v_exp_f32_e32 v0, v0
	v_pk_mul_f32 v[66:67], v[90:91], v[66:67]
	s_nop 0
	v_pk_mul_f32 v[66:67], v[74:75], v[66:67]
	v_add_f32_e32 v0, 1.0, v0
	v_rcp_f32_e32 v68, v0
	v_mul_f32_e32 v0, 0xbfb8aa3b, v93
	v_exp_f32_e32 v0, v0
	v_cvt_pk_bf16_f32 v66, v66, v67
	v_add_f32_e32 v0, 1.0, v0
	v_rcp_f32_e32 v69, v0
	v_mul_f32_e32 v0, 0xbfb8aa3b, v94
	v_exp_f32_e32 v0, v0
	v_pk_mul_f32 v[68:69], v[92:93], v[68:69]
	s_nop 0
	v_pk_mul_f32 v[68:69], v[76:77], v[68:69]
	v_add_f32_e32 v0, 1.0, v0
	v_cvt_pk_bf16_f32 v67, v68, v69
	v_rcp_f32_e32 v68, v0
	v_mul_f32_e32 v0, 0xbfb8aa3b, v95
	v_exp_f32_e32 v0, v0
	s_nop 0
	v_add_f32_e32 v0, 1.0, v0
	v_rcp_f32_e32 v69, v0
	v_mul_f32_e32 v0, 0xbfb8aa3b, v96
	v_exp_f32_e32 v0, v0
	v_pk_mul_f32 v[68:69], v[94:95], v[68:69]
	s_nop 0
	v_pk_mul_f32 v[68:69], v[78:79], v[68:69]
	v_add_f32_e32 v0, 1.0, v0
	v_rcp_f32_e32 v70, v0
	v_mul_f32_e32 v0, 0xbfb8aa3b, v97
	v_exp_f32_e32 v0, v0
	v_cvt_pk_bf16_f32 v68, v68, v69
	v_add_f32_e32 v0, 1.0, v0
	v_rcp_f32_e32 v71, v0
	s_nop 0
	v_pk_mul_f32 v[70:71], v[96:97], v[70:71]
	s_nop 0
	v_pk_mul_f32 v[70:71], v[80:81], v[70:71]
	s_nop 0
	v_cvt_pk_bf16_f32 v69, v70, v71
	global_store_dwordx4 v[98:99], v[66:69], off offset:16
	v_mul_f32_e32 v0, 0xbfb8aa3b, v50
	v_exp_f32_e32 v0, v0
	s_nop 0
	v_add_f32_e32 v0, 1.0, v0
	v_rcp_f32_e32 v66, v0
	v_mul_f32_e32 v0, 0xbfb8aa3b, v51
	v_exp_f32_e32 v0, v0
	s_nop 0
	v_add_f32_e32 v0, 1.0, v0
	v_rcp_f32_e32 v67, v0
	v_mul_f32_e32 v0, 0xbfb8aa3b, v52
	v_exp_f32_e32 v0, v0
	v_pk_mul_f32 v[50:51], v[50:51], v[66:67]
	s_nop 0
	v_pk_mul_f32 v[34:35], v[34:35], v[50:51]
	v_add_f32_e32 v0, 1.0, v0
	v_rcp_f32_e32 v50, v0
	v_mul_f32_e32 v0, 0xbfb8aa3b, v53
	v_exp_f32_e32 v0, v0
	v_cvt_pk_bf16_f32 v34, v34, v35
	v_add_f32_e32 v0, 1.0, v0
	v_rcp_f32_e32 v51, v0
	v_mul_f32_e32 v0, 0xbfb8aa3b, v54
	v_exp_f32_e32 v0, v0
	v_pk_mul_f32 v[50:51], v[52:53], v[50:51]
	s_nop 0
	v_pk_mul_f32 v[36:37], v[36:37], v[50:51]
	v_add_f32_e32 v0, 1.0, v0
	v_cvt_pk_bf16_f32 v35, v36, v37
	v_rcp_f32_e32 v36, v0
	v_mul_f32_e32 v0, 0xbfb8aa3b, v55
	v_exp_f32_e32 v0, v0
	s_nop 0
	v_add_f32_e32 v0, 1.0, v0
	v_rcp_f32_e32 v37, v0
	v_mul_f32_e32 v0, 0xbfb8aa3b, v56
	v_exp_f32_e32 v0, v0
	v_pk_mul_f32 v[36:37], v[54:55], v[36:37]
	s_nop 0
	v_pk_mul_f32 v[36:37], v[38:39], v[36:37]
	v_add_f32_e32 v0, 1.0, v0
	v_rcp_f32_e32 v38, v0
	v_mul_f32_e32 v0, 0xbfb8aa3b, v57
	v_exp_f32_e32 v0, v0
	v_cvt_pk_bf16_f32 v36, v36, v37
	v_add_f32_e32 v0, 1.0, v0
	v_rcp_f32_e32 v39, v0
	v_mul_f32_e32 v0, 0xbfb8aa3b, v58
	v_exp_f32_e32 v0, v0
	v_pk_mul_f32 v[38:39], v[56:57], v[38:39]
	s_nop 0
	v_pk_mul_f32 v[38:39], v[40:41], v[38:39]
	v_add_f32_e32 v0, 1.0, v0
	v_cvt_pk_bf16_f32 v37, v38, v39
	global_store_dwordx4 v[164:165], v[34:37], off offset:64
	s_nop 1
	v_rcp_f32_e32 v34, v0
	v_mul_f32_e32 v0, 0xbfb8aa3b, v59
	v_exp_f32_e32 v0, v0
	s_nop 0
	v_add_f32_e32 v0, 1.0, v0
	v_rcp_f32_e32 v35, v0
	v_mul_f32_e32 v0, 0xbfb8aa3b, v60
	v_exp_f32_e32 v0, v0
	v_pk_mul_f32 v[34:35], v[58:59], v[34:35]
	s_nop 0
	v_pk_mul_f32 v[34:35], v[42:43], v[34:35]
	v_add_f32_e32 v0, 1.0, v0
	v_rcp_f32_e32 v36, v0
	v_mul_f32_e32 v0, 0xbfb8aa3b, v61
	v_exp_f32_e32 v0, v0
	v_cvt_pk_bf16_f32 v34, v34, v35
	v_add_f32_e32 v0, 1.0, v0
	v_rcp_f32_e32 v37, v0
	v_mul_f32_e32 v0, 0xbfb8aa3b, v62
	v_exp_f32_e32 v0, v0
	v_pk_mul_f32 v[36:37], v[60:61], v[36:37]
	s_nop 0
	v_pk_mul_f32 v[36:37], v[44:45], v[36:37]
	v_add_f32_e32 v0, 1.0, v0
	v_cvt_pk_bf16_f32 v35, v36, v37
	v_rcp_f32_e32 v36, v0
	v_mul_f32_e32 v0, 0xbfb8aa3b, v63
	v_exp_f32_e32 v0, v0
	s_nop 0
	v_add_f32_e32 v0, 1.0, v0
	v_rcp_f32_e32 v37, v0
	v_mul_f32_e32 v0, 0xbfb8aa3b, v64
	v_exp_f32_e32 v0, v0
	v_pk_mul_f32 v[36:37], v[62:63], v[36:37]
	s_nop 0
	v_pk_mul_f32 v[36:37], v[46:47], v[36:37]
	v_add_f32_e32 v0, 1.0, v0
	v_rcp_f32_e32 v38, v0
	v_mul_f32_e32 v0, 0xbfb8aa3b, v65
; #define GAS __attribute__((address_space(1)))
; DI unsigned pk2(float lo, float hi) { f32x2 v = {lo, hi}; bf16x2v b = __builtin_convertvector(v, bf16x2v); return __builtin_bit_cast(unsigned, b); }
; DI float siluf_(float x) { return x * __builtin_amdgcn_rcpf(1.f + __builtin_amdgcn_exp2f(-LOG2E * x)); }
;   DI void operator()(int tok0, int feat0, f32x16 (&acc)[2][2], int r, int hh) const {
;     const int u0 = (feat0 >> 6) * 32;
; #pragma unroll
;     for (int mt = 0; mt < 2; ++mt) {
;       bf16_t* dst = act + (size_t)(tok0 + mt * 32 + r) * DFF + u0 + 16 * hh;
; #pragma unroll
;       for (int gp = 0; gp < 2; ++gp) {
;         u32x4 o;
; #pragma unroll
;         for (int q = 0; q < 4; ++q) { const int i = 8 * gp + 2 * q; o[q] = pk2(siluf_(acc[0][mt][i]) * acc[1][mt][i], siluf_(acc[0][mt][i + 1]) * acc[1][mt][i + 1]); }
;         *(u32x4*)(dst + 8 * gp) = o;
;       }
;     }
;   }
; DI void grid_barrier(unsigned* ctr, const unsigned target) {
;   asm volatile("s_waitcnt vmcnt(0)" ::: "memory");
;   __syncthreads();
;   if (threadIdx.x == 0) {
;     __builtin_amdgcn_fence(__ATOMIC_RELEASE, "agent");
;     asm volatile("s_waitcnt vmcnt(0)" ::: "memory");
;     __hip_atomic_fetch_add((GAS unsigned*)ctr, 1u, __ATOMIC_RELAXED, __HIP_MEMORY_SCOPE_AGENT);
;     while (__hip_atomic_load((GAS unsigned*)ctr, __ATOMIC_RELAXED, __HIP_MEMORY_SCOPE_AGENT) < target) __builtin_amdgcn_s_sleep(1);
	v_exp_f32_e32 v0, v0
	v_cvt_pk_bf16_f32 v36, v36, v37
	v_add_f32_e32 v0, 1.0, v0
	v_rcp_f32_e32 v39, v0
	v_mul_f32_e32 v0, 0xbfb8aa3b, v18
	v_exp_f32_e32 v0, v0
	v_pk_mul_f32 v[38:39], v[64:65], v[38:39]
	s_nop 0
	v_pk_mul_f32 v[38:39], v[48:49], v[38:39]
	v_add_f32_e32 v0, 1.0, v0
	v_cvt_pk_bf16_f32 v37, v38, v39
	global_store_dwordx4 v[164:165], v[34:37], off offset:80
	s_nop 1
	v_rcp_f32_e32 v34, v0
	v_mul_f32_e32 v0, 0xbfb8aa3b, v19
	v_exp_f32_e32 v0, v0
	s_nop 0
	v_add_f32_e32 v0, 1.0, v0
	v_rcp_f32_e32 v35, v0
	v_mul_f32_e32 v0, 0xbfb8aa3b, v20
	v_exp_f32_e32 v0, v0
	v_pk_mul_f32 v[18:19], v[18:19], v[34:35]
	s_nop 0
	v_pk_mul_f32 v[2:3], v[2:3], v[18:19]
	v_add_f32_e32 v0, 1.0, v0
	v_rcp_f32_e32 v18, v0
	v_mul_f32_e32 v0, 0xbfb8aa3b, v21
	v_exp_f32_e32 v0, v0
	v_cvt_pk_bf16_f32 v2, v2, v3
	v_add_f32_e32 v0, 1.0, v0
	v_rcp_f32_e32 v19, v0
	v_mul_f32_e32 v0, 0xbfb8aa3b, v22
	v_exp_f32_e32 v0, v0
	v_pk_mul_f32 v[18:19], v[20:21], v[18:19]
	s_nop 0
	v_pk_mul_f32 v[4:5], v[4:5], v[18:19]
	v_add_f32_e32 v0, 1.0, v0
	v_cvt_pk_bf16_f32 v3, v4, v5
	v_rcp_f32_e32 v4, v0
	v_mul_f32_e32 v0, 0xbfb8aa3b, v23
	v_exp_f32_e32 v0, v0
	s_nop 0
	v_add_f32_e32 v0, 1.0, v0
	v_rcp_f32_e32 v5, v0
	v_mul_f32_e32 v0, 0xbfb8aa3b, v24
	v_exp_f32_e32 v0, v0
	v_pk_mul_f32 v[4:5], v[22:23], v[4:5]
	s_nop 0
	v_pk_mul_f32 v[4:5], v[6:7], v[4:5]
	v_add_f32_e32 v0, 1.0, v0
	v_rcp_f32_e32 v6, v0
	v_mul_f32_e32 v0, 0xbfb8aa3b, v25
	v_exp_f32_e32 v0, v0
	v_cvt_pk_bf16_f32 v4, v4, v5
	v_add_f32_e32 v0, 1.0, v0
	v_rcp_f32_e32 v7, v0
	v_mul_f32_e32 v0, 0xbfb8aa3b, v26
	v_exp_f32_e32 v0, v0
	v_pk_mul_f32 v[6:7], v[24:25], v[6:7]
	s_nop 0
	v_pk_mul_f32 v[6:7], v[8:9], v[6:7]
	v_add_f32_e32 v0, 1.0, v0
	v_cvt_pk_bf16_f32 v5, v6, v7
	global_store_dwordx4 v[98:99], v[2:5], off offset:64
	s_nop 1
	v_rcp_f32_e32 v2, v0
	v_mul_f32_e32 v0, 0xbfb8aa3b, v27
	v_exp_f32_e32 v0, v0
	s_nop 0
	v_add_f32_e32 v0, 1.0, v0
	v_rcp_f32_e32 v3, v0
	v_mul_f32_e32 v0, 0xbfb8aa3b, v28
	v_exp_f32_e32 v0, v0
	v_pk_mul_f32 v[2:3], v[26:27], v[2:3]
	s_nop 0
	v_pk_mul_f32 v[2:3], v[10:11], v[2:3]
	v_add_f32_e32 v0, 1.0, v0
	v_rcp_f32_e32 v4, v0
	v_mul_f32_e32 v0, 0xbfb8aa3b, v29
	v_exp_f32_e32 v0, v0
	v_cvt_pk_bf16_f32 v2, v2, v3
	v_add_f32_e32 v0, 1.0, v0
	v_rcp_f32_e32 v5, v0
	v_mul_f32_e32 v0, 0xbfb8aa3b, v30
	v_exp_f32_e32 v0, v0
	v_pk_mul_f32 v[4:5], v[28:29], v[4:5]
	s_nop 0
	v_pk_mul_f32 v[4:5], v[12:13], v[4:5]
	v_add_f32_e32 v0, 1.0, v0
	v_cvt_pk_bf16_f32 v3, v4, v5
	v_rcp_f32_e32 v4, v0
	v_mul_f32_e32 v0, 0xbfb8aa3b, v31
	v_exp_f32_e32 v0, v0
	s_nop 0
	v_add_f32_e32 v0, 1.0, v0
	v_rcp_f32_e32 v5, v0
	v_mul_f32_e32 v0, 0xbfb8aa3b, v32
	v_exp_f32_e32 v0, v0
	v_pk_mul_f32 v[4:5], v[30:31], v[4:5]
	s_nop 0
	v_pk_mul_f32 v[4:5], v[14:15], v[4:5]
	v_add_f32_e32 v0, 1.0, v0
	v_rcp_f32_e32 v6, v0
	v_mul_f32_e32 v0, 0xbfb8aa3b, v33
	v_exp_f32_e32 v0, v0
	v_cvt_pk_bf16_f32 v4, v4, v5
	v_add_f32_e32 v0, 1.0, v0
	v_rcp_f32_e32 v7, v0
	s_nop 0
	v_pk_mul_f32 v[6:7], v[32:33], v[6:7]
	s_nop 0
	v_pk_mul_f32 v[6:7], v[16:17], v[6:7]
	s_nop 0
	v_cvt_pk_bf16_f32 v5, v6, v7
	global_store_dwordx4 v[98:99], v[2:5], off offset:80
	s_and_b64 vcc, exec, s[4:5]
	s_mov_b32 s16, s9
	s_cbranch_vccz .LBB0_736
	s_add_i32 s25, s24, 1
	s_cmp_ge_i32 s25, s79
	s_cbranch_scc1 .LBB0_762
	s_cmp_lg_u32 s24, s78
	s_mov_b64 s[4:5], -1
	v_mov_b32_e32 v206, v198
	v_mov_b32_e32 v207, v199
	s_cbranch_scc0 .LBB0_750
	s_waitcnt vmcnt(0)
	s_barrier
	s_mov_b64 s[4:5], exec
	v_readlane_b32 s2, v254, 26
	v_readlane_b32 s3, v254, 27
	s_and_b64 s[2:3], s[4:5], s[2:3]
	s_mov_b64 exec, s[2:3]
	s_cbranch_execz .LBB0_749
	s_load_dword s2, s[80:81], 0x0
	s_mov_b64 s[8:9], exec
	buffer_wbl2 sc1
	s_waitcnt vmcnt(0) lgkmcnt(0)
	s_waitcnt vmcnt(0)
	v_mbcnt_lo_u32_b32 v0, s8, 0
	s_add_u32 s6, s10, 0x1ee14400
	v_mbcnt_hi_u32_b32 v0, s9, v0
	s_addc_u32 s7, s11, 0
	v_cmp_eq_u32_e32 vcc, 0, v0
	s_and_saveexec_b64 s[10:11], vcc
	s_cbranch_execz .LBB0_746
	s_bcnt1_i32_b64 s3, s[8:9]
	v_mov_b32_e32 v0, s3
	global_atomic_add v1, v0, s[6:7]

; #define G_GLOAD(XR, WR, KT) { _Pragma("unroll") for (int i_ = 0; i_ < 4; ++i_) XR[i_] = *(const u32x4*)(Xt + ((size_t)(64 * i_) * ldx + (KT) * 64) * 2 + xoff); \
;     _Pragma("unroll") for (int i_ = 0; i_ < 4; ++i_) WR[i_] = *(const u32x4*)(Wtb + ((size_t)(64 * i_) * K + (KT) * 64) * 2 + woff); }
; #define G_LSTORE(XR, WR, STG) { char* xs_ = lds + (STG) * G_STAGE; char* ws_ = xs_ + G_XB; \
;     _Pragma("unroll") for (int i_ = 0; i_ < 4; ++i_) *(u32x4*)(xs_ + (lrow + 64 * i_) * LROW + lch * 16) = XR[i_]; \
;     _Pragma("unroll") for (int i_ = 0; i_ < 4; ++i_) *(u32x4*)(ws_ + (lrow + 64 * i_) * LROW + lch * 16) = WR[i_]; }
; template <class Epi>
; DI void gemm_phase(const bf16_t* __restrict__ X, const int ldx, const bf16_t* __restrict__ Wt, const int N, const int K, const Epi& epi, char* lds) {
;     ...
;     const int L = chunk * 32 + slot, band = L / (4 * nNt), rem = L % (4 * nNt);
;     const int mt_ = band * 4 + (rem & 3), nt_ = rem >> 2;
;     const char* Xt = (const char*)(X + (size_t)(mt_ * 256) * ldx);
;     const char* Wtb = (const char*)(Wt + (size_t)(nt_ * 256) * K);
;     const unsigned xoff = (unsigned)(lrow * ldx + lch * 8) * 2u, woff = (unsigned)(lrow * K + lch * 8) * 2u;
;     const bool has_next = !Epi::kFull && (chunk + 8 < nchunks);
;     const int Ln = (has_next ? chunk + 8 : chunk) * 32 + slot, band_n = Ln / (4 * nNt), rem_n = Ln % (4 * nNt);
;     const char* Xt_n = (const char*)(X + (size_t)((band_n * 4 + (rem_n & 3)) * 256) * ldx);
;     const char* Wtb_n = (const char*)(Wt + (size_t)((rem_n >> 2) * 256) * K);
;     f32x16 acc[2][2][2];
;     ...
;     asm volatile("" ::: "memory");
;     if (Epi::kFull || chunk == xcd) {
;       G_GLOAD(xr0, wr0, 0);
;       G_LSTORE(xr0, wr0, 0);
;       __syncthreads();
;       G_GLOAD(xr0, wr0, 1);
;     }
; #pragma unroll
;     for (int c = 0; c < 2; ++c)
; #pragma unroll
;       for (int a = 0; a < 2; ++a)
; #pragma unroll
;         for (int b = 0; b < 2; ++b)
; #pragma unroll
;           for (int i = 0; i < 16; ++i) acc[c][a][b][i] = 0.f;
.LBB0_768:
	s_lshl_b32 s2, s35, 5
	v_readlane_b32 s3, v254, 3
	s_add_i32 s2, s2, s3
	s_lshr_b32 s2, s2, 2
	s_and_b32 s2, s2, 0xffffffc
	s_or_b32 s36, s2, s90
	s_lshl_b32 s2, s36, 8
	s_mul_i32 s3, s36, 0x160000
	s_mul_hi_u32 s5, s2, 0x1600
	s_add_u32 s4, s31, s3
	s_addc_u32 s5, s34, s5
	v_lshl_add_u64 v[178:179], s[4:5], 0, v[162:163]
	v_add_co_u32_e32 v70, vcc, s93, v178
	s_mov_b64 s[18:19], 0xb0000
	s_nop 0
	v_addc_co_u32_e32 v71, vcc, 0, v179, vcc
	v_add_co_u32_e32 v72, vcc, s49, v178
	global_load_dwordx4 v[22:25], v[178:179], off
	global_load_dwordx4 v[26:29], v[70:71], off
	v_addc_co_u32_e32 v73, vcc, 0, v179, vcc
	global_load_dwordx4 v[30:33], v[72:73], off
	global_load_dwordx4 v[50:53], v[164:165], off
	global_load_dwordx4 v[54:57], v[198:199], off
	global_load_dwordx4 v[58:61], v[206:207], off
	global_load_dwordx4 v[62:65], v[170:171], off
	v_add_co_u32_e32 v74, vcc, s70, v178
	v_mov_b32_e32 v2, 0
	s_nop 0
	v_addc_co_u32_e32 v75, vcc, 0, v179, vcc
	global_load_dwordx4 v[66:69], v[74:75], off
	v_lshl_add_u64 v[180:181], v[178:179], 0, s[18:19]
	s_mov_b64 s[18:19], 0x108000
	s_mov_b32 s5, 0
	s_movk_i32 s3, 0x100
	v_mov_b32_e32 v3, v2
	s_waitcnt vmcnt(13)
	s_waitcnt vmcnt(12)
	s_waitcnt vmcnt(11)
	s_waitcnt vmcnt(10)
	v_lshl_add_u64 v[182:183], v[178:179], 0, s[18:19]
	s_waitcnt vmcnt(4)
	ds_write_b128 v224, v[50:53] offset:36864
	s_waitcnt vmcnt(3)
	ds_write_b128 v224, v[54:57] offset:46080
	s_waitcnt vmcnt(2)
	ds_write_b128 v224, v[58:61] offset:55296
	s_waitcnt vmcnt(1)
	ds_write_b128 v224, v[62:65] offset:64512
	ds_write_b128 v224, v[22:25]
	ds_write_b128 v224, v[30:33] offset:18432
	ds_write_b128 v224, v[26:29] offset:9216
	s_waitcnt vmcnt(0)
	ds_write_b128 v224, v[66:69] offset:27648
	s_waitcnt lgkmcnt(0)
	s_barrier
	global_load_dwordx4 v[130:133], v[174:175], off
	global_load_dwordx4 v[150:153], v[176:177], off
	global_load_dwordx4 v[158:161], v[172:173], off
	global_load_dwordx4 v[138:141], v[164:165], off offset:128
	global_load_dwordx4 v[146:149], v[74:75], off offset:128
	global_load_dwordx4 v[134:137], v[72:73], off offset:128
	global_load_dwordx4 v[154:157], v[70:71], off offset:128
	global_load_dwordx4 v[142:145], v[178:179], off offset:128
	v_mov_b32_e32 v116, v2
	v_mov_b32_e32 v117, v2
	v_mov_b32_e32 v118, v2
	v_mov_b32_e32 v119, v2
	v_mov_b32_e32 v120, v2
	v_mov_b32_e32 v121, v2
	v_mov_b32_e32 v122, v2
	v_mov_b32_e32 v123, v2
	v_mov_b32_e32 v124, v2
	v_mov_b32_e32 v125, v2
	v_mov_b32_e32 v126, v2
	v_mov_b32_e32 v127, v2
	v_mov_b32_e32 v128, v2
	v_mov_b32_e32 v129, v2
	v_readfirstlane_b32 vcc_lo, v162
	v_readfirstlane_b32 s98, v178
	v_readfirstlane_b32 s99, v179
	v_readfirstlane_b32 s100, v164
	v_readfirstlane_b32 s101, v165
	s_nop 4
	s_sub_u32 s98, s98, vcc_lo
	s_subb_u32 s99, s99, 0
	s_sub_u32 s100, s100, vcc_lo
	s_subb_u32 s101, s101, 0
	v_add_u32_e32 v179, s93, v162
	v_add_u32_e32 v181, s49, v162
	v_add_u32_e32 v183, s70, v162
	v_add_u32_e32 v178, v209, v210
	v_add_u32_e32 v180, v209, v211
	v_add_u32_e32 v182, v212, v208
	ds_read_b128 v[166:169], v178
	ds_read_b128 v[184:187], v178 offset:4608
	ds_read_b128 v[188:191], v180 offset:36864
	ds_read_b128 v[194:197], v180 offset:41472
	ds_read_b128 v[202:205], v180 offset:46080
	ds_read_b128 v[226:229], v180 offset:50688
	ds_read_b128 v[230:233], v214 offset:32
	ds_read_b128 v[234:237], v214 offset:4640
	s_add_i32 s18, s5, 2
	s_cmp_lt_u32 s5, 42
	s_cselect_b32 s96, s3, 0x1580
	s_min_u32 s4, s5, 40
	s_lshl_b32 s4, s4, 7
	s_addk_i32 s3, 0x100
	s_cmp_gt_u32 s5, 41
	s_waitcnt lgkmcnt(5)
	v_mfma_f32_32x32x16_bf16 v[114:129], v[188:191], v[166:169], 0
	v_mfma_f32_32x32x16_bf16 v[66:81], v[188:191], v[184:187], 0
	s_waitcnt lgkmcnt(4)
	v_mfma_f32_32x32x16_bf16 v[98:113], v[194:197], v[166:169], 0
	v_mfma_f32_32x32x16_bf16 v[50:65], v[194:197], v[184:187], 0
	s_waitcnt lgkmcnt(3)
	v_mfma_f32_32x32x16_bf16 v[82:97], v[202:205], v[166:169], 0
	v_mfma_f32_32x32x16_bf16 v[18:33], v[202:205], v[184:187], 0
	s_waitcnt lgkmcnt(2)
	v_mfma_f32_32x32x16_bf16 v[34:49], v[226:229], v[166:169], 0
	ds_read_b128 v[166:169], v215 offset:36896
	ds_read_b128 v[188:191], v215 offset:41504
	v_mfma_f32_32x32x16_bf16 v[2:17], v[226:229], v[184:187], 0
	s_waitcnt vmcnt(1)
	ds_write_b128 v216, v[154:157] offset:9216
	s_waitcnt vmcnt(0)
	ds_write_b128 v216, v[142:145]
	s_add_u32 vcc_lo, s98, s96
	s_addc_u32 vcc_hi, s99, 0
	global_load_dwordx4 v[142:145], v162, vcc
	global_load_dwordx4 v[154:157], v179, vcc
	ds_write_b128 v216, v[134:137] offset:18432
	ds_write_b128 v216, v[146:149] offset:27648
	global_load_dwordx4 v[134:137], v181, vcc
	global_load_dwordx4 v[146:149], v183, vcc
	ds_read_b128 v[184:187], v215 offset:46112
	ds_read_b128 v[194:197], v215 offset:50720
	ds_read_b128 v[202:205], v214 offset:64
	ds_read_b128 v[226:229], v214 offset:4672
	s_waitcnt lgkmcnt(9)
	v_mfma_f32_32x32x16_bf16 v[114:129], v[166:169], v[230:233], v[114:129]
	v_mfma_f32_32x32x16_bf16 v[66:81], v[166:169], v[234:237], v[66:81]
	s_waitcnt lgkmcnt(8)
	v_mfma_f32_32x32x16_bf16 v[98:113], v[188:191], v[230:233], v[98:113]
	v_mfma_f32_32x32x16_bf16 v[50:65], v[188:191], v[234:237], v[50:65]
	s_waitcnt lgkmcnt(3)
	v_mfma_f32_32x32x16_bf16 v[82:97], v[184:187], v[230:233], v[82:97]
	v_mfma_f32_32x32x16_bf16 v[18:33], v[184:187], v[234:237], v[18:33]
	ds_read_b128 v[166:169], v215 offset:36928
	ds_read_b128 v[184:187], v215 offset:41536
	s_waitcnt lgkmcnt(4)
; #define G_GLOAD(XR, WR, KT) { _Pragma("unroll") for (int i_ = 0; i_ < 4; ++i_) XR[i_] = *(const u32x4*)(Xt + ((size_t)(64 * i_) * ldx + (KT) * 64) * 2 + xoff); \
;     _Pragma("unroll") for (int i_ = 0; i_ < 4; ++i_) WR[i_] = *(const u32x4*)(Wtb + ((size_t)(64 * i_) * K + (KT) * 64) * 2 + woff); }
; #define G_LSTORE(XR, WR, STG) { char* xs_ = lds + (STG) * G_STAGE; char* ws_ = xs_ + G_XB; \
;     _Pragma("unroll") for (int i_ = 0; i_ < 4; ++i_) *(u32x4*)(xs_ + (lrow + 64 * i_) * LROW + lch * 16) = XR[i_]; \
;     _Pragma("unroll") for (int i_ = 0; i_ < 4; ++i_) *(u32x4*)(ws_ + (lrow + 64 * i_) * LROW + lch * 16) = WR[i_]; }
; template <class Epi>
; DI void gemm_phase(const bf16_t* __restrict__ X, const int ldx, const bf16_t* __restrict__ Wt, const int N, const int K, const Epi& epi, char* lds) {
;     ...
;     asm volatile("" ::: "memory");
;     if (Epi::kFull || chunk == xcd) {
;       G_GLOAD(xr0, wr0, 0);
;       G_LSTORE(xr0, wr0, 0);
;       __syncthreads();
;       G_GLOAD(xr0, wr0, 1);
;     }
; #pragma unroll
;     for (int c = 0; c < 2; ++c)
; #pragma unroll
;       for (int a = 0; a < 2; ++a)
; #pragma unroll
;         for (int b = 0; b < 2; ++b)
; #pragma unroll
;           for (int i = 0; i < 16; ++i) acc[c][a][b][i] = 0.f;
	v_mfma_f32_32x32x16_bf16 v[34:49], v[194:197], v[230:233], v[34:49]
	v_mfma_f32_32x32x16_bf16 v[2:17], v[194:197], v[234:237], v[2:17]
	ds_write_b128 v217, v[150:153] offset:9216
	ds_write_b128 v217, v[138:141]
	s_add_u32 vcc_lo, s100, s96
	s_addc_u32 vcc_hi, s101, 0
	global_load_dwordx4 v[138:141], v162, vcc
	global_load_dwordx4 v[150:153], v179, vcc
	ds_read_b128 v[188:191], v215 offset:46144
	ds_read_b128 v[194:197], v215 offset:50752
	ds_read_b128 v[230:233], v214 offset:96
	ds_read_b128 v[234:237], v214 offset:4704
	s_waitcnt lgkmcnt(7)
	v_mfma_f32_32x32x16_bf16 v[114:129], v[166:169], v[202:205], v[114:129]
	v_mfma_f32_32x32x16_bf16 v[66:81], v[166:169], v[226:229], v[66:81]
	s_waitcnt lgkmcnt(6)
	v_mfma_f32_32x32x16_bf16 v[98:113], v[184:187], v[202:205], v[98:113]
	v_mfma_f32_32x32x16_bf16 v[50:65], v[184:187], v[226:229], v[50:65]
	s_waitcnt lgkmcnt(3)
	v_mfma_f32_32x32x16_bf16 v[82:97], v[188:191], v[202:205], v[82:97]
	ds_read_b128 v[166:169], v215 offset:36960
	ds_read_b128 v[184:187], v215 offset:41568
	v_mfma_f32_32x32x16_bf16 v[18:33], v[188:191], v[226:229], v[18:33]
	s_waitcnt lgkmcnt(4)
	v_mfma_f32_32x32x16_bf16 v[34:49], v[194:197], v[202:205], v[34:49]
	v_mfma_f32_32x32x16_bf16 v[2:17], v[194:197], v[226:229], v[2:17]
	ds_write_b128 v217, v[130:133] offset:18432
	ds_write_b128 v217, v[158:161] offset:27648
	global_load_dwordx4 v[130:133], v181, vcc
	global_load_dwordx4 v[158:161], v183, vcc
	ds_read_b128 v[188:191], v215 offset:46176
	ds_read_b128 v[194:197], v215 offset:50784
	s_waitcnt lgkmcnt(5)
	v_mfma_f32_32x32x16_bf16 v[114:129], v[166:169], v[230:233], v[114:129]
	v_mfma_f32_32x32x16_bf16 v[66:81], v[166:169], v[234:237], v[66:81]
	s_waitcnt lgkmcnt(4)
	v_mfma_f32_32x32x16_bf16 v[98:113], v[184:187], v[230:233], v[98:113]
	v_mfma_f32_32x32x16_bf16 v[50:65], v[184:187], v[234:237], v[50:65]
	s_waitcnt lgkmcnt(1)
	v_mfma_f32_32x32x16_bf16 v[82:97], v[188:191], v[230:233], v[82:97]
	v_mfma_f32_32x32x16_bf16 v[18:33], v[188:191], v[234:237], v[18:33]
	s_waitcnt lgkmcnt(0)
	v_mfma_f32_32x32x16_bf16 v[34:49], v[194:197], v[230:233], v[34:49]
	v_mfma_f32_32x32x16_bf16 v[2:17], v[194:197], v[234:237], v[2:17]
	s_barrier
	ds_read_b128 v[166:169], v218
	ds_read_b128 v[184:187], v218 offset:4608
	ds_read_b128 v[188:191], v219
	ds_read_b128 v[194:197], v219 offset:4608
	ds_read_b128 v[202:205], v219 offset:9216
	ds_read_b128 v[226:229], v219 offset:13824
	ds_read_b128 v[230:233], v182 offset:32
	ds_read_b128 v[234:237], v220 offset:32
	s_waitcnt lgkmcnt(5)
	v_mfma_f32_32x32x16_bf16 v[114:129], v[188:191], v[166:169], v[114:129]
	v_mfma_f32_32x32x16_bf16 v[66:81], v[188:191], v[184:187], v[66:81]
	s_waitcnt lgkmcnt(4)
	v_mfma_f32_32x32x16_bf16 v[98:113], v[194:197], v[166:169], v[98:113]
	v_mfma_f32_32x32x16_bf16 v[50:65], v[194:197], v[184:187], v[50:65]
	s_waitcnt lgkmcnt(3)
	v_mfma_f32_32x32x16_bf16 v[82:97], v[202:205], v[166:169], v[82:97]
	v_add_u32_e32 v225, v213, v208
	v_mfma_f32_32x32x16_bf16 v[18:33], v[202:205], v[184:187], v[18:33]
	s_waitcnt lgkmcnt(2)
	v_mfma_f32_32x32x16_bf16 v[34:49], v[226:229], v[166:169], v[34:49]
	ds_read_b128 v[166:169], v225 offset:32
	ds_read_b128 v[188:191], v221 offset:32
	v_mfma_f32_32x32x16_bf16 v[2:17], v[226:229], v[184:187], v[2:17]
	s_mov_b32 s5, s97
	s_waitcnt vmcnt(6)
	ds_write_b128 v224, v[154:157] offset:9216
	ds_write_b128 v224, v[142:145]
	s_add_u32 vcc_lo, s98, s4
	s_addc_u32 vcc_hi, s99, 0
	global_load_dwordx4 v[142:145], v162, vcc offset:384
	global_load_dwordx4 v[154:157], v179, vcc offset:384
	s_waitcnt vmcnt(7)
	ds_write_b128 v224, v[134:137] offset:18432
	s_waitcnt vmcnt(6)
	ds_write_b128 v224, v[146:149] offset:27648
	global_load_dwordx4 v[134:137], v181, vcc offset:384
	global_load_dwordx4 v[146:149], v183, vcc offset:384
	ds_read_b128 v[184:187], v222 offset:32
	ds_read_b128 v[194:197], v223 offset:32
	ds_read_b128 v[202:205], v182 offset:64
	ds_read_b128 v[226:229], v220 offset:64
	s_waitcnt lgkmcnt(9)
	v_mfma_f32_32x32x16_bf16 v[114:129], v[166:169], v[230:233], v[114:129]
	v_mfma_f32_32x32x16_bf16 v[66:81], v[166:169], v[234:237], v[66:81]
	s_waitcnt lgkmcnt(8)
	v_mfma_f32_32x32x16_bf16 v[98:113], v[188:191], v[230:233], v[98:113]
	v_mfma_f32_32x32x16_bf16 v[50:65], v[188:191], v[234:237], v[50:65]
	s_waitcnt lgkmcnt(3)
	v_mfma_f32_32x32x16_bf16 v[82:97], v[184:187], v[230:233], v[82:97]
	v_mfma_f32_32x32x16_bf16 v[18:33], v[184:187], v[234:237], v[18:33]
	ds_read_b128 v[166:169], v225 offset:64
	ds_read_b128 v[184:187], v221 offset:64
	s_waitcnt lgkmcnt(4)
	v_mfma_f32_32x32x16_bf16 v[34:49], v[194:197], v[230:233], v[34:49]
	v_mfma_f32_32x32x16_bf16 v[2:17], v[194:197], v[234:237], v[2:17]
	s_waitcnt vmcnt(6)
	ds_write_b128 v224, v[150:153] offset:46080
	ds_write_b128 v224, v[138:141] offset:36864
	s_add_u32 vcc_lo, s100, s4
	s_addc_u32 vcc_hi, s101, 0
	global_load_dwordx4 v[138:141], v162, vcc offset:384
	global_load_dwordx4 v[150:153], v179, vcc offset:384
	ds_read_b128 v[188:191], v222 offset:64
	ds_read_b128 v[194:197], v223 offset:64
	ds_read_b128 v[230:233], v182 offset:96
	ds_read_b128 v[234:237], v220 offset:96
	s_waitcnt lgkmcnt(7)
	v_mfma_f32_32x32x16_bf16 v[114:129], v[166:169], v[202:205], v[114:129]
	v_mfma_f32_32x32x16_bf16 v[66:81], v[166:169], v[226:229], v[66:81]
	s_waitcnt lgkmcnt(6)
	v_mfma_f32_32x32x16_bf16 v[98:113], v[184:187], v[202:205], v[98:113]
	v_mfma_f32_32x32x16_bf16 v[50:65], v[184:187], v[226:229], v[50:65]
	s_waitcnt lgkmcnt(3)
	v_mfma_f32_32x32x16_bf16 v[82:97], v[188:191], v[202:205], v[82:97]
	ds_read_b128 v[166:169], v225 offset:96
	ds_read_b128 v[184:187], v221 offset:96
	v_mfma_f32_32x32x16_bf16 v[18:33], v[188:191], v[226:229], v[18:33]
	s_waitcnt lgkmcnt(4)
	v_mfma_f32_32x32x16_bf16 v[34:49], v[194:197], v[202:205], v[34:49]
	v_mfma_f32_32x32x16_bf16 v[2:17], v[194:197], v[226:229], v[2:17]
	s_waitcnt vmcnt(7)
	ds_write_b128 v224, v[130:133] offset:55296
	s_waitcnt vmcnt(6)
	ds_write_b128 v224, v[158:161] offset:64512
	global_load_dwordx4 v[130:133], v181, vcc offset:384
	global_load_dwordx4 v[158:161], v183, vcc offset:384
	ds_read_b128 v[188:191], v222 offset:96
	ds_read_b128 v[194:197], v223 offset:96
	s_waitcnt lgkmcnt(5)
	v_mfma_f32_32x32x16_bf16 v[114:129], v[166:169], v[230:233], v[114:129]
	v_mfma_f32_32x32x16_bf16 v[66:81], v[166:169], v[234:237], v[66:81]
	s_waitcnt lgkmcnt(4)
	v_mfma_f32_32x32x16_bf16 v[98:113], v[184:187], v[230:233], v[98:113]
	v_mfma_f32_32x32x16_bf16 v[50:65], v[184:187], v[234:237], v[50:65]
	s_waitcnt lgkmcnt(1)
	v_mfma_f32_32x32x16_bf16 v[82:97], v[188:191], v[230:233], v[82:97]
	v_mfma_f32_32x32x16_bf16 v[18:33], v[188:191], v[234:237], v[18:33]
	s_waitcnt lgkmcnt(0)
	v_mfma_f32_32x32x16_bf16 v[34:49], v[194:197], v[230:233], v[34:49]
	v_mfma_f32_32x32x16_bf16 v[2:17], v[194:197], v[234:237], v[2:17]
	s_mov_b32 s5, s18
	s_cmp_gt_u32 s5, 43
	s_barrier
	s_cbranch_scc0 .LBB0_769
	s_branch .Lkexit_5

; #define RL_LOAD(XV, G) { constexpr int mt__ = (G) >> 2, half__ = ((G) >> 1) & 1, nt__ = (G) & 1; \
;     _Pragma("unroll") for (int gq = 0; gq < 4; ++gq) XV[gq] = *(const f32x4*)(xin + rbase + (size_t)mt__ * 32 * 1024 + half__ * 64 + nt__ * 32 + 4 * gq); }
; #define RL_FOLD(XV, G, SM, SQ) { constexpr int mt__ = (G) >> 2, half__ = ((G) >> 1) & 1, nt__ = (G) & 1; \
;     _Pragma("unroll") for (int gq = 0; gq < 4; ++gq) _Pragma("unroll") for (int jj = 0; jj < 4; ++jj) { \
;       const float y = ALPHA * XV[gq][jj] + acc[half__][nt__][mt__][4 * gq + jj]; acc[half__][nt__][mt__][4 * gq + jj] = y; SM += y; SQ += y * y; } }
; #define SB __builtin_amdgcn_sched_barrier(0)
;   DI void full(const int mt_, const int nt_, f32x16 (&acc)[2][2][2], const int tw, const int fw, const int r, const int hh, char* lds, const int tid) const {
;     float* part = (float*)(lds + G_STAGE);
;     const size_t rbase = (size_t)(mt_ * 256 + tw * 64 + r) * 1024 + nt_ * 256 + fw * 128 + 16 * hh;
;     f32x4 xa[4], xc[4], xe[4];
;     ...
;     float sm0 = 0.f, sq0 = 0.f, sm1 = 0.f, sq1 = 0.f;
;     RL_LOAD(xa, 0); RL_LOAD(xc, 1); RL_LOAD(xe, 2); SB;
;     RL_FOLD(xa, 0, sm0, sq0); SB; RL_LOAD(xa, 3); SB;
;     RL_FOLD(xc, 1, sm0, sq0); SB; RL_LOAD(xc, 4); SB;
;     RL_FOLD(xe, 2, sm0, sq0); SB; RL_LOAD(xe, 5); SB;
;     RL_FOLD(xa, 3, sm0, sq0); SB; RL_LOAD(xa, 6); SB;
;     RL_FOLD(xc, 4, sm1, sq1); SB; RL_LOAD(xc, 7); SB;
;     RL_FOLD(xe, 5, sm1, sq1); SB;
;     RL_FOLD(xa, 6, sm1, sq1); SB;
;     RL_FOLD(xc, 7, sm1, sq1);
.Lkexit_5:
	v_mov_b32_e32 v186, v192
	s_waitcnt vmcnt(1)
	v_ashrrev_i32_e32 v130, 1, v186
	v_and_b32_e32 v225, 0xdf, v186
	v_and_b32_e32 v184, 0xffffff80, v130
	v_or_b32_e32 v0, s2, v225
	v_ashrrev_i32_e32 v185, 31, v184
	v_bfe_u32 v226, v186, 5, 1
	v_lshl_add_u64 v[130:131], v[184:185], 2, s[16:17]
	v_lshlrev_b64 v[132:133], 12, v[0:1]
	v_lshl_add_u64 v[130:131], v[130:131], 0, v[132:133]
	v_lshlrev_b32_e32 v132, 6, v226
	v_mov_b32_e32 v133, v1
	v_lshl_add_u64 v[188:189], v[130:131], 0, v[132:133]
	global_load_dwordx4 v[130:133], v[188:189], off offset:48
	global_load_dwordx4 v[134:137], v[188:189], off offset:32
	global_load_dwordx4 v[138:141], v[188:189], off offset:16
	global_load_dwordx4 v[142:145], v[188:189], off
	global_load_dwordx4 v[194:197], v[188:189], off offset:176
	global_load_dwordx4 v[202:205], v[188:189], off offset:160
	global_load_dwordx4 v[228:231], v[188:189], off offset:144
	global_load_dwordx4 v[146:149], v[188:189], off offset:128
	global_load_dwordx4 v[232:235], v[188:189], off offset:304
	global_load_dwordx4 v[236:239], v[188:189], off offset:288
	global_load_dwordx4 v[240:243], v[188:189], off offset:272
	global_load_dwordx4 v[244:247], v[188:189], off offset:256
	s_waitcnt vmcnt(8)
	v_pk_fma_f32 v[180:181], v[142:143], s[0:1], v[114:115] op_sel_hi:[1,0,1]
	v_pk_fma_f32 v[182:183], v[144:145], s[0:1], v[116:117] op_sel_hi:[1,0,1]
	v_add_f32_e32 v114, 0, v180
	v_add_f32_e32 v142, v181, v114
	v_mul_f32_e32 v114, v181, v181
	v_pk_fma_f32 v[114:115], v[180:181], v[180:181], v[114:115] op_sel_hi:[1,1,0]
	v_add_f32_e32 v116, v182, v142
	v_pk_fma_f32 v[114:115], v[182:183], v[182:183], v[114:115]
	v_add_f32_e32 v117, v183, v116
	v_mul_f32_e32 v116, v183, v183
	v_pk_fma_f32 v[160:161], v[138:139], s[0:1], v[118:119] op_sel_hi:[1,0,1]
	v_pk_add_f32 v[114:115], v[116:117], v[114:115] op_sel_hi:[0,1]
	v_add_f32_e32 v116, v160, v117
	v_pk_fma_f32 v[114:115], v[160:161], v[160:161], v[114:115]
	v_add_f32_e32 v117, v161, v116
	v_mul_f32_e32 v116, v161, v161
	v_pk_fma_f32 v[178:179], v[140:141], s[0:1], v[120:121] op_sel_hi:[1,0,1]
	v_pk_add_f32 v[114:115], v[116:117], v[114:115] op_sel_hi:[0,1]
	v_add_f32_e32 v116, v178, v117
	v_pk_fma_f32 v[114:115], v[178:179], v[178:179], v[114:115]
	v_add_f32_e32 v117, v179, v116
	v_mul_f32_e32 v116, v179, v179
	v_pk_fma_f32 v[156:157], v[134:135], s[0:1], v[122:123] op_sel_hi:[1,0,1]
	v_pk_add_f32 v[114:115], v[116:117], v[114:115] op_sel_hi:[0,1]
	v_add_f32_e32 v116, v156, v117
	v_pk_fma_f32 v[114:115], v[156:157], v[156:157], v[114:115]
	v_add_f32_e32 v117, v157, v116
	v_mul_f32_e32 v116, v157, v157
	v_pk_fma_f32 v[158:159], v[136:137], s[0:1], v[124:125] op_sel_hi:[1,0,1]
	v_pk_add_f32 v[114:115], v[116:117], v[114:115] op_sel_hi:[0,1]
	v_add_f32_e32 v116, v158, v117
	v_pk_fma_f32 v[114:115], v[158:159], v[158:159], v[114:115]
	v_add_f32_e32 v120, v159, v116
	v_mul_f32_e32 v116, v159, v159
	v_pk_add_f32 v[114:115], v[116:117], v[114:115] op_sel_hi:[0,1]
	v_pk_fma_f32 v[154:155], v[130:131], s[0:1], v[126:127] op_sel_hi:[1,0,1]
	v_pk_fma_f32 v[152:153], v[132:133], s[0:1], v[128:129] op_sel_hi:[1,0,1]
	v_pk_fma_f32 v[114:115], v[154:155], v[154:155], v[114:115]
	v_mul_f32_e32 v116, v155, v155
	v_pk_add_f32 v[114:115], v[116:117], v[114:115] op_sel_hi:[0,1]
	v_pk_fma_f32 v[114:115], v[152:153], v[152:153], v[114:115]
	v_mul_f32_e32 v116, v153, v153
	v_pk_add_f32 v[118:119], v[116:117], v[114:115] op_sel_hi:[0,1]
	global_load_dwordx4 v[114:117], v[188:189], off offset:432
	global_load_dwordx4 v[248:251], v[188:189], off offset:416
	global_load_dwordx4 v[166:169], v[188:189], off offset:400
	global_load_dwordx4 v[122:125], v[188:189], off offset:384
	v_add_f32_e32 v120, v154, v120
	v_add_f32_e32 v120, v155, v120
	v_add_f32_e32 v120, v152, v120
	v_add_f32_e32 v120, v153, v120
	s_waitcnt vmcnt(8)
	v_pk_fma_f32 v[146:147], v[146:147], s[0:1], v[98:99] op_sel_hi:[1,0,1]
	v_pk_fma_f32 v[150:151], v[148:149], s[0:1], v[100:101] op_sel_hi:[1,0,1]
	v_add_f32_e32 v120, v146, v120
	v_pk_fma_f32 v[98:99], v[146:147], v[146:147], v[118:119]
	v_add_f32_e32 v119, v147, v120
	v_mul_f32_e32 v118, v147, v147
	v_pk_add_f32 v[98:99], v[118:119], v[98:99] op_sel_hi:[0,1]
	v_add_f32_e32 v100, v150, v119
	v_pk_fma_f32 v[98:99], v[150:151], v[150:151], v[98:99]
	v_add_f32_e32 v101, v151, v100
	v_mul_f32_e32 v100, v151, v151
	v_pk_fma_f32 v[140:141], v[228:229], s[0:1], v[102:103] op_sel_hi:[1,0,1]
	v_pk_add_f32 v[98:99], v[100:101], v[98:99] op_sel_hi:[0,1]
	v_add_f32_e32 v100, v140, v101
	v_pk_fma_f32 v[98:99], v[140:141], v[140:141], v[98:99]
	v_add_f32_e32 v101, v141, v100
	v_mul_f32_e32 v100, v141, v141
	v_pk_fma_f32 v[148:149], v[230:231], s[0:1], v[104:105] op_sel_hi:[1,0,1]
	v_pk_add_f32 v[98:99], v[100:101], v[98:99] op_sel_hi:[0,1]
	v_add_f32_e32 v100, v148, v101
	v_pk_fma_f32 v[98:99], v[148:149], v[148:149], v[98:99]
	v_add_f32_e32 v101, v149, v100
	v_mul_f32_e32 v100, v149, v149
	v_pk_fma_f32 v[132:133], v[202:203], s[0:1], v[106:107] op_sel_hi:[1,0,1]
	v_pk_add_f32 v[98:99], v[100:101], v[98:99] op_sel_hi:[0,1]
	v_add_f32_e32 v100, v132, v101
	v_pk_fma_f32 v[98:99], v[132:133], v[132:133], v[98:99]
	v_add_f32_e32 v101, v133, v100
	v_mul_f32_e32 v100, v133, v133
	v_pk_fma_f32 v[142:143], v[204:205], s[0:1], v[108:109] op_sel_hi:[1,0,1]
	v_pk_add_f32 v[98:99], v[100:101], v[98:99] op_sel_hi:[0,1]
	v_add_f32_e32 v100, v142, v101
	v_pk_fma_f32 v[98:99], v[142:143], v[142:143], v[98:99]
	v_add_f32_e32 v106, v143, v100
	v_mul_f32_e32 v100, v143, v143
	v_pk_add_f32 v[102:103], v[100:101], v[98:99] op_sel_hi:[0,1]
	v_pk_fma_f32 v[126:127], v[194:195], s[0:1], v[110:111] op_sel_hi:[1,0,1]
	v_pk_fma_f32 v[136:137], v[196:197], s[0:1], v[112:113] op_sel_hi:[1,0,1]
	v_add_co_u32_e32 v190, vcc, s91, v188
	s_mov_b64 s[4:5], 0x20000
	s_nop 0
	v_addc_co_u32_e32 v191, vcc, 0, v189, vcc
	v_lshl_add_u64 v[104:105], v[188:189], 0, s[4:5]
	global_load_dwordx4 v[194:197], v[190:191], off
	global_load_dwordx4 v[98:101], v[104:105], off offset:48
	global_load_dwordx4 v[202:205], v[104:105], off offset:32
	global_load_dwordx4 v[228:231], v[104:105], off offset:16
	v_add_f32_e32 v104, v126, v106
	v_pk_fma_f32 v[102:103], v[126:127], v[126:127], v[102:103]
	v_add_f32_e32 v105, v127, v104
	v_mul_f32_e32 v104, v127, v127
	v_pk_add_f32 v[102:103], v[104:105], v[102:103] op_sel_hi:[0,1]
	v_add_f32_e32 v104, v136, v105
	v_pk_fma_f32 v[102:103], v[136:137], v[136:137], v[102:103]
	v_add_f32_e32 v105, v137, v104
	v_mul_f32_e32 v104, v137, v137
	v_pk_add_f32 v[102:103], v[104:105], v[102:103] op_sel_hi:[0,1]
	s_waitcnt vmcnt(8)
; #define RL_LOAD(XV, G) { constexpr int mt__ = (G) >> 2, half__ = ((G) >> 1) & 1, nt__ = (G) & 1; \
;     _Pragma("unroll") for (int gq = 0; gq < 4; ++gq) XV[gq] = *(const f32x4*)(xin + rbase + (size_t)mt__ * 32 * 1024 + half__ * 64 + nt__ * 32 + 4 * gq); }
; #define RL_FOLD(XV, G, SM, SQ) { constexpr int mt__ = (G) >> 2, half__ = ((G) >> 1) & 1, nt__ = (G) & 1; \
;     _Pragma("unroll") for (int gq = 0; gq < 4; ++gq) _Pragma("unroll") for (int jj = 0; jj < 4; ++jj) { \
;       const float y = ALPHA * XV[gq][jj] + acc[half__][nt__][mt__][4 * gq + jj]; acc[half__][nt__][mt__][4 * gq + jj] = y; SM += y; SQ += y * y; } }
; #define SB __builtin_amdgcn_sched_barrier(0)
;   DI void full(const int mt_, const int nt_, f32x16 (&acc)[2][2][2], const int tw, const int fw, const int r, const int hh, char* lds, const int tid) const {
;     ...
;     float sm0 = 0.f, sq0 = 0.f, sm1 = 0.f, sq1 = 0.f;
;     RL_LOAD(xa, 0); RL_LOAD(xc, 1); RL_LOAD(xe, 2); SB;
;     RL_FOLD(xa, 0, sm0, sq0); SB; RL_LOAD(xa, 3); SB;
;     RL_FOLD(xc, 1, sm0, sq0); SB; RL_LOAD(xc, 4); SB;
;     RL_FOLD(xe, 2, sm0, sq0); SB; RL_LOAD(xe, 5); SB;
;     RL_FOLD(xa, 3, sm0, sq0); SB; RL_LOAD(xa, 6); SB;
;     RL_FOLD(xc, 4, sm1, sq1); SB; RL_LOAD(xc, 7); SB;
;     RL_FOLD(xe, 5, sm1, sq1); SB;
;     RL_FOLD(xa, 6, sm1, sq1); SB;
;     RL_FOLD(xc, 7, sm1, sq1);
	v_pk_fma_f32 v[134:135], v[244:245], s[0:1], v[82:83] op_sel_hi:[1,0,1]
	v_pk_fma_f32 v[144:145], v[246:247], s[0:1], v[84:85] op_sel_hi:[1,0,1]
	v_add_f32_e32 v104, v134, v105
	v_pk_fma_f32 v[82:83], v[134:135], v[134:135], v[102:103]
	v_add_f32_e32 v103, v135, v104
	v_mul_f32_e32 v102, v135, v135
	v_pk_add_f32 v[82:83], v[102:103], v[82:83] op_sel_hi:[0,1]
	v_add_f32_e32 v84, v144, v103
	v_pk_fma_f32 v[82:83], v[144:145], v[144:145], v[82:83]
	v_add_f32_e32 v85, v145, v84
	v_mul_f32_e32 v84, v145, v145
	v_pk_fma_f32 v[128:129], v[240:241], s[0:1], v[86:87] op_sel_hi:[1,0,1]
	v_pk_add_f32 v[82:83], v[84:85], v[82:83] op_sel_hi:[0,1]
	v_add_f32_e32 v84, v128, v85
	v_pk_fma_f32 v[82:83], v[128:129], v[128:129], v[82:83]
	v_add_f32_e32 v85, v129, v84
	v_mul_f32_e32 v84, v129, v129
	v_pk_fma_f32 v[138:139], v[242:243], s[0:1], v[88:89] op_sel_hi:[1,0,1]
	v_pk_add_f32 v[82:83], v[84:85], v[82:83] op_sel_hi:[0,1]
	v_add_f32_e32 v84, v138, v85
	v_pk_fma_f32 v[82:83], v[138:139], v[138:139], v[82:83]
	v_add_f32_e32 v85, v139, v84
	v_mul_f32_e32 v84, v139, v139
	v_pk_fma_f32 v[118:119], v[236:237], s[0:1], v[90:91] op_sel_hi:[1,0,1]
	v_pk_add_f32 v[82:83], v[84:85], v[82:83] op_sel_hi:[0,1]
	v_add_f32_e32 v84, v118, v85
	v_pk_fma_f32 v[82:83], v[118:119], v[118:119], v[82:83]
	v_add_f32_e32 v85, v119, v84
	v_mul_f32_e32 v84, v119, v119
	v_pk_fma_f32 v[130:131], v[238:239], s[0:1], v[92:93] op_sel_hi:[1,0,1]
	v_pk_add_f32 v[82:83], v[84:85], v[82:83] op_sel_hi:[0,1]
	v_add_f32_e32 v84, v130, v85
	v_pk_fma_f32 v[82:83], v[130:131], v[130:131], v[82:83]
	v_add_f32_e32 v90, v131, v84
	v_mul_f32_e32 v84, v131, v131
	v_pk_add_f32 v[86:87], v[84:85], v[82:83] op_sel_hi:[0,1]
	v_pk_fma_f32 v[108:109], v[232:233], s[0:1], v[94:95] op_sel_hi:[1,0,1]
	v_pk_fma_f32 v[120:121], v[234:235], s[0:1], v[96:97] op_sel_hi:[1,0,1]
	s_mov_b64 s[4:5], 0x20080
	v_lshl_add_u64 v[88:89], v[188:189], 0, s[4:5]
	global_load_dwordx4 v[82:85], v[88:89], off offset:48
	global_load_dwordx4 v[232:235], v[88:89], off offset:32
	global_load_dwordx4 v[236:239], v[190:191], off offset:128
	global_load_dwordx4 v[240:243], v[88:89], off offset:16
	v_add_f32_e32 v88, v108, v90
	v_pk_fma_f32 v[86:87], v[108:109], v[108:109], v[86:87]
	v_add_f32_e32 v89, v109, v88
	v_mul_f32_e32 v88, v109, v109
	v_pk_add_f32 v[86:87], v[88:89], v[86:87] op_sel_hi:[0,1]
	v_add_f32_e32 v88, v120, v89
	v_pk_fma_f32 v[86:87], v[120:121], v[120:121], v[86:87]
	v_add_f32_e32 v89, v121, v88
	v_mul_f32_e32 v88, v121, v121
	v_pk_add_f32 v[86:87], v[88:89], v[86:87] op_sel_hi:[0,1]
	s_waitcnt vmcnt(8)
	v_pk_fma_f32 v[106:107], v[122:123], s[0:1], v[34:35] op_sel_hi:[1,0,1]
	v_pk_fma_f32 v[124:125], v[124:125], s[0:1], v[36:37] op_sel_hi:[1,0,1]
	v_add_f32_e32 v88, v106, v89
	v_pk_fma_f32 v[34:35], v[106:107], v[106:107], v[86:87]
	v_add_f32_e32 v87, v107, v88
	v_mul_f32_e32 v86, v107, v107
	v_add_f32_e32 v36, v124, v87
	v_pk_add_f32 v[34:35], v[86:87], v[34:35] op_sel_hi:[0,1]
	v_add_f32_e32 v36, v125, v36
	v_pk_fma_f32 v[104:105], v[166:167], s[0:1], v[38:39] op_sel_hi:[1,0,1]
	v_pk_fma_f32 v[34:35], v[124:125], v[124:125], v[34:35]
	v_add_f32_e32 v39, v104, v36
	v_mul_f32_e32 v38, v125, v125
	v_mov_b32_e32 v36, v104
	v_mov_b32_e32 v37, v125
	v_pk_add_f32 v[34:35], v[38:39], v[34:35] op_sel_hi:[0,1]
	v_pk_fma_f32 v[34:35], v[36:37], v[36:37], v[34:35]
	v_add_f32_e32 v36, v105, v39
	v_pk_fma_f32 v[122:123], v[168:169], s[0:1], v[40:41] op_sel_hi:[1,0,1]
	v_mul_f32_e32 v38, v105, v105
	v_add_f32_e32 v39, v122, v36
	v_mov_b32_e32 v36, v122
	v_mov_b32_e32 v37, v105
	v_pk_add_f32 v[34:35], v[38:39], v[34:35] op_sel_hi:[0,1]
	v_pk_fma_f32 v[34:35], v[36:37], v[36:37], v[34:35]
	v_add_f32_e32 v36, v123, v39
	v_pk_fma_f32 v[96:97], v[248:249], s[0:1], v[42:43] op_sel_hi:[1,0,1]
	v_mul_f32_e32 v38, v123, v123
	v_add_f32_e32 v39, v96, v36
	v_mov_b32_e32 v36, v96
	v_mov_b32_e32 v37, v123
	v_pk_add_f32 v[34:35], v[38:39], v[34:35] op_sel_hi:[0,1]
	v_pk_fma_f32 v[34:35], v[36:37], v[36:37], v[34:35]
	v_add_f32_e32 v36, v97, v39
	v_pk_fma_f32 v[110:111], v[250:251], s[0:1], v[44:45] op_sel_hi:[1,0,1]
	v_mul_f32_e32 v38, v97, v97
	v_add_f32_e32 v39, v110, v36
	v_mov_b32_e32 v36, v110
	v_mov_b32_e32 v37, v97
	v_pk_add_f32 v[34:35], v[38:39], v[34:35] op_sel_hi:[0,1]
	v_pk_fma_f32 v[102:103], v[114:115], s[0:1], v[46:47] op_sel_hi:[1,0,1]
	v_pk_fma_f32 v[112:113], v[116:117], s[0:1], v[48:49] op_sel_hi:[1,0,1]
	v_pk_fma_f32 v[34:35], v[36:37], v[36:37], v[34:35]
	v_add_f32_e32 v86, v111, v39
	v_mul_f32_e32 v38, v111, v111
	v_mov_b32_e32 v42, v112
	v_mov_b32_e32 v43, v103
	v_mov_b32_e32 v36, v102
	v_mov_b32_e32 v37, v111
	v_pk_add_f32 v[34:35], v[38:39], v[34:35] op_sel_hi:[0,1]
	v_pk_mul_f32 v[114:115], v[112:113], v[112:113]
	s_mov_b64 s[4:5], 0x20100
	v_lshl_add_u64 v[44:45], v[188:189], 0, s[4:5]
	global_load_dwordx4 v[166:169], v[44:45], off offset:48
	global_load_dwordx4 v[244:247], v[44:45], off offset:32
	global_load_dwordx4 v[38:41], v[190:191], off offset:256
	global_load_dwordx4 v[248:251], v[44:45], off offset:16
	v_add_f32_e32 v44, v102, v86
	v_add_f32_e32 v44, v103, v44
	v_add_f32_e32 v114, v112, v44
	s_waitcnt vmcnt(11)
	v_pk_fma_f32 v[92:93], v[194:195], s[0:1], v[66:67] op_sel_hi:[1,0,1]
	v_pk_fma_f32 v[94:95], v[196:197], s[0:1], v[68:69] op_sel_hi:[1,0,1]
	v_add_f32_e32 v44, 0, v92
	v_add_f32_e32 v46, v93, v44
	v_mul_f32_e32 v44, v93, v93
	v_pk_fma_f32 v[44:45], v[92:93], v[92:93], v[44:45] op_sel_hi:[1,1,0]
	v_add_f32_e32 v46, v94, v46
	v_pk_fma_f32 v[44:45], v[94:95], v[94:95], v[44:45]
	v_add_f32_e32 v47, v95, v46
	v_mul_f32_e32 v46, v95, v95
	s_waitcnt vmcnt(8)
; #define RL_LOAD(XV, G) { constexpr int mt__ = (G) >> 2, half__ = ((G) >> 1) & 1, nt__ = (G) & 1; \
;     _Pragma("unroll") for (int gq = 0; gq < 4; ++gq) XV[gq] = *(const f32x4*)(xin + rbase + (size_t)mt__ * 32 * 1024 + half__ * 64 + nt__ * 32 + 4 * gq); }
; #define RL_FOLD(XV, G, SM, SQ) { constexpr int mt__ = (G) >> 2, half__ = ((G) >> 1) & 1, nt__ = (G) & 1; \
;     _Pragma("unroll") for (int gq = 0; gq < 4; ++gq) _Pragma("unroll") for (int jj = 0; jj < 4; ++jj) { \
;       const float y = ALPHA * XV[gq][jj] + acc[half__][nt__][mt__][4 * gq + jj]; acc[half__][nt__][mt__][4 * gq + jj] = y; SM += y; SQ += y * y; } }
; #define SB __builtin_amdgcn_sched_barrier(0)
;   DI void full(const int mt_, const int nt_, f32x16 (&acc)[2][2][2], const int tw, const int fw, const int r, const int hh, char* lds, const int tid) const {
;     ...
;     float sm0 = 0.f, sq0 = 0.f, sm1 = 0.f, sq1 = 0.f;
;     RL_LOAD(xa, 0); RL_LOAD(xc, 1); RL_LOAD(xe, 2); SB;
;     RL_FOLD(xa, 0, sm0, sq0); SB; RL_LOAD(xa, 3); SB;
;     RL_FOLD(xc, 1, sm0, sq0); SB; RL_LOAD(xc, 4); SB;
;     RL_FOLD(xe, 2, sm0, sq0); SB; RL_LOAD(xe, 5); SB;
;     RL_FOLD(xa, 3, sm0, sq0); SB; RL_LOAD(xa, 6); SB;
;     RL_FOLD(xc, 4, sm1, sq1); SB; RL_LOAD(xc, 7); SB;
;     RL_FOLD(xe, 5, sm1, sq1); SB;
;     RL_FOLD(xa, 6, sm1, sq1); SB;
;     RL_FOLD(xc, 7, sm1, sq1);
	v_pk_fma_f32 v[88:89], v[228:229], s[0:1], v[70:71] op_sel_hi:[1,0,1]
	v_pk_add_f32 v[44:45], v[46:47], v[44:45] op_sel_hi:[0,1]
	v_add_f32_e32 v46, v88, v47
	v_pk_fma_f32 v[44:45], v[88:89], v[88:89], v[44:45]
	v_add_f32_e32 v47, v89, v46
	v_mul_f32_e32 v46, v89, v89
	v_pk_fma_f32 v[90:91], v[230:231], s[0:1], v[72:73] op_sel_hi:[1,0,1]
	v_pk_add_f32 v[44:45], v[46:47], v[44:45] op_sel_hi:[0,1]
	v_add_f32_e32 v46, v90, v47
	v_pk_fma_f32 v[44:45], v[90:91], v[90:91], v[44:45]
	v_add_f32_e32 v47, v91, v46
	v_mul_f32_e32 v46, v91, v91
	v_pk_fma_f32 v[86:87], v[202:203], s[0:1], v[74:75] op_sel_hi:[1,0,1]
	v_pk_add_f32 v[44:45], v[46:47], v[44:45] op_sel_hi:[0,1]
	v_add_f32_e32 v46, v86, v47
	v_pk_fma_f32 v[44:45], v[86:87], v[86:87], v[44:45]
	v_add_f32_e32 v47, v87, v46
	v_mul_f32_e32 v46, v87, v87
	v_pk_fma_f32 v[76:77], v[204:205], s[0:1], v[76:77] op_sel_hi:[1,0,1]
	v_pk_add_f32 v[44:45], v[46:47], v[44:45] op_sel_hi:[0,1]
	v_add_f32_e32 v46, v76, v47
	v_pk_fma_f32 v[44:45], v[76:77], v[76:77], v[44:45]
	v_add_f32_e32 v47, v77, v46
	v_mul_f32_e32 v46, v77, v77
	v_pk_fma_f32 v[34:35], v[36:37], v[36:37], v[34:35]
	v_mul_f32_e32 v36, v103, v103
	v_pk_add_f32 v[44:45], v[46:47], v[44:45] op_sel_hi:[0,1]
	v_pk_fma_f32 v[74:75], v[98:99], s[0:1], v[78:79] op_sel_hi:[1,0,1]
	v_pk_fma_f32 v[72:73], v[100:101], s[0:1], v[80:81] op_sel_hi:[1,0,1]
	v_pk_add_f32 v[34:35], v[36:37], v[34:35] op_sel_hi:[0,1]
	v_pk_fma_f32 v[78:79], v[42:43], v[42:43], v[34:35]
	s_mov_b64 s[4:5], 0x20180
	v_lshl_add_u64 v[42:43], v[188:189], 0, s[4:5]
	global_load_dwordx4 v[34:37], v[42:43], off offset:48
	global_load_dwordx4 v[98:101], v[42:43], off offset:32
	s_nop 0
	global_load_dwordx4 v[188:191], v[190:191], off offset:384
	s_nop 0
	global_load_dwordx4 v[194:197], v[42:43], off offset:16
	v_add_f32_e32 v46, v74, v47
	v_pk_fma_f32 v[42:43], v[74:75], v[74:75], v[44:45]
	v_add_f32_e32 v45, v75, v46
	v_mul_f32_e32 v44, v75, v75
	v_pk_add_f32 v[42:43], v[44:45], v[42:43] op_sel_hi:[0,1]
	v_add_f32_e32 v44, v72, v45
	v_pk_fma_f32 v[42:43], v[72:73], v[72:73], v[42:43]
	v_add_f32_e32 v45, v73, v44
	v_mul_f32_e32 v44, v73, v73
	v_pk_add_f32 v[42:43], v[44:45], v[42:43] op_sel_hi:[0,1]
	s_waitcnt vmcnt(9)
	v_pk_fma_f32 v[66:67], v[236:237], s[0:1], v[50:51] op_sel_hi:[1,0,1]
	v_pk_fma_f32 v[70:71], v[238:239], s[0:1], v[52:53] op_sel_hi:[1,0,1]
	v_add_f32_e32 v44, v66, v45
	v_pk_fma_f32 v[42:43], v[66:67], v[66:67], v[42:43]
	v_add_f32_e32 v45, v67, v44
	v_mul_f32_e32 v44, v67, v67
	v_pk_add_f32 v[42:43], v[44:45], v[42:43] op_sel_hi:[0,1]
	v_add_f32_e32 v44, v70, v45
	v_pk_fma_f32 v[42:43], v[70:71], v[70:71], v[42:43]
	v_add_f32_e32 v45, v71, v44
	v_mul_f32_e32 v44, v71, v71
	s_waitcnt vmcnt(8)
	v_pk_fma_f32 v[54:55], v[240:241], s[0:1], v[54:55] op_sel_hi:[1,0,1]
	v_pk_add_f32 v[42:43], v[44:45], v[42:43] op_sel_hi:[0,1]
	v_add_f32_e32 v44, v54, v45
	v_pk_fma_f32 v[42:43], v[54:55], v[54:55], v[42:43]
	v_add_f32_e32 v45, v55, v44
	v_mul_f32_e32 v44, v55, v55
	v_pk_fma_f32 v[68:69], v[242:243], s[0:1], v[56:57] op_sel_hi:[1,0,1]
	v_pk_add_f32 v[42:43], v[44:45], v[42:43] op_sel_hi:[0,1]
	v_add_f32_e32 v44, v68, v45
	v_pk_fma_f32 v[42:43], v[68:69], v[68:69], v[42:43]
	v_add_f32_e32 v45, v69, v44
	v_mul_f32_e32 v44, v69, v69
	v_pk_fma_f32 v[50:51], v[232:233], s[0:1], v[58:59] op_sel_hi:[1,0,1]
	v_pk_add_f32 v[42:43], v[44:45], v[42:43] op_sel_hi:[0,1]
	v_add_f32_e32 v44, v50, v45
	v_pk_fma_f32 v[42:43], v[50:51], v[50:51], v[42:43]
	v_add_f32_e32 v45, v51, v44
	v_mul_f32_e32 v44, v51, v51
	v_pk_fma_f32 v[56:57], v[234:235], s[0:1], v[60:61] op_sel_hi:[1,0,1]
	v_pk_add_f32 v[42:43], v[44:45], v[42:43] op_sel_hi:[0,1]
	v_add_f32_e32 v44, v56, v45
	v_pk_fma_f32 v[42:43], v[56:57], v[56:57], v[42:43]
	v_add_f32_e32 v45, v57, v44
	v_mul_f32_e32 v44, v57, v57
	v_pk_fma_f32 v[48:49], v[82:83], s[0:1], v[62:63] op_sel_hi:[1,0,1]
	v_pk_add_f32 v[42:43], v[44:45], v[42:43] op_sel_hi:[0,1]
	v_add_f32_e32 v44, v48, v45
	v_pk_fma_f32 v[42:43], v[48:49], v[48:49], v[42:43]
	v_add_f32_e32 v45, v49, v44
	v_mul_f32_e32 v44, v49, v49
	v_pk_fma_f32 v[52:53], v[84:85], s[0:1], v[64:65] op_sel_hi:[1,0,1]
	v_pk_add_f32 v[42:43], v[44:45], v[42:43] op_sel_hi:[0,1]
	v_add_f32_e32 v44, v52, v45
	v_pk_fma_f32 v[42:43], v[52:53], v[52:53], v[42:43]
	v_add_f32_e32 v46, v53, v44
	v_mul_f32_e32 v44, v53, v53
	v_pk_add_f32 v[44:45], v[44:45], v[42:43] op_sel_hi:[0,1]
	s_waitcnt vmcnt(5)
	v_pk_fma_f32 v[42:43], v[38:39], s[0:1], v[18:19] op_sel_hi:[1,0,1]
	v_pk_fma_f32 v[26:27], v[244:245], s[0:1], v[26:27] op_sel_hi:[1,0,1]
	v_add_f32_e32 v38, v42, v46
	v_pk_fma_f32 v[18:19], v[42:43], v[42:43], v[44:45]
	v_add_f32_e32 v39, v43, v38
	v_mul_f32_e32 v38, v43, v43
	v_pk_fma_f32 v[46:47], v[40:41], s[0:1], v[20:21] op_sel_hi:[1,0,1]
	v_pk_add_f32 v[18:19], v[38:39], v[18:19] op_sel_hi:[0,1]
	v_add_f32_e32 v20, v46, v39
	v_pk_fma_f32 v[18:19], v[46:47], v[46:47], v[18:19]
	v_add_f32_e32 v21, v47, v20
	v_mul_f32_e32 v20, v47, v47
	s_waitcnt vmcnt(4)
; #define RL_LOAD(XV, G) { constexpr int mt__ = (G) >> 2, half__ = ((G) >> 1) & 1, nt__ = (G) & 1; \
;     _Pragma("unroll") for (int gq = 0; gq < 4; ++gq) XV[gq] = *(const f32x4*)(xin + rbase + (size_t)mt__ * 32 * 1024 + half__ * 64 + nt__ * 32 + 4 * gq); }
; #define RL_FOLD(XV, G, SM, SQ) { constexpr int mt__ = (G) >> 2, half__ = ((G) >> 1) & 1, nt__ = (G) & 1; \
;     _Pragma("unroll") for (int gq = 0; gq < 4; ++gq) _Pragma("unroll") for (int jj = 0; jj < 4; ++jj) { \
;       const float y = ALPHA * XV[gq][jj] + acc[half__][nt__][mt__][4 * gq + jj]; acc[half__][nt__][mt__][4 * gq + jj] = y; SM += y; SQ += y * y; } }
; #define SB __builtin_amdgcn_sched_barrier(0)
;   DI void full(const int mt_, const int nt_, f32x16 (&acc)[2][2][2], const int tw, const int fw, const int r, const int hh, char* lds, const int tid) const {
;     ...
;     float sm0 = 0.f, sq0 = 0.f, sm1 = 0.f, sq1 = 0.f;
;     RL_LOAD(xa, 0); RL_LOAD(xc, 1); RL_LOAD(xe, 2); SB;
;     RL_FOLD(xa, 0, sm0, sq0); SB; RL_LOAD(xa, 3); SB;
;     RL_FOLD(xc, 1, sm0, sq0); SB; RL_LOAD(xc, 4); SB;
;     RL_FOLD(xe, 2, sm0, sq0); SB; RL_LOAD(xe, 5); SB;
;     RL_FOLD(xa, 3, sm0, sq0); SB; RL_LOAD(xa, 6); SB;
;     RL_FOLD(xc, 4, sm1, sq1); SB; RL_LOAD(xc, 7); SB;
;     RL_FOLD(xe, 5, sm1, sq1); SB;
;     RL_FOLD(xa, 6, sm1, sq1); SB;
;     RL_FOLD(xc, 7, sm1, sq1);
;     ...
;     sm0 += __shfl_xor(sm0, 32, 64); sq0 += __shfl_xor(sq0, 32, 64); sm1 += __shfl_xor(sm1, 32, 64); sq1 += __shfl_xor(sq1, 32, 64);
;     if (hh == 0) {
;       float* pp = part + ((fw * 256) + tw * 64 + r) * 2; pp[0] = sm0; pp[1] = sq0;
;       pp[64] = sm1; pp[65] = sq1;
	v_pk_fma_f32 v[38:39], v[248:249], s[0:1], v[22:23] op_sel_hi:[1,0,1]
	v_pk_add_f32 v[18:19], v[20:21], v[18:19] op_sel_hi:[0,1]
	v_add_f32_e32 v20, v38, v21
	v_pk_fma_f32 v[18:19], v[38:39], v[38:39], v[18:19]
	v_add_f32_e32 v21, v39, v20
	v_mul_f32_e32 v20, v39, v39
	v_pk_fma_f32 v[44:45], v[250:251], s[0:1], v[24:25] op_sel_hi:[1,0,1]
	v_pk_add_f32 v[18:19], v[20:21], v[18:19] op_sel_hi:[0,1]
	v_add_f32_e32 v20, v44, v21
	v_pk_fma_f32 v[18:19], v[44:45], v[44:45], v[18:19]
	v_add_f32_e32 v21, v45, v20
	v_mul_f32_e32 v20, v45, v45
	v_pk_add_f32 v[18:19], v[20:21], v[18:19] op_sel_hi:[0,1]
	v_add_f32_e32 v20, v26, v21
	v_pk_fma_f32 v[18:19], v[26:27], v[26:27], v[18:19]
	v_add_f32_e32 v21, v27, v20
	v_mul_f32_e32 v20, v27, v27
	v_pk_fma_f32 v[40:41], v[246:247], s[0:1], v[28:29] op_sel_hi:[1,0,1]
	v_pk_add_f32 v[18:19], v[20:21], v[18:19] op_sel_hi:[0,1]
	v_add_f32_e32 v20, v40, v21
	v_pk_fma_f32 v[18:19], v[40:41], v[40:41], v[18:19]
	v_add_f32_e32 v21, v41, v20
	v_mul_f32_e32 v20, v41, v41
	v_pk_fma_f32 v[24:25], v[166:167], s[0:1], v[30:31] op_sel_hi:[1,0,1]
	v_pk_add_f32 v[18:19], v[20:21], v[18:19] op_sel_hi:[0,1]
	v_add_f32_e32 v20, v24, v21
	v_pk_fma_f32 v[18:19], v[24:25], v[24:25], v[18:19]
	v_add_f32_e32 v21, v25, v20
	v_mul_f32_e32 v20, v25, v25
	v_pk_fma_f32 v[28:29], v[168:169], s[0:1], v[32:33] op_sel_hi:[1,0,1]
	v_pk_add_f32 v[18:19], v[20:21], v[18:19] op_sel_hi:[0,1]
	v_add_f32_e32 v20, v28, v21
	v_pk_fma_f32 v[18:19], v[28:29], v[28:29], v[18:19]
	v_add_f32_e32 v22, v29, v20
	v_mul_f32_e32 v20, v29, v29
	v_pk_add_f32 v[20:21], v[20:21], v[18:19] op_sel_hi:[0,1]
	s_waitcnt vmcnt(1)
	v_pk_fma_f32 v[18:19], v[188:189], s[0:1], v[2:3] op_sel_hi:[1,0,1]
	s_waitcnt vmcnt(0)
	v_pk_fma_f32 v[6:7], v[194:195], s[0:1], v[6:7] op_sel_hi:[1,0,1]
	v_add_f32_e32 v22, v18, v22
	v_pk_fma_f32 v[2:3], v[18:19], v[18:19], v[20:21]
	v_add_f32_e32 v21, v19, v22
	v_pk_fma_f32 v[22:23], v[190:191], s[0:1], v[4:5] op_sel_hi:[1,0,1]
	v_mul_f32_e32 v20, v19, v19
	v_add_f32_e32 v4, v22, v21
	v_pk_add_f32 v[2:3], v[20:21], v[2:3] op_sel_hi:[0,1]
	v_add_f32_e32 v4, v23, v4
	v_pk_fma_f32 v[2:3], v[22:23], v[22:23], v[2:3]
	v_add_f32_e32 v21, v6, v4
	v_mul_f32_e32 v20, v23, v23
	v_mov_b32_e32 v4, v6
	v_mov_b32_e32 v5, v23
	v_pk_add_f32 v[2:3], v[20:21], v[2:3] op_sel_hi:[0,1]
	v_pk_fma_f32 v[2:3], v[4:5], v[4:5], v[2:3]
	v_add_f32_e32 v4, v7, v21
	v_pk_fma_f32 v[20:21], v[196:197], s[0:1], v[8:9] op_sel_hi:[1,0,1]
	v_mul_f32_e32 v8, v7, v7
	v_add_f32_e32 v9, v20, v4
	v_mov_b32_e32 v4, v20
	v_mov_b32_e32 v5, v7
	v_pk_add_f32 v[2:3], v[8:9], v[2:3] op_sel_hi:[0,1]
	v_pk_fma_f32 v[4:5], v[4:5], v[4:5], v[2:3]
	v_add_f32_e32 v8, v21, v9
	v_pk_fma_f32 v[2:3], v[98:99], s[0:1], v[10:11] op_sel_hi:[1,0,1]
	v_mul_f32_e32 v10, v21, v21
	v_add_f32_e32 v11, v2, v8
	v_mov_b32_e32 v8, v2
	v_mov_b32_e32 v9, v21
	v_pk_add_f32 v[4:5], v[10:11], v[4:5] op_sel_hi:[0,1]
	v_pk_fma_f32 v[4:5], v[8:9], v[8:9], v[4:5]
	v_add_f32_e32 v10, v3, v11
	v_pk_fma_f32 v[8:9], v[100:101], s[0:1], v[12:13] op_sel_hi:[1,0,1]
	v_mul_f32_e32 v12, v3, v3
	v_add_f32_e32 v13, v8, v10
	v_mov_b32_e32 v10, v8
	v_mov_b32_e32 v11, v3
	v_pk_add_f32 v[4:5], v[12:13], v[4:5] op_sel_hi:[0,1]
	v_pk_fma_f32 v[10:11], v[10:11], v[10:11], v[4:5]
	v_add_f32_e32 v12, v9, v13
	v_pk_fma_f32 v[4:5], v[34:35], s[0:1], v[14:15] op_sel_hi:[1,0,1]
	v_mul_f32_e32 v14, v9, v9
	v_add_f32_e32 v15, v4, v12
	v_mov_b32_e32 v12, v4
	v_mov_b32_e32 v13, v9
	v_pk_add_f32 v[10:11], v[14:15], v[10:11] op_sel_hi:[0,1]
	v_pk_fma_f32 v[12:13], v[12:13], v[12:13], v[10:11]
	v_pk_fma_f32 v[10:11], v[36:37], s[0:1], v[16:17] op_sel_hi:[1,0,1]
	v_mul_f32_e32 v30, v5, v5
	v_mov_b32_e32 v16, v10
	v_mov_b32_e32 v17, v5
	v_pk_add_f32 v[12:13], v[30:31], v[12:13] op_sel_hi:[0,1]
	v_pk_fma_f32 v[12:13], v[16:17], v[16:17], v[12:13]
	v_pk_mul_f32 v[16:17], v[10:11], v[10:11]
	v_add_f32_e32 v14, v5, v15
	v_mov_b32_e32 v15, v17
	v_and_b32_e32 v17, 64, v201
	v_xor_b32_e32 v16, 32, v201
	v_add_u32_e32 v17, 64, v17
	v_add_f32_e32 v14, v10, v14
	v_pk_mov_b32 v[12:13], v[10:11], v[12:13] op_sel:[1,0]
	v_cmp_lt_i32_e32 vcc, v16, v17
	v_pk_add_f32 v[12:13], v[12:13], v[14:15]
	v_pk_mov_b32 v[14:15], v[112:113], v[78:79] op_sel:[1,0]
	v_cndmask_b32_e32 v16, v201, v16, vcc
	v_pk_add_f32 v[14:15], v[14:15], v[114:115]
	v_lshlrev_b32_e32 v31, 2, v16
	ds_bpermute_b32 v16, v31, v14
	ds_bpermute_b32 v17, v31, v15
	ds_bpermute_b32 v30, v31, v12
	ds_bpermute_b32 v31, v31, v13
	v_cmp_eq_u32_e32 vcc, 0, v226
	s_and_saveexec_b64 s[4:5], vcc
	s_cbranch_execz .LBB0_772
	v_lshlrev_b32_e32 v32, 3, v186
	v_and_b32_e32 v32, 0xfffffef8, v32
	v_add_u32_e32 v32, 0, v32
	v_add_u32_e32 v32, 0x12000, v32
	s_waitcnt lgkmcnt(2)
	v_pk_add_f32 v[14:15], v[14:15], v[16:17]
	s_waitcnt lgkmcnt(0)
	v_pk_add_f32 v[12:13], v[12:13], v[30:31]
	ds_write2_b64 v32, v[14:15], v[12:13] offset1:32
